# v033 plus the mid-segment s_setprio 0/1 flip pairs between the two 16-MFMA groups removed (80 sites)
# speedup vs baseline: 1.0251x; 1.0040x over previous
.LBB0_504:
	s_mov_b32 s39, 0
	s_mov_b64 s[66:67], -1
	s_mov_b64 s[72:73], 0
	s_add_u32 s20, s62, s39
	s_addc_u32 s21, s63, 0
	s_add_u32 s22, s20, 0x100
	s_addc_u32 s23, s21, 0
	s_and_b64 s[18:19], s[72:73], exec
	s_cselect_b32 vcc_hi, s49, s23
	s_cselect_b32 vcc_lo, s48, s22
	s_add_u32 s18, s60, s39
	s_addc_u32 s19, s61, 0
	s_add_u32 s22, s18, 0x100
	s_addc_u32 s23, s19, 0
	s_add_i32 s24, 0, 0x10000
	s_and_b64 s[18:19], s[72:73], exec
	s_cselect_b32 s51, s59, s23
	s_cselect_b32 s50, s58, s22
	s_add_i32 s22, 0, 0x14000
	s_add_u32 s64, s20, 0x40080
	s_addc_u32 s65, s21, 0
	s_add_i32 s21, s24, s69
	s_add_i32 m0, s4, 0xc000
	s_add_i32 s25, s4, 0xe000
	s_add_i32 s18, s21, 0x2000
	s_add_u32 s78, s50, 0x10000
	v_add_u32_e32 v140, s24, v170
	v_add_u32_e32 v162, s22, v170
	s_addc_u32 s79, s51, 0
	s_add_i32 s19, s22, s69
	ds_read_b128 v[128:131], v140
	ds_read_b128 v[132:135], v140 offset:1024
	ds_read_b128 v[136:139], v140 offset:2048
	ds_read_b128 v[140:143], v140 offset:3072
	ds_read_b128 v[152:155], v162
	ds_read_b128 v[156:159], v162 offset:1024
	ds_read_b128 v[164:167], v162 offset:2048
	ds_read_b128 v[172:175], v162 offset:3072
	s_add_i32 s20, s19, 0x2000
	s_add_i32 s54, 0, 0x18000
	s_add_i32 s43, 0, 0x1c000
	s_add_u32 s74, vcc_lo, 0x40000
	s_addc_u32 s75, vcc_hi, 0
	s_add_i32 s41, s54, s69
	s_add_i32 s39, s41, 0x2000
	s_add_u32 s72, s50, 0x10080
	s_addc_u32 s73, s51, 0
	s_add_i32 s23, s43, s69
	s_add_i32 s22, s23, 0x2000
	v_lshl_add_u64 v[200:201], s[64:65], 0, v[150:151]
	ds_read_b128 v[176:179], v171
	ds_read_b128 v[180:183], v171 offset:1024
	ds_read_b128 v[184:187], v171 offset:2048
	ds_read_b128 v[188:191], v171 offset:3072
	ds_read_b128 v[192:195], v171 offset:4096
	ds_read_b128 v[196:199], v171 offset:5120
	ds_read_b128 v[206:209], v171 offset:6144
	ds_read_b128 v[210:213], v171 offset:7168
	global_load_lds_dwordx4 v[200:201], off
	v_lshl_add_u64 v[200:201], s[64:65], 0, v[146:147]
	s_mov_b32 m0, s25
	s_nop 0
	global_load_lds_dwordx4 v[200:201], off
	s_waitcnt vmcnt(8)
	s_waitcnt lgkmcnt(0)
	s_setprio 1
	s_barrier
	v_mfma_f32_16x16x32_bf16 v[124:127], v[128:131], v[176:179], 0
	v_mfma_f32_16x16x32_bf16 v[120:123], v[136:139], v[176:179], 0
	v_mfma_f32_16x16x32_bf16 v[112:115], v[128:131], v[184:187], 0
	v_mfma_f32_16x16x32_bf16 v[104:107], v[136:139], v[184:187], 0
	v_mfma_f32_16x16x32_bf16 v[96:99], v[128:131], v[192:195], 0
	v_mfma_f32_16x16x32_bf16 v[88:91], v[136:139], v[192:195], 0
	v_mfma_f32_16x16x32_bf16 v[80:83], v[128:131], v[206:209], 0
	v_mfma_f32_16x16x32_bf16 v[72:75], v[136:139], v[206:209], 0
	v_mfma_f32_16x16x32_bf16 v[124:127], v[132:135], v[180:183], v[124:127]
	v_mfma_f32_16x16x32_bf16 v[120:123], v[140:143], v[180:183], v[120:123]
	v_mfma_f32_16x16x32_bf16 v[112:115], v[132:135], v[188:191], v[112:115]
	v_mfma_f32_16x16x32_bf16 v[104:107], v[140:143], v[188:191], v[104:107]
	v_mfma_f32_16x16x32_bf16 v[96:99], v[132:135], v[196:199], v[96:99]
	v_mfma_f32_16x16x32_bf16 v[88:91], v[140:143], v[196:199], v[88:91]
	v_mfma_f32_16x16x32_bf16 v[80:83], v[132:135], v[210:213], v[80:83]
	v_mfma_f32_16x16x32_bf16 v[72:75], v[140:143], v[210:213], v[72:75]
	v_mfma_f32_16x16x32_bf16 v[116:119], v[152:155], v[176:179], 0
	v_mfma_f32_16x16x32_bf16 v[108:111], v[164:167], v[176:179], 0
	v_mfma_f32_16x16x32_bf16 v[100:103], v[152:155], v[184:187], 0
	v_mfma_f32_16x16x32_bf16 v[92:95], v[164:167], v[184:187], 0
	v_mfma_f32_16x16x32_bf16 v[84:87], v[152:155], v[192:195], 0
	v_mfma_f32_16x16x32_bf16 v[76:79], v[164:167], v[192:195], 0
	v_mfma_f32_16x16x32_bf16 v[68:71], v[152:155], v[206:209], 0
	v_mfma_f32_16x16x32_bf16 v[64:67], v[164:167], v[206:209], 0
	v_mfma_f32_16x16x32_bf16 v[116:119], v[156:159], v[180:183], v[116:119]
	v_mfma_f32_16x16x32_bf16 v[108:111], v[172:175], v[180:183], v[108:111]
	v_mfma_f32_16x16x32_bf16 v[100:103], v[156:159], v[188:191], v[100:103]
	v_mfma_f32_16x16x32_bf16 v[92:95], v[172:175], v[188:191], v[92:95]
	v_mfma_f32_16x16x32_bf16 v[84:87], v[156:159], v[196:199], v[84:87]
	v_mfma_f32_16x16x32_bf16 v[76:79], v[172:175], v[196:199], v[76:79]
	v_mfma_f32_16x16x32_bf16 v[68:71], v[156:159], v[210:213], v[68:71]
	v_mfma_f32_16x16x32_bf16 v[64:67], v[172:175], v[210:213], v[64:67]
	s_barrier
	s_setprio 0
	s_mov_b32 m0, s21
	v_lshl_add_u64 v[200:201], s[50:51], 0, v[148:149]
	ds_read_b128 v[176:179], v171 offset:16384
	ds_read_b128 v[180:183], v171 offset:17408
	ds_read_b128 v[184:187], v171 offset:18432
	ds_read_b128 v[188:191], v171 offset:19456
	ds_read_b128 v[192:195], v171 offset:20480
	ds_read_b128 v[196:199], v171 offset:21504
	ds_read_b128 v[206:209], v171 offset:22528
	ds_read_b128 v[210:213], v171 offset:23552
	global_load_lds_dwordx4 v[200:201], off
	v_lshl_add_u64 v[214:215], s[50:51], 0, v[144:145]
	s_mov_b32 m0, s18
	v_lshl_add_u64 v[216:217], s[78:79], 0, v[148:149]
	global_load_lds_dwordx4 v[214:215], off
	s_mov_b32 m0, s19
	v_lshl_add_u64 v[218:219], vcc, 0, v[146:147]
	global_load_lds_dwordx4 v[216:217], off
	v_lshl_add_u64 v[216:217], s[78:79], 0, v[144:145]
	s_mov_b32 m0, s20
	s_nop 0
	global_load_lds_dwordx4 v[216:217], off
	v_lshl_add_u64 v[216:217], vcc, 0, v[150:151]
	s_mov_b32 m0, s4
	s_nop 0
	global_load_lds_dwordx4 v[216:217], off
	s_mov_b32 m0, s5
	s_nop 0
	global_load_lds_dwordx4 v[218:219], off
	s_waitcnt vmcnt(8)
	s_waitcnt lgkmcnt(0)
	s_setprio 1
	s_barrier
	v_mfma_f32_16x16x32_bf16 v[60:63], v[128:131], v[176:179], 0
	v_mfma_f32_16x16x32_bf16 v[56:59], v[136:139], v[176:179], 0
	v_mfma_f32_16x16x32_bf16 v[48:51], v[128:131], v[184:187], 0
	v_mfma_f32_16x16x32_bf16 v[40:43], v[136:139], v[184:187], 0
	v_mfma_f32_16x16x32_bf16 v[32:35], v[128:131], v[192:195], 0
	v_mfma_f32_16x16x32_bf16 v[24:27], v[136:139], v[192:195], 0
	v_mfma_f32_16x16x32_bf16 v[16:19], v[128:131], v[206:209], 0
	v_mfma_f32_16x16x32_bf16 v[8:11], v[136:139], v[206:209], 0
	v_mfma_f32_16x16x32_bf16 v[60:63], v[132:135], v[180:183], v[60:63]
	v_mfma_f32_16x16x32_bf16 v[56:59], v[140:143], v[180:183], v[56:59]
	v_mfma_f32_16x16x32_bf16 v[48:51], v[132:135], v[188:191], v[48:51]
	v_mfma_f32_16x16x32_bf16 v[40:43], v[140:143], v[188:191], v[40:43]
	v_mfma_f32_16x16x32_bf16 v[32:35], v[132:135], v[196:199], v[32:35]
	v_mfma_f32_16x16x32_bf16 v[24:27], v[140:143], v[196:199], v[24:27]
	v_mfma_f32_16x16x32_bf16 v[16:19], v[132:135], v[210:213], v[16:19]
	v_mfma_f32_16x16x32_bf16 v[8:11], v[140:143], v[210:213], v[8:11]
	v_mfma_f32_16x16x32_bf16 v[52:55], v[152:155], v[176:179], 0
	v_mfma_f32_16x16x32_bf16 v[44:47], v[164:167], v[176:179], 0
	v_mfma_f32_16x16x32_bf16 v[36:39], v[152:155], v[184:187], 0
	v_mfma_f32_16x16x32_bf16 v[28:31], v[164:167], v[184:187], 0
	v_mfma_f32_16x16x32_bf16 v[20:23], v[152:155], v[192:195], 0
	v_mfma_f32_16x16x32_bf16 v[12:15], v[164:167], v[192:195], 0
	v_mfma_f32_16x16x32_bf16 v[4:7], v[152:155], v[206:209], 0
	v_mfma_f32_16x16x32_bf16 v[0:3], v[164:167], v[206:209], 0
	v_mfma_f32_16x16x32_bf16 v[52:55], v[156:159], v[180:183], v[52:55]
	v_mfma_f32_16x16x32_bf16 v[44:47], v[172:175], v[180:183], v[44:47]
	v_mfma_f32_16x16x32_bf16 v[36:39], v[156:159], v[188:191], v[36:39]
	v_mfma_f32_16x16x32_bf16 v[28:31], v[172:175], v[188:191], v[28:31]
	v_mfma_f32_16x16x32_bf16 v[20:23], v[156:159], v[196:199], v[20:23]
	v_mfma_f32_16x16x32_bf16 v[12:15], v[172:175], v[196:199], v[12:15]
	v_mfma_f32_16x16x32_bf16 v[4:7], v[156:159], v[210:213], v[4:7]
	v_mfma_f32_16x16x32_bf16 v[0:3], v[172:175], v[210:213], v[0:3]
	s_barrier
	s_setprio 0
	v_add_u32_e32 v140, s54, v170
	v_add_u32_e32 v162, s43, v170
	ds_read_b128 v[128:131], v140
	ds_read_b128 v[132:135], v140 offset:1024
	ds_read_b128 v[136:139], v140 offset:2048
	ds_read_b128 v[140:143], v140 offset:3072
	ds_read_b128 v[152:155], v162
	ds_read_b128 v[156:159], v162 offset:1024
	ds_read_b128 v[164:167], v162 offset:2048
	ds_read_b128 v[172:175], v162 offset:3072
	s_mov_b32 m0, s6
	v_lshl_add_u64 v[220:221], s[74:75], 0, v[150:151]
	ds_read_b128 v[176:179], v171 offset:32768
	ds_read_b128 v[180:183], v171 offset:33792
	ds_read_b128 v[184:187], v171 offset:34816
	ds_read_b128 v[188:191], v171 offset:35840
	ds_read_b128 v[192:195], v171 offset:36864
	ds_read_b128 v[196:199], v171 offset:37888
	ds_read_b128 v[206:209], v171 offset:38912
	ds_read_b128 v[210:213], v171 offset:39936
	global_load_lds_dwordx4 v[220:221], off
	v_lshl_add_u64 v[220:221], s[74:75], 0, v[146:147]
	s_mov_b32 m0, s7
	s_nop 0
	global_load_lds_dwordx4 v[220:221], off
	s_waitcnt vmcnt(8)
	s_waitcnt lgkmcnt(0)
	s_setprio 1
	s_barrier
	v_mfma_f32_16x16x32_bf16 v[124:127], v[128:131], v[176:179], v[124:127]
	v_mfma_f32_16x16x32_bf16 v[120:123], v[136:139], v[176:179], v[120:123]
	v_mfma_f32_16x16x32_bf16 v[112:115], v[128:131], v[184:187], v[112:115]
	v_mfma_f32_16x16x32_bf16 v[104:107], v[136:139], v[184:187], v[104:107]
	v_mfma_f32_16x16x32_bf16 v[96:99], v[128:131], v[192:195], v[96:99]
	v_mfma_f32_16x16x32_bf16 v[88:91], v[136:139], v[192:195], v[88:91]
	v_mfma_f32_16x16x32_bf16 v[80:83], v[128:131], v[206:209], v[80:83]
	v_mfma_f32_16x16x32_bf16 v[72:75], v[136:139], v[206:209], v[72:75]
	v_mfma_f32_16x16x32_bf16 v[124:127], v[132:135], v[180:183], v[124:127]
	v_mfma_f32_16x16x32_bf16 v[120:123], v[140:143], v[180:183], v[120:123]
	v_mfma_f32_16x16x32_bf16 v[112:115], v[132:135], v[188:191], v[112:115]
	v_mfma_f32_16x16x32_bf16 v[104:107], v[140:143], v[188:191], v[104:107]
	v_mfma_f32_16x16x32_bf16 v[96:99], v[132:135], v[196:199], v[96:99]
	v_mfma_f32_16x16x32_bf16 v[88:91], v[140:143], v[196:199], v[88:91]
	v_mfma_f32_16x16x32_bf16 v[80:83], v[132:135], v[210:213], v[80:83]
	v_mfma_f32_16x16x32_bf16 v[72:75], v[140:143], v[210:213], v[72:75]
	v_mfma_f32_16x16x32_bf16 v[116:119], v[152:155], v[176:179], v[116:119]
	v_mfma_f32_16x16x32_bf16 v[108:111], v[164:167], v[176:179], v[108:111]
	v_mfma_f32_16x16x32_bf16 v[100:103], v[152:155], v[184:187], v[100:103]
	v_mfma_f32_16x16x32_bf16 v[92:95], v[164:167], v[184:187], v[92:95]
	v_mfma_f32_16x16x32_bf16 v[84:87], v[152:155], v[192:195], v[84:87]
	v_mfma_f32_16x16x32_bf16 v[76:79], v[164:167], v[192:195], v[76:79]
	v_mfma_f32_16x16x32_bf16 v[68:71], v[152:155], v[206:209], v[68:71]
	v_mfma_f32_16x16x32_bf16 v[64:67], v[164:167], v[206:209], v[64:67]
	v_mfma_f32_16x16x32_bf16 v[116:119], v[156:159], v[180:183], v[116:119]
	v_mfma_f32_16x16x32_bf16 v[108:111], v[172:175], v[180:183], v[108:111]
	v_mfma_f32_16x16x32_bf16 v[100:103], v[156:159], v[188:191], v[100:103]
	v_mfma_f32_16x16x32_bf16 v[92:95], v[172:175], v[188:191], v[92:95]
	v_mfma_f32_16x16x32_bf16 v[84:87], v[156:159], v[196:199], v[84:87]
	v_mfma_f32_16x16x32_bf16 v[76:79], v[172:175], v[196:199], v[76:79]
	v_mfma_f32_16x16x32_bf16 v[68:71], v[156:159], v[210:213], v[68:71]
	v_mfma_f32_16x16x32_bf16 v[64:67], v[172:175], v[210:213], v[64:67]
	s_barrier
	s_setprio 0
	s_mov_b32 m0, s41
	v_lshl_add_u64 v[200:201], v[200:201], 0, s[76:77]
	ds_read_b128 v[176:179], v171 offset:49152
	ds_read_b128 v[180:183], v171 offset:50176
	ds_read_b128 v[184:187], v171 offset:51200
	ds_read_b128 v[188:191], v171 offset:52224
	ds_read_b128 v[192:195], v171 offset:53248
	ds_read_b128 v[196:199], v171 offset:54272
	ds_read_b128 v[206:209], v171 offset:55296
	ds_read_b128 v[210:213], v171 offset:56320
	global_load_lds_dwordx4 v[200:201], off
	v_lshl_add_u64 v[200:201], v[214:215], 0, s[76:77]
	s_mov_b32 m0, s39
	s_nop 0
	global_load_lds_dwordx4 v[200:201], off
	v_lshl_add_u64 v[200:201], s[72:73], 0, v[148:149]
	s_mov_b32 m0, s23
	s_nop 0
	global_load_lds_dwordx4 v[200:201], off
	v_lshl_add_u64 v[200:201], s[72:73], 0, v[144:145]
	s_mov_b32 m0, s22
	s_nop 0
	global_load_lds_dwordx4 v[200:201], off
	v_lshl_add_u64 v[200:201], v[216:217], 0, s[76:77]
	s_mov_b32 m0, s11
	s_nop 0
	global_load_lds_dwordx4 v[200:201], off
	v_lshl_add_u64 v[200:201], v[218:219], 0, s[76:77]
	s_mov_b32 m0, s12
	s_nop 0
	global_load_lds_dwordx4 v[200:201], off
	s_waitcnt vmcnt(8)
	s_waitcnt lgkmcnt(0)
	s_setprio 1
	s_barrier
	v_mfma_f32_16x16x32_bf16 v[60:63], v[128:131], v[176:179], v[60:63]
	v_mfma_f32_16x16x32_bf16 v[56:59], v[136:139], v[176:179], v[56:59]
	v_mfma_f32_16x16x32_bf16 v[48:51], v[128:131], v[184:187], v[48:51]
	v_mfma_f32_16x16x32_bf16 v[40:43], v[136:139], v[184:187], v[40:43]
	v_mfma_f32_16x16x32_bf16 v[32:35], v[128:131], v[192:195], v[32:35]
	v_mfma_f32_16x16x32_bf16 v[24:27], v[136:139], v[192:195], v[24:27]
	v_mfma_f32_16x16x32_bf16 v[16:19], v[128:131], v[206:209], v[16:19]
	v_mfma_f32_16x16x32_bf16 v[8:11], v[136:139], v[206:209], v[8:11]
	v_mfma_f32_16x16x32_bf16 v[60:63], v[132:135], v[180:183], v[60:63]
	v_mfma_f32_16x16x32_bf16 v[56:59], v[140:143], v[180:183], v[56:59]
	v_mfma_f32_16x16x32_bf16 v[48:51], v[132:135], v[188:191], v[48:51]
	v_mfma_f32_16x16x32_bf16 v[40:43], v[140:143], v[188:191], v[40:43]
	v_mfma_f32_16x16x32_bf16 v[32:35], v[132:135], v[196:199], v[32:35]
	v_mfma_f32_16x16x32_bf16 v[24:27], v[140:143], v[196:199], v[24:27]
	v_mfma_f32_16x16x32_bf16 v[16:19], v[132:135], v[210:213], v[16:19]
	v_mfma_f32_16x16x32_bf16 v[8:11], v[140:143], v[210:213], v[8:11]
	v_mfma_f32_16x16x32_bf16 v[52:55], v[152:155], v[176:179], v[52:55]
	v_mfma_f32_16x16x32_bf16 v[44:47], v[164:167], v[176:179], v[44:47]
	v_mfma_f32_16x16x32_bf16 v[36:39], v[152:155], v[184:187], v[36:39]
	v_mfma_f32_16x16x32_bf16 v[28:31], v[164:167], v[184:187], v[28:31]
	v_mfma_f32_16x16x32_bf16 v[20:23], v[152:155], v[192:195], v[20:23]
	v_mfma_f32_16x16x32_bf16 v[12:15], v[164:167], v[192:195], v[12:15]
	v_mfma_f32_16x16x32_bf16 v[4:7], v[152:155], v[206:209], v[4:7]
	v_mfma_f32_16x16x32_bf16 v[0:3], v[164:167], v[206:209], v[0:3]
	v_mfma_f32_16x16x32_bf16 v[52:55], v[156:159], v[180:183], v[52:55]
	v_mfma_f32_16x16x32_bf16 v[44:47], v[172:175], v[180:183], v[44:47]
	v_mfma_f32_16x16x32_bf16 v[36:39], v[156:159], v[188:191], v[36:39]
	v_mfma_f32_16x16x32_bf16 v[28:31], v[172:175], v[188:191], v[28:31]
	v_mfma_f32_16x16x32_bf16 v[20:23], v[156:159], v[196:199], v[20:23]
	v_mfma_f32_16x16x32_bf16 v[12:15], v[172:175], v[196:199], v[12:15]
	v_mfma_f32_16x16x32_bf16 v[4:7], v[156:159], v[210:213], v[4:7]
	v_mfma_f32_16x16x32_bf16 v[0:3], v[172:175], v[210:213], v[0:3]
	s_barrier
	s_setprio 0
	s_movk_i32 s39, 0x100
	s_andn2_b64 vcc, exec, s[66:67]
	s_mov_b64 s[72:73], -1
	s_mov_b64 s[66:67], 0
	s_cbranch_vccz .LBB0_505
	s_branch .Lpeel_x_505
.LBB0_505:
	s_add_u32 s20, s62, s39
	s_addc_u32 s21, s63, 0
	s_add_u32 s22, s20, 0x100
	s_addc_u32 s23, s21, 0
	s_and_b64 s[18:19], s[72:73], exec
	s_cselect_b32 vcc_hi, s49, s23
	s_cselect_b32 vcc_lo, s48, s22
	s_add_u32 s18, s60, s39
	s_addc_u32 s19, s61, 0
	s_add_u32 s22, s18, 0x100
	s_addc_u32 s23, s19, 0
	s_add_i32 s24, 0, 0x10000
	s_and_b64 s[18:19], s[72:73], exec
	s_cselect_b32 s51, s59, s23
	s_cselect_b32 s50, s58, s22
	s_add_i32 s22, 0, 0x14000
	s_add_u32 s64, s20, 0x40080
	s_addc_u32 s65, s21, 0
	s_add_i32 s21, s24, s69
	s_add_i32 m0, s4, 0xc000
	s_add_i32 s25, s4, 0xe000
	s_add_i32 s18, s21, 0x2000
	s_add_u32 s78, s50, 0x10000
	v_add_u32_e32 v140, s24, v170
	v_add_u32_e32 v162, s22, v170
	s_addc_u32 s79, s51, 0
	s_add_i32 s19, s22, s69
	ds_read_b128 v[128:131], v140
	ds_read_b128 v[132:135], v140 offset:1024
	ds_read_b128 v[136:139], v140 offset:2048
	ds_read_b128 v[140:143], v140 offset:3072
	ds_read_b128 v[152:155], v162
	ds_read_b128 v[156:159], v162 offset:1024
	ds_read_b128 v[164:167], v162 offset:2048
	ds_read_b128 v[172:175], v162 offset:3072
	s_add_i32 s20, s19, 0x2000
	s_add_i32 s54, 0, 0x18000
	s_add_i32 s43, 0, 0x1c000
	s_add_u32 s74, vcc_lo, 0x40000
	s_addc_u32 s75, vcc_hi, 0
	s_add_i32 s41, s54, s69
	s_add_i32 s39, s41, 0x2000
	s_add_u32 s72, s50, 0x10080
	s_addc_u32 s73, s51, 0
	s_add_i32 s23, s43, s69
	s_add_i32 s22, s23, 0x2000
	v_lshl_add_u64 v[200:201], s[64:65], 0, v[150:151]
	ds_read_b128 v[176:179], v171
	ds_read_b128 v[180:183], v171 offset:1024
	ds_read_b128 v[184:187], v171 offset:2048
	ds_read_b128 v[188:191], v171 offset:3072
	ds_read_b128 v[192:195], v171 offset:4096
	ds_read_b128 v[196:199], v171 offset:5120
	ds_read_b128 v[206:209], v171 offset:6144
	ds_read_b128 v[210:213], v171 offset:7168
	global_load_lds_dwordx4 v[200:201], off
	v_lshl_add_u64 v[200:201], s[64:65], 0, v[146:147]
	s_mov_b32 m0, s25
	s_nop 0
	global_load_lds_dwordx4 v[200:201], off
	s_waitcnt vmcnt(8)
	s_waitcnt lgkmcnt(0)
	s_setprio 1
	s_barrier
	v_mfma_f32_16x16x32_bf16 v[124:127], v[128:131], v[176:179], v[124:127]
	v_mfma_f32_16x16x32_bf16 v[120:123], v[136:139], v[176:179], v[120:123]
	v_mfma_f32_16x16x32_bf16 v[112:115], v[128:131], v[184:187], v[112:115]
	v_mfma_f32_16x16x32_bf16 v[104:107], v[136:139], v[184:187], v[104:107]
	v_mfma_f32_16x16x32_bf16 v[96:99], v[128:131], v[192:195], v[96:99]
	v_mfma_f32_16x16x32_bf16 v[88:91], v[136:139], v[192:195], v[88:91]
	v_mfma_f32_16x16x32_bf16 v[80:83], v[128:131], v[206:209], v[80:83]
	v_mfma_f32_16x16x32_bf16 v[72:75], v[136:139], v[206:209], v[72:75]
	v_mfma_f32_16x16x32_bf16 v[124:127], v[132:135], v[180:183], v[124:127]
	v_mfma_f32_16x16x32_bf16 v[120:123], v[140:143], v[180:183], v[120:123]
	v_mfma_f32_16x16x32_bf16 v[112:115], v[132:135], v[188:191], v[112:115]
	v_mfma_f32_16x16x32_bf16 v[104:107], v[140:143], v[188:191], v[104:107]
	v_mfma_f32_16x16x32_bf16 v[96:99], v[132:135], v[196:199], v[96:99]
	v_mfma_f32_16x16x32_bf16 v[88:91], v[140:143], v[196:199], v[88:91]
	v_mfma_f32_16x16x32_bf16 v[80:83], v[132:135], v[210:213], v[80:83]
	v_mfma_f32_16x16x32_bf16 v[72:75], v[140:143], v[210:213], v[72:75]
	v_mfma_f32_16x16x32_bf16 v[116:119], v[152:155], v[176:179], v[116:119]
	v_mfma_f32_16x16x32_bf16 v[108:111], v[164:167], v[176:179], v[108:111]
	v_mfma_f32_16x16x32_bf16 v[100:103], v[152:155], v[184:187], v[100:103]
	v_mfma_f32_16x16x32_bf16 v[92:95], v[164:167], v[184:187], v[92:95]
	v_mfma_f32_16x16x32_bf16 v[84:87], v[152:155], v[192:195], v[84:87]
	v_mfma_f32_16x16x32_bf16 v[76:79], v[164:167], v[192:195], v[76:79]
	v_mfma_f32_16x16x32_bf16 v[68:71], v[152:155], v[206:209], v[68:71]
	v_mfma_f32_16x16x32_bf16 v[64:67], v[164:167], v[206:209], v[64:67]
	v_mfma_f32_16x16x32_bf16 v[116:119], v[156:159], v[180:183], v[116:119]
	v_mfma_f32_16x16x32_bf16 v[108:111], v[172:175], v[180:183], v[108:111]
	v_mfma_f32_16x16x32_bf16 v[100:103], v[156:159], v[188:191], v[100:103]
	v_mfma_f32_16x16x32_bf16 v[92:95], v[172:175], v[188:191], v[92:95]
	v_mfma_f32_16x16x32_bf16 v[84:87], v[156:159], v[196:199], v[84:87]
	v_mfma_f32_16x16x32_bf16 v[76:79], v[172:175], v[196:199], v[76:79]
	v_mfma_f32_16x16x32_bf16 v[68:71], v[156:159], v[210:213], v[68:71]
	v_mfma_f32_16x16x32_bf16 v[64:67], v[172:175], v[210:213], v[64:67]
	s_barrier
	s_setprio 0
	s_mov_b32 m0, s21
	v_lshl_add_u64 v[200:201], s[50:51], 0, v[148:149]
	ds_read_b128 v[176:179], v171 offset:16384
	ds_read_b128 v[180:183], v171 offset:17408
	ds_read_b128 v[184:187], v171 offset:18432
	ds_read_b128 v[188:191], v171 offset:19456
	ds_read_b128 v[192:195], v171 offset:20480
	ds_read_b128 v[196:199], v171 offset:21504
	ds_read_b128 v[206:209], v171 offset:22528
	ds_read_b128 v[210:213], v171 offset:23552
	global_load_lds_dwordx4 v[200:201], off
	v_lshl_add_u64 v[214:215], s[50:51], 0, v[144:145]
	s_mov_b32 m0, s18
	v_lshl_add_u64 v[216:217], s[78:79], 0, v[148:149]
	global_load_lds_dwordx4 v[214:215], off
	s_mov_b32 m0, s19
	v_lshl_add_u64 v[218:219], vcc, 0, v[146:147]
	global_load_lds_dwordx4 v[216:217], off
	v_lshl_add_u64 v[216:217], s[78:79], 0, v[144:145]
	s_mov_b32 m0, s20
	s_nop 0
	global_load_lds_dwordx4 v[216:217], off
	v_lshl_add_u64 v[216:217], vcc, 0, v[150:151]
	s_mov_b32 m0, s4
	s_nop 0
	global_load_lds_dwordx4 v[216:217], off
	s_mov_b32 m0, s5
	s_nop 0
	global_load_lds_dwordx4 v[218:219], off
	s_waitcnt vmcnt(8)
	s_waitcnt lgkmcnt(0)
	s_setprio 1
	s_barrier
	v_mfma_f32_16x16x32_bf16 v[60:63], v[128:131], v[176:179], v[60:63]
	v_mfma_f32_16x16x32_bf16 v[56:59], v[136:139], v[176:179], v[56:59]
	v_mfma_f32_16x16x32_bf16 v[48:51], v[128:131], v[184:187], v[48:51]
	v_mfma_f32_16x16x32_bf16 v[40:43], v[136:139], v[184:187], v[40:43]
	v_mfma_f32_16x16x32_bf16 v[32:35], v[128:131], v[192:195], v[32:35]
	v_mfma_f32_16x16x32_bf16 v[24:27], v[136:139], v[192:195], v[24:27]
	v_mfma_f32_16x16x32_bf16 v[16:19], v[128:131], v[206:209], v[16:19]
	v_mfma_f32_16x16x32_bf16 v[8:11], v[136:139], v[206:209], v[8:11]
	v_mfma_f32_16x16x32_bf16 v[60:63], v[132:135], v[180:183], v[60:63]
	v_mfma_f32_16x16x32_bf16 v[56:59], v[140:143], v[180:183], v[56:59]
	v_mfma_f32_16x16x32_bf16 v[48:51], v[132:135], v[188:191], v[48:51]
	v_mfma_f32_16x16x32_bf16 v[40:43], v[140:143], v[188:191], v[40:43]
	v_mfma_f32_16x16x32_bf16 v[32:35], v[132:135], v[196:199], v[32:35]
	v_mfma_f32_16x16x32_bf16 v[24:27], v[140:143], v[196:199], v[24:27]
	v_mfma_f32_16x16x32_bf16 v[16:19], v[132:135], v[210:213], v[16:19]
	v_mfma_f32_16x16x32_bf16 v[8:11], v[140:143], v[210:213], v[8:11]
	v_mfma_f32_16x16x32_bf16 v[52:55], v[152:155], v[176:179], v[52:55]
	v_mfma_f32_16x16x32_bf16 v[44:47], v[164:167], v[176:179], v[44:47]
	v_mfma_f32_16x16x32_bf16 v[36:39], v[152:155], v[184:187], v[36:39]
	v_mfma_f32_16x16x32_bf16 v[28:31], v[164:167], v[184:187], v[28:31]
	v_mfma_f32_16x16x32_bf16 v[20:23], v[152:155], v[192:195], v[20:23]
	v_mfma_f32_16x16x32_bf16 v[12:15], v[164:167], v[192:195], v[12:15]
	v_mfma_f32_16x16x32_bf16 v[4:7], v[152:155], v[206:209], v[4:7]
	v_mfma_f32_16x16x32_bf16 v[0:3], v[164:167], v[206:209], v[0:3]
	v_mfma_f32_16x16x32_bf16 v[52:55], v[156:159], v[180:183], v[52:55]
	v_mfma_f32_16x16x32_bf16 v[44:47], v[172:175], v[180:183], v[44:47]
	v_mfma_f32_16x16x32_bf16 v[36:39], v[156:159], v[188:191], v[36:39]
	v_mfma_f32_16x16x32_bf16 v[28:31], v[172:175], v[188:191], v[28:31]
	v_mfma_f32_16x16x32_bf16 v[20:23], v[156:159], v[196:199], v[20:23]
	v_mfma_f32_16x16x32_bf16 v[12:15], v[172:175], v[196:199], v[12:15]
	v_mfma_f32_16x16x32_bf16 v[4:7], v[156:159], v[210:213], v[4:7]
	v_mfma_f32_16x16x32_bf16 v[0:3], v[172:175], v[210:213], v[0:3]
	s_barrier
	s_setprio 0
	v_add_u32_e32 v140, s54, v170
	v_add_u32_e32 v162, s43, v170
	ds_read_b128 v[128:131], v140
	ds_read_b128 v[132:135], v140 offset:1024
	ds_read_b128 v[136:139], v140 offset:2048
	ds_read_b128 v[140:143], v140 offset:3072
	ds_read_b128 v[152:155], v162
	ds_read_b128 v[156:159], v162 offset:1024
	ds_read_b128 v[164:167], v162 offset:2048
	ds_read_b128 v[172:175], v162 offset:3072
	s_mov_b32 m0, s6
	v_lshl_add_u64 v[220:221], s[74:75], 0, v[150:151]
	ds_read_b128 v[176:179], v171 offset:32768
	ds_read_b128 v[180:183], v171 offset:33792
	ds_read_b128 v[184:187], v171 offset:34816
	ds_read_b128 v[188:191], v171 offset:35840
	ds_read_b128 v[192:195], v171 offset:36864
	ds_read_b128 v[196:199], v171 offset:37888
	ds_read_b128 v[206:209], v171 offset:38912
	ds_read_b128 v[210:213], v171 offset:39936
	global_load_lds_dwordx4 v[220:221], off
	v_lshl_add_u64 v[220:221], s[74:75], 0, v[146:147]
	s_mov_b32 m0, s7
	s_nop 0
	global_load_lds_dwordx4 v[220:221], off
	s_waitcnt vmcnt(8)
	s_waitcnt lgkmcnt(0)
	s_setprio 1
	s_barrier
	v_mfma_f32_16x16x32_bf16 v[124:127], v[128:131], v[176:179], v[124:127]
	v_mfma_f32_16x16x32_bf16 v[120:123], v[136:139], v[176:179], v[120:123]
	v_mfma_f32_16x16x32_bf16 v[112:115], v[128:131], v[184:187], v[112:115]
	v_mfma_f32_16x16x32_bf16 v[104:107], v[136:139], v[184:187], v[104:107]
	v_mfma_f32_16x16x32_bf16 v[96:99], v[128:131], v[192:195], v[96:99]
	v_mfma_f32_16x16x32_bf16 v[88:91], v[136:139], v[192:195], v[88:91]
	v_mfma_f32_16x16x32_bf16 v[80:83], v[128:131], v[206:209], v[80:83]
	v_mfma_f32_16x16x32_bf16 v[72:75], v[136:139], v[206:209], v[72:75]
	v_mfma_f32_16x16x32_bf16 v[124:127], v[132:135], v[180:183], v[124:127]
	v_mfma_f32_16x16x32_bf16 v[120:123], v[140:143], v[180:183], v[120:123]
	v_mfma_f32_16x16x32_bf16 v[112:115], v[132:135], v[188:191], v[112:115]
	v_mfma_f32_16x16x32_bf16 v[104:107], v[140:143], v[188:191], v[104:107]
	v_mfma_f32_16x16x32_bf16 v[96:99], v[132:135], v[196:199], v[96:99]
	v_mfma_f32_16x16x32_bf16 v[88:91], v[140:143], v[196:199], v[88:91]
	v_mfma_f32_16x16x32_bf16 v[80:83], v[132:135], v[210:213], v[80:83]
	v_mfma_f32_16x16x32_bf16 v[72:75], v[140:143], v[210:213], v[72:75]
	v_mfma_f32_16x16x32_bf16 v[116:119], v[152:155], v[176:179], v[116:119]
	v_mfma_f32_16x16x32_bf16 v[108:111], v[164:167], v[176:179], v[108:111]
	v_mfma_f32_16x16x32_bf16 v[100:103], v[152:155], v[184:187], v[100:103]
	v_mfma_f32_16x16x32_bf16 v[92:95], v[164:167], v[184:187], v[92:95]
	v_mfma_f32_16x16x32_bf16 v[84:87], v[152:155], v[192:195], v[84:87]
	v_mfma_f32_16x16x32_bf16 v[76:79], v[164:167], v[192:195], v[76:79]
	v_mfma_f32_16x16x32_bf16 v[68:71], v[152:155], v[206:209], v[68:71]
	v_mfma_f32_16x16x32_bf16 v[64:67], v[164:167], v[206:209], v[64:67]
	v_mfma_f32_16x16x32_bf16 v[116:119], v[156:159], v[180:183], v[116:119]
	v_mfma_f32_16x16x32_bf16 v[108:111], v[172:175], v[180:183], v[108:111]
	v_mfma_f32_16x16x32_bf16 v[100:103], v[156:159], v[188:191], v[100:103]
	v_mfma_f32_16x16x32_bf16 v[92:95], v[172:175], v[188:191], v[92:95]
	v_mfma_f32_16x16x32_bf16 v[84:87], v[156:159], v[196:199], v[84:87]
	v_mfma_f32_16x16x32_bf16 v[76:79], v[172:175], v[196:199], v[76:79]
	v_mfma_f32_16x16x32_bf16 v[68:71], v[156:159], v[210:213], v[68:71]
	v_mfma_f32_16x16x32_bf16 v[64:67], v[172:175], v[210:213], v[64:67]
	s_barrier
	s_setprio 0
	s_mov_b32 m0, s41
	v_lshl_add_u64 v[200:201], v[200:201], 0, s[76:77]
	ds_read_b128 v[176:179], v171 offset:49152
	ds_read_b128 v[180:183], v171 offset:50176
	ds_read_b128 v[184:187], v171 offset:51200
	ds_read_b128 v[188:191], v171 offset:52224
	ds_read_b128 v[192:195], v171 offset:53248
	ds_read_b128 v[196:199], v171 offset:54272
	ds_read_b128 v[206:209], v171 offset:55296
	ds_read_b128 v[210:213], v171 offset:56320
	global_load_lds_dwordx4 v[200:201], off
	v_lshl_add_u64 v[200:201], v[214:215], 0, s[76:77]
	s_mov_b32 m0, s39
	s_nop 0
	global_load_lds_dwordx4 v[200:201], off
	v_lshl_add_u64 v[200:201], s[72:73], 0, v[148:149]
	s_mov_b32 m0, s23
	s_nop 0
	global_load_lds_dwordx4 v[200:201], off
	v_lshl_add_u64 v[200:201], s[72:73], 0, v[144:145]
	s_mov_b32 m0, s22
	s_nop 0
	global_load_lds_dwordx4 v[200:201], off
	v_lshl_add_u64 v[200:201], v[216:217], 0, s[76:77]
	s_mov_b32 m0, s11
	s_nop 0
	global_load_lds_dwordx4 v[200:201], off
	v_lshl_add_u64 v[200:201], v[218:219], 0, s[76:77]
	s_mov_b32 m0, s12
	s_nop 0
	global_load_lds_dwordx4 v[200:201], off
	s_waitcnt vmcnt(8)
	s_waitcnt lgkmcnt(0)
	s_setprio 1
	s_barrier
	v_mfma_f32_16x16x32_bf16 v[60:63], v[128:131], v[176:179], v[60:63]
	v_mfma_f32_16x16x32_bf16 v[56:59], v[136:139], v[176:179], v[56:59]
	v_mfma_f32_16x16x32_bf16 v[48:51], v[128:131], v[184:187], v[48:51]
	v_mfma_f32_16x16x32_bf16 v[40:43], v[136:139], v[184:187], v[40:43]
	v_mfma_f32_16x16x32_bf16 v[32:35], v[128:131], v[192:195], v[32:35]
	v_mfma_f32_16x16x32_bf16 v[24:27], v[136:139], v[192:195], v[24:27]
	v_mfma_f32_16x16x32_bf16 v[16:19], v[128:131], v[206:209], v[16:19]
	v_mfma_f32_16x16x32_bf16 v[8:11], v[136:139], v[206:209], v[8:11]
	v_mfma_f32_16x16x32_bf16 v[60:63], v[132:135], v[180:183], v[60:63]
	v_mfma_f32_16x16x32_bf16 v[56:59], v[140:143], v[180:183], v[56:59]
	v_mfma_f32_16x16x32_bf16 v[48:51], v[132:135], v[188:191], v[48:51]
	v_mfma_f32_16x16x32_bf16 v[40:43], v[140:143], v[188:191], v[40:43]
	v_mfma_f32_16x16x32_bf16 v[32:35], v[132:135], v[196:199], v[32:35]
	v_mfma_f32_16x16x32_bf16 v[24:27], v[140:143], v[196:199], v[24:27]
	v_mfma_f32_16x16x32_bf16 v[16:19], v[132:135], v[210:213], v[16:19]
	v_mfma_f32_16x16x32_bf16 v[8:11], v[140:143], v[210:213], v[8:11]
	v_mfma_f32_16x16x32_bf16 v[52:55], v[152:155], v[176:179], v[52:55]
	v_mfma_f32_16x16x32_bf16 v[44:47], v[164:167], v[176:179], v[44:47]
	v_mfma_f32_16x16x32_bf16 v[36:39], v[152:155], v[184:187], v[36:39]
	v_mfma_f32_16x16x32_bf16 v[28:31], v[164:167], v[184:187], v[28:31]
	v_mfma_f32_16x16x32_bf16 v[20:23], v[152:155], v[192:195], v[20:23]
	v_mfma_f32_16x16x32_bf16 v[12:15], v[164:167], v[192:195], v[12:15]
	v_mfma_f32_16x16x32_bf16 v[4:7], v[152:155], v[206:209], v[4:7]
	v_mfma_f32_16x16x32_bf16 v[0:3], v[164:167], v[206:209], v[0:3]
	v_mfma_f32_16x16x32_bf16 v[52:55], v[156:159], v[180:183], v[52:55]
	v_mfma_f32_16x16x32_bf16 v[44:47], v[172:175], v[180:183], v[44:47]
	v_mfma_f32_16x16x32_bf16 v[36:39], v[156:159], v[188:191], v[36:39]
	v_mfma_f32_16x16x32_bf16 v[28:31], v[172:175], v[188:191], v[28:31]
	v_mfma_f32_16x16x32_bf16 v[20:23], v[156:159], v[196:199], v[20:23]
	v_mfma_f32_16x16x32_bf16 v[12:15], v[172:175], v[196:199], v[12:15]
	v_mfma_f32_16x16x32_bf16 v[4:7], v[156:159], v[210:213], v[4:7]
	v_mfma_f32_16x16x32_bf16 v[0:3], v[172:175], v[210:213], v[0:3]
	s_barrier
	s_setprio 0
	s_movk_i32 s39, 0x100
	s_andn2_b64 vcc, exec, s[66:67]
	s_mov_b64 s[72:73], -1
	s_mov_b64 s[66:67], 0
	s_cbranch_vccz .LBB0_505

.LBB0_649:
	s_ashr_i32 s59, s58, 31
	s_lshl_b64 s[6:7], s[58:59], 19
	s_add_u32 s62, s96, s6
	s_addc_u32 s63, s97, s7
	s_and_b64 s[6:7], s[72:73], exec
	s_cselect_b32 s6, s63, s39
	s_cselect_b32 s7, s62, s38
	s_ashr_i32 s61, s60, 31
	s_lshl_b64 s[8:9], s[60:61], 19
	s_add_u32 s74, s50, s8
	s_addc_u32 s75, s51, s9
	s_and_b64 s[8:9], s[72:73], exec
	s_cselect_b32 s8, s75, s41
	s_cselect_b32 s9, s74, s40
	s_add_u32 s38, s38, 0x40080
	s_addc_u32 s39, s39, 0
	s_add_u32 s10, s40, 0x100
	s_addc_u32 s11, s41, 0
	s_mov_b32 s12, -2
	s_add_u32 s13, s38, 0xfffc0080
	s_addc_u32 s14, s39, -1
	s_add_i32 s15, 0, 0x10000
	s_cmp_eq_u32 s12, 12
	s_cselect_b32 s43, s6, s14
	s_cselect_b32 s42, s7, s13
	s_cselect_b32 s41, s8, s11
	s_cselect_b32 s40, s9, s10
	s_add_i32 s13, 0, 0x14000
	v_add_u32_e32 v140, s15, v181
	v_add_u32_e32 v156, s13, v181
	ds_read_b128 v[128:131], v140
	ds_read_b128 v[132:135], v140 offset:1024
	ds_read_b128 v[136:139], v140 offset:2048
	ds_read_b128 v[140:143], v140 offset:3072
	ds_read_b128 v[144:147], v156
	ds_read_b128 v[148:151], v156 offset:1024
	ds_read_b128 v[152:155], v156 offset:2048
	ds_read_b128 v[156:159], v156 offset:3072
	v_lshl_add_u64 v[178:179], s[38:39], 0, v[174:175]
	s_add_i32 m0, s66, 0xc000
	ds_read_b128 v[186:189], v185
	ds_read_b128 v[190:193], v185 offset:1024
	ds_read_b128 v[194:197], v185 offset:2048
	ds_read_b128 v[198:201], v185 offset:3072
	ds_read_b128 v[206:209], v185 offset:4096
	ds_read_b128 v[210:213], v185 offset:5120
	ds_read_b128 v[214:217], v185 offset:6144
	ds_read_b128 v[218:221], v185 offset:7168
	global_load_lds_dwordx4 v[178:179], off
	v_lshl_add_u64 v[178:179], s[38:39], 0, v[176:177]
	s_add_i32 m0, s66, 0xe000
	s_nop 0
	global_load_lds_dwordx4 v[178:179], off
	s_waitcnt vmcnt(8)
	s_waitcnt lgkmcnt(0)
	s_setprio 1
	s_barrier
	v_mfma_f32_16x16x32_bf16 v[120:123], v[128:131], v[186:189], 0
	v_mfma_f32_16x16x32_bf16 v[124:127], v[136:139], v[186:189], 0
	v_mfma_f32_16x16x32_bf16 v[104:107], v[128:131], v[194:197], 0
	v_mfma_f32_16x16x32_bf16 v[108:111], v[136:139], v[194:197], 0
	v_mfma_f32_16x16x32_bf16 v[88:91], v[128:131], v[206:209], 0
	v_mfma_f32_16x16x32_bf16 v[92:95], v[136:139], v[206:209], 0
	v_mfma_f32_16x16x32_bf16 v[72:75], v[128:131], v[214:217], 0
	v_mfma_f32_16x16x32_bf16 v[76:79], v[136:139], v[214:217], 0
	v_mfma_f32_16x16x32_bf16 v[120:123], v[132:135], v[190:193], v[120:123]
	v_mfma_f32_16x16x32_bf16 v[124:127], v[140:143], v[190:193], v[124:127]
	v_mfma_f32_16x16x32_bf16 v[104:107], v[132:135], v[198:201], v[104:107]
	v_mfma_f32_16x16x32_bf16 v[108:111], v[140:143], v[198:201], v[108:111]
	v_mfma_f32_16x16x32_bf16 v[88:91], v[132:135], v[210:213], v[88:91]
	v_mfma_f32_16x16x32_bf16 v[92:95], v[140:143], v[210:213], v[92:95]
	v_mfma_f32_16x16x32_bf16 v[72:75], v[132:135], v[218:221], v[72:75]
	v_mfma_f32_16x16x32_bf16 v[76:79], v[140:143], v[218:221], v[76:79]
	v_mfma_f32_16x16x32_bf16 v[116:119], v[144:147], v[186:189], 0
	v_mfma_f32_16x16x32_bf16 v[112:115], v[152:155], v[186:189], 0
	v_mfma_f32_16x16x32_bf16 v[100:103], v[144:147], v[194:197], 0
	v_mfma_f32_16x16x32_bf16 v[96:99], v[152:155], v[194:197], 0
	v_mfma_f32_16x16x32_bf16 v[84:87], v[144:147], v[206:209], 0
	v_mfma_f32_16x16x32_bf16 v[80:83], v[152:155], v[206:209], 0
	v_mfma_f32_16x16x32_bf16 v[68:71], v[144:147], v[214:217], 0
	v_mfma_f32_16x16x32_bf16 v[64:67], v[152:155], v[214:217], 0
	v_mfma_f32_16x16x32_bf16 v[116:119], v[148:151], v[190:193], v[116:119]
	v_mfma_f32_16x16x32_bf16 v[112:115], v[156:159], v[190:193], v[112:115]
	v_mfma_f32_16x16x32_bf16 v[100:103], v[148:151], v[198:201], v[100:103]
	v_mfma_f32_16x16x32_bf16 v[96:99], v[156:159], v[198:201], v[96:99]
	v_mfma_f32_16x16x32_bf16 v[84:87], v[148:151], v[210:213], v[84:87]
	v_mfma_f32_16x16x32_bf16 v[80:83], v[156:159], v[210:213], v[80:83]
	v_mfma_f32_16x16x32_bf16 v[68:71], v[148:151], v[218:221], v[68:71]
	v_mfma_f32_16x16x32_bf16 v[64:67], v[156:159], v[218:221], v[64:67]
	s_barrier
	s_setprio 0
	s_add_i32 s14, s15, s65
	v_lshl_add_u64 v[178:179], s[40:41], 0, v[168:169]
	s_mov_b32 m0, s14
	ds_read_b128 v[186:189], v185 offset:16384
	ds_read_b128 v[190:193], v185 offset:17408
	ds_read_b128 v[194:197], v185 offset:18432
	ds_read_b128 v[198:201], v185 offset:19456
	ds_read_b128 v[206:209], v185 offset:20480
	ds_read_b128 v[210:213], v185 offset:21504
	ds_read_b128 v[214:217], v185 offset:22528
	ds_read_b128 v[218:221], v185 offset:23552
	global_load_lds_dwordx4 v[178:179], off
	s_add_i32 m0, s14, 0x2000
	s_add_u32 s14, s40, 0x40000
	v_lshl_add_u64 v[222:223], s[40:41], 0, v[164:165]
	s_addc_u32 s15, s41, 0
	s_add_i32 s13, s13, s65
	global_load_lds_dwordx4 v[222:223], off
	v_lshl_add_u64 v[224:225], s[14:15], 0, v[168:169]
	s_mov_b32 m0, s13
	v_lshl_add_u64 v[226:227], s[42:43], 0, v[166:167]
	global_load_lds_dwordx4 v[224:225], off
	v_lshl_add_u64 v[224:225], s[14:15], 0, v[164:165]
	s_add_i32 m0, s13, 0x2000
	s_nop 0
	global_load_lds_dwordx4 v[224:225], off
	v_lshl_add_u64 v[224:225], s[42:43], 0, v[170:171]
	s_mov_b32 m0, s66
	s_nop 0
	global_load_lds_dwordx4 v[224:225], off
	s_mov_b32 m0, s67
	s_nop 0
	global_load_lds_dwordx4 v[226:227], off
	s_waitcnt vmcnt(8)
	s_waitcnt lgkmcnt(0)
	s_setprio 1
	s_barrier
	v_mfma_f32_16x16x32_bf16 v[56:59], v[128:131], v[186:189], 0
	v_mfma_f32_16x16x32_bf16 v[60:63], v[136:139], v[186:189], 0
	v_mfma_f32_16x16x32_bf16 v[40:43], v[128:131], v[194:197], 0
	v_mfma_f32_16x16x32_bf16 v[44:47], v[136:139], v[194:197], 0
	v_mfma_f32_16x16x32_bf16 v[24:27], v[128:131], v[206:209], 0
	v_mfma_f32_16x16x32_bf16 v[28:31], v[136:139], v[206:209], 0
	v_mfma_f32_16x16x32_bf16 v[8:11], v[128:131], v[214:217], 0
	v_mfma_f32_16x16x32_bf16 v[12:15], v[136:139], v[214:217], 0
	v_mfma_f32_16x16x32_bf16 v[56:59], v[132:135], v[190:193], v[56:59]
	v_mfma_f32_16x16x32_bf16 v[60:63], v[140:143], v[190:193], v[60:63]
	v_mfma_f32_16x16x32_bf16 v[40:43], v[132:135], v[198:201], v[40:43]
	v_mfma_f32_16x16x32_bf16 v[44:47], v[140:143], v[198:201], v[44:47]
	v_mfma_f32_16x16x32_bf16 v[24:27], v[132:135], v[210:213], v[24:27]
	v_mfma_f32_16x16x32_bf16 v[28:31], v[140:143], v[210:213], v[28:31]
	v_mfma_f32_16x16x32_bf16 v[8:11], v[132:135], v[218:221], v[8:11]
	v_mfma_f32_16x16x32_bf16 v[12:15], v[140:143], v[218:221], v[12:15]
	v_mfma_f32_16x16x32_bf16 v[52:55], v[144:147], v[186:189], 0
	v_mfma_f32_16x16x32_bf16 v[48:51], v[152:155], v[186:189], 0
	v_mfma_f32_16x16x32_bf16 v[36:39], v[144:147], v[194:197], 0
	v_mfma_f32_16x16x32_bf16 v[32:35], v[152:155], v[194:197], 0
	v_mfma_f32_16x16x32_bf16 v[20:23], v[144:147], v[206:209], 0
	v_mfma_f32_16x16x32_bf16 v[16:19], v[152:155], v[206:209], 0
	v_mfma_f32_16x16x32_bf16 v[4:7], v[144:147], v[214:217], 0
	v_mfma_f32_16x16x32_bf16 v[0:3], v[152:155], v[214:217], 0
	v_mfma_f32_16x16x32_bf16 v[52:55], v[148:151], v[190:193], v[52:55]
	v_mfma_f32_16x16x32_bf16 v[48:51], v[156:159], v[190:193], v[48:51]
	v_mfma_f32_16x16x32_bf16 v[36:39], v[148:151], v[198:201], v[36:39]
	v_mfma_f32_16x16x32_bf16 v[32:35], v[156:159], v[198:201], v[32:35]
	v_mfma_f32_16x16x32_bf16 v[20:23], v[148:151], v[210:213], v[20:23]
	v_mfma_f32_16x16x32_bf16 v[16:19], v[156:159], v[210:213], v[16:19]
	v_mfma_f32_16x16x32_bf16 v[4:7], v[148:151], v[218:221], v[4:7]
	v_mfma_f32_16x16x32_bf16 v[0:3], v[156:159], v[218:221], v[0:3]
	s_barrier
	s_setprio 0
	s_add_i32 s13, 0, 0x18000
	s_add_i32 s16, 0, 0x1c000
	v_add_u32_e32 v140, s13, v181
	v_add_u32_e32 v156, s16, v181
	ds_read_b128 v[128:131], v140
	ds_read_b128 v[132:135], v140 offset:1024
	ds_read_b128 v[136:139], v140 offset:2048
	ds_read_b128 v[140:143], v140 offset:3072
	ds_read_b128 v[144:147], v156
	ds_read_b128 v[148:151], v156 offset:1024
	ds_read_b128 v[152:155], v156 offset:2048
	ds_read_b128 v[156:159], v156 offset:3072
	s_add_u32 s14, s42, 0x40000
	s_addc_u32 s15, s43, 0
	s_mov_b32 m0, s68
	v_lshl_add_u64 v[228:229], s[14:15], 0, v[170:171]
	ds_read_b128 v[186:189], v185 offset:32768
	ds_read_b128 v[190:193], v185 offset:33792
	ds_read_b128 v[194:197], v185 offset:34816
	ds_read_b128 v[198:201], v185 offset:35840
	ds_read_b128 v[206:209], v185 offset:36864
	ds_read_b128 v[210:213], v185 offset:37888
	ds_read_b128 v[214:217], v185 offset:38912
	ds_read_b128 v[218:221], v185 offset:39936
	global_load_lds_dwordx4 v[228:229], off
	v_lshl_add_u64 v[228:229], s[14:15], 0, v[166:167]
	s_mov_b32 m0, s69
	s_nop 0
	global_load_lds_dwordx4 v[228:229], off
	s_waitcnt vmcnt(8)
	s_waitcnt lgkmcnt(0)
	s_setprio 1
	s_barrier
	v_mfma_f32_16x16x32_bf16 v[120:123], v[128:131], v[186:189], v[120:123]
	v_mfma_f32_16x16x32_bf16 v[124:127], v[136:139], v[186:189], v[124:127]
	v_mfma_f32_16x16x32_bf16 v[104:107], v[128:131], v[194:197], v[104:107]
	v_mfma_f32_16x16x32_bf16 v[108:111], v[136:139], v[194:197], v[108:111]
	v_mfma_f32_16x16x32_bf16 v[88:91], v[128:131], v[206:209], v[88:91]
	v_mfma_f32_16x16x32_bf16 v[92:95], v[136:139], v[206:209], v[92:95]
	v_mfma_f32_16x16x32_bf16 v[72:75], v[128:131], v[214:217], v[72:75]
	v_mfma_f32_16x16x32_bf16 v[76:79], v[136:139], v[214:217], v[76:79]
	v_mfma_f32_16x16x32_bf16 v[120:123], v[132:135], v[190:193], v[120:123]
	v_mfma_f32_16x16x32_bf16 v[124:127], v[140:143], v[190:193], v[124:127]
	v_mfma_f32_16x16x32_bf16 v[104:107], v[132:135], v[198:201], v[104:107]
	v_mfma_f32_16x16x32_bf16 v[108:111], v[140:143], v[198:201], v[108:111]
	v_mfma_f32_16x16x32_bf16 v[88:91], v[132:135], v[210:213], v[88:91]
	v_mfma_f32_16x16x32_bf16 v[92:95], v[140:143], v[210:213], v[92:95]
	v_mfma_f32_16x16x32_bf16 v[72:75], v[132:135], v[218:221], v[72:75]
	v_mfma_f32_16x16x32_bf16 v[76:79], v[140:143], v[218:221], v[76:79]
	v_mfma_f32_16x16x32_bf16 v[116:119], v[144:147], v[186:189], v[116:119]
	v_mfma_f32_16x16x32_bf16 v[112:115], v[152:155], v[186:189], v[112:115]
	v_mfma_f32_16x16x32_bf16 v[100:103], v[144:147], v[194:197], v[100:103]
	v_mfma_f32_16x16x32_bf16 v[96:99], v[152:155], v[194:197], v[96:99]
	v_mfma_f32_16x16x32_bf16 v[84:87], v[144:147], v[206:209], v[84:87]
	v_mfma_f32_16x16x32_bf16 v[80:83], v[152:155], v[206:209], v[80:83]
	v_mfma_f32_16x16x32_bf16 v[68:71], v[144:147], v[214:217], v[68:71]
	v_mfma_f32_16x16x32_bf16 v[64:67], v[152:155], v[214:217], v[64:67]
	v_mfma_f32_16x16x32_bf16 v[116:119], v[148:151], v[190:193], v[116:119]
	v_mfma_f32_16x16x32_bf16 v[112:115], v[156:159], v[190:193], v[112:115]
	v_mfma_f32_16x16x32_bf16 v[100:103], v[148:151], v[198:201], v[100:103]
	v_mfma_f32_16x16x32_bf16 v[96:99], v[156:159], v[198:201], v[96:99]
	v_mfma_f32_16x16x32_bf16 v[84:87], v[148:151], v[210:213], v[84:87]
	v_mfma_f32_16x16x32_bf16 v[80:83], v[156:159], v[210:213], v[80:83]
	v_mfma_f32_16x16x32_bf16 v[68:71], v[148:151], v[218:221], v[68:71]
	v_mfma_f32_16x16x32_bf16 v[64:67], v[156:159], v[218:221], v[64:67]
	s_barrier
	s_setprio 0
	s_add_i32 s13, s13, s65
	v_lshl_add_u64 v[178:179], v[178:179], 0, s[76:77]
	s_mov_b32 m0, s13
	ds_read_b128 v[186:189], v185 offset:49152
	ds_read_b128 v[190:193], v185 offset:50176
	ds_read_b128 v[194:197], v185 offset:51200
	ds_read_b128 v[198:201], v185 offset:52224
	ds_read_b128 v[206:209], v185 offset:53248
	ds_read_b128 v[210:213], v185 offset:54272
	ds_read_b128 v[214:217], v185 offset:55296
	ds_read_b128 v[218:221], v185 offset:56320
	global_load_lds_dwordx4 v[178:179], off
	s_add_i32 m0, s13, 0x2000
	s_add_u32 s14, s40, 0x40080
	v_lshl_add_u64 v[178:179], v[222:223], 0, s[76:77]
	s_addc_u32 s15, s41, 0
	s_add_i32 s13, s16, s65
	global_load_lds_dwordx4 v[178:179], off
	v_lshl_add_u64 v[178:179], s[14:15], 0, v[168:169]
	s_mov_b32 m0, s13
	s_nop 0
	global_load_lds_dwordx4 v[178:179], off
	v_lshl_add_u64 v[178:179], s[14:15], 0, v[164:165]
	s_add_i32 m0, s13, 0x2000
	s_nop 0
	global_load_lds_dwordx4 v[178:179], off
	v_lshl_add_u64 v[178:179], v[224:225], 0, s[76:77]
	s_mov_b32 m0, s79
	s_nop 0
	global_load_lds_dwordx4 v[178:179], off
	v_lshl_add_u64 v[178:179], v[226:227], 0, s[76:77]
	s_mov_b32 m0, s46
	s_nop 0
	global_load_lds_dwordx4 v[178:179], off
	s_waitcnt vmcnt(8)
	s_waitcnt lgkmcnt(0)
	s_setprio 1
	s_barrier
	v_mfma_f32_16x16x32_bf16 v[56:59], v[128:131], v[186:189], v[56:59]
	v_mfma_f32_16x16x32_bf16 v[60:63], v[136:139], v[186:189], v[60:63]
	v_mfma_f32_16x16x32_bf16 v[40:43], v[128:131], v[194:197], v[40:43]
	v_mfma_f32_16x16x32_bf16 v[44:47], v[136:139], v[194:197], v[44:47]
	v_mfma_f32_16x16x32_bf16 v[24:27], v[128:131], v[206:209], v[24:27]
	v_mfma_f32_16x16x32_bf16 v[28:31], v[136:139], v[206:209], v[28:31]
	v_mfma_f32_16x16x32_bf16 v[8:11], v[128:131], v[214:217], v[8:11]
	v_mfma_f32_16x16x32_bf16 v[12:15], v[136:139], v[214:217], v[12:15]
	v_mfma_f32_16x16x32_bf16 v[56:59], v[132:135], v[190:193], v[56:59]
	v_mfma_f32_16x16x32_bf16 v[60:63], v[140:143], v[190:193], v[60:63]
	v_mfma_f32_16x16x32_bf16 v[40:43], v[132:135], v[198:201], v[40:43]
	v_mfma_f32_16x16x32_bf16 v[44:47], v[140:143], v[198:201], v[44:47]
	v_mfma_f32_16x16x32_bf16 v[24:27], v[132:135], v[210:213], v[24:27]
	v_mfma_f32_16x16x32_bf16 v[28:31], v[140:143], v[210:213], v[28:31]
	v_mfma_f32_16x16x32_bf16 v[8:11], v[132:135], v[218:221], v[8:11]
	v_mfma_f32_16x16x32_bf16 v[12:15], v[140:143], v[218:221], v[12:15]
	v_mfma_f32_16x16x32_bf16 v[52:55], v[144:147], v[186:189], v[52:55]
	v_mfma_f32_16x16x32_bf16 v[48:51], v[152:155], v[186:189], v[48:51]
	v_mfma_f32_16x16x32_bf16 v[36:39], v[144:147], v[194:197], v[36:39]
	v_mfma_f32_16x16x32_bf16 v[32:35], v[152:155], v[194:197], v[32:35]
	v_mfma_f32_16x16x32_bf16 v[20:23], v[144:147], v[206:209], v[20:23]
	v_mfma_f32_16x16x32_bf16 v[16:19], v[152:155], v[206:209], v[16:19]
	v_mfma_f32_16x16x32_bf16 v[4:7], v[144:147], v[214:217], v[4:7]
	v_mfma_f32_16x16x32_bf16 v[0:3], v[152:155], v[214:217], v[0:3]
	v_mfma_f32_16x16x32_bf16 v[52:55], v[148:151], v[190:193], v[52:55]
	v_mfma_f32_16x16x32_bf16 v[48:51], v[156:159], v[190:193], v[48:51]
	v_mfma_f32_16x16x32_bf16 v[36:39], v[148:151], v[198:201], v[36:39]
	v_mfma_f32_16x16x32_bf16 v[32:35], v[156:159], v[198:201], v[32:35]
	v_mfma_f32_16x16x32_bf16 v[20:23], v[148:151], v[210:213], v[20:23]
	v_mfma_f32_16x16x32_bf16 v[16:19], v[156:159], v[210:213], v[16:19]
	v_mfma_f32_16x16x32_bf16 v[4:7], v[148:151], v[218:221], v[4:7]
	v_mfma_f32_16x16x32_bf16 v[0:3], v[156:159], v[218:221], v[0:3]
	s_barrier
	s_setprio 0
	s_add_i32 s12, s12, 2
	s_add_u32 s38, s38, 0x100
	s_addc_u32 s39, s39, 0
	s_add_u32 s10, s10, 0x100
	s_addc_u32 s11, s11, 0
	s_cmp_gt_u32 s12, 13
	s_cbranch_scc0 .LBB0_650
	s_branch .Lpeel_x_650
.LBB0_650:
	s_add_u32 s13, s38, 0xfffc0080
	s_addc_u32 s14, s39, -1
	s_add_i32 s15, 0, 0x10000
	s_cmp_eq_u32 s12, 12
	s_cselect_b32 s43, s6, s14
	s_cselect_b32 s42, s7, s13
	s_cselect_b32 s41, s8, s11
	s_cselect_b32 s40, s9, s10
	s_add_i32 s13, 0, 0x14000
	v_add_u32_e32 v140, s15, v181
	v_add_u32_e32 v156, s13, v181
	ds_read_b128 v[128:131], v140
	ds_read_b128 v[132:135], v140 offset:1024
	ds_read_b128 v[136:139], v140 offset:2048
	ds_read_b128 v[140:143], v140 offset:3072
	ds_read_b128 v[144:147], v156
	ds_read_b128 v[148:151], v156 offset:1024
	ds_read_b128 v[152:155], v156 offset:2048
	ds_read_b128 v[156:159], v156 offset:3072
	v_lshl_add_u64 v[178:179], s[38:39], 0, v[174:175]
	s_add_i32 m0, s66, 0xc000
	ds_read_b128 v[186:189], v185
	ds_read_b128 v[190:193], v185 offset:1024
	ds_read_b128 v[194:197], v185 offset:2048
	ds_read_b128 v[198:201], v185 offset:3072
	ds_read_b128 v[206:209], v185 offset:4096
	ds_read_b128 v[210:213], v185 offset:5120
	ds_read_b128 v[214:217], v185 offset:6144
	ds_read_b128 v[218:221], v185 offset:7168
	global_load_lds_dwordx4 v[178:179], off
	v_lshl_add_u64 v[178:179], s[38:39], 0, v[176:177]
	s_add_i32 m0, s66, 0xe000
	s_nop 0
	global_load_lds_dwordx4 v[178:179], off
	s_waitcnt vmcnt(8)
	s_waitcnt lgkmcnt(0)
	s_setprio 1
	s_barrier
	v_mfma_f32_16x16x32_bf16 v[120:123], v[128:131], v[186:189], v[120:123]
	v_mfma_f32_16x16x32_bf16 v[124:127], v[136:139], v[186:189], v[124:127]
	v_mfma_f32_16x16x32_bf16 v[104:107], v[128:131], v[194:197], v[104:107]
	v_mfma_f32_16x16x32_bf16 v[108:111], v[136:139], v[194:197], v[108:111]
	v_mfma_f32_16x16x32_bf16 v[88:91], v[128:131], v[206:209], v[88:91]
	v_mfma_f32_16x16x32_bf16 v[92:95], v[136:139], v[206:209], v[92:95]
	v_mfma_f32_16x16x32_bf16 v[72:75], v[128:131], v[214:217], v[72:75]
	v_mfma_f32_16x16x32_bf16 v[76:79], v[136:139], v[214:217], v[76:79]
	v_mfma_f32_16x16x32_bf16 v[120:123], v[132:135], v[190:193], v[120:123]
	v_mfma_f32_16x16x32_bf16 v[124:127], v[140:143], v[190:193], v[124:127]
	v_mfma_f32_16x16x32_bf16 v[104:107], v[132:135], v[198:201], v[104:107]
	v_mfma_f32_16x16x32_bf16 v[108:111], v[140:143], v[198:201], v[108:111]
	v_mfma_f32_16x16x32_bf16 v[88:91], v[132:135], v[210:213], v[88:91]
	v_mfma_f32_16x16x32_bf16 v[92:95], v[140:143], v[210:213], v[92:95]
	v_mfma_f32_16x16x32_bf16 v[72:75], v[132:135], v[218:221], v[72:75]
	v_mfma_f32_16x16x32_bf16 v[76:79], v[140:143], v[218:221], v[76:79]
	v_mfma_f32_16x16x32_bf16 v[116:119], v[144:147], v[186:189], v[116:119]
	v_mfma_f32_16x16x32_bf16 v[112:115], v[152:155], v[186:189], v[112:115]
	v_mfma_f32_16x16x32_bf16 v[100:103], v[144:147], v[194:197], v[100:103]
	v_mfma_f32_16x16x32_bf16 v[96:99], v[152:155], v[194:197], v[96:99]
	v_mfma_f32_16x16x32_bf16 v[84:87], v[144:147], v[206:209], v[84:87]
	v_mfma_f32_16x16x32_bf16 v[80:83], v[152:155], v[206:209], v[80:83]
	v_mfma_f32_16x16x32_bf16 v[68:71], v[144:147], v[214:217], v[68:71]
	v_mfma_f32_16x16x32_bf16 v[64:67], v[152:155], v[214:217], v[64:67]
	v_mfma_f32_16x16x32_bf16 v[116:119], v[148:151], v[190:193], v[116:119]
	v_mfma_f32_16x16x32_bf16 v[112:115], v[156:159], v[190:193], v[112:115]
	v_mfma_f32_16x16x32_bf16 v[100:103], v[148:151], v[198:201], v[100:103]
	v_mfma_f32_16x16x32_bf16 v[96:99], v[156:159], v[198:201], v[96:99]
	v_mfma_f32_16x16x32_bf16 v[84:87], v[148:151], v[210:213], v[84:87]
	v_mfma_f32_16x16x32_bf16 v[80:83], v[156:159], v[210:213], v[80:83]
	v_mfma_f32_16x16x32_bf16 v[68:71], v[148:151], v[218:221], v[68:71]
	v_mfma_f32_16x16x32_bf16 v[64:67], v[156:159], v[218:221], v[64:67]
	s_barrier
	s_setprio 0
	s_add_i32 s14, s15, s65
	v_lshl_add_u64 v[178:179], s[40:41], 0, v[168:169]
	s_mov_b32 m0, s14
	ds_read_b128 v[186:189], v185 offset:16384
	ds_read_b128 v[190:193], v185 offset:17408
	ds_read_b128 v[194:197], v185 offset:18432
	ds_read_b128 v[198:201], v185 offset:19456
	ds_read_b128 v[206:209], v185 offset:20480
	ds_read_b128 v[210:213], v185 offset:21504
	ds_read_b128 v[214:217], v185 offset:22528
	ds_read_b128 v[218:221], v185 offset:23552
	global_load_lds_dwordx4 v[178:179], off
	s_add_i32 m0, s14, 0x2000
	s_add_u32 s14, s40, 0x40000
	v_lshl_add_u64 v[222:223], s[40:41], 0, v[164:165]
	s_addc_u32 s15, s41, 0
	s_add_i32 s13, s13, s65
	global_load_lds_dwordx4 v[222:223], off
	v_lshl_add_u64 v[224:225], s[14:15], 0, v[168:169]
	s_mov_b32 m0, s13
	v_lshl_add_u64 v[226:227], s[42:43], 0, v[166:167]
	global_load_lds_dwordx4 v[224:225], off
	v_lshl_add_u64 v[224:225], s[14:15], 0, v[164:165]
	s_add_i32 m0, s13, 0x2000
	s_nop 0
	global_load_lds_dwordx4 v[224:225], off
	v_lshl_add_u64 v[224:225], s[42:43], 0, v[170:171]
	s_mov_b32 m0, s66
	s_nop 0
	global_load_lds_dwordx4 v[224:225], off
	s_mov_b32 m0, s67
	s_nop 0
	global_load_lds_dwordx4 v[226:227], off
	s_waitcnt vmcnt(8)
	s_waitcnt lgkmcnt(0)
	s_setprio 1
	s_barrier
	v_mfma_f32_16x16x32_bf16 v[56:59], v[128:131], v[186:189], v[56:59]
	v_mfma_f32_16x16x32_bf16 v[60:63], v[136:139], v[186:189], v[60:63]
	v_mfma_f32_16x16x32_bf16 v[40:43], v[128:131], v[194:197], v[40:43]
	v_mfma_f32_16x16x32_bf16 v[44:47], v[136:139], v[194:197], v[44:47]
	v_mfma_f32_16x16x32_bf16 v[24:27], v[128:131], v[206:209], v[24:27]
	v_mfma_f32_16x16x32_bf16 v[28:31], v[136:139], v[206:209], v[28:31]
	v_mfma_f32_16x16x32_bf16 v[8:11], v[128:131], v[214:217], v[8:11]
	v_mfma_f32_16x16x32_bf16 v[12:15], v[136:139], v[214:217], v[12:15]
	v_mfma_f32_16x16x32_bf16 v[56:59], v[132:135], v[190:193], v[56:59]
	v_mfma_f32_16x16x32_bf16 v[60:63], v[140:143], v[190:193], v[60:63]
	v_mfma_f32_16x16x32_bf16 v[40:43], v[132:135], v[198:201], v[40:43]
	v_mfma_f32_16x16x32_bf16 v[44:47], v[140:143], v[198:201], v[44:47]
	v_mfma_f32_16x16x32_bf16 v[24:27], v[132:135], v[210:213], v[24:27]
	v_mfma_f32_16x16x32_bf16 v[28:31], v[140:143], v[210:213], v[28:31]
	v_mfma_f32_16x16x32_bf16 v[8:11], v[132:135], v[218:221], v[8:11]
	v_mfma_f32_16x16x32_bf16 v[12:15], v[140:143], v[218:221], v[12:15]
	v_mfma_f32_16x16x32_bf16 v[52:55], v[144:147], v[186:189], v[52:55]
	v_mfma_f32_16x16x32_bf16 v[48:51], v[152:155], v[186:189], v[48:51]
	v_mfma_f32_16x16x32_bf16 v[36:39], v[144:147], v[194:197], v[36:39]
	v_mfma_f32_16x16x32_bf16 v[32:35], v[152:155], v[194:197], v[32:35]
	v_mfma_f32_16x16x32_bf16 v[20:23], v[144:147], v[206:209], v[20:23]
	v_mfma_f32_16x16x32_bf16 v[16:19], v[152:155], v[206:209], v[16:19]
	v_mfma_f32_16x16x32_bf16 v[4:7], v[144:147], v[214:217], v[4:7]
	v_mfma_f32_16x16x32_bf16 v[0:3], v[152:155], v[214:217], v[0:3]
	v_mfma_f32_16x16x32_bf16 v[52:55], v[148:151], v[190:193], v[52:55]
	v_mfma_f32_16x16x32_bf16 v[48:51], v[156:159], v[190:193], v[48:51]
	v_mfma_f32_16x16x32_bf16 v[36:39], v[148:151], v[198:201], v[36:39]
	v_mfma_f32_16x16x32_bf16 v[32:35], v[156:159], v[198:201], v[32:35]
	v_mfma_f32_16x16x32_bf16 v[20:23], v[148:151], v[210:213], v[20:23]
	v_mfma_f32_16x16x32_bf16 v[16:19], v[156:159], v[210:213], v[16:19]
	v_mfma_f32_16x16x32_bf16 v[4:7], v[148:151], v[218:221], v[4:7]
	v_mfma_f32_16x16x32_bf16 v[0:3], v[156:159], v[218:221], v[0:3]
	s_barrier
	s_setprio 0
	s_add_i32 s13, 0, 0x18000
	s_add_i32 s16, 0, 0x1c000
	v_add_u32_e32 v140, s13, v181
	v_add_u32_e32 v156, s16, v181
	ds_read_b128 v[128:131], v140
	ds_read_b128 v[132:135], v140 offset:1024
	ds_read_b128 v[136:139], v140 offset:2048
	ds_read_b128 v[140:143], v140 offset:3072
	ds_read_b128 v[144:147], v156
	ds_read_b128 v[148:151], v156 offset:1024
	ds_read_b128 v[152:155], v156 offset:2048
	ds_read_b128 v[156:159], v156 offset:3072
	s_add_u32 s14, s42, 0x40000
	s_addc_u32 s15, s43, 0
	s_mov_b32 m0, s68
	v_lshl_add_u64 v[228:229], s[14:15], 0, v[170:171]
	ds_read_b128 v[186:189], v185 offset:32768
	ds_read_b128 v[190:193], v185 offset:33792
	ds_read_b128 v[194:197], v185 offset:34816
	ds_read_b128 v[198:201], v185 offset:35840
	ds_read_b128 v[206:209], v185 offset:36864
	ds_read_b128 v[210:213], v185 offset:37888
	ds_read_b128 v[214:217], v185 offset:38912
	ds_read_b128 v[218:221], v185 offset:39936
	global_load_lds_dwordx4 v[228:229], off
	v_lshl_add_u64 v[228:229], s[14:15], 0, v[166:167]
	s_mov_b32 m0, s69
	s_nop 0
	global_load_lds_dwordx4 v[228:229], off
	s_waitcnt vmcnt(8)
	s_waitcnt lgkmcnt(0)
	s_setprio 1
	s_barrier
	v_mfma_f32_16x16x32_bf16 v[120:123], v[128:131], v[186:189], v[120:123]
	v_mfma_f32_16x16x32_bf16 v[124:127], v[136:139], v[186:189], v[124:127]
	v_mfma_f32_16x16x32_bf16 v[104:107], v[128:131], v[194:197], v[104:107]
	v_mfma_f32_16x16x32_bf16 v[108:111], v[136:139], v[194:197], v[108:111]
	v_mfma_f32_16x16x32_bf16 v[88:91], v[128:131], v[206:209], v[88:91]
	v_mfma_f32_16x16x32_bf16 v[92:95], v[136:139], v[206:209], v[92:95]
	v_mfma_f32_16x16x32_bf16 v[72:75], v[128:131], v[214:217], v[72:75]
	v_mfma_f32_16x16x32_bf16 v[76:79], v[136:139], v[214:217], v[76:79]
	v_mfma_f32_16x16x32_bf16 v[120:123], v[132:135], v[190:193], v[120:123]
	v_mfma_f32_16x16x32_bf16 v[124:127], v[140:143], v[190:193], v[124:127]
	v_mfma_f32_16x16x32_bf16 v[104:107], v[132:135], v[198:201], v[104:107]
	v_mfma_f32_16x16x32_bf16 v[108:111], v[140:143], v[198:201], v[108:111]
	v_mfma_f32_16x16x32_bf16 v[88:91], v[132:135], v[210:213], v[88:91]
	v_mfma_f32_16x16x32_bf16 v[92:95], v[140:143], v[210:213], v[92:95]
	v_mfma_f32_16x16x32_bf16 v[72:75], v[132:135], v[218:221], v[72:75]
	v_mfma_f32_16x16x32_bf16 v[76:79], v[140:143], v[218:221], v[76:79]
	v_mfma_f32_16x16x32_bf16 v[116:119], v[144:147], v[186:189], v[116:119]
	v_mfma_f32_16x16x32_bf16 v[112:115], v[152:155], v[186:189], v[112:115]
	v_mfma_f32_16x16x32_bf16 v[100:103], v[144:147], v[194:197], v[100:103]
	v_mfma_f32_16x16x32_bf16 v[96:99], v[152:155], v[194:197], v[96:99]
	v_mfma_f32_16x16x32_bf16 v[84:87], v[144:147], v[206:209], v[84:87]
	v_mfma_f32_16x16x32_bf16 v[80:83], v[152:155], v[206:209], v[80:83]
	v_mfma_f32_16x16x32_bf16 v[68:71], v[144:147], v[214:217], v[68:71]
	v_mfma_f32_16x16x32_bf16 v[64:67], v[152:155], v[214:217], v[64:67]
	v_mfma_f32_16x16x32_bf16 v[116:119], v[148:151], v[190:193], v[116:119]
	v_mfma_f32_16x16x32_bf16 v[112:115], v[156:159], v[190:193], v[112:115]
	v_mfma_f32_16x16x32_bf16 v[100:103], v[148:151], v[198:201], v[100:103]
	v_mfma_f32_16x16x32_bf16 v[96:99], v[156:159], v[198:201], v[96:99]
	v_mfma_f32_16x16x32_bf16 v[84:87], v[148:151], v[210:213], v[84:87]
	v_mfma_f32_16x16x32_bf16 v[80:83], v[156:159], v[210:213], v[80:83]
	v_mfma_f32_16x16x32_bf16 v[68:71], v[148:151], v[218:221], v[68:71]
	v_mfma_f32_16x16x32_bf16 v[64:67], v[156:159], v[218:221], v[64:67]
	s_barrier
	s_setprio 0
	s_add_i32 s13, s13, s65
	v_lshl_add_u64 v[178:179], v[178:179], 0, s[76:77]
	s_mov_b32 m0, s13
	ds_read_b128 v[186:189], v185 offset:49152
	ds_read_b128 v[190:193], v185 offset:50176
	ds_read_b128 v[194:197], v185 offset:51200
	ds_read_b128 v[198:201], v185 offset:52224
	ds_read_b128 v[206:209], v185 offset:53248
	ds_read_b128 v[210:213], v185 offset:54272
	ds_read_b128 v[214:217], v185 offset:55296
	ds_read_b128 v[218:221], v185 offset:56320
	global_load_lds_dwordx4 v[178:179], off
	s_add_i32 m0, s13, 0x2000
	s_add_u32 s14, s40, 0x40080
	v_lshl_add_u64 v[178:179], v[222:223], 0, s[76:77]
	s_addc_u32 s15, s41, 0
	s_add_i32 s13, s16, s65
	global_load_lds_dwordx4 v[178:179], off
	v_lshl_add_u64 v[178:179], s[14:15], 0, v[168:169]
	s_mov_b32 m0, s13
	s_nop 0
	global_load_lds_dwordx4 v[178:179], off
	v_lshl_add_u64 v[178:179], s[14:15], 0, v[164:165]
	s_add_i32 m0, s13, 0x2000
	s_nop 0
	global_load_lds_dwordx4 v[178:179], off
	v_lshl_add_u64 v[178:179], v[224:225], 0, s[76:77]
	s_mov_b32 m0, s79
	s_nop 0
	global_load_lds_dwordx4 v[178:179], off
	v_lshl_add_u64 v[178:179], v[226:227], 0, s[76:77]
	s_mov_b32 m0, s46
	s_nop 0
	global_load_lds_dwordx4 v[178:179], off
	s_waitcnt vmcnt(8)
	s_waitcnt lgkmcnt(0)
	s_setprio 1
	s_barrier
	v_mfma_f32_16x16x32_bf16 v[56:59], v[128:131], v[186:189], v[56:59]
	v_mfma_f32_16x16x32_bf16 v[60:63], v[136:139], v[186:189], v[60:63]
	v_mfma_f32_16x16x32_bf16 v[40:43], v[128:131], v[194:197], v[40:43]
	v_mfma_f32_16x16x32_bf16 v[44:47], v[136:139], v[194:197], v[44:47]
	v_mfma_f32_16x16x32_bf16 v[24:27], v[128:131], v[206:209], v[24:27]
	v_mfma_f32_16x16x32_bf16 v[28:31], v[136:139], v[206:209], v[28:31]
	v_mfma_f32_16x16x32_bf16 v[8:11], v[128:131], v[214:217], v[8:11]
	v_mfma_f32_16x16x32_bf16 v[12:15], v[136:139], v[214:217], v[12:15]
	v_mfma_f32_16x16x32_bf16 v[56:59], v[132:135], v[190:193], v[56:59]
	v_mfma_f32_16x16x32_bf16 v[60:63], v[140:143], v[190:193], v[60:63]
	v_mfma_f32_16x16x32_bf16 v[40:43], v[132:135], v[198:201], v[40:43]
	v_mfma_f32_16x16x32_bf16 v[44:47], v[140:143], v[198:201], v[44:47]
	v_mfma_f32_16x16x32_bf16 v[24:27], v[132:135], v[210:213], v[24:27]
	v_mfma_f32_16x16x32_bf16 v[28:31], v[140:143], v[210:213], v[28:31]
	v_mfma_f32_16x16x32_bf16 v[8:11], v[132:135], v[218:221], v[8:11]
	v_mfma_f32_16x16x32_bf16 v[12:15], v[140:143], v[218:221], v[12:15]
	v_mfma_f32_16x16x32_bf16 v[52:55], v[144:147], v[186:189], v[52:55]
	v_mfma_f32_16x16x32_bf16 v[48:51], v[152:155], v[186:189], v[48:51]
	v_mfma_f32_16x16x32_bf16 v[36:39], v[144:147], v[194:197], v[36:39]
	v_mfma_f32_16x16x32_bf16 v[32:35], v[152:155], v[194:197], v[32:35]
	v_mfma_f32_16x16x32_bf16 v[20:23], v[144:147], v[206:209], v[20:23]
	v_mfma_f32_16x16x32_bf16 v[16:19], v[152:155], v[206:209], v[16:19]
	v_mfma_f32_16x16x32_bf16 v[4:7], v[144:147], v[214:217], v[4:7]
	v_mfma_f32_16x16x32_bf16 v[0:3], v[152:155], v[214:217], v[0:3]
	v_mfma_f32_16x16x32_bf16 v[52:55], v[148:151], v[190:193], v[52:55]
	v_mfma_f32_16x16x32_bf16 v[48:51], v[156:159], v[190:193], v[48:51]
	v_mfma_f32_16x16x32_bf16 v[36:39], v[148:151], v[198:201], v[36:39]
	v_mfma_f32_16x16x32_bf16 v[32:35], v[156:159], v[198:201], v[32:35]
	v_mfma_f32_16x16x32_bf16 v[20:23], v[148:151], v[210:213], v[20:23]
	v_mfma_f32_16x16x32_bf16 v[16:19], v[156:159], v[210:213], v[16:19]
	v_mfma_f32_16x16x32_bf16 v[4:7], v[148:151], v[218:221], v[4:7]
	v_mfma_f32_16x16x32_bf16 v[0:3], v[156:159], v[218:221], v[0:3]
	s_barrier
	s_setprio 0
	s_add_i32 s12, s12, 2
	s_add_u32 s38, s38, 0x100
	s_addc_u32 s39, s39, 0
	s_add_u32 s10, s10, 0x100
	s_addc_u32 s11, s11, 0
	s_cmp_gt_u32 s12, 13
	s_cbranch_scc0 .LBB0_650

.LBB0_698:
	s_ashr_i32 s39, s38, 31
	s_lshl_b64 s[16:17], s[38:39], 19
	s_add_u32 s42, s4, s16
	s_addc_u32 s43, s5, s17
	s_and_b64 s[16:17], s[48:49], exec
	s_cselect_b32 s16, s43, s63
	s_cselect_b32 s17, s42, s62
	s_ashr_i32 s41, s40, 31
	s_lshl_b64 s[18:19], s[40:41], 19
	s_add_u32 s58, s96, s18
	s_addc_u32 s59, s97, s19
	s_and_b64 s[18:19], s[48:49], exec
	s_cselect_b32 s39, s59, s67
	s_cselect_b32 s41, s58, s66
	s_add_u32 s62, s62, 0x40080
	s_addc_u32 s63, s63, 0
	s_add_u32 s47, s66, 0x100
	s_addc_u32 s54, s67, 0
	s_mov_b32 s61, -2
	s_add_u32 s18, s62, 0xfffc0080
	s_addc_u32 s19, s63, -1
	s_add_i32 s20, 0, 0x10000
	s_cmp_eq_u32 s61, 12
	s_cselect_b32 s65, s16, s19
	s_cselect_b32 s64, s17, s18
	s_cselect_b32 s51, s39, s54
	s_cselect_b32 s50, s41, s47
	s_add_i32 s21, 0, 0x14000
	v_add_u32_e32 v156, s20, v141
	v_add_u32_e32 v162, s21, v141
	ds_read_b128 v[144:147], v156
	ds_read_b128 v[148:151], v156 offset:1024
	ds_read_b128 v[152:155], v156 offset:2048
	ds_read_b128 v[156:159], v156 offset:3072
	ds_read_b128 v[164:167], v162
	ds_read_b128 v[168:171], v162 offset:1024
	ds_read_b128 v[172:175], v162 offset:2048
	ds_read_b128 v[176:179], v162 offset:3072
	v_lshl_add_u64 v[200:201], s[62:63], 0, v[136:137]
	s_add_i32 m0, s8, 0xc000
	ds_read_b128 v[180:183], v143
	ds_read_b128 v[184:187], v143 offset:1024
	ds_read_b128 v[188:191], v143 offset:2048
	ds_read_b128 v[192:195], v143 offset:3072
	ds_read_b128 v[196:199], v143 offset:4096
	ds_read_b128 v[206:209], v143 offset:5120
	ds_read_b128 v[210:213], v143 offset:6144
	ds_read_b128 v[214:217], v143 offset:7168
	global_load_lds_dwordx4 v[200:201], off
	v_lshl_add_u64 v[200:201], s[62:63], 0, v[138:139]
	s_add_i32 m0, s8, 0xe000
	s_nop 0
	global_load_lds_dwordx4 v[200:201], off
	s_waitcnt vmcnt(8)
	s_waitcnt lgkmcnt(0)
	s_setprio 1
	s_barrier
	v_mfma_f32_16x16x32_bf16 v[124:127], v[144:147], v[180:183], 0
	v_mfma_f32_16x16x32_bf16 v[120:123], v[152:155], v[180:183], 0
	v_mfma_f32_16x16x32_bf16 v[116:119], v[144:147], v[188:191], 0
	v_mfma_f32_16x16x32_bf16 v[108:111], v[152:155], v[188:191], 0
	v_mfma_f32_16x16x32_bf16 v[100:103], v[144:147], v[196:199], 0
	v_mfma_f32_16x16x32_bf16 v[92:95], v[152:155], v[196:199], 0
	v_mfma_f32_16x16x32_bf16 v[84:87], v[144:147], v[210:213], 0
	v_mfma_f32_16x16x32_bf16 v[76:79], v[152:155], v[210:213], 0
	v_mfma_f32_16x16x32_bf16 v[124:127], v[148:151], v[184:187], v[124:127]
	v_mfma_f32_16x16x32_bf16 v[120:123], v[156:159], v[184:187], v[120:123]
	v_mfma_f32_16x16x32_bf16 v[116:119], v[148:151], v[192:195], v[116:119]
	v_mfma_f32_16x16x32_bf16 v[108:111], v[156:159], v[192:195], v[108:111]
	v_mfma_f32_16x16x32_bf16 v[100:103], v[148:151], v[206:209], v[100:103]
	v_mfma_f32_16x16x32_bf16 v[92:95], v[156:159], v[206:209], v[92:95]
	v_mfma_f32_16x16x32_bf16 v[84:87], v[148:151], v[214:217], v[84:87]
	v_mfma_f32_16x16x32_bf16 v[76:79], v[156:159], v[214:217], v[76:79]
	v_mfma_f32_16x16x32_bf16 v[112:115], v[164:167], v[180:183], 0
	v_mfma_f32_16x16x32_bf16 v[104:107], v[172:175], v[180:183], 0
	v_mfma_f32_16x16x32_bf16 v[96:99], v[164:167], v[188:191], 0
	v_mfma_f32_16x16x32_bf16 v[88:91], v[172:175], v[188:191], 0
	v_mfma_f32_16x16x32_bf16 v[80:83], v[164:167], v[196:199], 0
	v_mfma_f32_16x16x32_bf16 v[72:75], v[172:175], v[196:199], 0
	v_mfma_f32_16x16x32_bf16 v[68:71], v[164:167], v[210:213], 0
	v_mfma_f32_16x16x32_bf16 v[64:67], v[172:175], v[210:213], 0
	v_mfma_f32_16x16x32_bf16 v[112:115], v[168:171], v[184:187], v[112:115]
	v_mfma_f32_16x16x32_bf16 v[104:107], v[176:179], v[184:187], v[104:107]
	v_mfma_f32_16x16x32_bf16 v[96:99], v[168:171], v[192:195], v[96:99]
	v_mfma_f32_16x16x32_bf16 v[88:91], v[176:179], v[192:195], v[88:91]
	v_mfma_f32_16x16x32_bf16 v[80:83], v[168:171], v[206:209], v[80:83]
	v_mfma_f32_16x16x32_bf16 v[72:75], v[176:179], v[206:209], v[72:75]
	v_mfma_f32_16x16x32_bf16 v[68:71], v[168:171], v[214:217], v[68:71]
	v_mfma_f32_16x16x32_bf16 v[64:67], v[176:179], v[214:217], v[64:67]
	s_barrier
	s_setprio 0
	s_add_i32 s18, s20, s7
	v_lshl_add_u64 v[200:201], s[50:51], 0, v[132:133]
	s_mov_b32 m0, s18
	ds_read_b128 v[180:183], v143 offset:16384
	ds_read_b128 v[184:187], v143 offset:17408
	ds_read_b128 v[188:191], v143 offset:18432
	ds_read_b128 v[192:195], v143 offset:19456
	ds_read_b128 v[196:199], v143 offset:20480
	ds_read_b128 v[206:209], v143 offset:21504
	ds_read_b128 v[210:213], v143 offset:22528
	ds_read_b128 v[214:217], v143 offset:23552
	global_load_lds_dwordx4 v[200:201], off
	s_add_i32 m0, s18, 0x2000
	s_add_u32 s18, s50, 0x40000
	v_lshl_add_u64 v[218:219], s[50:51], 0, v[128:129]
	s_addc_u32 s19, s51, 0
	s_add_i32 s20, s21, s7
	global_load_lds_dwordx4 v[218:219], off
	v_lshl_add_u64 v[220:221], s[18:19], 0, v[132:133]
	s_mov_b32 m0, s20
	v_lshl_add_u64 v[222:223], s[64:65], 0, v[130:131]
	global_load_lds_dwordx4 v[220:221], off
	v_lshl_add_u64 v[220:221], s[18:19], 0, v[128:129]
	s_add_i32 m0, s20, 0x2000
	s_nop 0
	global_load_lds_dwordx4 v[220:221], off
	v_lshl_add_u64 v[220:221], s[64:65], 0, v[134:135]
	s_mov_b32 m0, s8
	s_nop 0
	global_load_lds_dwordx4 v[220:221], off
	s_mov_b32 m0, s9
	s_nop 0
	global_load_lds_dwordx4 v[222:223], off
	s_waitcnt vmcnt(8)
	s_waitcnt lgkmcnt(0)
	s_setprio 1
	s_barrier
	v_mfma_f32_16x16x32_bf16 v[60:63], v[144:147], v[180:183], 0
	v_mfma_f32_16x16x32_bf16 v[56:59], v[152:155], v[180:183], 0
	v_mfma_f32_16x16x32_bf16 v[52:55], v[144:147], v[188:191], 0
	v_mfma_f32_16x16x32_bf16 v[44:47], v[152:155], v[188:191], 0
	v_mfma_f32_16x16x32_bf16 v[36:39], v[144:147], v[196:199], 0
	v_mfma_f32_16x16x32_bf16 v[28:31], v[152:155], v[196:199], 0
	v_mfma_f32_16x16x32_bf16 v[20:23], v[144:147], v[210:213], 0
	v_mfma_f32_16x16x32_bf16 v[12:15], v[152:155], v[210:213], 0
	v_mfma_f32_16x16x32_bf16 v[60:63], v[148:151], v[184:187], v[60:63]
	v_mfma_f32_16x16x32_bf16 v[56:59], v[156:159], v[184:187], v[56:59]
	v_mfma_f32_16x16x32_bf16 v[52:55], v[148:151], v[192:195], v[52:55]
	v_mfma_f32_16x16x32_bf16 v[44:47], v[156:159], v[192:195], v[44:47]
	v_mfma_f32_16x16x32_bf16 v[36:39], v[148:151], v[206:209], v[36:39]
	v_mfma_f32_16x16x32_bf16 v[28:31], v[156:159], v[206:209], v[28:31]
	v_mfma_f32_16x16x32_bf16 v[20:23], v[148:151], v[214:217], v[20:23]
	v_mfma_f32_16x16x32_bf16 v[12:15], v[156:159], v[214:217], v[12:15]
	v_mfma_f32_16x16x32_bf16 v[48:51], v[164:167], v[180:183], 0
	v_mfma_f32_16x16x32_bf16 v[40:43], v[172:175], v[180:183], 0
	v_mfma_f32_16x16x32_bf16 v[32:35], v[164:167], v[188:191], 0
	v_mfma_f32_16x16x32_bf16 v[24:27], v[172:175], v[188:191], 0
	v_mfma_f32_16x16x32_bf16 v[16:19], v[164:167], v[196:199], 0
	v_mfma_f32_16x16x32_bf16 v[8:11], v[172:175], v[196:199], 0
	v_mfma_f32_16x16x32_bf16 v[4:7], v[164:167], v[210:213], 0
	v_mfma_f32_16x16x32_bf16 v[0:3], v[172:175], v[210:213], 0
	v_mfma_f32_16x16x32_bf16 v[48:51], v[168:171], v[184:187], v[48:51]
	v_mfma_f32_16x16x32_bf16 v[40:43], v[176:179], v[184:187], v[40:43]
	v_mfma_f32_16x16x32_bf16 v[32:35], v[168:171], v[192:195], v[32:35]
	v_mfma_f32_16x16x32_bf16 v[24:27], v[176:179], v[192:195], v[24:27]
	v_mfma_f32_16x16x32_bf16 v[16:19], v[168:171], v[206:209], v[16:19]
	v_mfma_f32_16x16x32_bf16 v[8:11], v[176:179], v[206:209], v[8:11]
	v_mfma_f32_16x16x32_bf16 v[4:7], v[168:171], v[214:217], v[4:7]
	v_mfma_f32_16x16x32_bf16 v[0:3], v[176:179], v[214:217], v[0:3]
	s_barrier
	s_setprio 0
	s_add_i32 s20, 0, 0x18000
	s_add_i32 s21, 0, 0x1c000
	v_add_u32_e32 v156, s20, v141
	v_add_u32_e32 v162, s21, v141
	ds_read_b128 v[144:147], v156
	ds_read_b128 v[148:151], v156 offset:1024
	ds_read_b128 v[152:155], v156 offset:2048
	ds_read_b128 v[156:159], v156 offset:3072
	ds_read_b128 v[164:167], v162
	ds_read_b128 v[168:171], v162 offset:1024
	ds_read_b128 v[172:175], v162 offset:2048
	ds_read_b128 v[176:179], v162 offset:3072
	s_add_u32 s18, s64, 0x40000
	s_addc_u32 s19, s65, 0
	s_mov_b32 m0, s10
	v_lshl_add_u64 v[224:225], s[18:19], 0, v[134:135]
	ds_read_b128 v[180:183], v143 offset:32768
	ds_read_b128 v[184:187], v143 offset:33792
	ds_read_b128 v[188:191], v143 offset:34816
	ds_read_b128 v[192:195], v143 offset:35840
	ds_read_b128 v[196:199], v143 offset:36864
	ds_read_b128 v[206:209], v143 offset:37888
	ds_read_b128 v[210:213], v143 offset:38912
	ds_read_b128 v[214:217], v143 offset:39936
	global_load_lds_dwordx4 v[224:225], off
	v_lshl_add_u64 v[224:225], s[18:19], 0, v[130:131]
	s_mov_b32 m0, s11
	s_nop 0
	global_load_lds_dwordx4 v[224:225], off
	s_waitcnt vmcnt(8)
	s_waitcnt lgkmcnt(0)
	s_setprio 1
	s_barrier
	v_mfma_f32_16x16x32_bf16 v[124:127], v[144:147], v[180:183], v[124:127]
	v_mfma_f32_16x16x32_bf16 v[120:123], v[152:155], v[180:183], v[120:123]
	v_mfma_f32_16x16x32_bf16 v[116:119], v[144:147], v[188:191], v[116:119]
	v_mfma_f32_16x16x32_bf16 v[108:111], v[152:155], v[188:191], v[108:111]
	v_mfma_f32_16x16x32_bf16 v[100:103], v[144:147], v[196:199], v[100:103]
	v_mfma_f32_16x16x32_bf16 v[92:95], v[152:155], v[196:199], v[92:95]
	v_mfma_f32_16x16x32_bf16 v[84:87], v[144:147], v[210:213], v[84:87]
	v_mfma_f32_16x16x32_bf16 v[76:79], v[152:155], v[210:213], v[76:79]
	v_mfma_f32_16x16x32_bf16 v[124:127], v[148:151], v[184:187], v[124:127]
	v_mfma_f32_16x16x32_bf16 v[120:123], v[156:159], v[184:187], v[120:123]
	v_mfma_f32_16x16x32_bf16 v[116:119], v[148:151], v[192:195], v[116:119]
	v_mfma_f32_16x16x32_bf16 v[108:111], v[156:159], v[192:195], v[108:111]
	v_mfma_f32_16x16x32_bf16 v[100:103], v[148:151], v[206:209], v[100:103]
	v_mfma_f32_16x16x32_bf16 v[92:95], v[156:159], v[206:209], v[92:95]
	v_mfma_f32_16x16x32_bf16 v[84:87], v[148:151], v[214:217], v[84:87]
	v_mfma_f32_16x16x32_bf16 v[76:79], v[156:159], v[214:217], v[76:79]
	v_mfma_f32_16x16x32_bf16 v[112:115], v[164:167], v[180:183], v[112:115]
	v_mfma_f32_16x16x32_bf16 v[104:107], v[172:175], v[180:183], v[104:107]
	v_mfma_f32_16x16x32_bf16 v[96:99], v[164:167], v[188:191], v[96:99]
	v_mfma_f32_16x16x32_bf16 v[88:91], v[172:175], v[188:191], v[88:91]
	v_mfma_f32_16x16x32_bf16 v[80:83], v[164:167], v[196:199], v[80:83]
	v_mfma_f32_16x16x32_bf16 v[72:75], v[172:175], v[196:199], v[72:75]
	v_mfma_f32_16x16x32_bf16 v[68:71], v[164:167], v[210:213], v[68:71]
	v_mfma_f32_16x16x32_bf16 v[64:67], v[172:175], v[210:213], v[64:67]
	v_mfma_f32_16x16x32_bf16 v[112:115], v[168:171], v[184:187], v[112:115]
	v_mfma_f32_16x16x32_bf16 v[104:107], v[176:179], v[184:187], v[104:107]
	v_mfma_f32_16x16x32_bf16 v[96:99], v[168:171], v[192:195], v[96:99]
	v_mfma_f32_16x16x32_bf16 v[88:91], v[176:179], v[192:195], v[88:91]
	v_mfma_f32_16x16x32_bf16 v[80:83], v[168:171], v[206:209], v[80:83]
	v_mfma_f32_16x16x32_bf16 v[72:75], v[176:179], v[206:209], v[72:75]
	v_mfma_f32_16x16x32_bf16 v[68:71], v[168:171], v[214:217], v[68:71]
	v_mfma_f32_16x16x32_bf16 v[64:67], v[176:179], v[214:217], v[64:67]
	s_barrier
	s_setprio 0
	s_add_i32 s18, s20, s7
	v_lshl_add_u64 v[200:201], v[200:201], 0, s[76:77]
	s_mov_b32 m0, s18
	ds_read_b128 v[180:183], v143 offset:49152
	ds_read_b128 v[184:187], v143 offset:50176
	ds_read_b128 v[188:191], v143 offset:51200
	ds_read_b128 v[192:195], v143 offset:52224
	ds_read_b128 v[196:199], v143 offset:53248
	ds_read_b128 v[206:209], v143 offset:54272
	ds_read_b128 v[210:213], v143 offset:55296
	ds_read_b128 v[214:217], v143 offset:56320
	global_load_lds_dwordx4 v[200:201], off
	s_add_i32 m0, s18, 0x2000
	s_add_u32 s18, s50, 0x40080
	v_lshl_add_u64 v[200:201], v[218:219], 0, s[76:77]
	s_addc_u32 s19, s51, 0
	s_add_i32 s20, s21, s7
	global_load_lds_dwordx4 v[200:201], off
	v_lshl_add_u64 v[200:201], s[18:19], 0, v[132:133]
	s_mov_b32 m0, s20
	s_nop 0
	global_load_lds_dwordx4 v[200:201], off
	v_lshl_add_u64 v[200:201], s[18:19], 0, v[128:129]
	s_add_i32 m0, s20, 0x2000
	s_nop 0
	global_load_lds_dwordx4 v[200:201], off
	v_lshl_add_u64 v[200:201], v[220:221], 0, s[76:77]
	s_mov_b32 m0, s13
	s_nop 0
	global_load_lds_dwordx4 v[200:201], off
	v_lshl_add_u64 v[200:201], v[222:223], 0, s[76:77]
	s_mov_b32 m0, s14
	s_nop 0
	global_load_lds_dwordx4 v[200:201], off
	s_waitcnt vmcnt(8)
	s_waitcnt lgkmcnt(0)
	s_setprio 1
	s_barrier
	v_mfma_f32_16x16x32_bf16 v[60:63], v[144:147], v[180:183], v[60:63]
	v_mfma_f32_16x16x32_bf16 v[56:59], v[152:155], v[180:183], v[56:59]
	v_mfma_f32_16x16x32_bf16 v[52:55], v[144:147], v[188:191], v[52:55]
	v_mfma_f32_16x16x32_bf16 v[44:47], v[152:155], v[188:191], v[44:47]
	v_mfma_f32_16x16x32_bf16 v[36:39], v[144:147], v[196:199], v[36:39]
	v_mfma_f32_16x16x32_bf16 v[28:31], v[152:155], v[196:199], v[28:31]
	v_mfma_f32_16x16x32_bf16 v[20:23], v[144:147], v[210:213], v[20:23]
	v_mfma_f32_16x16x32_bf16 v[12:15], v[152:155], v[210:213], v[12:15]
	v_mfma_f32_16x16x32_bf16 v[60:63], v[148:151], v[184:187], v[60:63]
	v_mfma_f32_16x16x32_bf16 v[56:59], v[156:159], v[184:187], v[56:59]
	v_mfma_f32_16x16x32_bf16 v[52:55], v[148:151], v[192:195], v[52:55]
	v_mfma_f32_16x16x32_bf16 v[44:47], v[156:159], v[192:195], v[44:47]
	v_mfma_f32_16x16x32_bf16 v[36:39], v[148:151], v[206:209], v[36:39]
	v_mfma_f32_16x16x32_bf16 v[28:31], v[156:159], v[206:209], v[28:31]
	v_mfma_f32_16x16x32_bf16 v[20:23], v[148:151], v[214:217], v[20:23]
	v_mfma_f32_16x16x32_bf16 v[12:15], v[156:159], v[214:217], v[12:15]
	v_mfma_f32_16x16x32_bf16 v[48:51], v[164:167], v[180:183], v[48:51]
	v_mfma_f32_16x16x32_bf16 v[40:43], v[172:175], v[180:183], v[40:43]
	v_mfma_f32_16x16x32_bf16 v[32:35], v[164:167], v[188:191], v[32:35]
	v_mfma_f32_16x16x32_bf16 v[24:27], v[172:175], v[188:191], v[24:27]
	v_mfma_f32_16x16x32_bf16 v[16:19], v[164:167], v[196:199], v[16:19]
	v_mfma_f32_16x16x32_bf16 v[8:11], v[172:175], v[196:199], v[8:11]
	v_mfma_f32_16x16x32_bf16 v[4:7], v[164:167], v[210:213], v[4:7]
	v_mfma_f32_16x16x32_bf16 v[0:3], v[172:175], v[210:213], v[0:3]
	v_mfma_f32_16x16x32_bf16 v[48:51], v[168:171], v[184:187], v[48:51]
	v_mfma_f32_16x16x32_bf16 v[40:43], v[176:179], v[184:187], v[40:43]
	v_mfma_f32_16x16x32_bf16 v[32:35], v[168:171], v[192:195], v[32:35]
	v_mfma_f32_16x16x32_bf16 v[24:27], v[176:179], v[192:195], v[24:27]
	v_mfma_f32_16x16x32_bf16 v[16:19], v[168:171], v[206:209], v[16:19]
	v_mfma_f32_16x16x32_bf16 v[8:11], v[176:179], v[206:209], v[8:11]
	v_mfma_f32_16x16x32_bf16 v[4:7], v[168:171], v[214:217], v[4:7]
	v_mfma_f32_16x16x32_bf16 v[0:3], v[176:179], v[214:217], v[0:3]
	s_barrier
	s_setprio 0
	s_add_i32 s61, s61, 2
	s_add_u32 s62, s62, 0x100
	s_addc_u32 s63, s63, 0
	s_add_u32 s47, s47, 0x100
	s_addc_u32 s54, s54, 0
	s_cmp_gt_u32 s61, 13
	s_cbranch_scc0 .LBB0_699
	s_branch .Lpeel_x_699
.LBB0_699:
	s_add_u32 s18, s62, 0xfffc0080
	s_addc_u32 s19, s63, -1
	s_add_i32 s20, 0, 0x10000
	s_cmp_eq_u32 s61, 12
	s_cselect_b32 s65, s16, s19
	s_cselect_b32 s64, s17, s18
	s_cselect_b32 s51, s39, s54
	s_cselect_b32 s50, s41, s47
	s_add_i32 s21, 0, 0x14000
	v_add_u32_e32 v156, s20, v141
	v_add_u32_e32 v162, s21, v141
	ds_read_b128 v[144:147], v156
	ds_read_b128 v[148:151], v156 offset:1024
	ds_read_b128 v[152:155], v156 offset:2048
	ds_read_b128 v[156:159], v156 offset:3072
	ds_read_b128 v[164:167], v162
	ds_read_b128 v[168:171], v162 offset:1024
	ds_read_b128 v[172:175], v162 offset:2048
	ds_read_b128 v[176:179], v162 offset:3072
	v_lshl_add_u64 v[200:201], s[62:63], 0, v[136:137]
	s_add_i32 m0, s8, 0xc000
	ds_read_b128 v[180:183], v143
	ds_read_b128 v[184:187], v143 offset:1024
	ds_read_b128 v[188:191], v143 offset:2048
	ds_read_b128 v[192:195], v143 offset:3072
	ds_read_b128 v[196:199], v143 offset:4096
	ds_read_b128 v[206:209], v143 offset:5120
	ds_read_b128 v[210:213], v143 offset:6144
	ds_read_b128 v[214:217], v143 offset:7168
	global_load_lds_dwordx4 v[200:201], off
	v_lshl_add_u64 v[200:201], s[62:63], 0, v[138:139]
	s_add_i32 m0, s8, 0xe000
	s_nop 0
	global_load_lds_dwordx4 v[200:201], off
	s_waitcnt vmcnt(8)
	s_waitcnt lgkmcnt(0)
	s_setprio 1
	s_barrier
	v_mfma_f32_16x16x32_bf16 v[124:127], v[144:147], v[180:183], v[124:127]
	v_mfma_f32_16x16x32_bf16 v[120:123], v[152:155], v[180:183], v[120:123]
	v_mfma_f32_16x16x32_bf16 v[116:119], v[144:147], v[188:191], v[116:119]
	v_mfma_f32_16x16x32_bf16 v[108:111], v[152:155], v[188:191], v[108:111]
	v_mfma_f32_16x16x32_bf16 v[100:103], v[144:147], v[196:199], v[100:103]
	v_mfma_f32_16x16x32_bf16 v[92:95], v[152:155], v[196:199], v[92:95]
	v_mfma_f32_16x16x32_bf16 v[84:87], v[144:147], v[210:213], v[84:87]
	v_mfma_f32_16x16x32_bf16 v[76:79], v[152:155], v[210:213], v[76:79]
	v_mfma_f32_16x16x32_bf16 v[124:127], v[148:151], v[184:187], v[124:127]
	v_mfma_f32_16x16x32_bf16 v[120:123], v[156:159], v[184:187], v[120:123]
	v_mfma_f32_16x16x32_bf16 v[116:119], v[148:151], v[192:195], v[116:119]
	v_mfma_f32_16x16x32_bf16 v[108:111], v[156:159], v[192:195], v[108:111]
	v_mfma_f32_16x16x32_bf16 v[100:103], v[148:151], v[206:209], v[100:103]
	v_mfma_f32_16x16x32_bf16 v[92:95], v[156:159], v[206:209], v[92:95]
	v_mfma_f32_16x16x32_bf16 v[84:87], v[148:151], v[214:217], v[84:87]
	v_mfma_f32_16x16x32_bf16 v[76:79], v[156:159], v[214:217], v[76:79]
	v_mfma_f32_16x16x32_bf16 v[112:115], v[164:167], v[180:183], v[112:115]
	v_mfma_f32_16x16x32_bf16 v[104:107], v[172:175], v[180:183], v[104:107]
	v_mfma_f32_16x16x32_bf16 v[96:99], v[164:167], v[188:191], v[96:99]
	v_mfma_f32_16x16x32_bf16 v[88:91], v[172:175], v[188:191], v[88:91]
	v_mfma_f32_16x16x32_bf16 v[80:83], v[164:167], v[196:199], v[80:83]
	v_mfma_f32_16x16x32_bf16 v[72:75], v[172:175], v[196:199], v[72:75]
	v_mfma_f32_16x16x32_bf16 v[68:71], v[164:167], v[210:213], v[68:71]
	v_mfma_f32_16x16x32_bf16 v[64:67], v[172:175], v[210:213], v[64:67]
	v_mfma_f32_16x16x32_bf16 v[112:115], v[168:171], v[184:187], v[112:115]
	v_mfma_f32_16x16x32_bf16 v[104:107], v[176:179], v[184:187], v[104:107]
	v_mfma_f32_16x16x32_bf16 v[96:99], v[168:171], v[192:195], v[96:99]
	v_mfma_f32_16x16x32_bf16 v[88:91], v[176:179], v[192:195], v[88:91]
	v_mfma_f32_16x16x32_bf16 v[80:83], v[168:171], v[206:209], v[80:83]
	v_mfma_f32_16x16x32_bf16 v[72:75], v[176:179], v[206:209], v[72:75]
	v_mfma_f32_16x16x32_bf16 v[68:71], v[168:171], v[214:217], v[68:71]
	v_mfma_f32_16x16x32_bf16 v[64:67], v[176:179], v[214:217], v[64:67]
	s_barrier
	s_setprio 0
	s_add_i32 s18, s20, s7
	v_lshl_add_u64 v[200:201], s[50:51], 0, v[132:133]
	s_mov_b32 m0, s18
	ds_read_b128 v[180:183], v143 offset:16384
	ds_read_b128 v[184:187], v143 offset:17408
	ds_read_b128 v[188:191], v143 offset:18432
	ds_read_b128 v[192:195], v143 offset:19456
	ds_read_b128 v[196:199], v143 offset:20480
	ds_read_b128 v[206:209], v143 offset:21504
	ds_read_b128 v[210:213], v143 offset:22528
	ds_read_b128 v[214:217], v143 offset:23552
	global_load_lds_dwordx4 v[200:201], off
	s_add_i32 m0, s18, 0x2000
	s_add_u32 s18, s50, 0x40000
	v_lshl_add_u64 v[218:219], s[50:51], 0, v[128:129]
	s_addc_u32 s19, s51, 0
	s_add_i32 s20, s21, s7
	global_load_lds_dwordx4 v[218:219], off
	v_lshl_add_u64 v[220:221], s[18:19], 0, v[132:133]
	s_mov_b32 m0, s20
	v_lshl_add_u64 v[222:223], s[64:65], 0, v[130:131]
	global_load_lds_dwordx4 v[220:221], off
	v_lshl_add_u64 v[220:221], s[18:19], 0, v[128:129]
	s_add_i32 m0, s20, 0x2000
	s_nop 0
	global_load_lds_dwordx4 v[220:221], off
	v_lshl_add_u64 v[220:221], s[64:65], 0, v[134:135]
	s_mov_b32 m0, s8
	s_nop 0
	global_load_lds_dwordx4 v[220:221], off
	s_mov_b32 m0, s9
	s_nop 0
	global_load_lds_dwordx4 v[222:223], off
	s_waitcnt vmcnt(8)
	s_waitcnt lgkmcnt(0)
	s_setprio 1
	s_barrier
	v_mfma_f32_16x16x32_bf16 v[60:63], v[144:147], v[180:183], v[60:63]
	v_mfma_f32_16x16x32_bf16 v[56:59], v[152:155], v[180:183], v[56:59]
	v_mfma_f32_16x16x32_bf16 v[52:55], v[144:147], v[188:191], v[52:55]
	v_mfma_f32_16x16x32_bf16 v[44:47], v[152:155], v[188:191], v[44:47]
	v_mfma_f32_16x16x32_bf16 v[36:39], v[144:147], v[196:199], v[36:39]
	v_mfma_f32_16x16x32_bf16 v[28:31], v[152:155], v[196:199], v[28:31]
	v_mfma_f32_16x16x32_bf16 v[20:23], v[144:147], v[210:213], v[20:23]
	v_mfma_f32_16x16x32_bf16 v[12:15], v[152:155], v[210:213], v[12:15]
	v_mfma_f32_16x16x32_bf16 v[60:63], v[148:151], v[184:187], v[60:63]
	v_mfma_f32_16x16x32_bf16 v[56:59], v[156:159], v[184:187], v[56:59]
	v_mfma_f32_16x16x32_bf16 v[52:55], v[148:151], v[192:195], v[52:55]
	v_mfma_f32_16x16x32_bf16 v[44:47], v[156:159], v[192:195], v[44:47]
	v_mfma_f32_16x16x32_bf16 v[36:39], v[148:151], v[206:209], v[36:39]
	v_mfma_f32_16x16x32_bf16 v[28:31], v[156:159], v[206:209], v[28:31]
	v_mfma_f32_16x16x32_bf16 v[20:23], v[148:151], v[214:217], v[20:23]
	v_mfma_f32_16x16x32_bf16 v[12:15], v[156:159], v[214:217], v[12:15]
	v_mfma_f32_16x16x32_bf16 v[48:51], v[164:167], v[180:183], v[48:51]
	v_mfma_f32_16x16x32_bf16 v[40:43], v[172:175], v[180:183], v[40:43]
	v_mfma_f32_16x16x32_bf16 v[32:35], v[164:167], v[188:191], v[32:35]
	v_mfma_f32_16x16x32_bf16 v[24:27], v[172:175], v[188:191], v[24:27]
	v_mfma_f32_16x16x32_bf16 v[16:19], v[164:167], v[196:199], v[16:19]
	v_mfma_f32_16x16x32_bf16 v[8:11], v[172:175], v[196:199], v[8:11]
	v_mfma_f32_16x16x32_bf16 v[4:7], v[164:167], v[210:213], v[4:7]
	v_mfma_f32_16x16x32_bf16 v[0:3], v[172:175], v[210:213], v[0:3]
	v_mfma_f32_16x16x32_bf16 v[48:51], v[168:171], v[184:187], v[48:51]
	v_mfma_f32_16x16x32_bf16 v[40:43], v[176:179], v[184:187], v[40:43]
	v_mfma_f32_16x16x32_bf16 v[32:35], v[168:171], v[192:195], v[32:35]
	v_mfma_f32_16x16x32_bf16 v[24:27], v[176:179], v[192:195], v[24:27]
	v_mfma_f32_16x16x32_bf16 v[16:19], v[168:171], v[206:209], v[16:19]
	v_mfma_f32_16x16x32_bf16 v[8:11], v[176:179], v[206:209], v[8:11]
	v_mfma_f32_16x16x32_bf16 v[4:7], v[168:171], v[214:217], v[4:7]
	v_mfma_f32_16x16x32_bf16 v[0:3], v[176:179], v[214:217], v[0:3]
	s_barrier
	s_setprio 0
	s_add_i32 s20, 0, 0x18000
	s_add_i32 s21, 0, 0x1c000
	v_add_u32_e32 v156, s20, v141
	v_add_u32_e32 v162, s21, v141
	ds_read_b128 v[144:147], v156
	ds_read_b128 v[148:151], v156 offset:1024
	ds_read_b128 v[152:155], v156 offset:2048
	ds_read_b128 v[156:159], v156 offset:3072
	ds_read_b128 v[164:167], v162
	ds_read_b128 v[168:171], v162 offset:1024
	ds_read_b128 v[172:175], v162 offset:2048
	ds_read_b128 v[176:179], v162 offset:3072
	s_add_u32 s18, s64, 0x40000
	s_addc_u32 s19, s65, 0
	s_mov_b32 m0, s10
	v_lshl_add_u64 v[224:225], s[18:19], 0, v[134:135]
	ds_read_b128 v[180:183], v143 offset:32768
	ds_read_b128 v[184:187], v143 offset:33792
	ds_read_b128 v[188:191], v143 offset:34816
	ds_read_b128 v[192:195], v143 offset:35840
	ds_read_b128 v[196:199], v143 offset:36864
	ds_read_b128 v[206:209], v143 offset:37888
	ds_read_b128 v[210:213], v143 offset:38912
	ds_read_b128 v[214:217], v143 offset:39936
	global_load_lds_dwordx4 v[224:225], off
	v_lshl_add_u64 v[224:225], s[18:19], 0, v[130:131]
	s_mov_b32 m0, s11
	s_nop 0
	global_load_lds_dwordx4 v[224:225], off
	s_waitcnt vmcnt(8)
	s_waitcnt lgkmcnt(0)
	s_setprio 1
	s_barrier
	v_mfma_f32_16x16x32_bf16 v[124:127], v[144:147], v[180:183], v[124:127]
	v_mfma_f32_16x16x32_bf16 v[120:123], v[152:155], v[180:183], v[120:123]
	v_mfma_f32_16x16x32_bf16 v[116:119], v[144:147], v[188:191], v[116:119]
	v_mfma_f32_16x16x32_bf16 v[108:111], v[152:155], v[188:191], v[108:111]
	v_mfma_f32_16x16x32_bf16 v[100:103], v[144:147], v[196:199], v[100:103]
	v_mfma_f32_16x16x32_bf16 v[92:95], v[152:155], v[196:199], v[92:95]
	v_mfma_f32_16x16x32_bf16 v[84:87], v[144:147], v[210:213], v[84:87]
	v_mfma_f32_16x16x32_bf16 v[76:79], v[152:155], v[210:213], v[76:79]
	v_mfma_f32_16x16x32_bf16 v[124:127], v[148:151], v[184:187], v[124:127]
	v_mfma_f32_16x16x32_bf16 v[120:123], v[156:159], v[184:187], v[120:123]
	v_mfma_f32_16x16x32_bf16 v[116:119], v[148:151], v[192:195], v[116:119]
	v_mfma_f32_16x16x32_bf16 v[108:111], v[156:159], v[192:195], v[108:111]
	v_mfma_f32_16x16x32_bf16 v[100:103], v[148:151], v[206:209], v[100:103]
	v_mfma_f32_16x16x32_bf16 v[92:95], v[156:159], v[206:209], v[92:95]
	v_mfma_f32_16x16x32_bf16 v[84:87], v[148:151], v[214:217], v[84:87]
	v_mfma_f32_16x16x32_bf16 v[76:79], v[156:159], v[214:217], v[76:79]
	v_mfma_f32_16x16x32_bf16 v[112:115], v[164:167], v[180:183], v[112:115]
	v_mfma_f32_16x16x32_bf16 v[104:107], v[172:175], v[180:183], v[104:107]
	v_mfma_f32_16x16x32_bf16 v[96:99], v[164:167], v[188:191], v[96:99]
	v_mfma_f32_16x16x32_bf16 v[88:91], v[172:175], v[188:191], v[88:91]
	v_mfma_f32_16x16x32_bf16 v[80:83], v[164:167], v[196:199], v[80:83]
	v_mfma_f32_16x16x32_bf16 v[72:75], v[172:175], v[196:199], v[72:75]
	v_mfma_f32_16x16x32_bf16 v[68:71], v[164:167], v[210:213], v[68:71]
	v_mfma_f32_16x16x32_bf16 v[64:67], v[172:175], v[210:213], v[64:67]
	v_mfma_f32_16x16x32_bf16 v[112:115], v[168:171], v[184:187], v[112:115]
	v_mfma_f32_16x16x32_bf16 v[104:107], v[176:179], v[184:187], v[104:107]
	v_mfma_f32_16x16x32_bf16 v[96:99], v[168:171], v[192:195], v[96:99]
	v_mfma_f32_16x16x32_bf16 v[88:91], v[176:179], v[192:195], v[88:91]
	v_mfma_f32_16x16x32_bf16 v[80:83], v[168:171], v[206:209], v[80:83]
	v_mfma_f32_16x16x32_bf16 v[72:75], v[176:179], v[206:209], v[72:75]
	v_mfma_f32_16x16x32_bf16 v[68:71], v[168:171], v[214:217], v[68:71]
	v_mfma_f32_16x16x32_bf16 v[64:67], v[176:179], v[214:217], v[64:67]
	s_barrier
	s_setprio 0
	s_add_i32 s18, s20, s7
	v_lshl_add_u64 v[200:201], v[200:201], 0, s[76:77]
	s_mov_b32 m0, s18
	ds_read_b128 v[180:183], v143 offset:49152
	ds_read_b128 v[184:187], v143 offset:50176
	ds_read_b128 v[188:191], v143 offset:51200
	ds_read_b128 v[192:195], v143 offset:52224
	ds_read_b128 v[196:199], v143 offset:53248
	ds_read_b128 v[206:209], v143 offset:54272
	ds_read_b128 v[210:213], v143 offset:55296
	ds_read_b128 v[214:217], v143 offset:56320
	global_load_lds_dwordx4 v[200:201], off
	s_add_i32 m0, s18, 0x2000
	s_add_u32 s18, s50, 0x40080
	v_lshl_add_u64 v[200:201], v[218:219], 0, s[76:77]
	s_addc_u32 s19, s51, 0
	s_add_i32 s20, s21, s7
	global_load_lds_dwordx4 v[200:201], off
	v_lshl_add_u64 v[200:201], s[18:19], 0, v[132:133]
	s_mov_b32 m0, s20
	s_nop 0
	global_load_lds_dwordx4 v[200:201], off
	v_lshl_add_u64 v[200:201], s[18:19], 0, v[128:129]
	s_add_i32 m0, s20, 0x2000
	s_nop 0
	global_load_lds_dwordx4 v[200:201], off
	v_lshl_add_u64 v[200:201], v[220:221], 0, s[76:77]
	s_mov_b32 m0, s13
	s_nop 0
	global_load_lds_dwordx4 v[200:201], off
	v_lshl_add_u64 v[200:201], v[222:223], 0, s[76:77]
	s_mov_b32 m0, s14
	s_nop 0
	global_load_lds_dwordx4 v[200:201], off
	s_waitcnt vmcnt(8)
	s_waitcnt lgkmcnt(0)
	s_setprio 1
	s_barrier
	v_mfma_f32_16x16x32_bf16 v[60:63], v[144:147], v[180:183], v[60:63]
	v_mfma_f32_16x16x32_bf16 v[56:59], v[152:155], v[180:183], v[56:59]
	v_mfma_f32_16x16x32_bf16 v[52:55], v[144:147], v[188:191], v[52:55]
	v_mfma_f32_16x16x32_bf16 v[44:47], v[152:155], v[188:191], v[44:47]
	v_mfma_f32_16x16x32_bf16 v[36:39], v[144:147], v[196:199], v[36:39]
	v_mfma_f32_16x16x32_bf16 v[28:31], v[152:155], v[196:199], v[28:31]
	v_mfma_f32_16x16x32_bf16 v[20:23], v[144:147], v[210:213], v[20:23]
	v_mfma_f32_16x16x32_bf16 v[12:15], v[152:155], v[210:213], v[12:15]
	v_mfma_f32_16x16x32_bf16 v[60:63], v[148:151], v[184:187], v[60:63]
	v_mfma_f32_16x16x32_bf16 v[56:59], v[156:159], v[184:187], v[56:59]
	v_mfma_f32_16x16x32_bf16 v[52:55], v[148:151], v[192:195], v[52:55]
	v_mfma_f32_16x16x32_bf16 v[44:47], v[156:159], v[192:195], v[44:47]
	v_mfma_f32_16x16x32_bf16 v[36:39], v[148:151], v[206:209], v[36:39]
	v_mfma_f32_16x16x32_bf16 v[28:31], v[156:159], v[206:209], v[28:31]
	v_mfma_f32_16x16x32_bf16 v[20:23], v[148:151], v[214:217], v[20:23]
	v_mfma_f32_16x16x32_bf16 v[12:15], v[156:159], v[214:217], v[12:15]
	v_mfma_f32_16x16x32_bf16 v[48:51], v[164:167], v[180:183], v[48:51]
	v_mfma_f32_16x16x32_bf16 v[40:43], v[172:175], v[180:183], v[40:43]
	v_mfma_f32_16x16x32_bf16 v[32:35], v[164:167], v[188:191], v[32:35]
	v_mfma_f32_16x16x32_bf16 v[24:27], v[172:175], v[188:191], v[24:27]
	v_mfma_f32_16x16x32_bf16 v[16:19], v[164:167], v[196:199], v[16:19]
	v_mfma_f32_16x16x32_bf16 v[8:11], v[172:175], v[196:199], v[8:11]
	v_mfma_f32_16x16x32_bf16 v[4:7], v[164:167], v[210:213], v[4:7]
	v_mfma_f32_16x16x32_bf16 v[0:3], v[172:175], v[210:213], v[0:3]
	v_mfma_f32_16x16x32_bf16 v[48:51], v[168:171], v[184:187], v[48:51]
	v_mfma_f32_16x16x32_bf16 v[40:43], v[176:179], v[184:187], v[40:43]
	v_mfma_f32_16x16x32_bf16 v[32:35], v[168:171], v[192:195], v[32:35]
	v_mfma_f32_16x16x32_bf16 v[24:27], v[176:179], v[192:195], v[24:27]
	v_mfma_f32_16x16x32_bf16 v[16:19], v[168:171], v[206:209], v[16:19]
	v_mfma_f32_16x16x32_bf16 v[8:11], v[176:179], v[206:209], v[8:11]
	v_mfma_f32_16x16x32_bf16 v[4:7], v[168:171], v[214:217], v[4:7]
	v_mfma_f32_16x16x32_bf16 v[0:3], v[176:179], v[214:217], v[0:3]
	s_barrier
	s_setprio 0
	s_add_i32 s61, s61, 2
	s_add_u32 s62, s62, 0x100
	s_addc_u32 s63, s63, 0
	s_add_u32 s47, s47, 0x100
	s_addc_u32 s54, s54, 0
	s_cmp_gt_u32 s61, 13
	s_cbranch_scc0 .LBB0_699

.LBB0_778:
	s_add_i32 s11, s11, 1
	s_mov_b32 s14, s12
	s_mul_i32 s12, s11, s86
	v_readlane_b32 s15, v245, 26
	s_add_i32 s12, s12, s15
	s_cmp_lt_u32 s12, 16
	s_mov_b32 s26, s40
	s_cselect_b64 s[48:49], -1, 0
	s_lshr_b32 s40, s12, 1
	s_and_b32 s12, s12, 1
	s_and_b64 s[16:17], s[48:49], exec
	s_mov_b32 s41, s27
	s_cselect_b32 s15, s89, s51
	s_cselect_b32 s16, s88, s50
	s_lshl_b64 s[20:21], s[40:41], 19
	v_readlane_b32 s17, v244, 0
	s_add_u32 s17, s17, s20
	v_readlane_b32 s20, v244, 1
	s_addc_u32 s20, s20, s21
	s_lshl_b32 s21, s12, 18
	s_add_u32 s17, s17, s21
	s_addc_u32 s22, s20, 0
	s_mov_b64 s[18:19], s[42:43]
	s_and_b64 s[20:21], s[48:49], exec
	s_cselect_b32 s43, s22, s19
	s_cselect_b32 s42, s17, s18
	s_add_u32 s58, s50, 0x20080
	s_addc_u32 s59, s51, 0
	s_add_u32 s17, s18, 0x100
	s_addc_u32 s39, s19, 0
	s_mov_b32 s41, -2
	s_add_u32 s18, s58, 0xfffe0080
	s_addc_u32 s19, s59, -1
	s_add_i32 s20, 0, 0x10000
	s_cmp_eq_u32 s41, 4
	s_cselect_b32 s61, s15, s19
	s_cselect_b32 s60, s16, s18
	v_add_u32_e32 v140, s20, v143
	s_cselect_b32 s51, s43, s39
	s_cselect_b32 s50, s42, s17
	s_add_i32 s21, 0, 0x14000
	ds_read_b128 v[146:149], v140
	ds_read_b128 v[150:153], v140 offset:1024
	ds_read_b128 v[154:157], v140 offset:2048
	ds_read_b128 v[164:167], v140 offset:3072
	v_add_u32_e32 v140, s21, v143
	ds_read_b128 v[168:171], v140
	ds_read_b128 v[172:175], v140 offset:1024
	ds_read_b128 v[176:179], v140 offset:2048
	ds_read_b128 v[180:183], v140 offset:3072
	v_lshl_add_u64 v[140:141], s[58:59], 0, v[136:137]
	s_add_i32 m0, s5, 0xc000
	ds_read_b128 v[184:187], v144
	ds_read_b128 v[188:191], v144 offset:1024
	ds_read_b128 v[192:195], v144 offset:2048
	ds_read_b128 v[196:199], v144 offset:3072
	ds_read_b128 v[206:209], v144 offset:4096
	ds_read_b128 v[210:213], v144 offset:5120
	ds_read_b128 v[214:217], v144 offset:6144
	ds_read_b128 v[218:221], v144 offset:7168
	global_load_lds_dwordx4 v[140:141], off
	v_lshl_add_u64 v[140:141], s[58:59], 0, v[138:139]
	s_add_i32 m0, s5, 0xe000
	s_nop 0
	global_load_lds_dwordx4 v[140:141], off
	s_waitcnt vmcnt(8)
	s_waitcnt lgkmcnt(0)
	s_setprio 1
	s_barrier
	v_mfma_f32_16x16x32_bf16 v[124:127], v[146:149], v[184:187], 0
	v_mfma_f32_16x16x32_bf16 v[120:123], v[154:157], v[184:187], 0
	v_mfma_f32_16x16x32_bf16 v[116:119], v[146:149], v[192:195], 0
	v_mfma_f32_16x16x32_bf16 v[108:111], v[154:157], v[192:195], 0
	v_mfma_f32_16x16x32_bf16 v[100:103], v[146:149], v[206:209], 0
	v_mfma_f32_16x16x32_bf16 v[92:95], v[154:157], v[206:209], 0
	v_mfma_f32_16x16x32_bf16 v[84:87], v[146:149], v[214:217], 0
	v_mfma_f32_16x16x32_bf16 v[76:79], v[154:157], v[214:217], 0
	v_mfma_f32_16x16x32_bf16 v[124:127], v[150:153], v[188:191], v[124:127]
	v_mfma_f32_16x16x32_bf16 v[120:123], v[164:167], v[188:191], v[120:123]
	v_mfma_f32_16x16x32_bf16 v[116:119], v[150:153], v[196:199], v[116:119]
	v_mfma_f32_16x16x32_bf16 v[108:111], v[164:167], v[196:199], v[108:111]
	v_mfma_f32_16x16x32_bf16 v[100:103], v[150:153], v[210:213], v[100:103]
	v_mfma_f32_16x16x32_bf16 v[92:95], v[164:167], v[210:213], v[92:95]
	v_mfma_f32_16x16x32_bf16 v[84:87], v[150:153], v[218:221], v[84:87]
	v_mfma_f32_16x16x32_bf16 v[76:79], v[164:167], v[218:221], v[76:79]
	v_mfma_f32_16x16x32_bf16 v[112:115], v[168:171], v[184:187], 0
	v_mfma_f32_16x16x32_bf16 v[104:107], v[176:179], v[184:187], 0
	v_mfma_f32_16x16x32_bf16 v[96:99], v[168:171], v[192:195], 0
	v_mfma_f32_16x16x32_bf16 v[88:91], v[176:179], v[192:195], 0
	v_mfma_f32_16x16x32_bf16 v[80:83], v[168:171], v[206:209], 0
	v_mfma_f32_16x16x32_bf16 v[72:75], v[176:179], v[206:209], 0
	v_mfma_f32_16x16x32_bf16 v[68:71], v[168:171], v[214:217], 0
	v_mfma_f32_16x16x32_bf16 v[64:67], v[176:179], v[214:217], 0
	v_mfma_f32_16x16x32_bf16 v[112:115], v[172:175], v[188:191], v[112:115]
	v_mfma_f32_16x16x32_bf16 v[104:107], v[180:183], v[188:191], v[104:107]
	v_mfma_f32_16x16x32_bf16 v[96:99], v[172:175], v[196:199], v[96:99]
	v_mfma_f32_16x16x32_bf16 v[88:91], v[180:183], v[196:199], v[88:91]
	v_mfma_f32_16x16x32_bf16 v[80:83], v[172:175], v[210:213], v[80:83]
	v_mfma_f32_16x16x32_bf16 v[72:75], v[180:183], v[210:213], v[72:75]
	v_mfma_f32_16x16x32_bf16 v[68:71], v[172:175], v[218:221], v[68:71]
	v_mfma_f32_16x16x32_bf16 v[64:67], v[180:183], v[218:221], v[64:67]
	s_barrier
	s_setprio 0
	s_add_i32 s18, s20, s4
	v_lshl_add_u64 v[140:141], s[50:51], 0, v[130:131]
	s_mov_b32 m0, s18
	ds_read_b128 v[184:187], v144 offset:16384
	ds_read_b128 v[188:191], v144 offset:17408
	ds_read_b128 v[192:195], v144 offset:18432
	ds_read_b128 v[196:199], v144 offset:19456
	ds_read_b128 v[206:209], v144 offset:20480
	ds_read_b128 v[210:213], v144 offset:21504
	ds_read_b128 v[214:217], v144 offset:22528
	ds_read_b128 v[218:221], v144 offset:23552
	global_load_lds_dwordx4 v[140:141], off
	s_add_i32 m0, s18, 0x2000
	s_add_u32 s18, s50, 0x20000
	v_lshl_add_u64 v[158:159], s[50:51], 0, v[134:135]
	s_addc_u32 s19, s51, 0
	s_add_i32 s20, s21, s4
	global_load_lds_dwordx4 v[158:159], off
	v_lshl_add_u64 v[200:201], s[18:19], 0, v[130:131]
	s_mov_b32 m0, s20
	v_lshl_add_u64 v[222:223], s[60:61], 0, v[132:133]
	global_load_lds_dwordx4 v[200:201], off
	v_lshl_add_u64 v[200:201], s[18:19], 0, v[134:135]
	s_add_i32 m0, s20, 0x2000
	s_nop 0
	global_load_lds_dwordx4 v[200:201], off
	v_lshl_add_u64 v[200:201], s[60:61], 0, v[128:129]
	s_mov_b32 m0, s5
	s_nop 0
	global_load_lds_dwordx4 v[200:201], off
	s_mov_b32 m0, s6
	s_nop 0
	global_load_lds_dwordx4 v[222:223], off
	s_waitcnt vmcnt(8)
	s_waitcnt lgkmcnt(0)
	s_setprio 1
	s_barrier
	v_mfma_f32_16x16x32_bf16 v[60:63], v[146:149], v[184:187], 0
	v_mfma_f32_16x16x32_bf16 v[56:59], v[154:157], v[184:187], 0
	v_mfma_f32_16x16x32_bf16 v[52:55], v[146:149], v[192:195], 0
	v_mfma_f32_16x16x32_bf16 v[44:47], v[154:157], v[192:195], 0
	v_mfma_f32_16x16x32_bf16 v[36:39], v[146:149], v[206:209], 0
	v_mfma_f32_16x16x32_bf16 v[28:31], v[154:157], v[206:209], 0
	v_mfma_f32_16x16x32_bf16 v[20:23], v[146:149], v[214:217], 0
	v_mfma_f32_16x16x32_bf16 v[12:15], v[154:157], v[214:217], 0
	v_mfma_f32_16x16x32_bf16 v[60:63], v[150:153], v[188:191], v[60:63]
	v_mfma_f32_16x16x32_bf16 v[56:59], v[164:167], v[188:191], v[56:59]
	v_mfma_f32_16x16x32_bf16 v[52:55], v[150:153], v[196:199], v[52:55]
	v_mfma_f32_16x16x32_bf16 v[44:47], v[164:167], v[196:199], v[44:47]
	v_mfma_f32_16x16x32_bf16 v[36:39], v[150:153], v[210:213], v[36:39]
	v_mfma_f32_16x16x32_bf16 v[28:31], v[164:167], v[210:213], v[28:31]
	v_mfma_f32_16x16x32_bf16 v[20:23], v[150:153], v[218:221], v[20:23]
	v_mfma_f32_16x16x32_bf16 v[12:15], v[164:167], v[218:221], v[12:15]
	v_mfma_f32_16x16x32_bf16 v[48:51], v[168:171], v[184:187], 0
	v_mfma_f32_16x16x32_bf16 v[40:43], v[176:179], v[184:187], 0
	v_mfma_f32_16x16x32_bf16 v[32:35], v[168:171], v[192:195], 0
	v_mfma_f32_16x16x32_bf16 v[24:27], v[176:179], v[192:195], 0
	v_mfma_f32_16x16x32_bf16 v[16:19], v[168:171], v[206:209], 0
	v_mfma_f32_16x16x32_bf16 v[8:11], v[176:179], v[206:209], 0
	v_mfma_f32_16x16x32_bf16 v[4:7], v[168:171], v[214:217], 0
	v_mfma_f32_16x16x32_bf16 v[0:3], v[176:179], v[214:217], 0
	v_mfma_f32_16x16x32_bf16 v[48:51], v[172:175], v[188:191], v[48:51]
	v_mfma_f32_16x16x32_bf16 v[40:43], v[180:183], v[188:191], v[40:43]
	v_mfma_f32_16x16x32_bf16 v[32:35], v[172:175], v[196:199], v[32:35]
	v_mfma_f32_16x16x32_bf16 v[24:27], v[180:183], v[196:199], v[24:27]
	v_mfma_f32_16x16x32_bf16 v[16:19], v[172:175], v[210:213], v[16:19]
	v_mfma_f32_16x16x32_bf16 v[8:11], v[180:183], v[210:213], v[8:11]
	v_mfma_f32_16x16x32_bf16 v[4:7], v[172:175], v[218:221], v[4:7]
	v_mfma_f32_16x16x32_bf16 v[0:3], v[180:183], v[218:221], v[0:3]
	s_barrier
	s_setprio 0
	s_add_i32 s20, 0, 0x18000
	v_add_u32_e32 v145, s20, v143
	s_add_i32 s21, 0, 0x1c000
	ds_read_b128 v[146:149], v145
	ds_read_b128 v[150:153], v145 offset:1024
	ds_read_b128 v[154:157], v145 offset:2048
	ds_read_b128 v[164:167], v145 offset:3072
	v_add_u32_e32 v145, s21, v143
	ds_read_b128 v[168:171], v145
	ds_read_b128 v[172:175], v145 offset:1024
	ds_read_b128 v[176:179], v145 offset:2048
	ds_read_b128 v[180:183], v145 offset:3072
	s_add_u32 s18, s60, 0x20000
	s_addc_u32 s19, s61, 0
	s_mov_b32 m0, s7
	v_lshl_add_u64 v[224:225], s[18:19], 0, v[128:129]
	ds_read_b128 v[184:187], v144 offset:32768
	ds_read_b128 v[188:191], v144 offset:33792
	ds_read_b128 v[192:195], v144 offset:34816
	ds_read_b128 v[196:199], v144 offset:35840
	ds_read_b128 v[206:209], v144 offset:36864
	ds_read_b128 v[210:213], v144 offset:37888
	ds_read_b128 v[214:217], v144 offset:38912
	ds_read_b128 v[218:221], v144 offset:39936
	global_load_lds_dwordx4 v[224:225], off
	v_lshl_add_u64 v[224:225], s[18:19], 0, v[132:133]
	s_mov_b32 m0, s8
	s_nop 0
	global_load_lds_dwordx4 v[224:225], off
	s_waitcnt vmcnt(8)
	s_waitcnt lgkmcnt(0)
	s_setprio 1
	s_barrier
	v_mfma_f32_16x16x32_bf16 v[124:127], v[146:149], v[184:187], v[124:127]
	v_mfma_f32_16x16x32_bf16 v[120:123], v[154:157], v[184:187], v[120:123]
	v_mfma_f32_16x16x32_bf16 v[116:119], v[146:149], v[192:195], v[116:119]
	v_mfma_f32_16x16x32_bf16 v[108:111], v[154:157], v[192:195], v[108:111]
	v_mfma_f32_16x16x32_bf16 v[100:103], v[146:149], v[206:209], v[100:103]
	v_mfma_f32_16x16x32_bf16 v[92:95], v[154:157], v[206:209], v[92:95]
	v_mfma_f32_16x16x32_bf16 v[84:87], v[146:149], v[214:217], v[84:87]
	v_mfma_f32_16x16x32_bf16 v[76:79], v[154:157], v[214:217], v[76:79]
	v_mfma_f32_16x16x32_bf16 v[124:127], v[150:153], v[188:191], v[124:127]
	v_mfma_f32_16x16x32_bf16 v[120:123], v[164:167], v[188:191], v[120:123]
	v_mfma_f32_16x16x32_bf16 v[116:119], v[150:153], v[196:199], v[116:119]
	v_mfma_f32_16x16x32_bf16 v[108:111], v[164:167], v[196:199], v[108:111]
	v_mfma_f32_16x16x32_bf16 v[100:103], v[150:153], v[210:213], v[100:103]
	v_mfma_f32_16x16x32_bf16 v[92:95], v[164:167], v[210:213], v[92:95]
	v_mfma_f32_16x16x32_bf16 v[84:87], v[150:153], v[218:221], v[84:87]
	v_mfma_f32_16x16x32_bf16 v[76:79], v[164:167], v[218:221], v[76:79]
	v_mfma_f32_16x16x32_bf16 v[112:115], v[168:171], v[184:187], v[112:115]
	v_mfma_f32_16x16x32_bf16 v[104:107], v[176:179], v[184:187], v[104:107]
	v_mfma_f32_16x16x32_bf16 v[96:99], v[168:171], v[192:195], v[96:99]
	v_mfma_f32_16x16x32_bf16 v[88:91], v[176:179], v[192:195], v[88:91]
	v_mfma_f32_16x16x32_bf16 v[80:83], v[168:171], v[206:209], v[80:83]
	v_mfma_f32_16x16x32_bf16 v[72:75], v[176:179], v[206:209], v[72:75]
	v_mfma_f32_16x16x32_bf16 v[68:71], v[168:171], v[214:217], v[68:71]
	v_mfma_f32_16x16x32_bf16 v[64:67], v[176:179], v[214:217], v[64:67]
	v_mfma_f32_16x16x32_bf16 v[112:115], v[172:175], v[188:191], v[112:115]
	v_mfma_f32_16x16x32_bf16 v[104:107], v[180:183], v[188:191], v[104:107]
	v_mfma_f32_16x16x32_bf16 v[96:99], v[172:175], v[196:199], v[96:99]
	v_mfma_f32_16x16x32_bf16 v[88:91], v[180:183], v[196:199], v[88:91]
	v_mfma_f32_16x16x32_bf16 v[80:83], v[172:175], v[210:213], v[80:83]
	v_mfma_f32_16x16x32_bf16 v[72:75], v[180:183], v[210:213], v[72:75]
	v_mfma_f32_16x16x32_bf16 v[68:71], v[172:175], v[218:221], v[68:71]
	v_mfma_f32_16x16x32_bf16 v[64:67], v[180:183], v[218:221], v[64:67]
	s_barrier
	s_setprio 0
	s_add_i32 s18, s20, s4
	v_lshl_add_u64 v[140:141], v[140:141], 0, s[76:77]
	s_mov_b32 m0, s18
	ds_read_b128 v[184:187], v144 offset:49152
	ds_read_b128 v[188:191], v144 offset:50176
	ds_read_b128 v[192:195], v144 offset:51200
	ds_read_b128 v[196:199], v144 offset:52224
	ds_read_b128 v[206:209], v144 offset:53248
	ds_read_b128 v[210:213], v144 offset:54272
	ds_read_b128 v[214:217], v144 offset:55296
	ds_read_b128 v[218:221], v144 offset:56320
	global_load_lds_dwordx4 v[140:141], off
	s_add_i32 m0, s18, 0x2000
	s_add_u32 s18, s50, 0x20080
	v_lshl_add_u64 v[140:141], v[158:159], 0, s[76:77]
	s_addc_u32 s19, s51, 0
	s_add_i32 s20, s21, s4
	global_load_lds_dwordx4 v[140:141], off
	v_lshl_add_u64 v[140:141], s[18:19], 0, v[130:131]
	s_mov_b32 m0, s20
	s_nop 0
	global_load_lds_dwordx4 v[140:141], off
	v_lshl_add_u64 v[140:141], s[18:19], 0, v[134:135]
	s_add_i32 m0, s20, 0x2000
	s_nop 0
	global_load_lds_dwordx4 v[140:141], off
	v_lshl_add_u64 v[140:141], v[200:201], 0, s[76:77]
	s_mov_b32 m0, s9
	s_nop 0
	global_load_lds_dwordx4 v[140:141], off
	v_lshl_add_u64 v[140:141], v[222:223], 0, s[76:77]
	s_mov_b32 m0, s10
	s_nop 0
	global_load_lds_dwordx4 v[140:141], off
	s_waitcnt vmcnt(8)
	s_waitcnt lgkmcnt(0)
	s_setprio 1
	s_barrier
	v_mfma_f32_16x16x32_bf16 v[60:63], v[146:149], v[184:187], v[60:63]
	v_mfma_f32_16x16x32_bf16 v[56:59], v[154:157], v[184:187], v[56:59]
	v_mfma_f32_16x16x32_bf16 v[52:55], v[146:149], v[192:195], v[52:55]
	v_mfma_f32_16x16x32_bf16 v[44:47], v[154:157], v[192:195], v[44:47]
	v_mfma_f32_16x16x32_bf16 v[36:39], v[146:149], v[206:209], v[36:39]
	v_mfma_f32_16x16x32_bf16 v[28:31], v[154:157], v[206:209], v[28:31]
	v_mfma_f32_16x16x32_bf16 v[20:23], v[146:149], v[214:217], v[20:23]
	v_mfma_f32_16x16x32_bf16 v[12:15], v[154:157], v[214:217], v[12:15]
	v_mfma_f32_16x16x32_bf16 v[60:63], v[150:153], v[188:191], v[60:63]
	v_mfma_f32_16x16x32_bf16 v[56:59], v[164:167], v[188:191], v[56:59]
	v_mfma_f32_16x16x32_bf16 v[52:55], v[150:153], v[196:199], v[52:55]
	v_mfma_f32_16x16x32_bf16 v[44:47], v[164:167], v[196:199], v[44:47]
	v_mfma_f32_16x16x32_bf16 v[36:39], v[150:153], v[210:213], v[36:39]
	v_mfma_f32_16x16x32_bf16 v[28:31], v[164:167], v[210:213], v[28:31]
	v_mfma_f32_16x16x32_bf16 v[20:23], v[150:153], v[218:221], v[20:23]
	v_mfma_f32_16x16x32_bf16 v[12:15], v[164:167], v[218:221], v[12:15]
	v_mfma_f32_16x16x32_bf16 v[48:51], v[168:171], v[184:187], v[48:51]
	v_mfma_f32_16x16x32_bf16 v[40:43], v[176:179], v[184:187], v[40:43]
	v_mfma_f32_16x16x32_bf16 v[32:35], v[168:171], v[192:195], v[32:35]
	v_mfma_f32_16x16x32_bf16 v[24:27], v[176:179], v[192:195], v[24:27]
	v_mfma_f32_16x16x32_bf16 v[16:19], v[168:171], v[206:209], v[16:19]
	v_mfma_f32_16x16x32_bf16 v[8:11], v[176:179], v[206:209], v[8:11]
	v_mfma_f32_16x16x32_bf16 v[4:7], v[168:171], v[214:217], v[4:7]
	v_mfma_f32_16x16x32_bf16 v[0:3], v[176:179], v[214:217], v[0:3]
	v_mfma_f32_16x16x32_bf16 v[48:51], v[172:175], v[188:191], v[48:51]
	v_mfma_f32_16x16x32_bf16 v[40:43], v[180:183], v[188:191], v[40:43]
	v_mfma_f32_16x16x32_bf16 v[32:35], v[172:175], v[196:199], v[32:35]
	v_mfma_f32_16x16x32_bf16 v[24:27], v[180:183], v[196:199], v[24:27]
	v_mfma_f32_16x16x32_bf16 v[16:19], v[172:175], v[210:213], v[16:19]
	v_mfma_f32_16x16x32_bf16 v[8:11], v[180:183], v[210:213], v[8:11]
	v_mfma_f32_16x16x32_bf16 v[4:7], v[172:175], v[218:221], v[4:7]
	v_mfma_f32_16x16x32_bf16 v[0:3], v[180:183], v[218:221], v[0:3]
	s_barrier
	s_setprio 0
	s_add_i32 s41, s41, 2
	s_add_u32 s58, s58, 0x100
	s_addc_u32 s59, s59, 0
	s_add_u32 s17, s17, 0x100
	s_addc_u32 s39, s39, 0
	s_cmp_gt_u32 s41, 5
	s_cbranch_scc0 .LBB0_779
	s_branch .Lpeel_x_779
.LBB0_779:
	s_add_u32 s18, s58, 0xfffe0080
	s_addc_u32 s19, s59, -1
	s_add_i32 s20, 0, 0x10000
	s_cmp_eq_u32 s41, 4
	s_cselect_b32 s61, s15, s19
	s_cselect_b32 s60, s16, s18
	v_add_u32_e32 v140, s20, v143
	s_cselect_b32 s51, s43, s39
	s_cselect_b32 s50, s42, s17
	s_add_i32 s21, 0, 0x14000
	ds_read_b128 v[146:149], v140
	ds_read_b128 v[150:153], v140 offset:1024
	ds_read_b128 v[154:157], v140 offset:2048
	ds_read_b128 v[164:167], v140 offset:3072
	v_add_u32_e32 v140, s21, v143
	ds_read_b128 v[168:171], v140
	ds_read_b128 v[172:175], v140 offset:1024
	ds_read_b128 v[176:179], v140 offset:2048
	ds_read_b128 v[180:183], v140 offset:3072
	v_lshl_add_u64 v[140:141], s[58:59], 0, v[136:137]
	s_add_i32 m0, s5, 0xc000
	ds_read_b128 v[184:187], v144
	ds_read_b128 v[188:191], v144 offset:1024
	ds_read_b128 v[192:195], v144 offset:2048
	ds_read_b128 v[196:199], v144 offset:3072
	ds_read_b128 v[206:209], v144 offset:4096
	ds_read_b128 v[210:213], v144 offset:5120
	ds_read_b128 v[214:217], v144 offset:6144
	ds_read_b128 v[218:221], v144 offset:7168
	global_load_lds_dwordx4 v[140:141], off
	v_lshl_add_u64 v[140:141], s[58:59], 0, v[138:139]
	s_add_i32 m0, s5, 0xe000
	s_nop 0
	global_load_lds_dwordx4 v[140:141], off
	s_waitcnt vmcnt(8)
	s_waitcnt lgkmcnt(0)
	s_setprio 1
	s_barrier
	v_mfma_f32_16x16x32_bf16 v[124:127], v[146:149], v[184:187], v[124:127]
	v_mfma_f32_16x16x32_bf16 v[120:123], v[154:157], v[184:187], v[120:123]
	v_mfma_f32_16x16x32_bf16 v[116:119], v[146:149], v[192:195], v[116:119]
	v_mfma_f32_16x16x32_bf16 v[108:111], v[154:157], v[192:195], v[108:111]
	v_mfma_f32_16x16x32_bf16 v[100:103], v[146:149], v[206:209], v[100:103]
	v_mfma_f32_16x16x32_bf16 v[92:95], v[154:157], v[206:209], v[92:95]
	v_mfma_f32_16x16x32_bf16 v[84:87], v[146:149], v[214:217], v[84:87]
	v_mfma_f32_16x16x32_bf16 v[76:79], v[154:157], v[214:217], v[76:79]
	v_mfma_f32_16x16x32_bf16 v[124:127], v[150:153], v[188:191], v[124:127]
	v_mfma_f32_16x16x32_bf16 v[120:123], v[164:167], v[188:191], v[120:123]
	v_mfma_f32_16x16x32_bf16 v[116:119], v[150:153], v[196:199], v[116:119]
	v_mfma_f32_16x16x32_bf16 v[108:111], v[164:167], v[196:199], v[108:111]
	v_mfma_f32_16x16x32_bf16 v[100:103], v[150:153], v[210:213], v[100:103]
	v_mfma_f32_16x16x32_bf16 v[92:95], v[164:167], v[210:213], v[92:95]
	v_mfma_f32_16x16x32_bf16 v[84:87], v[150:153], v[218:221], v[84:87]
	v_mfma_f32_16x16x32_bf16 v[76:79], v[164:167], v[218:221], v[76:79]
	v_mfma_f32_16x16x32_bf16 v[112:115], v[168:171], v[184:187], v[112:115]
	v_mfma_f32_16x16x32_bf16 v[104:107], v[176:179], v[184:187], v[104:107]
	v_mfma_f32_16x16x32_bf16 v[96:99], v[168:171], v[192:195], v[96:99]
	v_mfma_f32_16x16x32_bf16 v[88:91], v[176:179], v[192:195], v[88:91]
	v_mfma_f32_16x16x32_bf16 v[80:83], v[168:171], v[206:209], v[80:83]
	v_mfma_f32_16x16x32_bf16 v[72:75], v[176:179], v[206:209], v[72:75]
	v_mfma_f32_16x16x32_bf16 v[68:71], v[168:171], v[214:217], v[68:71]
	v_mfma_f32_16x16x32_bf16 v[64:67], v[176:179], v[214:217], v[64:67]
	v_mfma_f32_16x16x32_bf16 v[112:115], v[172:175], v[188:191], v[112:115]
	v_mfma_f32_16x16x32_bf16 v[104:107], v[180:183], v[188:191], v[104:107]
	v_mfma_f32_16x16x32_bf16 v[96:99], v[172:175], v[196:199], v[96:99]
	v_mfma_f32_16x16x32_bf16 v[88:91], v[180:183], v[196:199], v[88:91]
	v_mfma_f32_16x16x32_bf16 v[80:83], v[172:175], v[210:213], v[80:83]
	v_mfma_f32_16x16x32_bf16 v[72:75], v[180:183], v[210:213], v[72:75]
	v_mfma_f32_16x16x32_bf16 v[68:71], v[172:175], v[218:221], v[68:71]
	v_mfma_f32_16x16x32_bf16 v[64:67], v[180:183], v[218:221], v[64:67]
	s_barrier
	s_setprio 0
	s_add_i32 s18, s20, s4
	v_lshl_add_u64 v[140:141], s[50:51], 0, v[130:131]
	s_mov_b32 m0, s18
	ds_read_b128 v[184:187], v144 offset:16384
	ds_read_b128 v[188:191], v144 offset:17408
	ds_read_b128 v[192:195], v144 offset:18432
	ds_read_b128 v[196:199], v144 offset:19456
	ds_read_b128 v[206:209], v144 offset:20480
	ds_read_b128 v[210:213], v144 offset:21504
	ds_read_b128 v[214:217], v144 offset:22528
	ds_read_b128 v[218:221], v144 offset:23552
	global_load_lds_dwordx4 v[140:141], off
	s_add_i32 m0, s18, 0x2000
	s_add_u32 s18, s50, 0x20000
	v_lshl_add_u64 v[158:159], s[50:51], 0, v[134:135]
	s_addc_u32 s19, s51, 0
	s_add_i32 s20, s21, s4
	global_load_lds_dwordx4 v[158:159], off
	v_lshl_add_u64 v[200:201], s[18:19], 0, v[130:131]
	s_mov_b32 m0, s20
	v_lshl_add_u64 v[222:223], s[60:61], 0, v[132:133]
	global_load_lds_dwordx4 v[200:201], off
	v_lshl_add_u64 v[200:201], s[18:19], 0, v[134:135]
	s_add_i32 m0, s20, 0x2000
	s_nop 0
	global_load_lds_dwordx4 v[200:201], off
	v_lshl_add_u64 v[200:201], s[60:61], 0, v[128:129]
	s_mov_b32 m0, s5
	s_nop 0
	global_load_lds_dwordx4 v[200:201], off
	s_mov_b32 m0, s6
	s_nop 0
	global_load_lds_dwordx4 v[222:223], off
	s_waitcnt vmcnt(8)
	s_waitcnt lgkmcnt(0)
	s_setprio 1
	s_barrier
	v_mfma_f32_16x16x32_bf16 v[60:63], v[146:149], v[184:187], v[60:63]
	v_mfma_f32_16x16x32_bf16 v[56:59], v[154:157], v[184:187], v[56:59]
	v_mfma_f32_16x16x32_bf16 v[52:55], v[146:149], v[192:195], v[52:55]
	v_mfma_f32_16x16x32_bf16 v[44:47], v[154:157], v[192:195], v[44:47]
	v_mfma_f32_16x16x32_bf16 v[36:39], v[146:149], v[206:209], v[36:39]
	v_mfma_f32_16x16x32_bf16 v[28:31], v[154:157], v[206:209], v[28:31]
	v_mfma_f32_16x16x32_bf16 v[20:23], v[146:149], v[214:217], v[20:23]
	v_mfma_f32_16x16x32_bf16 v[12:15], v[154:157], v[214:217], v[12:15]
	v_mfma_f32_16x16x32_bf16 v[60:63], v[150:153], v[188:191], v[60:63]
	v_mfma_f32_16x16x32_bf16 v[56:59], v[164:167], v[188:191], v[56:59]
	v_mfma_f32_16x16x32_bf16 v[52:55], v[150:153], v[196:199], v[52:55]
	v_mfma_f32_16x16x32_bf16 v[44:47], v[164:167], v[196:199], v[44:47]
	v_mfma_f32_16x16x32_bf16 v[36:39], v[150:153], v[210:213], v[36:39]
	v_mfma_f32_16x16x32_bf16 v[28:31], v[164:167], v[210:213], v[28:31]
	v_mfma_f32_16x16x32_bf16 v[20:23], v[150:153], v[218:221], v[20:23]
	v_mfma_f32_16x16x32_bf16 v[12:15], v[164:167], v[218:221], v[12:15]
	v_mfma_f32_16x16x32_bf16 v[48:51], v[168:171], v[184:187], v[48:51]
	v_mfma_f32_16x16x32_bf16 v[40:43], v[176:179], v[184:187], v[40:43]
	v_mfma_f32_16x16x32_bf16 v[32:35], v[168:171], v[192:195], v[32:35]
	v_mfma_f32_16x16x32_bf16 v[24:27], v[176:179], v[192:195], v[24:27]
	v_mfma_f32_16x16x32_bf16 v[16:19], v[168:171], v[206:209], v[16:19]
	v_mfma_f32_16x16x32_bf16 v[8:11], v[176:179], v[206:209], v[8:11]
	v_mfma_f32_16x16x32_bf16 v[4:7], v[168:171], v[214:217], v[4:7]
	v_mfma_f32_16x16x32_bf16 v[0:3], v[176:179], v[214:217], v[0:3]
	v_mfma_f32_16x16x32_bf16 v[48:51], v[172:175], v[188:191], v[48:51]
	v_mfma_f32_16x16x32_bf16 v[40:43], v[180:183], v[188:191], v[40:43]
	v_mfma_f32_16x16x32_bf16 v[32:35], v[172:175], v[196:199], v[32:35]
	v_mfma_f32_16x16x32_bf16 v[24:27], v[180:183], v[196:199], v[24:27]
	v_mfma_f32_16x16x32_bf16 v[16:19], v[172:175], v[210:213], v[16:19]
	v_mfma_f32_16x16x32_bf16 v[8:11], v[180:183], v[210:213], v[8:11]
	v_mfma_f32_16x16x32_bf16 v[4:7], v[172:175], v[218:221], v[4:7]
	v_mfma_f32_16x16x32_bf16 v[0:3], v[180:183], v[218:221], v[0:3]
	s_barrier
	s_setprio 0
	s_add_i32 s20, 0, 0x18000
	v_add_u32_e32 v145, s20, v143
	s_add_i32 s21, 0, 0x1c000
	ds_read_b128 v[146:149], v145
	ds_read_b128 v[150:153], v145 offset:1024
	ds_read_b128 v[154:157], v145 offset:2048
	ds_read_b128 v[164:167], v145 offset:3072
	v_add_u32_e32 v145, s21, v143
	ds_read_b128 v[168:171], v145
	ds_read_b128 v[172:175], v145 offset:1024
	ds_read_b128 v[176:179], v145 offset:2048
	ds_read_b128 v[180:183], v145 offset:3072
	s_add_u32 s18, s60, 0x20000
	s_addc_u32 s19, s61, 0
	s_mov_b32 m0, s7
	v_lshl_add_u64 v[224:225], s[18:19], 0, v[128:129]
	ds_read_b128 v[184:187], v144 offset:32768
	ds_read_b128 v[188:191], v144 offset:33792
	ds_read_b128 v[192:195], v144 offset:34816
	ds_read_b128 v[196:199], v144 offset:35840
	ds_read_b128 v[206:209], v144 offset:36864
	ds_read_b128 v[210:213], v144 offset:37888
	ds_read_b128 v[214:217], v144 offset:38912
	ds_read_b128 v[218:221], v144 offset:39936
	global_load_lds_dwordx4 v[224:225], off
	v_lshl_add_u64 v[224:225], s[18:19], 0, v[132:133]
	s_mov_b32 m0, s8
	s_nop 0
	global_load_lds_dwordx4 v[224:225], off
	s_waitcnt vmcnt(8)
	s_waitcnt lgkmcnt(0)
	s_setprio 1
	s_barrier
	v_mfma_f32_16x16x32_bf16 v[124:127], v[146:149], v[184:187], v[124:127]
	v_mfma_f32_16x16x32_bf16 v[120:123], v[154:157], v[184:187], v[120:123]
	v_mfma_f32_16x16x32_bf16 v[116:119], v[146:149], v[192:195], v[116:119]
	v_mfma_f32_16x16x32_bf16 v[108:111], v[154:157], v[192:195], v[108:111]
	v_mfma_f32_16x16x32_bf16 v[100:103], v[146:149], v[206:209], v[100:103]
	v_mfma_f32_16x16x32_bf16 v[92:95], v[154:157], v[206:209], v[92:95]
	v_mfma_f32_16x16x32_bf16 v[84:87], v[146:149], v[214:217], v[84:87]
	v_mfma_f32_16x16x32_bf16 v[76:79], v[154:157], v[214:217], v[76:79]
	v_mfma_f32_16x16x32_bf16 v[124:127], v[150:153], v[188:191], v[124:127]
	v_mfma_f32_16x16x32_bf16 v[120:123], v[164:167], v[188:191], v[120:123]
	v_mfma_f32_16x16x32_bf16 v[116:119], v[150:153], v[196:199], v[116:119]
	v_mfma_f32_16x16x32_bf16 v[108:111], v[164:167], v[196:199], v[108:111]
	v_mfma_f32_16x16x32_bf16 v[100:103], v[150:153], v[210:213], v[100:103]
	v_mfma_f32_16x16x32_bf16 v[92:95], v[164:167], v[210:213], v[92:95]
	v_mfma_f32_16x16x32_bf16 v[84:87], v[150:153], v[218:221], v[84:87]
	v_mfma_f32_16x16x32_bf16 v[76:79], v[164:167], v[218:221], v[76:79]
	v_mfma_f32_16x16x32_bf16 v[112:115], v[168:171], v[184:187], v[112:115]
	v_mfma_f32_16x16x32_bf16 v[104:107], v[176:179], v[184:187], v[104:107]
	v_mfma_f32_16x16x32_bf16 v[96:99], v[168:171], v[192:195], v[96:99]
	v_mfma_f32_16x16x32_bf16 v[88:91], v[176:179], v[192:195], v[88:91]
	v_mfma_f32_16x16x32_bf16 v[80:83], v[168:171], v[206:209], v[80:83]
	v_mfma_f32_16x16x32_bf16 v[72:75], v[176:179], v[206:209], v[72:75]
	v_mfma_f32_16x16x32_bf16 v[68:71], v[168:171], v[214:217], v[68:71]
	v_mfma_f32_16x16x32_bf16 v[64:67], v[176:179], v[214:217], v[64:67]
	v_mfma_f32_16x16x32_bf16 v[112:115], v[172:175], v[188:191], v[112:115]
	v_mfma_f32_16x16x32_bf16 v[104:107], v[180:183], v[188:191], v[104:107]
	v_mfma_f32_16x16x32_bf16 v[96:99], v[172:175], v[196:199], v[96:99]
	v_mfma_f32_16x16x32_bf16 v[88:91], v[180:183], v[196:199], v[88:91]
	v_mfma_f32_16x16x32_bf16 v[80:83], v[172:175], v[210:213], v[80:83]
	v_mfma_f32_16x16x32_bf16 v[72:75], v[180:183], v[210:213], v[72:75]
	v_mfma_f32_16x16x32_bf16 v[68:71], v[172:175], v[218:221], v[68:71]
	v_mfma_f32_16x16x32_bf16 v[64:67], v[180:183], v[218:221], v[64:67]
	s_barrier
	s_setprio 0
	s_add_i32 s18, s20, s4
	v_lshl_add_u64 v[140:141], v[140:141], 0, s[76:77]
	s_mov_b32 m0, s18
	ds_read_b128 v[184:187], v144 offset:49152
	ds_read_b128 v[188:191], v144 offset:50176
	ds_read_b128 v[192:195], v144 offset:51200
	ds_read_b128 v[196:199], v144 offset:52224
	ds_read_b128 v[206:209], v144 offset:53248
	ds_read_b128 v[210:213], v144 offset:54272
	ds_read_b128 v[214:217], v144 offset:55296
	ds_read_b128 v[218:221], v144 offset:56320
	global_load_lds_dwordx4 v[140:141], off
	s_add_i32 m0, s18, 0x2000
	s_add_u32 s18, s50, 0x20080
	v_lshl_add_u64 v[140:141], v[158:159], 0, s[76:77]
	s_addc_u32 s19, s51, 0
	s_add_i32 s20, s21, s4
	global_load_lds_dwordx4 v[140:141], off
	v_lshl_add_u64 v[140:141], s[18:19], 0, v[130:131]
	s_mov_b32 m0, s20
	s_nop 0
	global_load_lds_dwordx4 v[140:141], off
	v_lshl_add_u64 v[140:141], s[18:19], 0, v[134:135]
	s_add_i32 m0, s20, 0x2000
	s_nop 0
	global_load_lds_dwordx4 v[140:141], off
	v_lshl_add_u64 v[140:141], v[200:201], 0, s[76:77]
	s_mov_b32 m0, s9
	s_nop 0
	global_load_lds_dwordx4 v[140:141], off
	v_lshl_add_u64 v[140:141], v[222:223], 0, s[76:77]
	s_mov_b32 m0, s10
	s_nop 0
	global_load_lds_dwordx4 v[140:141], off
	s_waitcnt vmcnt(8)
	s_waitcnt lgkmcnt(0)
	s_setprio 1
	s_barrier
	v_mfma_f32_16x16x32_bf16 v[60:63], v[146:149], v[184:187], v[60:63]
	v_mfma_f32_16x16x32_bf16 v[56:59], v[154:157], v[184:187], v[56:59]
	v_mfma_f32_16x16x32_bf16 v[52:55], v[146:149], v[192:195], v[52:55]
	v_mfma_f32_16x16x32_bf16 v[44:47], v[154:157], v[192:195], v[44:47]
	v_mfma_f32_16x16x32_bf16 v[36:39], v[146:149], v[206:209], v[36:39]
	v_mfma_f32_16x16x32_bf16 v[28:31], v[154:157], v[206:209], v[28:31]
	v_mfma_f32_16x16x32_bf16 v[20:23], v[146:149], v[214:217], v[20:23]
	v_mfma_f32_16x16x32_bf16 v[12:15], v[154:157], v[214:217], v[12:15]
	v_mfma_f32_16x16x32_bf16 v[60:63], v[150:153], v[188:191], v[60:63]
	v_mfma_f32_16x16x32_bf16 v[56:59], v[164:167], v[188:191], v[56:59]
	v_mfma_f32_16x16x32_bf16 v[52:55], v[150:153], v[196:199], v[52:55]
	v_mfma_f32_16x16x32_bf16 v[44:47], v[164:167], v[196:199], v[44:47]
	v_mfma_f32_16x16x32_bf16 v[36:39], v[150:153], v[210:213], v[36:39]
	v_mfma_f32_16x16x32_bf16 v[28:31], v[164:167], v[210:213], v[28:31]
	v_mfma_f32_16x16x32_bf16 v[20:23], v[150:153], v[218:221], v[20:23]
	v_mfma_f32_16x16x32_bf16 v[12:15], v[164:167], v[218:221], v[12:15]
	v_mfma_f32_16x16x32_bf16 v[48:51], v[168:171], v[184:187], v[48:51]
	v_mfma_f32_16x16x32_bf16 v[40:43], v[176:179], v[184:187], v[40:43]
	v_mfma_f32_16x16x32_bf16 v[32:35], v[168:171], v[192:195], v[32:35]
	v_mfma_f32_16x16x32_bf16 v[24:27], v[176:179], v[192:195], v[24:27]
	v_mfma_f32_16x16x32_bf16 v[16:19], v[168:171], v[206:209], v[16:19]
	v_mfma_f32_16x16x32_bf16 v[8:11], v[176:179], v[206:209], v[8:11]
	v_mfma_f32_16x16x32_bf16 v[4:7], v[168:171], v[214:217], v[4:7]
	v_mfma_f32_16x16x32_bf16 v[0:3], v[176:179], v[214:217], v[0:3]
	v_mfma_f32_16x16x32_bf16 v[48:51], v[172:175], v[188:191], v[48:51]
	v_mfma_f32_16x16x32_bf16 v[40:43], v[180:183], v[188:191], v[40:43]
	v_mfma_f32_16x16x32_bf16 v[32:35], v[172:175], v[196:199], v[32:35]
	v_mfma_f32_16x16x32_bf16 v[24:27], v[180:183], v[196:199], v[24:27]
	v_mfma_f32_16x16x32_bf16 v[16:19], v[172:175], v[210:213], v[16:19]
	v_mfma_f32_16x16x32_bf16 v[8:11], v[180:183], v[210:213], v[8:11]
	v_mfma_f32_16x16x32_bf16 v[4:7], v[172:175], v[218:221], v[4:7]
	v_mfma_f32_16x16x32_bf16 v[0:3], v[180:183], v[218:221], v[0:3]
	s_barrier
	s_setprio 0
	s_add_i32 s41, s41, 2
	s_add_u32 s58, s58, 0x100
	s_addc_u32 s59, s59, 0
	s_add_u32 s17, s17, 0x100
	s_addc_u32 s39, s39, 0
	s_cmp_gt_u32 s41, 5
	s_cbranch_scc0 .LBB0_779

.LBB0_913:
	s_add_i32 s11, s11, 1
	s_mov_b32 s13, s12
	s_mul_i32 s12, s11, s86
	s_add_i32 s12, s12, s45
	s_cmp_lt_u32 s12, 16
	s_mov_b32 s26, s40
	s_cselect_b64 s[48:49], -1, 0
	s_lshr_b32 s40, s12, 1
	s_mov_b32 s41, s27
	s_and_b32 s12, s12, 1
	s_lshl_b64 s[16:17], s[40:41], 19
	s_add_u32 s16, s21, s16
	s_addc_u32 s17, s22, s17
	s_lshl_b32 s18, s12, 18
	s_add_u32 s18, s16, s18
	s_addc_u32 s19, s17, 0
	s_mov_b64 s[14:15], s[42:43]
	s_and_b64 s[16:17], s[48:49], exec
	s_cselect_b32 s43, s19, s15
	s_cselect_b32 s42, s18, s14
	s_add_u32 s14, s14, 0x100
	s_addc_u32 s15, s15, 0
	s_mov_b32 s16, -2
	s_mov_b64 s[58:59], 0
	s_add_u32 s60, s58, 0x100
	s_addc_u32 s61, s59, 0
	s_add_u32 s17, s14, s58
	s_addc_u32 s18, s15, s59
	s_cmp_eq_u32 s16, 4
	s_cselect_b32 s20, 0, s60
	s_cselect_b32 s19, 0, s61
	s_cselect_b32 s50, s42, s17
	s_cselect_b32 s51, s43, s18
	s_add_u32 s62, s88, s20
	s_addc_u32 s63, s89, s19
	s_add_i32 s17, 0, 0x10000
	v_add_u32_e32 v142, s17, v144
	s_add_i32 s20, 0, 0x14000
	ds_read_b128 v[146:149], v142
	ds_read_b128 v[150:153], v142 offset:1024
	ds_read_b128 v[154:157], v142 offset:2048
	ds_read_b128 v[164:167], v142 offset:3072
	v_add_u32_e32 v142, s20, v144
	ds_read_b128 v[168:171], v142
	ds_read_b128 v[172:175], v142 offset:1024
	ds_read_b128 v[176:179], v142 offset:2048
	ds_read_b128 v[180:183], v142 offset:3072
	v_lshl_add_u64 v[142:143], v[138:139], 0, s[58:59]
	s_add_i32 m0, s5, 0xc000
	ds_read_b128 v[184:187], v145
	ds_read_b128 v[188:191], v145 offset:1024
	ds_read_b128 v[192:195], v145 offset:2048
	ds_read_b128 v[196:199], v145 offset:3072
	ds_read_b128 v[206:209], v145 offset:4096
	ds_read_b128 v[210:213], v145 offset:5120
	ds_read_b128 v[214:217], v145 offset:6144
	ds_read_b128 v[218:221], v145 offset:7168
	global_load_lds_dwordx4 v[142:143], off
	v_lshl_add_u64 v[142:143], v[140:141], 0, s[58:59]
	s_add_i32 m0, s5, 0xe000
	s_nop 0
	global_load_lds_dwordx4 v[142:143], off
	s_waitcnt vmcnt(8)
	s_waitcnt lgkmcnt(0)
	s_setprio 1
	s_barrier
	v_mfma_f32_16x16x32_bf16 v[124:127], v[146:149], v[184:187], 0
	v_mfma_f32_16x16x32_bf16 v[120:123], v[154:157], v[184:187], 0
	v_mfma_f32_16x16x32_bf16 v[116:119], v[146:149], v[192:195], 0
	v_mfma_f32_16x16x32_bf16 v[108:111], v[154:157], v[192:195], 0
	v_mfma_f32_16x16x32_bf16 v[100:103], v[146:149], v[206:209], 0
	v_mfma_f32_16x16x32_bf16 v[92:95], v[154:157], v[206:209], 0
	v_mfma_f32_16x16x32_bf16 v[84:87], v[146:149], v[214:217], 0
	v_mfma_f32_16x16x32_bf16 v[76:79], v[154:157], v[214:217], 0
	v_mfma_f32_16x16x32_bf16 v[124:127], v[150:153], v[188:191], v[124:127]
	v_mfma_f32_16x16x32_bf16 v[120:123], v[164:167], v[188:191], v[120:123]
	v_mfma_f32_16x16x32_bf16 v[116:119], v[150:153], v[196:199], v[116:119]
	v_mfma_f32_16x16x32_bf16 v[108:111], v[164:167], v[196:199], v[108:111]
	v_mfma_f32_16x16x32_bf16 v[100:103], v[150:153], v[210:213], v[100:103]
	v_mfma_f32_16x16x32_bf16 v[92:95], v[164:167], v[210:213], v[92:95]
	v_mfma_f32_16x16x32_bf16 v[84:87], v[150:153], v[218:221], v[84:87]
	v_mfma_f32_16x16x32_bf16 v[76:79], v[164:167], v[218:221], v[76:79]
	v_mfma_f32_16x16x32_bf16 v[112:115], v[168:171], v[184:187], 0
	v_mfma_f32_16x16x32_bf16 v[104:107], v[176:179], v[184:187], 0
	v_mfma_f32_16x16x32_bf16 v[96:99], v[168:171], v[192:195], 0
	v_mfma_f32_16x16x32_bf16 v[88:91], v[176:179], v[192:195], 0
	v_mfma_f32_16x16x32_bf16 v[80:83], v[168:171], v[206:209], 0
	v_mfma_f32_16x16x32_bf16 v[72:75], v[176:179], v[206:209], 0
	v_mfma_f32_16x16x32_bf16 v[68:71], v[168:171], v[214:217], 0
	v_mfma_f32_16x16x32_bf16 v[64:67], v[176:179], v[214:217], 0
	v_mfma_f32_16x16x32_bf16 v[112:115], v[172:175], v[188:191], v[112:115]
	v_mfma_f32_16x16x32_bf16 v[104:107], v[180:183], v[188:191], v[104:107]
	v_mfma_f32_16x16x32_bf16 v[96:99], v[172:175], v[196:199], v[96:99]
	v_mfma_f32_16x16x32_bf16 v[88:91], v[180:183], v[196:199], v[88:91]
	v_mfma_f32_16x16x32_bf16 v[80:83], v[172:175], v[210:213], v[80:83]
	v_mfma_f32_16x16x32_bf16 v[72:75], v[180:183], v[210:213], v[72:75]
	v_mfma_f32_16x16x32_bf16 v[68:71], v[172:175], v[218:221], v[68:71]
	v_mfma_f32_16x16x32_bf16 v[64:67], v[180:183], v[218:221], v[64:67]
	s_barrier
	s_setprio 0
	s_add_i32 s17, s17, s4
	v_lshl_add_u64 v[142:143], s[50:51], 0, v[132:133]
	s_mov_b32 m0, s17
	ds_read_b128 v[184:187], v145 offset:16384
	ds_read_b128 v[188:191], v145 offset:17408
	ds_read_b128 v[192:195], v145 offset:18432
	ds_read_b128 v[196:199], v145 offset:19456
	ds_read_b128 v[206:209], v145 offset:20480
	ds_read_b128 v[210:213], v145 offset:21504
	ds_read_b128 v[214:217], v145 offset:22528
	ds_read_b128 v[218:221], v145 offset:23552
	global_load_lds_dwordx4 v[142:143], off
	s_add_i32 m0, s17, 0x2000
	s_add_u32 s18, s50, 0x20000
	v_lshl_add_u64 v[158:159], s[50:51], 0, v[128:129]
	s_addc_u32 s19, s51, 0
	s_add_i32 s17, s20, s4
	global_load_lds_dwordx4 v[158:159], off
	v_lshl_add_u64 v[200:201], s[18:19], 0, v[132:133]
	s_mov_b32 m0, s17
	v_lshl_add_u64 v[222:223], s[62:63], 0, v[130:131]
	global_load_lds_dwordx4 v[200:201], off
	v_lshl_add_u64 v[200:201], s[18:19], 0, v[128:129]
	s_add_i32 m0, s17, 0x2000
	s_nop 0
	global_load_lds_dwordx4 v[200:201], off
	v_lshl_add_u64 v[200:201], s[62:63], 0, v[134:135]
	s_mov_b32 m0, s5
	s_nop 0
	global_load_lds_dwordx4 v[200:201], off
	s_mov_b32 m0, s6
	s_nop 0
	global_load_lds_dwordx4 v[222:223], off
	s_waitcnt vmcnt(8)
	s_waitcnt lgkmcnt(0)
	s_setprio 1
	s_barrier
	v_mfma_f32_16x16x32_bf16 v[60:63], v[146:149], v[184:187], 0
	v_mfma_f32_16x16x32_bf16 v[56:59], v[154:157], v[184:187], 0
	v_mfma_f32_16x16x32_bf16 v[52:55], v[146:149], v[192:195], 0
	v_mfma_f32_16x16x32_bf16 v[44:47], v[154:157], v[192:195], 0
	v_mfma_f32_16x16x32_bf16 v[36:39], v[146:149], v[206:209], 0
	v_mfma_f32_16x16x32_bf16 v[28:31], v[154:157], v[206:209], 0
	v_mfma_f32_16x16x32_bf16 v[20:23], v[146:149], v[214:217], 0
	v_mfma_f32_16x16x32_bf16 v[12:15], v[154:157], v[214:217], 0
	v_mfma_f32_16x16x32_bf16 v[60:63], v[150:153], v[188:191], v[60:63]
	v_mfma_f32_16x16x32_bf16 v[56:59], v[164:167], v[188:191], v[56:59]
	v_mfma_f32_16x16x32_bf16 v[52:55], v[150:153], v[196:199], v[52:55]
	v_mfma_f32_16x16x32_bf16 v[44:47], v[164:167], v[196:199], v[44:47]
	v_mfma_f32_16x16x32_bf16 v[36:39], v[150:153], v[210:213], v[36:39]
	v_mfma_f32_16x16x32_bf16 v[28:31], v[164:167], v[210:213], v[28:31]
	v_mfma_f32_16x16x32_bf16 v[20:23], v[150:153], v[218:221], v[20:23]
	v_mfma_f32_16x16x32_bf16 v[12:15], v[164:167], v[218:221], v[12:15]
	v_mfma_f32_16x16x32_bf16 v[48:51], v[168:171], v[184:187], 0
	v_mfma_f32_16x16x32_bf16 v[40:43], v[176:179], v[184:187], 0
	v_mfma_f32_16x16x32_bf16 v[32:35], v[168:171], v[192:195], 0
	v_mfma_f32_16x16x32_bf16 v[24:27], v[176:179], v[192:195], 0
	v_mfma_f32_16x16x32_bf16 v[16:19], v[168:171], v[206:209], 0
	v_mfma_f32_16x16x32_bf16 v[8:11], v[176:179], v[206:209], 0
	v_mfma_f32_16x16x32_bf16 v[4:7], v[168:171], v[214:217], 0
	v_mfma_f32_16x16x32_bf16 v[0:3], v[176:179], v[214:217], 0
	v_mfma_f32_16x16x32_bf16 v[48:51], v[172:175], v[188:191], v[48:51]
	v_mfma_f32_16x16x32_bf16 v[40:43], v[180:183], v[188:191], v[40:43]
	v_mfma_f32_16x16x32_bf16 v[32:35], v[172:175], v[196:199], v[32:35]
	v_mfma_f32_16x16x32_bf16 v[24:27], v[180:183], v[196:199], v[24:27]
	v_mfma_f32_16x16x32_bf16 v[16:19], v[172:175], v[210:213], v[16:19]
	v_mfma_f32_16x16x32_bf16 v[8:11], v[180:183], v[210:213], v[8:11]
	v_mfma_f32_16x16x32_bf16 v[4:7], v[172:175], v[218:221], v[4:7]
	v_mfma_f32_16x16x32_bf16 v[0:3], v[180:183], v[218:221], v[0:3]
	s_barrier
	s_setprio 0
	s_add_i32 s17, 0, 0x18000
	s_add_i32 s20, 0, 0x1c000
	v_add_u32_e32 v164, s17, v144
	v_add_u32_e32 v180, s20, v144
	ds_read_b128 v[146:149], v164
	ds_read_b128 v[150:153], v164 offset:1024
	ds_read_b128 v[154:157], v164 offset:2048
	ds_read_b128 v[164:167], v164 offset:3072
	ds_read_b128 v[168:171], v180
	ds_read_b128 v[172:175], v180 offset:1024
	ds_read_b128 v[176:179], v180 offset:2048
	ds_read_b128 v[180:183], v180 offset:3072
	s_add_u32 s18, s62, 0x20000
	s_addc_u32 s19, s63, 0
	s_mov_b32 m0, s7
	v_lshl_add_u64 v[224:225], s[18:19], 0, v[134:135]
	ds_read_b128 v[184:187], v145 offset:32768
	ds_read_b128 v[188:191], v145 offset:33792
	ds_read_b128 v[192:195], v145 offset:34816
	ds_read_b128 v[196:199], v145 offset:35840
	ds_read_b128 v[206:209], v145 offset:36864
	ds_read_b128 v[210:213], v145 offset:37888
	ds_read_b128 v[214:217], v145 offset:38912
	ds_read_b128 v[218:221], v145 offset:39936
	global_load_lds_dwordx4 v[224:225], off
	v_lshl_add_u64 v[224:225], s[18:19], 0, v[130:131]
	s_mov_b32 m0, s8
	s_nop 0
	global_load_lds_dwordx4 v[224:225], off
	s_waitcnt vmcnt(8)
	s_waitcnt lgkmcnt(0)
	s_setprio 1
	s_barrier
	v_mfma_f32_16x16x32_bf16 v[124:127], v[146:149], v[184:187], v[124:127]
	v_mfma_f32_16x16x32_bf16 v[120:123], v[154:157], v[184:187], v[120:123]
	v_mfma_f32_16x16x32_bf16 v[116:119], v[146:149], v[192:195], v[116:119]
	v_mfma_f32_16x16x32_bf16 v[108:111], v[154:157], v[192:195], v[108:111]
	v_mfma_f32_16x16x32_bf16 v[100:103], v[146:149], v[206:209], v[100:103]
	v_mfma_f32_16x16x32_bf16 v[92:95], v[154:157], v[206:209], v[92:95]
	v_mfma_f32_16x16x32_bf16 v[84:87], v[146:149], v[214:217], v[84:87]
	v_mfma_f32_16x16x32_bf16 v[76:79], v[154:157], v[214:217], v[76:79]
	v_mfma_f32_16x16x32_bf16 v[124:127], v[150:153], v[188:191], v[124:127]
	v_mfma_f32_16x16x32_bf16 v[120:123], v[164:167], v[188:191], v[120:123]
	v_mfma_f32_16x16x32_bf16 v[116:119], v[150:153], v[196:199], v[116:119]
	v_mfma_f32_16x16x32_bf16 v[108:111], v[164:167], v[196:199], v[108:111]
	v_mfma_f32_16x16x32_bf16 v[100:103], v[150:153], v[210:213], v[100:103]
	v_mfma_f32_16x16x32_bf16 v[92:95], v[164:167], v[210:213], v[92:95]
	v_mfma_f32_16x16x32_bf16 v[84:87], v[150:153], v[218:221], v[84:87]
	v_mfma_f32_16x16x32_bf16 v[76:79], v[164:167], v[218:221], v[76:79]
	v_mfma_f32_16x16x32_bf16 v[112:115], v[168:171], v[184:187], v[112:115]
	v_mfma_f32_16x16x32_bf16 v[104:107], v[176:179], v[184:187], v[104:107]
	v_mfma_f32_16x16x32_bf16 v[96:99], v[168:171], v[192:195], v[96:99]
	v_mfma_f32_16x16x32_bf16 v[88:91], v[176:179], v[192:195], v[88:91]
	v_mfma_f32_16x16x32_bf16 v[80:83], v[168:171], v[206:209], v[80:83]
	v_mfma_f32_16x16x32_bf16 v[72:75], v[176:179], v[206:209], v[72:75]
	v_mfma_f32_16x16x32_bf16 v[68:71], v[168:171], v[214:217], v[68:71]
	v_mfma_f32_16x16x32_bf16 v[64:67], v[176:179], v[214:217], v[64:67]
	v_mfma_f32_16x16x32_bf16 v[112:115], v[172:175], v[188:191], v[112:115]
	v_mfma_f32_16x16x32_bf16 v[104:107], v[180:183], v[188:191], v[104:107]
	v_mfma_f32_16x16x32_bf16 v[96:99], v[172:175], v[196:199], v[96:99]
	v_mfma_f32_16x16x32_bf16 v[88:91], v[180:183], v[196:199], v[88:91]
	v_mfma_f32_16x16x32_bf16 v[80:83], v[172:175], v[210:213], v[80:83]
	v_mfma_f32_16x16x32_bf16 v[72:75], v[180:183], v[210:213], v[72:75]
	v_mfma_f32_16x16x32_bf16 v[68:71], v[172:175], v[218:221], v[68:71]
	v_mfma_f32_16x16x32_bf16 v[64:67], v[180:183], v[218:221], v[64:67]
	s_barrier
	s_setprio 0
	s_add_i32 s17, s17, s4
	v_lshl_add_u64 v[142:143], v[142:143], 0, s[76:77]
	s_mov_b32 m0, s17
	ds_read_b128 v[184:187], v145 offset:49152
	ds_read_b128 v[188:191], v145 offset:50176
	ds_read_b128 v[192:195], v145 offset:51200
	ds_read_b128 v[196:199], v145 offset:52224
	ds_read_b128 v[206:209], v145 offset:53248
	ds_read_b128 v[210:213], v145 offset:54272
	ds_read_b128 v[214:217], v145 offset:55296
	ds_read_b128 v[218:221], v145 offset:56320
	global_load_lds_dwordx4 v[142:143], off
	s_add_i32 m0, s17, 0x2000
	s_add_u32 s18, s50, 0x20080
	v_lshl_add_u64 v[142:143], v[158:159], 0, s[76:77]
	s_addc_u32 s19, s51, 0
	s_add_i32 s17, s20, s4
	global_load_lds_dwordx4 v[142:143], off
	v_lshl_add_u64 v[142:143], s[18:19], 0, v[132:133]
	s_mov_b32 m0, s17
	s_nop 0
	global_load_lds_dwordx4 v[142:143], off
	v_lshl_add_u64 v[142:143], s[18:19], 0, v[128:129]
	s_add_i32 m0, s17, 0x2000
	s_nop 0
	global_load_lds_dwordx4 v[142:143], off
	v_lshl_add_u64 v[142:143], v[200:201], 0, s[76:77]
	s_mov_b32 m0, s9
	s_nop 0
	global_load_lds_dwordx4 v[142:143], off
	v_lshl_add_u64 v[142:143], v[222:223], 0, s[76:77]
	s_mov_b32 m0, s10
	s_nop 0
	global_load_lds_dwordx4 v[142:143], off
	s_waitcnt vmcnt(8)
	s_waitcnt lgkmcnt(0)
	s_setprio 1
	s_barrier
	v_mfma_f32_16x16x32_bf16 v[60:63], v[146:149], v[184:187], v[60:63]
	v_mfma_f32_16x16x32_bf16 v[56:59], v[154:157], v[184:187], v[56:59]
	v_mfma_f32_16x16x32_bf16 v[52:55], v[146:149], v[192:195], v[52:55]
	v_mfma_f32_16x16x32_bf16 v[44:47], v[154:157], v[192:195], v[44:47]
	v_mfma_f32_16x16x32_bf16 v[36:39], v[146:149], v[206:209], v[36:39]
	v_mfma_f32_16x16x32_bf16 v[28:31], v[154:157], v[206:209], v[28:31]
	v_mfma_f32_16x16x32_bf16 v[20:23], v[146:149], v[214:217], v[20:23]
	v_mfma_f32_16x16x32_bf16 v[12:15], v[154:157], v[214:217], v[12:15]
	v_mfma_f32_16x16x32_bf16 v[60:63], v[150:153], v[188:191], v[60:63]
	v_mfma_f32_16x16x32_bf16 v[56:59], v[164:167], v[188:191], v[56:59]
	v_mfma_f32_16x16x32_bf16 v[52:55], v[150:153], v[196:199], v[52:55]
	v_mfma_f32_16x16x32_bf16 v[44:47], v[164:167], v[196:199], v[44:47]
	v_mfma_f32_16x16x32_bf16 v[36:39], v[150:153], v[210:213], v[36:39]
	v_mfma_f32_16x16x32_bf16 v[28:31], v[164:167], v[210:213], v[28:31]
	v_mfma_f32_16x16x32_bf16 v[20:23], v[150:153], v[218:221], v[20:23]
	v_mfma_f32_16x16x32_bf16 v[12:15], v[164:167], v[218:221], v[12:15]
	v_mfma_f32_16x16x32_bf16 v[48:51], v[168:171], v[184:187], v[48:51]
	v_mfma_f32_16x16x32_bf16 v[40:43], v[176:179], v[184:187], v[40:43]
	v_mfma_f32_16x16x32_bf16 v[32:35], v[168:171], v[192:195], v[32:35]
	v_mfma_f32_16x16x32_bf16 v[24:27], v[176:179], v[192:195], v[24:27]
	v_mfma_f32_16x16x32_bf16 v[16:19], v[168:171], v[206:209], v[16:19]
	v_mfma_f32_16x16x32_bf16 v[8:11], v[176:179], v[206:209], v[8:11]
	v_mfma_f32_16x16x32_bf16 v[4:7], v[168:171], v[214:217], v[4:7]
	v_mfma_f32_16x16x32_bf16 v[0:3], v[176:179], v[214:217], v[0:3]
	v_mfma_f32_16x16x32_bf16 v[48:51], v[172:175], v[188:191], v[48:51]
	v_mfma_f32_16x16x32_bf16 v[40:43], v[180:183], v[188:191], v[40:43]
	v_mfma_f32_16x16x32_bf16 v[32:35], v[172:175], v[196:199], v[32:35]
	v_mfma_f32_16x16x32_bf16 v[24:27], v[180:183], v[196:199], v[24:27]
	v_mfma_f32_16x16x32_bf16 v[16:19], v[172:175], v[210:213], v[16:19]
	v_mfma_f32_16x16x32_bf16 v[8:11], v[180:183], v[210:213], v[8:11]
	v_mfma_f32_16x16x32_bf16 v[4:7], v[172:175], v[218:221], v[4:7]
	v_mfma_f32_16x16x32_bf16 v[0:3], v[180:183], v[218:221], v[0:3]
	s_barrier
	s_setprio 0
	s_add_i32 s16, s16, 2
	s_cmp_gt_u32 s16, 5
	s_mov_b64 s[58:59], s[60:61]
	s_cbranch_scc0 .LBB0_914
	s_branch .Lpeel_x_914
.LBB0_914:
	s_add_u32 s60, s58, 0x100
	s_addc_u32 s61, s59, 0
	s_add_u32 s17, s14, s58
	s_addc_u32 s18, s15, s59
	s_cmp_eq_u32 s16, 4
	s_cselect_b32 s20, 0, s60
	s_cselect_b32 s19, 0, s61
	s_cselect_b32 s50, s42, s17
	s_cselect_b32 s51, s43, s18
	s_add_u32 s62, s88, s20
	s_addc_u32 s63, s89, s19
	s_add_i32 s17, 0, 0x10000
	v_add_u32_e32 v142, s17, v144
	s_add_i32 s20, 0, 0x14000
	ds_read_b128 v[146:149], v142
	ds_read_b128 v[150:153], v142 offset:1024
	ds_read_b128 v[154:157], v142 offset:2048
	ds_read_b128 v[164:167], v142 offset:3072
	v_add_u32_e32 v142, s20, v144
	ds_read_b128 v[168:171], v142
	ds_read_b128 v[172:175], v142 offset:1024
	ds_read_b128 v[176:179], v142 offset:2048
	ds_read_b128 v[180:183], v142 offset:3072
	v_lshl_add_u64 v[142:143], v[138:139], 0, s[58:59]
	s_add_i32 m0, s5, 0xc000
	ds_read_b128 v[184:187], v145
	ds_read_b128 v[188:191], v145 offset:1024
	ds_read_b128 v[192:195], v145 offset:2048
	ds_read_b128 v[196:199], v145 offset:3072
	ds_read_b128 v[206:209], v145 offset:4096
	ds_read_b128 v[210:213], v145 offset:5120
	ds_read_b128 v[214:217], v145 offset:6144
	ds_read_b128 v[218:221], v145 offset:7168
	global_load_lds_dwordx4 v[142:143], off
	v_lshl_add_u64 v[142:143], v[140:141], 0, s[58:59]
	s_add_i32 m0, s5, 0xe000
	s_nop 0
	global_load_lds_dwordx4 v[142:143], off
	s_waitcnt vmcnt(8)
	s_waitcnt lgkmcnt(0)
	s_setprio 1
	s_barrier
	v_mfma_f32_16x16x32_bf16 v[124:127], v[146:149], v[184:187], v[124:127]
	v_mfma_f32_16x16x32_bf16 v[120:123], v[154:157], v[184:187], v[120:123]
	v_mfma_f32_16x16x32_bf16 v[116:119], v[146:149], v[192:195], v[116:119]
	v_mfma_f32_16x16x32_bf16 v[108:111], v[154:157], v[192:195], v[108:111]
	v_mfma_f32_16x16x32_bf16 v[100:103], v[146:149], v[206:209], v[100:103]
	v_mfma_f32_16x16x32_bf16 v[92:95], v[154:157], v[206:209], v[92:95]
	v_mfma_f32_16x16x32_bf16 v[84:87], v[146:149], v[214:217], v[84:87]
	v_mfma_f32_16x16x32_bf16 v[76:79], v[154:157], v[214:217], v[76:79]
	v_mfma_f32_16x16x32_bf16 v[124:127], v[150:153], v[188:191], v[124:127]
	v_mfma_f32_16x16x32_bf16 v[120:123], v[164:167], v[188:191], v[120:123]
	v_mfma_f32_16x16x32_bf16 v[116:119], v[150:153], v[196:199], v[116:119]
	v_mfma_f32_16x16x32_bf16 v[108:111], v[164:167], v[196:199], v[108:111]
	v_mfma_f32_16x16x32_bf16 v[100:103], v[150:153], v[210:213], v[100:103]
	v_mfma_f32_16x16x32_bf16 v[92:95], v[164:167], v[210:213], v[92:95]
	v_mfma_f32_16x16x32_bf16 v[84:87], v[150:153], v[218:221], v[84:87]
	v_mfma_f32_16x16x32_bf16 v[76:79], v[164:167], v[218:221], v[76:79]
	v_mfma_f32_16x16x32_bf16 v[112:115], v[168:171], v[184:187], v[112:115]
	v_mfma_f32_16x16x32_bf16 v[104:107], v[176:179], v[184:187], v[104:107]
	v_mfma_f32_16x16x32_bf16 v[96:99], v[168:171], v[192:195], v[96:99]
	v_mfma_f32_16x16x32_bf16 v[88:91], v[176:179], v[192:195], v[88:91]
	v_mfma_f32_16x16x32_bf16 v[80:83], v[168:171], v[206:209], v[80:83]
	v_mfma_f32_16x16x32_bf16 v[72:75], v[176:179], v[206:209], v[72:75]
	v_mfma_f32_16x16x32_bf16 v[68:71], v[168:171], v[214:217], v[68:71]
	v_mfma_f32_16x16x32_bf16 v[64:67], v[176:179], v[214:217], v[64:67]
	v_mfma_f32_16x16x32_bf16 v[112:115], v[172:175], v[188:191], v[112:115]
	v_mfma_f32_16x16x32_bf16 v[104:107], v[180:183], v[188:191], v[104:107]
	v_mfma_f32_16x16x32_bf16 v[96:99], v[172:175], v[196:199], v[96:99]
	v_mfma_f32_16x16x32_bf16 v[88:91], v[180:183], v[196:199], v[88:91]
	v_mfma_f32_16x16x32_bf16 v[80:83], v[172:175], v[210:213], v[80:83]
	v_mfma_f32_16x16x32_bf16 v[72:75], v[180:183], v[210:213], v[72:75]
	v_mfma_f32_16x16x32_bf16 v[68:71], v[172:175], v[218:221], v[68:71]
	v_mfma_f32_16x16x32_bf16 v[64:67], v[180:183], v[218:221], v[64:67]
	s_barrier
	s_setprio 0
	s_add_i32 s17, s17, s4
	v_lshl_add_u64 v[142:143], s[50:51], 0, v[132:133]
	s_mov_b32 m0, s17
	ds_read_b128 v[184:187], v145 offset:16384
	ds_read_b128 v[188:191], v145 offset:17408
	ds_read_b128 v[192:195], v145 offset:18432
	ds_read_b128 v[196:199], v145 offset:19456
	ds_read_b128 v[206:209], v145 offset:20480
	ds_read_b128 v[210:213], v145 offset:21504
	ds_read_b128 v[214:217], v145 offset:22528
	ds_read_b128 v[218:221], v145 offset:23552
	global_load_lds_dwordx4 v[142:143], off
	s_add_i32 m0, s17, 0x2000
	s_add_u32 s18, s50, 0x20000
	v_lshl_add_u64 v[158:159], s[50:51], 0, v[128:129]
	s_addc_u32 s19, s51, 0
	s_add_i32 s17, s20, s4
	global_load_lds_dwordx4 v[158:159], off
	v_lshl_add_u64 v[200:201], s[18:19], 0, v[132:133]
	s_mov_b32 m0, s17
	v_lshl_add_u64 v[222:223], s[62:63], 0, v[130:131]
	global_load_lds_dwordx4 v[200:201], off
	v_lshl_add_u64 v[200:201], s[18:19], 0, v[128:129]
	s_add_i32 m0, s17, 0x2000
	s_nop 0
	global_load_lds_dwordx4 v[200:201], off
	v_lshl_add_u64 v[200:201], s[62:63], 0, v[134:135]
	s_mov_b32 m0, s5
	s_nop 0
	global_load_lds_dwordx4 v[200:201], off
	s_mov_b32 m0, s6
	s_nop 0
	global_load_lds_dwordx4 v[222:223], off
	s_waitcnt vmcnt(8)
	s_waitcnt lgkmcnt(0)
	s_setprio 1
	s_barrier
	v_mfma_f32_16x16x32_bf16 v[60:63], v[146:149], v[184:187], v[60:63]
	v_mfma_f32_16x16x32_bf16 v[56:59], v[154:157], v[184:187], v[56:59]
	v_mfma_f32_16x16x32_bf16 v[52:55], v[146:149], v[192:195], v[52:55]
	v_mfma_f32_16x16x32_bf16 v[44:47], v[154:157], v[192:195], v[44:47]
	v_mfma_f32_16x16x32_bf16 v[36:39], v[146:149], v[206:209], v[36:39]
	v_mfma_f32_16x16x32_bf16 v[28:31], v[154:157], v[206:209], v[28:31]
	v_mfma_f32_16x16x32_bf16 v[20:23], v[146:149], v[214:217], v[20:23]
	v_mfma_f32_16x16x32_bf16 v[12:15], v[154:157], v[214:217], v[12:15]
	v_mfma_f32_16x16x32_bf16 v[60:63], v[150:153], v[188:191], v[60:63]
	v_mfma_f32_16x16x32_bf16 v[56:59], v[164:167], v[188:191], v[56:59]
	v_mfma_f32_16x16x32_bf16 v[52:55], v[150:153], v[196:199], v[52:55]
	v_mfma_f32_16x16x32_bf16 v[44:47], v[164:167], v[196:199], v[44:47]
	v_mfma_f32_16x16x32_bf16 v[36:39], v[150:153], v[210:213], v[36:39]
	v_mfma_f32_16x16x32_bf16 v[28:31], v[164:167], v[210:213], v[28:31]
	v_mfma_f32_16x16x32_bf16 v[20:23], v[150:153], v[218:221], v[20:23]
	v_mfma_f32_16x16x32_bf16 v[12:15], v[164:167], v[218:221], v[12:15]
	v_mfma_f32_16x16x32_bf16 v[48:51], v[168:171], v[184:187], v[48:51]
	v_mfma_f32_16x16x32_bf16 v[40:43], v[176:179], v[184:187], v[40:43]
	v_mfma_f32_16x16x32_bf16 v[32:35], v[168:171], v[192:195], v[32:35]
	v_mfma_f32_16x16x32_bf16 v[24:27], v[176:179], v[192:195], v[24:27]
	v_mfma_f32_16x16x32_bf16 v[16:19], v[168:171], v[206:209], v[16:19]
	v_mfma_f32_16x16x32_bf16 v[8:11], v[176:179], v[206:209], v[8:11]
	v_mfma_f32_16x16x32_bf16 v[4:7], v[168:171], v[214:217], v[4:7]
	v_mfma_f32_16x16x32_bf16 v[0:3], v[176:179], v[214:217], v[0:3]
	v_mfma_f32_16x16x32_bf16 v[48:51], v[172:175], v[188:191], v[48:51]
	v_mfma_f32_16x16x32_bf16 v[40:43], v[180:183], v[188:191], v[40:43]
	v_mfma_f32_16x16x32_bf16 v[32:35], v[172:175], v[196:199], v[32:35]
	v_mfma_f32_16x16x32_bf16 v[24:27], v[180:183], v[196:199], v[24:27]
	v_mfma_f32_16x16x32_bf16 v[16:19], v[172:175], v[210:213], v[16:19]
	v_mfma_f32_16x16x32_bf16 v[8:11], v[180:183], v[210:213], v[8:11]
	v_mfma_f32_16x16x32_bf16 v[4:7], v[172:175], v[218:221], v[4:7]
	v_mfma_f32_16x16x32_bf16 v[0:3], v[180:183], v[218:221], v[0:3]
	s_barrier
	s_setprio 0
	s_add_i32 s17, 0, 0x18000
	s_add_i32 s20, 0, 0x1c000
	v_add_u32_e32 v164, s17, v144
	v_add_u32_e32 v180, s20, v144
	ds_read_b128 v[146:149], v164
	ds_read_b128 v[150:153], v164 offset:1024
	ds_read_b128 v[154:157], v164 offset:2048
	ds_read_b128 v[164:167], v164 offset:3072
	ds_read_b128 v[168:171], v180
	ds_read_b128 v[172:175], v180 offset:1024
	ds_read_b128 v[176:179], v180 offset:2048
	ds_read_b128 v[180:183], v180 offset:3072
	s_add_u32 s18, s62, 0x20000
	s_addc_u32 s19, s63, 0
	s_mov_b32 m0, s7
	v_lshl_add_u64 v[224:225], s[18:19], 0, v[134:135]
	ds_read_b128 v[184:187], v145 offset:32768
	ds_read_b128 v[188:191], v145 offset:33792
	ds_read_b128 v[192:195], v145 offset:34816
	ds_read_b128 v[196:199], v145 offset:35840
	ds_read_b128 v[206:209], v145 offset:36864
	ds_read_b128 v[210:213], v145 offset:37888
	ds_read_b128 v[214:217], v145 offset:38912
	ds_read_b128 v[218:221], v145 offset:39936
	global_load_lds_dwordx4 v[224:225], off
	v_lshl_add_u64 v[224:225], s[18:19], 0, v[130:131]
	s_mov_b32 m0, s8
	s_nop 0
	global_load_lds_dwordx4 v[224:225], off
	s_waitcnt vmcnt(8)
	s_waitcnt lgkmcnt(0)
	s_setprio 1
	s_barrier
	v_mfma_f32_16x16x32_bf16 v[124:127], v[146:149], v[184:187], v[124:127]
	v_mfma_f32_16x16x32_bf16 v[120:123], v[154:157], v[184:187], v[120:123]
	v_mfma_f32_16x16x32_bf16 v[116:119], v[146:149], v[192:195], v[116:119]
	v_mfma_f32_16x16x32_bf16 v[108:111], v[154:157], v[192:195], v[108:111]
	v_mfma_f32_16x16x32_bf16 v[100:103], v[146:149], v[206:209], v[100:103]
	v_mfma_f32_16x16x32_bf16 v[92:95], v[154:157], v[206:209], v[92:95]
	v_mfma_f32_16x16x32_bf16 v[84:87], v[146:149], v[214:217], v[84:87]
	v_mfma_f32_16x16x32_bf16 v[76:79], v[154:157], v[214:217], v[76:79]
	v_mfma_f32_16x16x32_bf16 v[124:127], v[150:153], v[188:191], v[124:127]
	v_mfma_f32_16x16x32_bf16 v[120:123], v[164:167], v[188:191], v[120:123]
	v_mfma_f32_16x16x32_bf16 v[116:119], v[150:153], v[196:199], v[116:119]
	v_mfma_f32_16x16x32_bf16 v[108:111], v[164:167], v[196:199], v[108:111]
	v_mfma_f32_16x16x32_bf16 v[100:103], v[150:153], v[210:213], v[100:103]
	v_mfma_f32_16x16x32_bf16 v[92:95], v[164:167], v[210:213], v[92:95]
	v_mfma_f32_16x16x32_bf16 v[84:87], v[150:153], v[218:221], v[84:87]
	v_mfma_f32_16x16x32_bf16 v[76:79], v[164:167], v[218:221], v[76:79]
	v_mfma_f32_16x16x32_bf16 v[112:115], v[168:171], v[184:187], v[112:115]
	v_mfma_f32_16x16x32_bf16 v[104:107], v[176:179], v[184:187], v[104:107]
	v_mfma_f32_16x16x32_bf16 v[96:99], v[168:171], v[192:195], v[96:99]
	v_mfma_f32_16x16x32_bf16 v[88:91], v[176:179], v[192:195], v[88:91]
	v_mfma_f32_16x16x32_bf16 v[80:83], v[168:171], v[206:209], v[80:83]
	v_mfma_f32_16x16x32_bf16 v[72:75], v[176:179], v[206:209], v[72:75]
	v_mfma_f32_16x16x32_bf16 v[68:71], v[168:171], v[214:217], v[68:71]
	v_mfma_f32_16x16x32_bf16 v[64:67], v[176:179], v[214:217], v[64:67]
	v_mfma_f32_16x16x32_bf16 v[112:115], v[172:175], v[188:191], v[112:115]
	v_mfma_f32_16x16x32_bf16 v[104:107], v[180:183], v[188:191], v[104:107]
	v_mfma_f32_16x16x32_bf16 v[96:99], v[172:175], v[196:199], v[96:99]
	v_mfma_f32_16x16x32_bf16 v[88:91], v[180:183], v[196:199], v[88:91]
	v_mfma_f32_16x16x32_bf16 v[80:83], v[172:175], v[210:213], v[80:83]
	v_mfma_f32_16x16x32_bf16 v[72:75], v[180:183], v[210:213], v[72:75]
	v_mfma_f32_16x16x32_bf16 v[68:71], v[172:175], v[218:221], v[68:71]
	v_mfma_f32_16x16x32_bf16 v[64:67], v[180:183], v[218:221], v[64:67]
	s_barrier
	s_setprio 0
	s_add_i32 s17, s17, s4
	v_lshl_add_u64 v[142:143], v[142:143], 0, s[76:77]
	s_mov_b32 m0, s17
	ds_read_b128 v[184:187], v145 offset:49152
	ds_read_b128 v[188:191], v145 offset:50176
	ds_read_b128 v[192:195], v145 offset:51200
	ds_read_b128 v[196:199], v145 offset:52224
	ds_read_b128 v[206:209], v145 offset:53248
	ds_read_b128 v[210:213], v145 offset:54272
	ds_read_b128 v[214:217], v145 offset:55296
	ds_read_b128 v[218:221], v145 offset:56320
	global_load_lds_dwordx4 v[142:143], off
	s_add_i32 m0, s17, 0x2000
	s_add_u32 s18, s50, 0x20080
	v_lshl_add_u64 v[142:143], v[158:159], 0, s[76:77]
	s_addc_u32 s19, s51, 0
	s_add_i32 s17, s20, s4
	global_load_lds_dwordx4 v[142:143], off
	v_lshl_add_u64 v[142:143], s[18:19], 0, v[132:133]
	s_mov_b32 m0, s17
	s_nop 0
	global_load_lds_dwordx4 v[142:143], off
	v_lshl_add_u64 v[142:143], s[18:19], 0, v[128:129]
	s_add_i32 m0, s17, 0x2000
	s_nop 0
	global_load_lds_dwordx4 v[142:143], off
	v_lshl_add_u64 v[142:143], v[200:201], 0, s[76:77]
	s_mov_b32 m0, s9
	s_nop 0
	global_load_lds_dwordx4 v[142:143], off
	v_lshl_add_u64 v[142:143], v[222:223], 0, s[76:77]
	s_mov_b32 m0, s10
	s_nop 0
	global_load_lds_dwordx4 v[142:143], off
	s_waitcnt vmcnt(8)
	s_waitcnt lgkmcnt(0)
	s_setprio 1
	s_barrier
	v_mfma_f32_16x16x32_bf16 v[60:63], v[146:149], v[184:187], v[60:63]
	v_mfma_f32_16x16x32_bf16 v[56:59], v[154:157], v[184:187], v[56:59]
	v_mfma_f32_16x16x32_bf16 v[52:55], v[146:149], v[192:195], v[52:55]
	v_mfma_f32_16x16x32_bf16 v[44:47], v[154:157], v[192:195], v[44:47]
	v_mfma_f32_16x16x32_bf16 v[36:39], v[146:149], v[206:209], v[36:39]
	v_mfma_f32_16x16x32_bf16 v[28:31], v[154:157], v[206:209], v[28:31]
	v_mfma_f32_16x16x32_bf16 v[20:23], v[146:149], v[214:217], v[20:23]
	v_mfma_f32_16x16x32_bf16 v[12:15], v[154:157], v[214:217], v[12:15]
	v_mfma_f32_16x16x32_bf16 v[60:63], v[150:153], v[188:191], v[60:63]
	v_mfma_f32_16x16x32_bf16 v[56:59], v[164:167], v[188:191], v[56:59]
	v_mfma_f32_16x16x32_bf16 v[52:55], v[150:153], v[196:199], v[52:55]
	v_mfma_f32_16x16x32_bf16 v[44:47], v[164:167], v[196:199], v[44:47]
	v_mfma_f32_16x16x32_bf16 v[36:39], v[150:153], v[210:213], v[36:39]
	v_mfma_f32_16x16x32_bf16 v[28:31], v[164:167], v[210:213], v[28:31]
	v_mfma_f32_16x16x32_bf16 v[20:23], v[150:153], v[218:221], v[20:23]
	v_mfma_f32_16x16x32_bf16 v[12:15], v[164:167], v[218:221], v[12:15]
	v_mfma_f32_16x16x32_bf16 v[48:51], v[168:171], v[184:187], v[48:51]
	v_mfma_f32_16x16x32_bf16 v[40:43], v[176:179], v[184:187], v[40:43]
	v_mfma_f32_16x16x32_bf16 v[32:35], v[168:171], v[192:195], v[32:35]
	v_mfma_f32_16x16x32_bf16 v[24:27], v[176:179], v[192:195], v[24:27]
	v_mfma_f32_16x16x32_bf16 v[16:19], v[168:171], v[206:209], v[16:19]
	v_mfma_f32_16x16x32_bf16 v[8:11], v[176:179], v[206:209], v[8:11]
	v_mfma_f32_16x16x32_bf16 v[4:7], v[168:171], v[214:217], v[4:7]
	v_mfma_f32_16x16x32_bf16 v[0:3], v[176:179], v[214:217], v[0:3]
	v_mfma_f32_16x16x32_bf16 v[48:51], v[172:175], v[188:191], v[48:51]
	v_mfma_f32_16x16x32_bf16 v[40:43], v[180:183], v[188:191], v[40:43]
	v_mfma_f32_16x16x32_bf16 v[32:35], v[172:175], v[196:199], v[32:35]
	v_mfma_f32_16x16x32_bf16 v[24:27], v[180:183], v[196:199], v[24:27]
	v_mfma_f32_16x16x32_bf16 v[16:19], v[172:175], v[210:213], v[16:19]
	v_mfma_f32_16x16x32_bf16 v[8:11], v[180:183], v[210:213], v[8:11]
	v_mfma_f32_16x16x32_bf16 v[4:7], v[172:175], v[218:221], v[4:7]
	v_mfma_f32_16x16x32_bf16 v[0:3], v[180:183], v[218:221], v[0:3]
	s_barrier
	s_setprio 0
	s_add_i32 s16, s16, 2
	s_cmp_gt_u32 s16, 5
	s_mov_b64 s[58:59], s[60:61]
	s_cbranch_scc0 .LBB0_914

.LBB0_982:
	s_ashr_i32 s37, s36, 31
	s_lshl_b64 s[16:17], s[36:37], 19
	s_add_u32 s40, s94, s16
	s_addc_u32 s41, s95, s17
	s_and_b64 s[16:17], s[42:43], exec
	s_cselect_b32 s15, s41, s51
	s_cselect_b32 s16, s40, s50
	s_ashr_i32 s39, s38, 31
	s_lshl_b64 s[18:19], s[38:39], 19
	s_add_u32 s48, s22, s18
	s_addc_u32 s49, s23, s19
	s_and_b64 s[18:19], s[42:43], exec
	s_cselect_b32 s17, s49, s61
	s_cselect_b32 s37, s48, s60
	s_add_u32 s58, s50, 0x40080
	s_addc_u32 s59, s51, 0
	s_add_u32 s39, s60, 0x100
	s_addc_u32 s47, s61, 0
	s_mov_b32 s54, -2
	s_add_u32 s18, s58, 0xfffc0080
	s_addc_u32 s19, s59, -1
	s_add_i32 s20, 0, 0x10000
	s_cmp_eq_u32 s54, 12
	s_cselect_b32 s61, s15, s19
	s_cselect_b32 s60, s16, s18
	s_cselect_b32 s51, s17, s47
	s_cselect_b32 s50, s37, s39
	s_add_i32 s21, 0, 0x14000
	v_add_u32_e32 v140, s20, v174
	v_add_u32_e32 v162, s21, v174
	ds_read_b128 v[128:131], v140
	ds_read_b128 v[132:135], v140 offset:1024
	ds_read_b128 v[136:139], v140 offset:2048
	ds_read_b128 v[140:143], v140 offset:3072
	ds_read_b128 v[156:159], v162
	ds_read_b128 v[164:167], v162 offset:1024
	ds_read_b128 v[168:171], v162 offset:2048
	ds_read_b128 v[176:179], v162 offset:3072
	v_lshl_add_u64 v[200:201], s[58:59], 0, v[152:153]
	s_add_i32 m0, s4, 0xc000
	ds_read_b128 v[180:183], v175
	ds_read_b128 v[184:187], v175 offset:1024
	ds_read_b128 v[188:191], v175 offset:2048
	ds_read_b128 v[192:195], v175 offset:3072
	ds_read_b128 v[196:199], v175 offset:4096
	ds_read_b128 v[206:209], v175 offset:5120
	ds_read_b128 v[210:213], v175 offset:6144
	ds_read_b128 v[214:217], v175 offset:7168
	global_load_lds_dwordx4 v[200:201], off
	v_lshl_add_u64 v[200:201], s[58:59], 0, v[154:155]
	s_add_i32 m0, s4, 0xe000
	s_nop 0
	global_load_lds_dwordx4 v[200:201], off
	s_waitcnt vmcnt(8)
	s_waitcnt lgkmcnt(0)
	s_setprio 1
	s_barrier
	v_mfma_f32_16x16x32_bf16 v[124:127], v[128:131], v[180:183], 0
	v_mfma_f32_16x16x32_bf16 v[120:123], v[136:139], v[180:183], 0
	v_mfma_f32_16x16x32_bf16 v[112:115], v[128:131], v[188:191], 0
	v_mfma_f32_16x16x32_bf16 v[104:107], v[136:139], v[188:191], 0
	v_mfma_f32_16x16x32_bf16 v[96:99], v[128:131], v[196:199], 0
	v_mfma_f32_16x16x32_bf16 v[88:91], v[136:139], v[196:199], 0
	v_mfma_f32_16x16x32_bf16 v[80:83], v[128:131], v[210:213], 0
	v_mfma_f32_16x16x32_bf16 v[72:75], v[136:139], v[210:213], 0
	v_mfma_f32_16x16x32_bf16 v[124:127], v[132:135], v[184:187], v[124:127]
	v_mfma_f32_16x16x32_bf16 v[120:123], v[140:143], v[184:187], v[120:123]
	v_mfma_f32_16x16x32_bf16 v[112:115], v[132:135], v[192:195], v[112:115]
	v_mfma_f32_16x16x32_bf16 v[104:107], v[140:143], v[192:195], v[104:107]
	v_mfma_f32_16x16x32_bf16 v[96:99], v[132:135], v[206:209], v[96:99]
	v_mfma_f32_16x16x32_bf16 v[88:91], v[140:143], v[206:209], v[88:91]
	v_mfma_f32_16x16x32_bf16 v[80:83], v[132:135], v[214:217], v[80:83]
	v_mfma_f32_16x16x32_bf16 v[72:75], v[140:143], v[214:217], v[72:75]
	v_mfma_f32_16x16x32_bf16 v[116:119], v[156:159], v[180:183], 0
	v_mfma_f32_16x16x32_bf16 v[108:111], v[168:171], v[180:183], 0
	v_mfma_f32_16x16x32_bf16 v[100:103], v[156:159], v[188:191], 0
	v_mfma_f32_16x16x32_bf16 v[92:95], v[168:171], v[188:191], 0
	v_mfma_f32_16x16x32_bf16 v[84:87], v[156:159], v[196:199], 0
	v_mfma_f32_16x16x32_bf16 v[76:79], v[168:171], v[196:199], 0
	v_mfma_f32_16x16x32_bf16 v[68:71], v[156:159], v[210:213], 0
	v_mfma_f32_16x16x32_bf16 v[64:67], v[168:171], v[210:213], 0
	v_mfma_f32_16x16x32_bf16 v[116:119], v[164:167], v[184:187], v[116:119]
	v_mfma_f32_16x16x32_bf16 v[108:111], v[176:179], v[184:187], v[108:111]
	v_mfma_f32_16x16x32_bf16 v[100:103], v[164:167], v[192:195], v[100:103]
	v_mfma_f32_16x16x32_bf16 v[92:95], v[176:179], v[192:195], v[92:95]
	v_mfma_f32_16x16x32_bf16 v[84:87], v[164:167], v[206:209], v[84:87]
	v_mfma_f32_16x16x32_bf16 v[76:79], v[176:179], v[206:209], v[76:79]
	v_mfma_f32_16x16x32_bf16 v[68:71], v[164:167], v[214:217], v[68:71]
	v_mfma_f32_16x16x32_bf16 v[64:67], v[176:179], v[214:217], v[64:67]
	s_barrier
	s_setprio 0
	s_add_i32 s18, s20, s46
	v_lshl_add_u64 v[200:201], s[50:51], 0, v[148:149]
	s_mov_b32 m0, s18
	ds_read_b128 v[180:183], v175 offset:16384
	ds_read_b128 v[184:187], v175 offset:17408
	ds_read_b128 v[188:191], v175 offset:18432
	ds_read_b128 v[192:195], v175 offset:19456
	ds_read_b128 v[196:199], v175 offset:20480
	ds_read_b128 v[206:209], v175 offset:21504
	ds_read_b128 v[210:213], v175 offset:22528
	ds_read_b128 v[214:217], v175 offset:23552
	global_load_lds_dwordx4 v[200:201], off
	s_add_i32 m0, s18, 0x2000
	s_add_u32 s18, s50, 0x40000
	v_lshl_add_u64 v[218:219], s[50:51], 0, v[144:145]
	s_addc_u32 s19, s51, 0
	s_add_i32 s20, s21, s46
	global_load_lds_dwordx4 v[218:219], off
	v_lshl_add_u64 v[220:221], s[18:19], 0, v[148:149]
	s_mov_b32 m0, s20
	v_lshl_add_u64 v[222:223], s[60:61], 0, v[146:147]
	global_load_lds_dwordx4 v[220:221], off
	v_lshl_add_u64 v[220:221], s[18:19], 0, v[144:145]
	s_add_i32 m0, s20, 0x2000
	s_nop 0
	global_load_lds_dwordx4 v[220:221], off
	v_lshl_add_u64 v[220:221], s[60:61], 0, v[150:151]
	s_mov_b32 m0, s4
	s_nop 0
	global_load_lds_dwordx4 v[220:221], off
	s_mov_b32 m0, s5
	s_nop 0
	global_load_lds_dwordx4 v[222:223], off
	s_waitcnt vmcnt(8)
	s_waitcnt lgkmcnt(0)
	s_setprio 1
	s_barrier
	v_mfma_f32_16x16x32_bf16 v[60:63], v[128:131], v[180:183], 0
	v_mfma_f32_16x16x32_bf16 v[56:59], v[136:139], v[180:183], 0
	v_mfma_f32_16x16x32_bf16 v[48:51], v[128:131], v[188:191], 0
	v_mfma_f32_16x16x32_bf16 v[40:43], v[136:139], v[188:191], 0
	v_mfma_f32_16x16x32_bf16 v[32:35], v[128:131], v[196:199], 0
	v_mfma_f32_16x16x32_bf16 v[24:27], v[136:139], v[196:199], 0
	v_mfma_f32_16x16x32_bf16 v[16:19], v[128:131], v[210:213], 0
	v_mfma_f32_16x16x32_bf16 v[8:11], v[136:139], v[210:213], 0
	v_mfma_f32_16x16x32_bf16 v[60:63], v[132:135], v[184:187], v[60:63]
	v_mfma_f32_16x16x32_bf16 v[56:59], v[140:143], v[184:187], v[56:59]
	v_mfma_f32_16x16x32_bf16 v[48:51], v[132:135], v[192:195], v[48:51]
	v_mfma_f32_16x16x32_bf16 v[40:43], v[140:143], v[192:195], v[40:43]
	v_mfma_f32_16x16x32_bf16 v[32:35], v[132:135], v[206:209], v[32:35]
	v_mfma_f32_16x16x32_bf16 v[24:27], v[140:143], v[206:209], v[24:27]
	v_mfma_f32_16x16x32_bf16 v[16:19], v[132:135], v[214:217], v[16:19]
	v_mfma_f32_16x16x32_bf16 v[8:11], v[140:143], v[214:217], v[8:11]
	v_mfma_f32_16x16x32_bf16 v[52:55], v[156:159], v[180:183], 0
	v_mfma_f32_16x16x32_bf16 v[44:47], v[168:171], v[180:183], 0
	v_mfma_f32_16x16x32_bf16 v[36:39], v[156:159], v[188:191], 0
	v_mfma_f32_16x16x32_bf16 v[28:31], v[168:171], v[188:191], 0
	v_mfma_f32_16x16x32_bf16 v[20:23], v[156:159], v[196:199], 0
	v_mfma_f32_16x16x32_bf16 v[12:15], v[168:171], v[196:199], 0
	v_mfma_f32_16x16x32_bf16 v[4:7], v[156:159], v[210:213], 0
	v_mfma_f32_16x16x32_bf16 v[0:3], v[168:171], v[210:213], 0
	v_mfma_f32_16x16x32_bf16 v[52:55], v[164:167], v[184:187], v[52:55]
	v_mfma_f32_16x16x32_bf16 v[44:47], v[176:179], v[184:187], v[44:47]
	v_mfma_f32_16x16x32_bf16 v[36:39], v[164:167], v[192:195], v[36:39]
	v_mfma_f32_16x16x32_bf16 v[28:31], v[176:179], v[192:195], v[28:31]
	v_mfma_f32_16x16x32_bf16 v[20:23], v[164:167], v[206:209], v[20:23]
	v_mfma_f32_16x16x32_bf16 v[12:15], v[176:179], v[206:209], v[12:15]
	v_mfma_f32_16x16x32_bf16 v[4:7], v[164:167], v[214:217], v[4:7]
	v_mfma_f32_16x16x32_bf16 v[0:3], v[176:179], v[214:217], v[0:3]
	s_barrier
	s_setprio 0
	s_add_i32 s20, 0, 0x18000
	s_add_i32 s21, 0, 0x1c000
	v_add_u32_e32 v140, s20, v174
	v_add_u32_e32 v162, s21, v174
	ds_read_b128 v[128:131], v140
	ds_read_b128 v[132:135], v140 offset:1024
	ds_read_b128 v[136:139], v140 offset:2048
	ds_read_b128 v[140:143], v140 offset:3072
	ds_read_b128 v[156:159], v162
	ds_read_b128 v[164:167], v162 offset:1024
	ds_read_b128 v[168:171], v162 offset:2048
	ds_read_b128 v[176:179], v162 offset:3072
	s_add_u32 s18, s60, 0x40000
	s_addc_u32 s19, s61, 0
	s_mov_b32 m0, s6
	v_lshl_add_u64 v[224:225], s[18:19], 0, v[150:151]
	ds_read_b128 v[180:183], v175 offset:32768
	ds_read_b128 v[184:187], v175 offset:33792
	ds_read_b128 v[188:191], v175 offset:34816
	ds_read_b128 v[192:195], v175 offset:35840
	ds_read_b128 v[196:199], v175 offset:36864
	ds_read_b128 v[206:209], v175 offset:37888
	ds_read_b128 v[210:213], v175 offset:38912
	ds_read_b128 v[214:217], v175 offset:39936
	global_load_lds_dwordx4 v[224:225], off
	v_lshl_add_u64 v[224:225], s[18:19], 0, v[146:147]
	s_mov_b32 m0, s7
	s_nop 0
	global_load_lds_dwordx4 v[224:225], off
	s_waitcnt vmcnt(8)
	s_waitcnt lgkmcnt(0)
	s_setprio 1
	s_barrier
	v_mfma_f32_16x16x32_bf16 v[124:127], v[128:131], v[180:183], v[124:127]
	v_mfma_f32_16x16x32_bf16 v[120:123], v[136:139], v[180:183], v[120:123]
	v_mfma_f32_16x16x32_bf16 v[112:115], v[128:131], v[188:191], v[112:115]
	v_mfma_f32_16x16x32_bf16 v[104:107], v[136:139], v[188:191], v[104:107]
	v_mfma_f32_16x16x32_bf16 v[96:99], v[128:131], v[196:199], v[96:99]
	v_mfma_f32_16x16x32_bf16 v[88:91], v[136:139], v[196:199], v[88:91]
	v_mfma_f32_16x16x32_bf16 v[80:83], v[128:131], v[210:213], v[80:83]
	v_mfma_f32_16x16x32_bf16 v[72:75], v[136:139], v[210:213], v[72:75]
	v_mfma_f32_16x16x32_bf16 v[124:127], v[132:135], v[184:187], v[124:127]
	v_mfma_f32_16x16x32_bf16 v[120:123], v[140:143], v[184:187], v[120:123]
	v_mfma_f32_16x16x32_bf16 v[112:115], v[132:135], v[192:195], v[112:115]
	v_mfma_f32_16x16x32_bf16 v[104:107], v[140:143], v[192:195], v[104:107]
	v_mfma_f32_16x16x32_bf16 v[96:99], v[132:135], v[206:209], v[96:99]
	v_mfma_f32_16x16x32_bf16 v[88:91], v[140:143], v[206:209], v[88:91]
	v_mfma_f32_16x16x32_bf16 v[80:83], v[132:135], v[214:217], v[80:83]
	v_mfma_f32_16x16x32_bf16 v[72:75], v[140:143], v[214:217], v[72:75]
	v_mfma_f32_16x16x32_bf16 v[116:119], v[156:159], v[180:183], v[116:119]
	v_mfma_f32_16x16x32_bf16 v[108:111], v[168:171], v[180:183], v[108:111]
	v_mfma_f32_16x16x32_bf16 v[100:103], v[156:159], v[188:191], v[100:103]
	v_mfma_f32_16x16x32_bf16 v[92:95], v[168:171], v[188:191], v[92:95]
	v_mfma_f32_16x16x32_bf16 v[84:87], v[156:159], v[196:199], v[84:87]
	v_mfma_f32_16x16x32_bf16 v[76:79], v[168:171], v[196:199], v[76:79]
	v_mfma_f32_16x16x32_bf16 v[68:71], v[156:159], v[210:213], v[68:71]
	v_mfma_f32_16x16x32_bf16 v[64:67], v[168:171], v[210:213], v[64:67]
	v_mfma_f32_16x16x32_bf16 v[116:119], v[164:167], v[184:187], v[116:119]
	v_mfma_f32_16x16x32_bf16 v[108:111], v[176:179], v[184:187], v[108:111]
	v_mfma_f32_16x16x32_bf16 v[100:103], v[164:167], v[192:195], v[100:103]
	v_mfma_f32_16x16x32_bf16 v[92:95], v[176:179], v[192:195], v[92:95]
	v_mfma_f32_16x16x32_bf16 v[84:87], v[164:167], v[206:209], v[84:87]
	v_mfma_f32_16x16x32_bf16 v[76:79], v[176:179], v[206:209], v[76:79]
	v_mfma_f32_16x16x32_bf16 v[68:71], v[164:167], v[214:217], v[68:71]
	v_mfma_f32_16x16x32_bf16 v[64:67], v[176:179], v[214:217], v[64:67]
	s_barrier
	s_setprio 0
	s_add_i32 s18, s20, s46
	v_lshl_add_u64 v[200:201], v[200:201], 0, s[76:77]
	s_mov_b32 m0, s18
	ds_read_b128 v[180:183], v175 offset:49152
	ds_read_b128 v[184:187], v175 offset:50176
	ds_read_b128 v[188:191], v175 offset:51200
	ds_read_b128 v[192:195], v175 offset:52224
	ds_read_b128 v[196:199], v175 offset:53248
	ds_read_b128 v[206:209], v175 offset:54272
	ds_read_b128 v[210:213], v175 offset:55296
	ds_read_b128 v[214:217], v175 offset:56320
	global_load_lds_dwordx4 v[200:201], off
	s_add_i32 m0, s18, 0x2000
	s_add_u32 s18, s50, 0x40080
	v_lshl_add_u64 v[200:201], v[218:219], 0, s[76:77]
	s_addc_u32 s19, s51, 0
	s_add_i32 s20, s21, s46
	global_load_lds_dwordx4 v[200:201], off
	v_lshl_add_u64 v[200:201], s[18:19], 0, v[148:149]
	s_mov_b32 m0, s20
	s_nop 0
	global_load_lds_dwordx4 v[200:201], off
	v_lshl_add_u64 v[200:201], s[18:19], 0, v[144:145]
	s_add_i32 m0, s20, 0x2000
	s_nop 0
	global_load_lds_dwordx4 v[200:201], off
	v_lshl_add_u64 v[200:201], v[220:221], 0, s[76:77]
	s_mov_b32 m0, s9
	s_nop 0
	global_load_lds_dwordx4 v[200:201], off
	v_lshl_add_u64 v[200:201], v[222:223], 0, s[76:77]
	s_mov_b32 m0, s10
	s_nop 0
	global_load_lds_dwordx4 v[200:201], off
	s_waitcnt vmcnt(8)
	s_waitcnt lgkmcnt(0)
	s_setprio 1
	s_barrier
	v_mfma_f32_16x16x32_bf16 v[60:63], v[128:131], v[180:183], v[60:63]
	v_mfma_f32_16x16x32_bf16 v[56:59], v[136:139], v[180:183], v[56:59]
	v_mfma_f32_16x16x32_bf16 v[48:51], v[128:131], v[188:191], v[48:51]
	v_mfma_f32_16x16x32_bf16 v[40:43], v[136:139], v[188:191], v[40:43]
	v_mfma_f32_16x16x32_bf16 v[32:35], v[128:131], v[196:199], v[32:35]
	v_mfma_f32_16x16x32_bf16 v[24:27], v[136:139], v[196:199], v[24:27]
	v_mfma_f32_16x16x32_bf16 v[16:19], v[128:131], v[210:213], v[16:19]
	v_mfma_f32_16x16x32_bf16 v[8:11], v[136:139], v[210:213], v[8:11]
	v_mfma_f32_16x16x32_bf16 v[60:63], v[132:135], v[184:187], v[60:63]
	v_mfma_f32_16x16x32_bf16 v[56:59], v[140:143], v[184:187], v[56:59]
	v_mfma_f32_16x16x32_bf16 v[48:51], v[132:135], v[192:195], v[48:51]
	v_mfma_f32_16x16x32_bf16 v[40:43], v[140:143], v[192:195], v[40:43]
	v_mfma_f32_16x16x32_bf16 v[32:35], v[132:135], v[206:209], v[32:35]
	v_mfma_f32_16x16x32_bf16 v[24:27], v[140:143], v[206:209], v[24:27]
	v_mfma_f32_16x16x32_bf16 v[16:19], v[132:135], v[214:217], v[16:19]
	v_mfma_f32_16x16x32_bf16 v[8:11], v[140:143], v[214:217], v[8:11]
	v_mfma_f32_16x16x32_bf16 v[52:55], v[156:159], v[180:183], v[52:55]
	v_mfma_f32_16x16x32_bf16 v[44:47], v[168:171], v[180:183], v[44:47]
	v_mfma_f32_16x16x32_bf16 v[36:39], v[156:159], v[188:191], v[36:39]
	v_mfma_f32_16x16x32_bf16 v[28:31], v[168:171], v[188:191], v[28:31]
	v_mfma_f32_16x16x32_bf16 v[20:23], v[156:159], v[196:199], v[20:23]
	v_mfma_f32_16x16x32_bf16 v[12:15], v[168:171], v[196:199], v[12:15]
	v_mfma_f32_16x16x32_bf16 v[4:7], v[156:159], v[210:213], v[4:7]
	v_mfma_f32_16x16x32_bf16 v[0:3], v[168:171], v[210:213], v[0:3]
	v_mfma_f32_16x16x32_bf16 v[52:55], v[164:167], v[184:187], v[52:55]
	v_mfma_f32_16x16x32_bf16 v[44:47], v[176:179], v[184:187], v[44:47]
	v_mfma_f32_16x16x32_bf16 v[36:39], v[164:167], v[192:195], v[36:39]
	v_mfma_f32_16x16x32_bf16 v[28:31], v[176:179], v[192:195], v[28:31]
	v_mfma_f32_16x16x32_bf16 v[20:23], v[164:167], v[206:209], v[20:23]
	v_mfma_f32_16x16x32_bf16 v[12:15], v[176:179], v[206:209], v[12:15]
	v_mfma_f32_16x16x32_bf16 v[4:7], v[164:167], v[214:217], v[4:7]
	v_mfma_f32_16x16x32_bf16 v[0:3], v[176:179], v[214:217], v[0:3]
	s_barrier
	s_setprio 0
	s_add_i32 s54, s54, 2
	s_add_u32 s58, s58, 0x100
	s_addc_u32 s59, s59, 0
	s_add_u32 s39, s39, 0x100
	s_addc_u32 s47, s47, 0
	s_cmp_gt_u32 s54, 13
	s_cbranch_scc0 .LBB0_983
	s_branch .Lpeel_x_983
.LBB0_983:
	s_add_u32 s18, s58, 0xfffc0080
	s_addc_u32 s19, s59, -1
	s_add_i32 s20, 0, 0x10000
	s_cmp_eq_u32 s54, 12
	s_cselect_b32 s61, s15, s19
	s_cselect_b32 s60, s16, s18
	s_cselect_b32 s51, s17, s47
	s_cselect_b32 s50, s37, s39
	s_add_i32 s21, 0, 0x14000
	v_add_u32_e32 v140, s20, v174
	v_add_u32_e32 v162, s21, v174
	ds_read_b128 v[128:131], v140
	ds_read_b128 v[132:135], v140 offset:1024
	ds_read_b128 v[136:139], v140 offset:2048
	ds_read_b128 v[140:143], v140 offset:3072
	ds_read_b128 v[156:159], v162
	ds_read_b128 v[164:167], v162 offset:1024
	ds_read_b128 v[168:171], v162 offset:2048
	ds_read_b128 v[176:179], v162 offset:3072
	v_lshl_add_u64 v[200:201], s[58:59], 0, v[152:153]
	s_add_i32 m0, s4, 0xc000
	ds_read_b128 v[180:183], v175
	ds_read_b128 v[184:187], v175 offset:1024
	ds_read_b128 v[188:191], v175 offset:2048
	ds_read_b128 v[192:195], v175 offset:3072
	ds_read_b128 v[196:199], v175 offset:4096
	ds_read_b128 v[206:209], v175 offset:5120
	ds_read_b128 v[210:213], v175 offset:6144
	ds_read_b128 v[214:217], v175 offset:7168
	global_load_lds_dwordx4 v[200:201], off
	v_lshl_add_u64 v[200:201], s[58:59], 0, v[154:155]
	s_add_i32 m0, s4, 0xe000
	s_nop 0
	global_load_lds_dwordx4 v[200:201], off
	s_waitcnt vmcnt(8)
	s_waitcnt lgkmcnt(0)
	s_setprio 1
	s_barrier
	v_mfma_f32_16x16x32_bf16 v[124:127], v[128:131], v[180:183], v[124:127]
	v_mfma_f32_16x16x32_bf16 v[120:123], v[136:139], v[180:183], v[120:123]
	v_mfma_f32_16x16x32_bf16 v[112:115], v[128:131], v[188:191], v[112:115]
	v_mfma_f32_16x16x32_bf16 v[104:107], v[136:139], v[188:191], v[104:107]
	v_mfma_f32_16x16x32_bf16 v[96:99], v[128:131], v[196:199], v[96:99]
	v_mfma_f32_16x16x32_bf16 v[88:91], v[136:139], v[196:199], v[88:91]
	v_mfma_f32_16x16x32_bf16 v[80:83], v[128:131], v[210:213], v[80:83]
	v_mfma_f32_16x16x32_bf16 v[72:75], v[136:139], v[210:213], v[72:75]
	v_mfma_f32_16x16x32_bf16 v[124:127], v[132:135], v[184:187], v[124:127]
	v_mfma_f32_16x16x32_bf16 v[120:123], v[140:143], v[184:187], v[120:123]
	v_mfma_f32_16x16x32_bf16 v[112:115], v[132:135], v[192:195], v[112:115]
	v_mfma_f32_16x16x32_bf16 v[104:107], v[140:143], v[192:195], v[104:107]
	v_mfma_f32_16x16x32_bf16 v[96:99], v[132:135], v[206:209], v[96:99]
	v_mfma_f32_16x16x32_bf16 v[88:91], v[140:143], v[206:209], v[88:91]
	v_mfma_f32_16x16x32_bf16 v[80:83], v[132:135], v[214:217], v[80:83]
	v_mfma_f32_16x16x32_bf16 v[72:75], v[140:143], v[214:217], v[72:75]
	v_mfma_f32_16x16x32_bf16 v[116:119], v[156:159], v[180:183], v[116:119]
	v_mfma_f32_16x16x32_bf16 v[108:111], v[168:171], v[180:183], v[108:111]
	v_mfma_f32_16x16x32_bf16 v[100:103], v[156:159], v[188:191], v[100:103]
	v_mfma_f32_16x16x32_bf16 v[92:95], v[168:171], v[188:191], v[92:95]
	v_mfma_f32_16x16x32_bf16 v[84:87], v[156:159], v[196:199], v[84:87]
	v_mfma_f32_16x16x32_bf16 v[76:79], v[168:171], v[196:199], v[76:79]
	v_mfma_f32_16x16x32_bf16 v[68:71], v[156:159], v[210:213], v[68:71]
	v_mfma_f32_16x16x32_bf16 v[64:67], v[168:171], v[210:213], v[64:67]
	v_mfma_f32_16x16x32_bf16 v[116:119], v[164:167], v[184:187], v[116:119]
	v_mfma_f32_16x16x32_bf16 v[108:111], v[176:179], v[184:187], v[108:111]
	v_mfma_f32_16x16x32_bf16 v[100:103], v[164:167], v[192:195], v[100:103]
	v_mfma_f32_16x16x32_bf16 v[92:95], v[176:179], v[192:195], v[92:95]
	v_mfma_f32_16x16x32_bf16 v[84:87], v[164:167], v[206:209], v[84:87]
	v_mfma_f32_16x16x32_bf16 v[76:79], v[176:179], v[206:209], v[76:79]
	v_mfma_f32_16x16x32_bf16 v[68:71], v[164:167], v[214:217], v[68:71]
	v_mfma_f32_16x16x32_bf16 v[64:67], v[176:179], v[214:217], v[64:67]
	s_barrier
	s_setprio 0
	s_add_i32 s18, s20, s46
	v_lshl_add_u64 v[200:201], s[50:51], 0, v[148:149]
	s_mov_b32 m0, s18
	ds_read_b128 v[180:183], v175 offset:16384
	ds_read_b128 v[184:187], v175 offset:17408
	ds_read_b128 v[188:191], v175 offset:18432
	ds_read_b128 v[192:195], v175 offset:19456
	ds_read_b128 v[196:199], v175 offset:20480
	ds_read_b128 v[206:209], v175 offset:21504
	ds_read_b128 v[210:213], v175 offset:22528
	ds_read_b128 v[214:217], v175 offset:23552
	global_load_lds_dwordx4 v[200:201], off
	s_add_i32 m0, s18, 0x2000
	s_add_u32 s18, s50, 0x40000
	v_lshl_add_u64 v[218:219], s[50:51], 0, v[144:145]
	s_addc_u32 s19, s51, 0
	s_add_i32 s20, s21, s46
	global_load_lds_dwordx4 v[218:219], off
	v_lshl_add_u64 v[220:221], s[18:19], 0, v[148:149]
	s_mov_b32 m0, s20
	v_lshl_add_u64 v[222:223], s[60:61], 0, v[146:147]
	global_load_lds_dwordx4 v[220:221], off
	v_lshl_add_u64 v[220:221], s[18:19], 0, v[144:145]
	s_add_i32 m0, s20, 0x2000
	s_nop 0
	global_load_lds_dwordx4 v[220:221], off
	v_lshl_add_u64 v[220:221], s[60:61], 0, v[150:151]
	s_mov_b32 m0, s4
	s_nop 0
	global_load_lds_dwordx4 v[220:221], off
	s_mov_b32 m0, s5
	s_nop 0
	global_load_lds_dwordx4 v[222:223], off
	s_waitcnt vmcnt(8)
	s_waitcnt lgkmcnt(0)
	s_setprio 1
	s_barrier
	v_mfma_f32_16x16x32_bf16 v[60:63], v[128:131], v[180:183], v[60:63]
	v_mfma_f32_16x16x32_bf16 v[56:59], v[136:139], v[180:183], v[56:59]
	v_mfma_f32_16x16x32_bf16 v[48:51], v[128:131], v[188:191], v[48:51]
	v_mfma_f32_16x16x32_bf16 v[40:43], v[136:139], v[188:191], v[40:43]
	v_mfma_f32_16x16x32_bf16 v[32:35], v[128:131], v[196:199], v[32:35]
	v_mfma_f32_16x16x32_bf16 v[24:27], v[136:139], v[196:199], v[24:27]
	v_mfma_f32_16x16x32_bf16 v[16:19], v[128:131], v[210:213], v[16:19]
	v_mfma_f32_16x16x32_bf16 v[8:11], v[136:139], v[210:213], v[8:11]
	v_mfma_f32_16x16x32_bf16 v[60:63], v[132:135], v[184:187], v[60:63]
	v_mfma_f32_16x16x32_bf16 v[56:59], v[140:143], v[184:187], v[56:59]
	v_mfma_f32_16x16x32_bf16 v[48:51], v[132:135], v[192:195], v[48:51]
	v_mfma_f32_16x16x32_bf16 v[40:43], v[140:143], v[192:195], v[40:43]
	v_mfma_f32_16x16x32_bf16 v[32:35], v[132:135], v[206:209], v[32:35]
	v_mfma_f32_16x16x32_bf16 v[24:27], v[140:143], v[206:209], v[24:27]
	v_mfma_f32_16x16x32_bf16 v[16:19], v[132:135], v[214:217], v[16:19]
	v_mfma_f32_16x16x32_bf16 v[8:11], v[140:143], v[214:217], v[8:11]
	v_mfma_f32_16x16x32_bf16 v[52:55], v[156:159], v[180:183], v[52:55]
	v_mfma_f32_16x16x32_bf16 v[44:47], v[168:171], v[180:183], v[44:47]
	v_mfma_f32_16x16x32_bf16 v[36:39], v[156:159], v[188:191], v[36:39]
	v_mfma_f32_16x16x32_bf16 v[28:31], v[168:171], v[188:191], v[28:31]
	v_mfma_f32_16x16x32_bf16 v[20:23], v[156:159], v[196:199], v[20:23]
	v_mfma_f32_16x16x32_bf16 v[12:15], v[168:171], v[196:199], v[12:15]
	v_mfma_f32_16x16x32_bf16 v[4:7], v[156:159], v[210:213], v[4:7]
	v_mfma_f32_16x16x32_bf16 v[0:3], v[168:171], v[210:213], v[0:3]
	v_mfma_f32_16x16x32_bf16 v[52:55], v[164:167], v[184:187], v[52:55]
	v_mfma_f32_16x16x32_bf16 v[44:47], v[176:179], v[184:187], v[44:47]
	v_mfma_f32_16x16x32_bf16 v[36:39], v[164:167], v[192:195], v[36:39]
	v_mfma_f32_16x16x32_bf16 v[28:31], v[176:179], v[192:195], v[28:31]
	v_mfma_f32_16x16x32_bf16 v[20:23], v[164:167], v[206:209], v[20:23]
	v_mfma_f32_16x16x32_bf16 v[12:15], v[176:179], v[206:209], v[12:15]
	v_mfma_f32_16x16x32_bf16 v[4:7], v[164:167], v[214:217], v[4:7]
	v_mfma_f32_16x16x32_bf16 v[0:3], v[176:179], v[214:217], v[0:3]
	s_barrier
	s_setprio 0
	s_add_i32 s20, 0, 0x18000
	s_add_i32 s21, 0, 0x1c000
	v_add_u32_e32 v140, s20, v174
	v_add_u32_e32 v162, s21, v174
	ds_read_b128 v[128:131], v140
	ds_read_b128 v[132:135], v140 offset:1024
	ds_read_b128 v[136:139], v140 offset:2048
	ds_read_b128 v[140:143], v140 offset:3072
	ds_read_b128 v[156:159], v162
	ds_read_b128 v[164:167], v162 offset:1024
	ds_read_b128 v[168:171], v162 offset:2048
	ds_read_b128 v[176:179], v162 offset:3072
	s_add_u32 s18, s60, 0x40000
	s_addc_u32 s19, s61, 0
	s_mov_b32 m0, s6
	v_lshl_add_u64 v[224:225], s[18:19], 0, v[150:151]
	ds_read_b128 v[180:183], v175 offset:32768
	ds_read_b128 v[184:187], v175 offset:33792
	ds_read_b128 v[188:191], v175 offset:34816
	ds_read_b128 v[192:195], v175 offset:35840
	ds_read_b128 v[196:199], v175 offset:36864
	ds_read_b128 v[206:209], v175 offset:37888
	ds_read_b128 v[210:213], v175 offset:38912
	ds_read_b128 v[214:217], v175 offset:39936
	global_load_lds_dwordx4 v[224:225], off
	v_lshl_add_u64 v[224:225], s[18:19], 0, v[146:147]
	s_mov_b32 m0, s7
	s_nop 0
	global_load_lds_dwordx4 v[224:225], off
	s_waitcnt vmcnt(8)
	s_waitcnt lgkmcnt(0)
	s_setprio 1
	s_barrier
	v_mfma_f32_16x16x32_bf16 v[124:127], v[128:131], v[180:183], v[124:127]
	v_mfma_f32_16x16x32_bf16 v[120:123], v[136:139], v[180:183], v[120:123]
	v_mfma_f32_16x16x32_bf16 v[112:115], v[128:131], v[188:191], v[112:115]
	v_mfma_f32_16x16x32_bf16 v[104:107], v[136:139], v[188:191], v[104:107]
	v_mfma_f32_16x16x32_bf16 v[96:99], v[128:131], v[196:199], v[96:99]
	v_mfma_f32_16x16x32_bf16 v[88:91], v[136:139], v[196:199], v[88:91]
	v_mfma_f32_16x16x32_bf16 v[80:83], v[128:131], v[210:213], v[80:83]
	v_mfma_f32_16x16x32_bf16 v[72:75], v[136:139], v[210:213], v[72:75]
	v_mfma_f32_16x16x32_bf16 v[124:127], v[132:135], v[184:187], v[124:127]
	v_mfma_f32_16x16x32_bf16 v[120:123], v[140:143], v[184:187], v[120:123]
	v_mfma_f32_16x16x32_bf16 v[112:115], v[132:135], v[192:195], v[112:115]
	v_mfma_f32_16x16x32_bf16 v[104:107], v[140:143], v[192:195], v[104:107]
	v_mfma_f32_16x16x32_bf16 v[96:99], v[132:135], v[206:209], v[96:99]
	v_mfma_f32_16x16x32_bf16 v[88:91], v[140:143], v[206:209], v[88:91]
	v_mfma_f32_16x16x32_bf16 v[80:83], v[132:135], v[214:217], v[80:83]
	v_mfma_f32_16x16x32_bf16 v[72:75], v[140:143], v[214:217], v[72:75]
	v_mfma_f32_16x16x32_bf16 v[116:119], v[156:159], v[180:183], v[116:119]
	v_mfma_f32_16x16x32_bf16 v[108:111], v[168:171], v[180:183], v[108:111]
	v_mfma_f32_16x16x32_bf16 v[100:103], v[156:159], v[188:191], v[100:103]
	v_mfma_f32_16x16x32_bf16 v[92:95], v[168:171], v[188:191], v[92:95]
	v_mfma_f32_16x16x32_bf16 v[84:87], v[156:159], v[196:199], v[84:87]
	v_mfma_f32_16x16x32_bf16 v[76:79], v[168:171], v[196:199], v[76:79]
	v_mfma_f32_16x16x32_bf16 v[68:71], v[156:159], v[210:213], v[68:71]
	v_mfma_f32_16x16x32_bf16 v[64:67], v[168:171], v[210:213], v[64:67]
	v_mfma_f32_16x16x32_bf16 v[116:119], v[164:167], v[184:187], v[116:119]
	v_mfma_f32_16x16x32_bf16 v[108:111], v[176:179], v[184:187], v[108:111]
	v_mfma_f32_16x16x32_bf16 v[100:103], v[164:167], v[192:195], v[100:103]
	v_mfma_f32_16x16x32_bf16 v[92:95], v[176:179], v[192:195], v[92:95]
	v_mfma_f32_16x16x32_bf16 v[84:87], v[164:167], v[206:209], v[84:87]
	v_mfma_f32_16x16x32_bf16 v[76:79], v[176:179], v[206:209], v[76:79]
	v_mfma_f32_16x16x32_bf16 v[68:71], v[164:167], v[214:217], v[68:71]
	v_mfma_f32_16x16x32_bf16 v[64:67], v[176:179], v[214:217], v[64:67]
	s_barrier
	s_setprio 0
	s_add_i32 s18, s20, s46
	v_lshl_add_u64 v[200:201], v[200:201], 0, s[76:77]
	s_mov_b32 m0, s18
	ds_read_b128 v[180:183], v175 offset:49152
	ds_read_b128 v[184:187], v175 offset:50176
	ds_read_b128 v[188:191], v175 offset:51200
	ds_read_b128 v[192:195], v175 offset:52224
	ds_read_b128 v[196:199], v175 offset:53248
	ds_read_b128 v[206:209], v175 offset:54272
	ds_read_b128 v[210:213], v175 offset:55296
	ds_read_b128 v[214:217], v175 offset:56320
	global_load_lds_dwordx4 v[200:201], off
	s_add_i32 m0, s18, 0x2000
	s_add_u32 s18, s50, 0x40080
	v_lshl_add_u64 v[200:201], v[218:219], 0, s[76:77]
	s_addc_u32 s19, s51, 0
	s_add_i32 s20, s21, s46
	global_load_lds_dwordx4 v[200:201], off
	v_lshl_add_u64 v[200:201], s[18:19], 0, v[148:149]
	s_mov_b32 m0, s20
	s_nop 0
	global_load_lds_dwordx4 v[200:201], off
	v_lshl_add_u64 v[200:201], s[18:19], 0, v[144:145]
	s_add_i32 m0, s20, 0x2000
	s_nop 0
	global_load_lds_dwordx4 v[200:201], off
	v_lshl_add_u64 v[200:201], v[220:221], 0, s[76:77]
	s_mov_b32 m0, s9
	s_nop 0
	global_load_lds_dwordx4 v[200:201], off
	v_lshl_add_u64 v[200:201], v[222:223], 0, s[76:77]
	s_mov_b32 m0, s10
	s_nop 0
	global_load_lds_dwordx4 v[200:201], off
	s_waitcnt vmcnt(8)
	s_waitcnt lgkmcnt(0)
	s_setprio 1
	s_barrier
	v_mfma_f32_16x16x32_bf16 v[60:63], v[128:131], v[180:183], v[60:63]
	v_mfma_f32_16x16x32_bf16 v[56:59], v[136:139], v[180:183], v[56:59]
	v_mfma_f32_16x16x32_bf16 v[48:51], v[128:131], v[188:191], v[48:51]
	v_mfma_f32_16x16x32_bf16 v[40:43], v[136:139], v[188:191], v[40:43]
	v_mfma_f32_16x16x32_bf16 v[32:35], v[128:131], v[196:199], v[32:35]
	v_mfma_f32_16x16x32_bf16 v[24:27], v[136:139], v[196:199], v[24:27]
	v_mfma_f32_16x16x32_bf16 v[16:19], v[128:131], v[210:213], v[16:19]
	v_mfma_f32_16x16x32_bf16 v[8:11], v[136:139], v[210:213], v[8:11]
	v_mfma_f32_16x16x32_bf16 v[60:63], v[132:135], v[184:187], v[60:63]
	v_mfma_f32_16x16x32_bf16 v[56:59], v[140:143], v[184:187], v[56:59]
	v_mfma_f32_16x16x32_bf16 v[48:51], v[132:135], v[192:195], v[48:51]
	v_mfma_f32_16x16x32_bf16 v[40:43], v[140:143], v[192:195], v[40:43]
	v_mfma_f32_16x16x32_bf16 v[32:35], v[132:135], v[206:209], v[32:35]
	v_mfma_f32_16x16x32_bf16 v[24:27], v[140:143], v[206:209], v[24:27]
	v_mfma_f32_16x16x32_bf16 v[16:19], v[132:135], v[214:217], v[16:19]
	v_mfma_f32_16x16x32_bf16 v[8:11], v[140:143], v[214:217], v[8:11]
	v_mfma_f32_16x16x32_bf16 v[52:55], v[156:159], v[180:183], v[52:55]
	v_mfma_f32_16x16x32_bf16 v[44:47], v[168:171], v[180:183], v[44:47]
	v_mfma_f32_16x16x32_bf16 v[36:39], v[156:159], v[188:191], v[36:39]
	v_mfma_f32_16x16x32_bf16 v[28:31], v[168:171], v[188:191], v[28:31]
	v_mfma_f32_16x16x32_bf16 v[20:23], v[156:159], v[196:199], v[20:23]
	v_mfma_f32_16x16x32_bf16 v[12:15], v[168:171], v[196:199], v[12:15]
	v_mfma_f32_16x16x32_bf16 v[4:7], v[156:159], v[210:213], v[4:7]
	v_mfma_f32_16x16x32_bf16 v[0:3], v[168:171], v[210:213], v[0:3]
	v_mfma_f32_16x16x32_bf16 v[52:55], v[164:167], v[184:187], v[52:55]
	v_mfma_f32_16x16x32_bf16 v[44:47], v[176:179], v[184:187], v[44:47]
	v_mfma_f32_16x16x32_bf16 v[36:39], v[164:167], v[192:195], v[36:39]
	v_mfma_f32_16x16x32_bf16 v[28:31], v[176:179], v[192:195], v[28:31]
	v_mfma_f32_16x16x32_bf16 v[20:23], v[164:167], v[206:209], v[20:23]
	v_mfma_f32_16x16x32_bf16 v[12:15], v[176:179], v[206:209], v[12:15]
	v_mfma_f32_16x16x32_bf16 v[4:7], v[164:167], v[214:217], v[4:7]
	v_mfma_f32_16x16x32_bf16 v[0:3], v[176:179], v[214:217], v[0:3]
	s_barrier
	s_setprio 0
	s_add_i32 s54, s54, 2
	s_add_u32 s58, s58, 0x100
	s_addc_u32 s59, s59, 0
	s_add_u32 s39, s39, 0x100
	s_addc_u32 s47, s47, 0
	s_cmp_gt_u32 s54, 13
	s_cbranch_scc0 .LBB0_983

.LBB0_1004:
	s_ashr_i32 s37, s36, 31
	s_lshl_b64 s[16:17], s[36:37], 19
	s_add_u32 s40, s94, s16
	s_addc_u32 s41, s95, s17
	s_and_b64 s[16:17], s[42:43], exec
	s_cselect_b32 s16, s41, s51
	s_cselect_b32 s17, s40, s50
	s_ashr_i32 s39, s38, 31
	s_lshl_b64 s[18:19], s[38:39], 19
	s_add_u32 s48, s22, s18
	s_addc_u32 s49, s23, s19
	s_and_b64 s[18:19], s[42:43], exec
	s_cselect_b32 s37, s49, s61
	s_cselect_b32 s39, s48, s60
	s_add_u32 s58, s50, 0x40080
	s_addc_u32 s59, s51, 0
	s_add_u32 s46, s60, 0x100
	s_addc_u32 s47, s61, 0
	s_mov_b32 s54, -2
	s_add_u32 s18, s58, 0xfffc0080
	s_addc_u32 s19, s59, -1
	s_add_i32 s20, 0, 0x10000
	s_cmp_eq_u32 s54, 12
	s_cselect_b32 s61, s16, s19
	s_cselect_b32 s60, s17, s18
	s_cselect_b32 s51, s37, s47
	s_cselect_b32 s50, s39, s46
	s_add_i32 s21, 0, 0x14000
	v_add_u32_e32 v140, s20, v170
	v_add_u32_e32 v162, s21, v170
	ds_read_b128 v[128:131], v140
	ds_read_b128 v[132:135], v140 offset:1024
	ds_read_b128 v[136:139], v140 offset:2048
	ds_read_b128 v[140:143], v140 offset:3072
	ds_read_b128 v[144:147], v162
	ds_read_b128 v[148:151], v162 offset:1024
	ds_read_b128 v[172:175], v162 offset:2048
	ds_read_b128 v[176:179], v162 offset:3072
	v_lshl_add_u64 v[200:201], s[58:59], 0, v[164:165]
	s_add_i32 m0, s5, 0xc000
	ds_read_b128 v[180:183], v171
	ds_read_b128 v[184:187], v171 offset:1024
	ds_read_b128 v[188:191], v171 offset:2048
	ds_read_b128 v[192:195], v171 offset:3072
	ds_read_b128 v[196:199], v171 offset:4096
	ds_read_b128 v[206:209], v171 offset:5120
	ds_read_b128 v[210:213], v171 offset:6144
	ds_read_b128 v[214:217], v171 offset:7168
	global_load_lds_dwordx4 v[200:201], off
	v_lshl_add_u64 v[200:201], s[58:59], 0, v[166:167]
	s_add_i32 m0, s5, 0xe000
	s_nop 0
	global_load_lds_dwordx4 v[200:201], off
	s_waitcnt vmcnt(8)
	s_waitcnt lgkmcnt(0)
	s_setprio 1
	s_barrier
	v_mfma_f32_16x16x32_bf16 v[124:127], v[128:131], v[180:183], 0
	v_mfma_f32_16x16x32_bf16 v[120:123], v[136:139], v[180:183], 0
	v_mfma_f32_16x16x32_bf16 v[116:119], v[128:131], v[188:191], 0
	v_mfma_f32_16x16x32_bf16 v[112:115], v[136:139], v[188:191], 0
	v_mfma_f32_16x16x32_bf16 v[104:107], v[128:131], v[196:199], 0
	v_mfma_f32_16x16x32_bf16 v[96:99], v[136:139], v[196:199], 0
	v_mfma_f32_16x16x32_bf16 v[80:83], v[128:131], v[210:213], 0
	v_mfma_f32_16x16x32_bf16 v[72:75], v[136:139], v[210:213], 0
	v_mfma_f32_16x16x32_bf16 v[124:127], v[132:135], v[184:187], v[124:127]
	v_mfma_f32_16x16x32_bf16 v[120:123], v[140:143], v[184:187], v[120:123]
	v_mfma_f32_16x16x32_bf16 v[116:119], v[132:135], v[192:195], v[116:119]
	v_mfma_f32_16x16x32_bf16 v[112:115], v[140:143], v[192:195], v[112:115]
	v_mfma_f32_16x16x32_bf16 v[104:107], v[132:135], v[206:209], v[104:107]
	v_mfma_f32_16x16x32_bf16 v[96:99], v[140:143], v[206:209], v[96:99]
	v_mfma_f32_16x16x32_bf16 v[80:83], v[132:135], v[214:217], v[80:83]
	v_mfma_f32_16x16x32_bf16 v[72:75], v[140:143], v[214:217], v[72:75]
	v_mfma_f32_16x16x32_bf16 v[108:111], v[144:147], v[180:183], 0
	v_mfma_f32_16x16x32_bf16 v[100:103], v[172:175], v[180:183], 0
	v_mfma_f32_16x16x32_bf16 v[92:95], v[144:147], v[188:191], 0
	v_mfma_f32_16x16x32_bf16 v[88:91], v[172:175], v[188:191], 0
	v_mfma_f32_16x16x32_bf16 v[84:87], v[144:147], v[196:199], 0
	v_mfma_f32_16x16x32_bf16 v[76:79], v[172:175], v[196:199], 0
	v_mfma_f32_16x16x32_bf16 v[68:71], v[144:147], v[210:213], 0
	v_mfma_f32_16x16x32_bf16 v[64:67], v[172:175], v[210:213], 0
	v_mfma_f32_16x16x32_bf16 v[108:111], v[148:151], v[184:187], v[108:111]
	v_mfma_f32_16x16x32_bf16 v[100:103], v[176:179], v[184:187], v[100:103]
	v_mfma_f32_16x16x32_bf16 v[92:95], v[148:151], v[192:195], v[92:95]
	v_mfma_f32_16x16x32_bf16 v[88:91], v[176:179], v[192:195], v[88:91]
	v_mfma_f32_16x16x32_bf16 v[84:87], v[148:151], v[206:209], v[84:87]
	v_mfma_f32_16x16x32_bf16 v[76:79], v[176:179], v[206:209], v[76:79]
	v_mfma_f32_16x16x32_bf16 v[68:71], v[148:151], v[214:217], v[68:71]
	v_mfma_f32_16x16x32_bf16 v[64:67], v[176:179], v[214:217], v[64:67]
	s_barrier
	s_setprio 0
	s_add_i32 s18, s20, s4
	v_lshl_add_u64 v[200:201], s[50:51], 0, v[156:157]
	s_mov_b32 m0, s18
	ds_read_b128 v[180:183], v171 offset:16384
	ds_read_b128 v[184:187], v171 offset:17408
	ds_read_b128 v[188:191], v171 offset:18432
	ds_read_b128 v[192:195], v171 offset:19456
	ds_read_b128 v[196:199], v171 offset:20480
	ds_read_b128 v[206:209], v171 offset:21504
	ds_read_b128 v[210:213], v171 offset:22528
	ds_read_b128 v[214:217], v171 offset:23552
	global_load_lds_dwordx4 v[200:201], off
	s_add_i32 m0, s18, 0x2000
	s_add_u32 s18, s50, 0x40000
	v_lshl_add_u64 v[218:219], s[50:51], 0, v[152:153]
	s_addc_u32 s19, s51, 0
	s_add_i32 s20, s21, s4
	global_load_lds_dwordx4 v[218:219], off
	v_lshl_add_u64 v[220:221], s[18:19], 0, v[156:157]
	s_mov_b32 m0, s20
	v_lshl_add_u64 v[222:223], s[60:61], 0, v[154:155]
	global_load_lds_dwordx4 v[220:221], off
	v_lshl_add_u64 v[220:221], s[18:19], 0, v[152:153]
	s_add_i32 m0, s20, 0x2000
	s_nop 0
	global_load_lds_dwordx4 v[220:221], off
	v_lshl_add_u64 v[220:221], s[60:61], 0, v[158:159]
	s_mov_b32 m0, s5
	s_nop 0
	global_load_lds_dwordx4 v[220:221], off
	s_mov_b32 m0, s6
	s_nop 0
	global_load_lds_dwordx4 v[222:223], off
	s_waitcnt vmcnt(8)
	s_waitcnt lgkmcnt(0)
	s_setprio 1
	s_barrier
	v_mfma_f32_16x16x32_bf16 v[60:63], v[128:131], v[180:183], 0
	v_mfma_f32_16x16x32_bf16 v[56:59], v[136:139], v[180:183], 0
	v_mfma_f32_16x16x32_bf16 v[52:55], v[128:131], v[188:191], 0
	v_mfma_f32_16x16x32_bf16 v[48:51], v[136:139], v[188:191], 0
	v_mfma_f32_16x16x32_bf16 v[28:31], v[128:131], v[196:199], 0
	v_mfma_f32_16x16x32_bf16 v[24:27], v[136:139], v[196:199], 0
	v_mfma_f32_16x16x32_bf16 v[16:19], v[128:131], v[210:213], 0
	v_mfma_f32_16x16x32_bf16 v[8:11], v[136:139], v[210:213], 0
	v_mfma_f32_16x16x32_bf16 v[60:63], v[132:135], v[184:187], v[60:63]
	v_mfma_f32_16x16x32_bf16 v[56:59], v[140:143], v[184:187], v[56:59]
	v_mfma_f32_16x16x32_bf16 v[52:55], v[132:135], v[192:195], v[52:55]
	v_mfma_f32_16x16x32_bf16 v[48:51], v[140:143], v[192:195], v[48:51]
	v_mfma_f32_16x16x32_bf16 v[28:31], v[132:135], v[206:209], v[28:31]
	v_mfma_f32_16x16x32_bf16 v[24:27], v[140:143], v[206:209], v[24:27]
	v_mfma_f32_16x16x32_bf16 v[16:19], v[132:135], v[214:217], v[16:19]
	v_mfma_f32_16x16x32_bf16 v[8:11], v[140:143], v[214:217], v[8:11]
	v_mfma_f32_16x16x32_bf16 v[44:47], v[144:147], v[180:183], 0
	v_mfma_f32_16x16x32_bf16 v[40:43], v[172:175], v[180:183], 0
	v_mfma_f32_16x16x32_bf16 v[36:39], v[144:147], v[188:191], 0
	v_mfma_f32_16x16x32_bf16 v[32:35], v[172:175], v[188:191], 0
	v_mfma_f32_16x16x32_bf16 v[20:23], v[144:147], v[196:199], 0
	v_mfma_f32_16x16x32_bf16 v[12:15], v[172:175], v[196:199], 0
	v_mfma_f32_16x16x32_bf16 v[4:7], v[144:147], v[210:213], 0
	v_mfma_f32_16x16x32_bf16 v[0:3], v[172:175], v[210:213], 0
	v_mfma_f32_16x16x32_bf16 v[44:47], v[148:151], v[184:187], v[44:47]
	v_mfma_f32_16x16x32_bf16 v[40:43], v[176:179], v[184:187], v[40:43]
	v_mfma_f32_16x16x32_bf16 v[36:39], v[148:151], v[192:195], v[36:39]
	v_mfma_f32_16x16x32_bf16 v[32:35], v[176:179], v[192:195], v[32:35]
	v_mfma_f32_16x16x32_bf16 v[20:23], v[148:151], v[206:209], v[20:23]
	v_mfma_f32_16x16x32_bf16 v[12:15], v[176:179], v[206:209], v[12:15]
	v_mfma_f32_16x16x32_bf16 v[4:7], v[148:151], v[214:217], v[4:7]
	v_mfma_f32_16x16x32_bf16 v[0:3], v[176:179], v[214:217], v[0:3]
	s_barrier
	s_setprio 0
	s_add_i32 s20, 0, 0x18000
	s_add_i32 s21, 0, 0x1c000
	v_add_u32_e32 v140, s20, v170
	v_add_u32_e32 v162, s21, v170
	ds_read_b128 v[128:131], v140
	ds_read_b128 v[132:135], v140 offset:1024
	ds_read_b128 v[136:139], v140 offset:2048
	ds_read_b128 v[140:143], v140 offset:3072
	ds_read_b128 v[144:147], v162
	ds_read_b128 v[148:151], v162 offset:1024
	ds_read_b128 v[172:175], v162 offset:2048
	ds_read_b128 v[176:179], v162 offset:3072
	s_add_u32 s18, s60, 0x40000
	s_addc_u32 s19, s61, 0
	s_mov_b32 m0, s7
	v_lshl_add_u64 v[224:225], s[18:19], 0, v[158:159]
	ds_read_b128 v[180:183], v171 offset:32768
	ds_read_b128 v[184:187], v171 offset:33792
	ds_read_b128 v[188:191], v171 offset:34816
	ds_read_b128 v[192:195], v171 offset:35840
	ds_read_b128 v[196:199], v171 offset:36864
	ds_read_b128 v[206:209], v171 offset:37888
	ds_read_b128 v[210:213], v171 offset:38912
	ds_read_b128 v[214:217], v171 offset:39936
	global_load_lds_dwordx4 v[224:225], off
	v_lshl_add_u64 v[224:225], s[18:19], 0, v[154:155]
	s_mov_b32 m0, s8
	s_nop 0
	global_load_lds_dwordx4 v[224:225], off
	s_waitcnt vmcnt(8)
	s_waitcnt lgkmcnt(0)
	s_setprio 1
	s_barrier
	v_mfma_f32_16x16x32_bf16 v[124:127], v[128:131], v[180:183], v[124:127]
	v_mfma_f32_16x16x32_bf16 v[120:123], v[136:139], v[180:183], v[120:123]
	v_mfma_f32_16x16x32_bf16 v[116:119], v[128:131], v[188:191], v[116:119]
	v_mfma_f32_16x16x32_bf16 v[112:115], v[136:139], v[188:191], v[112:115]
	v_mfma_f32_16x16x32_bf16 v[104:107], v[128:131], v[196:199], v[104:107]
	v_mfma_f32_16x16x32_bf16 v[96:99], v[136:139], v[196:199], v[96:99]
	v_mfma_f32_16x16x32_bf16 v[80:83], v[128:131], v[210:213], v[80:83]
	v_mfma_f32_16x16x32_bf16 v[72:75], v[136:139], v[210:213], v[72:75]
	v_mfma_f32_16x16x32_bf16 v[124:127], v[132:135], v[184:187], v[124:127]
	v_mfma_f32_16x16x32_bf16 v[120:123], v[140:143], v[184:187], v[120:123]
	v_mfma_f32_16x16x32_bf16 v[116:119], v[132:135], v[192:195], v[116:119]
	v_mfma_f32_16x16x32_bf16 v[112:115], v[140:143], v[192:195], v[112:115]
	v_mfma_f32_16x16x32_bf16 v[104:107], v[132:135], v[206:209], v[104:107]
	v_mfma_f32_16x16x32_bf16 v[96:99], v[140:143], v[206:209], v[96:99]
	v_mfma_f32_16x16x32_bf16 v[80:83], v[132:135], v[214:217], v[80:83]
	v_mfma_f32_16x16x32_bf16 v[72:75], v[140:143], v[214:217], v[72:75]
	v_mfma_f32_16x16x32_bf16 v[108:111], v[144:147], v[180:183], v[108:111]
	v_mfma_f32_16x16x32_bf16 v[100:103], v[172:175], v[180:183], v[100:103]
	v_mfma_f32_16x16x32_bf16 v[92:95], v[144:147], v[188:191], v[92:95]
	v_mfma_f32_16x16x32_bf16 v[88:91], v[172:175], v[188:191], v[88:91]
	v_mfma_f32_16x16x32_bf16 v[84:87], v[144:147], v[196:199], v[84:87]
	v_mfma_f32_16x16x32_bf16 v[76:79], v[172:175], v[196:199], v[76:79]
	v_mfma_f32_16x16x32_bf16 v[68:71], v[144:147], v[210:213], v[68:71]
	v_mfma_f32_16x16x32_bf16 v[64:67], v[172:175], v[210:213], v[64:67]
	v_mfma_f32_16x16x32_bf16 v[108:111], v[148:151], v[184:187], v[108:111]
	v_mfma_f32_16x16x32_bf16 v[100:103], v[176:179], v[184:187], v[100:103]
	v_mfma_f32_16x16x32_bf16 v[92:95], v[148:151], v[192:195], v[92:95]
	v_mfma_f32_16x16x32_bf16 v[88:91], v[176:179], v[192:195], v[88:91]
	v_mfma_f32_16x16x32_bf16 v[84:87], v[148:151], v[206:209], v[84:87]
	v_mfma_f32_16x16x32_bf16 v[76:79], v[176:179], v[206:209], v[76:79]
	v_mfma_f32_16x16x32_bf16 v[68:71], v[148:151], v[214:217], v[68:71]
	v_mfma_f32_16x16x32_bf16 v[64:67], v[176:179], v[214:217], v[64:67]
	s_barrier
	s_setprio 0
	s_add_i32 s18, s20, s4
	v_lshl_add_u64 v[200:201], v[200:201], 0, s[76:77]
	s_mov_b32 m0, s18
	ds_read_b128 v[180:183], v171 offset:49152
	ds_read_b128 v[184:187], v171 offset:50176
	ds_read_b128 v[188:191], v171 offset:51200
	ds_read_b128 v[192:195], v171 offset:52224
	ds_read_b128 v[196:199], v171 offset:53248
	ds_read_b128 v[206:209], v171 offset:54272
	ds_read_b128 v[210:213], v171 offset:55296
	ds_read_b128 v[214:217], v171 offset:56320
	global_load_lds_dwordx4 v[200:201], off
	s_add_i32 m0, s18, 0x2000
	s_add_u32 s18, s50, 0x40080
	v_lshl_add_u64 v[200:201], v[218:219], 0, s[76:77]
	s_addc_u32 s19, s51, 0
	s_add_i32 s20, s21, s4
	global_load_lds_dwordx4 v[200:201], off
	v_lshl_add_u64 v[200:201], s[18:19], 0, v[156:157]
	s_mov_b32 m0, s20
	s_nop 0
	global_load_lds_dwordx4 v[200:201], off
	v_lshl_add_u64 v[200:201], s[18:19], 0, v[152:153]
	s_add_i32 m0, s20, 0x2000
	s_nop 0
	global_load_lds_dwordx4 v[200:201], off
	v_lshl_add_u64 v[200:201], v[220:221], 0, s[76:77]
	s_mov_b32 m0, s10
	s_nop 0
	global_load_lds_dwordx4 v[200:201], off
	v_lshl_add_u64 v[200:201], v[222:223], 0, s[76:77]
	s_mov_b32 m0, s11
	s_nop 0
	global_load_lds_dwordx4 v[200:201], off
	s_waitcnt vmcnt(8)
	s_waitcnt lgkmcnt(0)
	s_setprio 1
	s_barrier
	v_mfma_f32_16x16x32_bf16 v[60:63], v[128:131], v[180:183], v[60:63]
	v_mfma_f32_16x16x32_bf16 v[56:59], v[136:139], v[180:183], v[56:59]
	v_mfma_f32_16x16x32_bf16 v[52:55], v[128:131], v[188:191], v[52:55]
	v_mfma_f32_16x16x32_bf16 v[48:51], v[136:139], v[188:191], v[48:51]
	v_mfma_f32_16x16x32_bf16 v[28:31], v[128:131], v[196:199], v[28:31]
	v_mfma_f32_16x16x32_bf16 v[24:27], v[136:139], v[196:199], v[24:27]
	v_mfma_f32_16x16x32_bf16 v[16:19], v[128:131], v[210:213], v[16:19]
	v_mfma_f32_16x16x32_bf16 v[8:11], v[136:139], v[210:213], v[8:11]
	v_mfma_f32_16x16x32_bf16 v[60:63], v[132:135], v[184:187], v[60:63]
	v_mfma_f32_16x16x32_bf16 v[56:59], v[140:143], v[184:187], v[56:59]
	v_mfma_f32_16x16x32_bf16 v[52:55], v[132:135], v[192:195], v[52:55]
	v_mfma_f32_16x16x32_bf16 v[48:51], v[140:143], v[192:195], v[48:51]
	v_mfma_f32_16x16x32_bf16 v[28:31], v[132:135], v[206:209], v[28:31]
	v_mfma_f32_16x16x32_bf16 v[24:27], v[140:143], v[206:209], v[24:27]
	v_mfma_f32_16x16x32_bf16 v[16:19], v[132:135], v[214:217], v[16:19]
	v_mfma_f32_16x16x32_bf16 v[8:11], v[140:143], v[214:217], v[8:11]
	v_mfma_f32_16x16x32_bf16 v[44:47], v[144:147], v[180:183], v[44:47]
	v_mfma_f32_16x16x32_bf16 v[40:43], v[172:175], v[180:183], v[40:43]
	v_mfma_f32_16x16x32_bf16 v[36:39], v[144:147], v[188:191], v[36:39]
	v_mfma_f32_16x16x32_bf16 v[32:35], v[172:175], v[188:191], v[32:35]
	v_mfma_f32_16x16x32_bf16 v[20:23], v[144:147], v[196:199], v[20:23]
	v_mfma_f32_16x16x32_bf16 v[12:15], v[172:175], v[196:199], v[12:15]
	v_mfma_f32_16x16x32_bf16 v[4:7], v[144:147], v[210:213], v[4:7]
	v_mfma_f32_16x16x32_bf16 v[0:3], v[172:175], v[210:213], v[0:3]
	v_mfma_f32_16x16x32_bf16 v[44:47], v[148:151], v[184:187], v[44:47]
	v_mfma_f32_16x16x32_bf16 v[40:43], v[176:179], v[184:187], v[40:43]
	v_mfma_f32_16x16x32_bf16 v[36:39], v[148:151], v[192:195], v[36:39]
	v_mfma_f32_16x16x32_bf16 v[32:35], v[176:179], v[192:195], v[32:35]
	v_mfma_f32_16x16x32_bf16 v[20:23], v[148:151], v[206:209], v[20:23]
	v_mfma_f32_16x16x32_bf16 v[12:15], v[176:179], v[206:209], v[12:15]
	v_mfma_f32_16x16x32_bf16 v[4:7], v[148:151], v[214:217], v[4:7]
	v_mfma_f32_16x16x32_bf16 v[0:3], v[176:179], v[214:217], v[0:3]
	s_barrier
	s_setprio 0
	s_add_i32 s54, s54, 2
	s_add_u32 s58, s58, 0x100
	s_addc_u32 s59, s59, 0
	s_add_u32 s46, s46, 0x100
	s_addc_u32 s47, s47, 0
	s_cmp_gt_u32 s54, 13
	s_cbranch_scc0 .LBB0_1005
	s_branch .Lpeel_x_1005
.LBB0_1005:
	s_add_u32 s18, s58, 0xfffc0080
	s_addc_u32 s19, s59, -1
	s_add_i32 s20, 0, 0x10000
	s_cmp_eq_u32 s54, 12
	s_cselect_b32 s61, s16, s19
	s_cselect_b32 s60, s17, s18
	s_cselect_b32 s51, s37, s47
	s_cselect_b32 s50, s39, s46
	s_add_i32 s21, 0, 0x14000
	v_add_u32_e32 v140, s20, v170
	v_add_u32_e32 v162, s21, v170
	ds_read_b128 v[128:131], v140
	ds_read_b128 v[132:135], v140 offset:1024
	ds_read_b128 v[136:139], v140 offset:2048
	ds_read_b128 v[140:143], v140 offset:3072
	ds_read_b128 v[144:147], v162
	ds_read_b128 v[148:151], v162 offset:1024
	ds_read_b128 v[172:175], v162 offset:2048
	ds_read_b128 v[176:179], v162 offset:3072
	v_lshl_add_u64 v[200:201], s[58:59], 0, v[164:165]
	s_add_i32 m0, s5, 0xc000
	ds_read_b128 v[180:183], v171
	ds_read_b128 v[184:187], v171 offset:1024
	ds_read_b128 v[188:191], v171 offset:2048
	ds_read_b128 v[192:195], v171 offset:3072
	ds_read_b128 v[196:199], v171 offset:4096
	ds_read_b128 v[206:209], v171 offset:5120
	ds_read_b128 v[210:213], v171 offset:6144
	ds_read_b128 v[214:217], v171 offset:7168
	global_load_lds_dwordx4 v[200:201], off
	v_lshl_add_u64 v[200:201], s[58:59], 0, v[166:167]
	s_add_i32 m0, s5, 0xe000
	s_nop 0
	global_load_lds_dwordx4 v[200:201], off
	s_waitcnt vmcnt(8)
	s_waitcnt lgkmcnt(0)
	s_setprio 1
	s_barrier
	v_mfma_f32_16x16x32_bf16 v[124:127], v[128:131], v[180:183], v[124:127]
	v_mfma_f32_16x16x32_bf16 v[120:123], v[136:139], v[180:183], v[120:123]
	v_mfma_f32_16x16x32_bf16 v[116:119], v[128:131], v[188:191], v[116:119]
	v_mfma_f32_16x16x32_bf16 v[112:115], v[136:139], v[188:191], v[112:115]
	v_mfma_f32_16x16x32_bf16 v[104:107], v[128:131], v[196:199], v[104:107]
	v_mfma_f32_16x16x32_bf16 v[96:99], v[136:139], v[196:199], v[96:99]
	v_mfma_f32_16x16x32_bf16 v[80:83], v[128:131], v[210:213], v[80:83]
	v_mfma_f32_16x16x32_bf16 v[72:75], v[136:139], v[210:213], v[72:75]
	v_mfma_f32_16x16x32_bf16 v[124:127], v[132:135], v[184:187], v[124:127]
	v_mfma_f32_16x16x32_bf16 v[120:123], v[140:143], v[184:187], v[120:123]
	v_mfma_f32_16x16x32_bf16 v[116:119], v[132:135], v[192:195], v[116:119]
	v_mfma_f32_16x16x32_bf16 v[112:115], v[140:143], v[192:195], v[112:115]
	v_mfma_f32_16x16x32_bf16 v[104:107], v[132:135], v[206:209], v[104:107]
	v_mfma_f32_16x16x32_bf16 v[96:99], v[140:143], v[206:209], v[96:99]
	v_mfma_f32_16x16x32_bf16 v[80:83], v[132:135], v[214:217], v[80:83]
	v_mfma_f32_16x16x32_bf16 v[72:75], v[140:143], v[214:217], v[72:75]
	v_mfma_f32_16x16x32_bf16 v[108:111], v[144:147], v[180:183], v[108:111]
	v_mfma_f32_16x16x32_bf16 v[100:103], v[172:175], v[180:183], v[100:103]
	v_mfma_f32_16x16x32_bf16 v[92:95], v[144:147], v[188:191], v[92:95]
	v_mfma_f32_16x16x32_bf16 v[88:91], v[172:175], v[188:191], v[88:91]
	v_mfma_f32_16x16x32_bf16 v[84:87], v[144:147], v[196:199], v[84:87]
	v_mfma_f32_16x16x32_bf16 v[76:79], v[172:175], v[196:199], v[76:79]
	v_mfma_f32_16x16x32_bf16 v[68:71], v[144:147], v[210:213], v[68:71]
	v_mfma_f32_16x16x32_bf16 v[64:67], v[172:175], v[210:213], v[64:67]
	v_mfma_f32_16x16x32_bf16 v[108:111], v[148:151], v[184:187], v[108:111]
	v_mfma_f32_16x16x32_bf16 v[100:103], v[176:179], v[184:187], v[100:103]
	v_mfma_f32_16x16x32_bf16 v[92:95], v[148:151], v[192:195], v[92:95]
	v_mfma_f32_16x16x32_bf16 v[88:91], v[176:179], v[192:195], v[88:91]
	v_mfma_f32_16x16x32_bf16 v[84:87], v[148:151], v[206:209], v[84:87]
	v_mfma_f32_16x16x32_bf16 v[76:79], v[176:179], v[206:209], v[76:79]
	v_mfma_f32_16x16x32_bf16 v[68:71], v[148:151], v[214:217], v[68:71]
	v_mfma_f32_16x16x32_bf16 v[64:67], v[176:179], v[214:217], v[64:67]
	s_barrier
	s_setprio 0
	s_add_i32 s18, s20, s4
	v_lshl_add_u64 v[200:201], s[50:51], 0, v[156:157]
	s_mov_b32 m0, s18
	ds_read_b128 v[180:183], v171 offset:16384
	ds_read_b128 v[184:187], v171 offset:17408
	ds_read_b128 v[188:191], v171 offset:18432
	ds_read_b128 v[192:195], v171 offset:19456
	ds_read_b128 v[196:199], v171 offset:20480
	ds_read_b128 v[206:209], v171 offset:21504
	ds_read_b128 v[210:213], v171 offset:22528
	ds_read_b128 v[214:217], v171 offset:23552
	global_load_lds_dwordx4 v[200:201], off
	s_add_i32 m0, s18, 0x2000
	s_add_u32 s18, s50, 0x40000
	v_lshl_add_u64 v[218:219], s[50:51], 0, v[152:153]
	s_addc_u32 s19, s51, 0
	s_add_i32 s20, s21, s4
	global_load_lds_dwordx4 v[218:219], off
	v_lshl_add_u64 v[220:221], s[18:19], 0, v[156:157]
	s_mov_b32 m0, s20
	v_lshl_add_u64 v[222:223], s[60:61], 0, v[154:155]
	global_load_lds_dwordx4 v[220:221], off
	v_lshl_add_u64 v[220:221], s[18:19], 0, v[152:153]
	s_add_i32 m0, s20, 0x2000
	s_nop 0
	global_load_lds_dwordx4 v[220:221], off
	v_lshl_add_u64 v[220:221], s[60:61], 0, v[158:159]
	s_mov_b32 m0, s5
	s_nop 0
	global_load_lds_dwordx4 v[220:221], off
	s_mov_b32 m0, s6
	s_nop 0
	global_load_lds_dwordx4 v[222:223], off
	s_waitcnt vmcnt(8)
	s_waitcnt lgkmcnt(0)
	s_setprio 1
	s_barrier
	v_mfma_f32_16x16x32_bf16 v[60:63], v[128:131], v[180:183], v[60:63]
	v_mfma_f32_16x16x32_bf16 v[56:59], v[136:139], v[180:183], v[56:59]
	v_mfma_f32_16x16x32_bf16 v[52:55], v[128:131], v[188:191], v[52:55]
	v_mfma_f32_16x16x32_bf16 v[48:51], v[136:139], v[188:191], v[48:51]
	v_mfma_f32_16x16x32_bf16 v[28:31], v[128:131], v[196:199], v[28:31]
	v_mfma_f32_16x16x32_bf16 v[24:27], v[136:139], v[196:199], v[24:27]
	v_mfma_f32_16x16x32_bf16 v[16:19], v[128:131], v[210:213], v[16:19]
	v_mfma_f32_16x16x32_bf16 v[8:11], v[136:139], v[210:213], v[8:11]
	v_mfma_f32_16x16x32_bf16 v[60:63], v[132:135], v[184:187], v[60:63]
	v_mfma_f32_16x16x32_bf16 v[56:59], v[140:143], v[184:187], v[56:59]
	v_mfma_f32_16x16x32_bf16 v[52:55], v[132:135], v[192:195], v[52:55]
	v_mfma_f32_16x16x32_bf16 v[48:51], v[140:143], v[192:195], v[48:51]
	v_mfma_f32_16x16x32_bf16 v[28:31], v[132:135], v[206:209], v[28:31]
	v_mfma_f32_16x16x32_bf16 v[24:27], v[140:143], v[206:209], v[24:27]
	v_mfma_f32_16x16x32_bf16 v[16:19], v[132:135], v[214:217], v[16:19]
	v_mfma_f32_16x16x32_bf16 v[8:11], v[140:143], v[214:217], v[8:11]
	v_mfma_f32_16x16x32_bf16 v[44:47], v[144:147], v[180:183], v[44:47]
	v_mfma_f32_16x16x32_bf16 v[40:43], v[172:175], v[180:183], v[40:43]
	v_mfma_f32_16x16x32_bf16 v[36:39], v[144:147], v[188:191], v[36:39]
	v_mfma_f32_16x16x32_bf16 v[32:35], v[172:175], v[188:191], v[32:35]
	v_mfma_f32_16x16x32_bf16 v[20:23], v[144:147], v[196:199], v[20:23]
	v_mfma_f32_16x16x32_bf16 v[12:15], v[172:175], v[196:199], v[12:15]
	v_mfma_f32_16x16x32_bf16 v[4:7], v[144:147], v[210:213], v[4:7]
	v_mfma_f32_16x16x32_bf16 v[0:3], v[172:175], v[210:213], v[0:3]
	v_mfma_f32_16x16x32_bf16 v[44:47], v[148:151], v[184:187], v[44:47]
	v_mfma_f32_16x16x32_bf16 v[40:43], v[176:179], v[184:187], v[40:43]
	v_mfma_f32_16x16x32_bf16 v[36:39], v[148:151], v[192:195], v[36:39]
	v_mfma_f32_16x16x32_bf16 v[32:35], v[176:179], v[192:195], v[32:35]
	v_mfma_f32_16x16x32_bf16 v[20:23], v[148:151], v[206:209], v[20:23]
	v_mfma_f32_16x16x32_bf16 v[12:15], v[176:179], v[206:209], v[12:15]
	v_mfma_f32_16x16x32_bf16 v[4:7], v[148:151], v[214:217], v[4:7]
	v_mfma_f32_16x16x32_bf16 v[0:3], v[176:179], v[214:217], v[0:3]
	s_barrier
	s_setprio 0
	s_add_i32 s20, 0, 0x18000
	s_add_i32 s21, 0, 0x1c000
	v_add_u32_e32 v140, s20, v170
	v_add_u32_e32 v162, s21, v170
	ds_read_b128 v[128:131], v140
	ds_read_b128 v[132:135], v140 offset:1024
	ds_read_b128 v[136:139], v140 offset:2048
	ds_read_b128 v[140:143], v140 offset:3072
	ds_read_b128 v[144:147], v162
	ds_read_b128 v[148:151], v162 offset:1024
	ds_read_b128 v[172:175], v162 offset:2048
	ds_read_b128 v[176:179], v162 offset:3072
	s_add_u32 s18, s60, 0x40000
	s_addc_u32 s19, s61, 0
	s_mov_b32 m0, s7
	v_lshl_add_u64 v[224:225], s[18:19], 0, v[158:159]
	ds_read_b128 v[180:183], v171 offset:32768
	ds_read_b128 v[184:187], v171 offset:33792
	ds_read_b128 v[188:191], v171 offset:34816
	ds_read_b128 v[192:195], v171 offset:35840
	ds_read_b128 v[196:199], v171 offset:36864
	ds_read_b128 v[206:209], v171 offset:37888
	ds_read_b128 v[210:213], v171 offset:38912
	ds_read_b128 v[214:217], v171 offset:39936
	global_load_lds_dwordx4 v[224:225], off
	v_lshl_add_u64 v[224:225], s[18:19], 0, v[154:155]
	s_mov_b32 m0, s8
	s_nop 0
	global_load_lds_dwordx4 v[224:225], off
	s_waitcnt vmcnt(8)
	s_waitcnt lgkmcnt(0)
	s_setprio 1
	s_barrier
	v_mfma_f32_16x16x32_bf16 v[124:127], v[128:131], v[180:183], v[124:127]
	v_mfma_f32_16x16x32_bf16 v[120:123], v[136:139], v[180:183], v[120:123]
	v_mfma_f32_16x16x32_bf16 v[116:119], v[128:131], v[188:191], v[116:119]
	v_mfma_f32_16x16x32_bf16 v[112:115], v[136:139], v[188:191], v[112:115]
	v_mfma_f32_16x16x32_bf16 v[104:107], v[128:131], v[196:199], v[104:107]
	v_mfma_f32_16x16x32_bf16 v[96:99], v[136:139], v[196:199], v[96:99]
	v_mfma_f32_16x16x32_bf16 v[80:83], v[128:131], v[210:213], v[80:83]
	v_mfma_f32_16x16x32_bf16 v[72:75], v[136:139], v[210:213], v[72:75]
	v_mfma_f32_16x16x32_bf16 v[124:127], v[132:135], v[184:187], v[124:127]
	v_mfma_f32_16x16x32_bf16 v[120:123], v[140:143], v[184:187], v[120:123]
	v_mfma_f32_16x16x32_bf16 v[116:119], v[132:135], v[192:195], v[116:119]
	v_mfma_f32_16x16x32_bf16 v[112:115], v[140:143], v[192:195], v[112:115]
	v_mfma_f32_16x16x32_bf16 v[104:107], v[132:135], v[206:209], v[104:107]
	v_mfma_f32_16x16x32_bf16 v[96:99], v[140:143], v[206:209], v[96:99]
	v_mfma_f32_16x16x32_bf16 v[80:83], v[132:135], v[214:217], v[80:83]
	v_mfma_f32_16x16x32_bf16 v[72:75], v[140:143], v[214:217], v[72:75]
	v_mfma_f32_16x16x32_bf16 v[108:111], v[144:147], v[180:183], v[108:111]
	v_mfma_f32_16x16x32_bf16 v[100:103], v[172:175], v[180:183], v[100:103]
	v_mfma_f32_16x16x32_bf16 v[92:95], v[144:147], v[188:191], v[92:95]
	v_mfma_f32_16x16x32_bf16 v[88:91], v[172:175], v[188:191], v[88:91]
	v_mfma_f32_16x16x32_bf16 v[84:87], v[144:147], v[196:199], v[84:87]
	v_mfma_f32_16x16x32_bf16 v[76:79], v[172:175], v[196:199], v[76:79]
	v_mfma_f32_16x16x32_bf16 v[68:71], v[144:147], v[210:213], v[68:71]
	v_mfma_f32_16x16x32_bf16 v[64:67], v[172:175], v[210:213], v[64:67]
	v_mfma_f32_16x16x32_bf16 v[108:111], v[148:151], v[184:187], v[108:111]
	v_mfma_f32_16x16x32_bf16 v[100:103], v[176:179], v[184:187], v[100:103]
	v_mfma_f32_16x16x32_bf16 v[92:95], v[148:151], v[192:195], v[92:95]
	v_mfma_f32_16x16x32_bf16 v[88:91], v[176:179], v[192:195], v[88:91]
	v_mfma_f32_16x16x32_bf16 v[84:87], v[148:151], v[206:209], v[84:87]
	v_mfma_f32_16x16x32_bf16 v[76:79], v[176:179], v[206:209], v[76:79]
	v_mfma_f32_16x16x32_bf16 v[68:71], v[148:151], v[214:217], v[68:71]
	v_mfma_f32_16x16x32_bf16 v[64:67], v[176:179], v[214:217], v[64:67]
	s_barrier
	s_setprio 0
	s_add_i32 s18, s20, s4
	v_lshl_add_u64 v[200:201], v[200:201], 0, s[76:77]
	s_mov_b32 m0, s18
	ds_read_b128 v[180:183], v171 offset:49152
	ds_read_b128 v[184:187], v171 offset:50176
	ds_read_b128 v[188:191], v171 offset:51200
	ds_read_b128 v[192:195], v171 offset:52224
	ds_read_b128 v[196:199], v171 offset:53248
	ds_read_b128 v[206:209], v171 offset:54272
	ds_read_b128 v[210:213], v171 offset:55296
	ds_read_b128 v[214:217], v171 offset:56320
	global_load_lds_dwordx4 v[200:201], off
	s_add_i32 m0, s18, 0x2000
	s_add_u32 s18, s50, 0x40080
	v_lshl_add_u64 v[200:201], v[218:219], 0, s[76:77]
	s_addc_u32 s19, s51, 0
	s_add_i32 s20, s21, s4
	global_load_lds_dwordx4 v[200:201], off
	v_lshl_add_u64 v[200:201], s[18:19], 0, v[156:157]
	s_mov_b32 m0, s20
	s_nop 0
	global_load_lds_dwordx4 v[200:201], off
	v_lshl_add_u64 v[200:201], s[18:19], 0, v[152:153]
	s_add_i32 m0, s20, 0x2000
	s_nop 0
	global_load_lds_dwordx4 v[200:201], off
	v_lshl_add_u64 v[200:201], v[220:221], 0, s[76:77]
	s_mov_b32 m0, s10
	s_nop 0
	global_load_lds_dwordx4 v[200:201], off
	v_lshl_add_u64 v[200:201], v[222:223], 0, s[76:77]
	s_mov_b32 m0, s11
	s_nop 0
	global_load_lds_dwordx4 v[200:201], off
	s_waitcnt vmcnt(8)
	s_waitcnt lgkmcnt(0)
	s_setprio 1
	s_barrier
	v_mfma_f32_16x16x32_bf16 v[60:63], v[128:131], v[180:183], v[60:63]
	v_mfma_f32_16x16x32_bf16 v[56:59], v[136:139], v[180:183], v[56:59]
	v_mfma_f32_16x16x32_bf16 v[52:55], v[128:131], v[188:191], v[52:55]
	v_mfma_f32_16x16x32_bf16 v[48:51], v[136:139], v[188:191], v[48:51]
	v_mfma_f32_16x16x32_bf16 v[28:31], v[128:131], v[196:199], v[28:31]
	v_mfma_f32_16x16x32_bf16 v[24:27], v[136:139], v[196:199], v[24:27]
	v_mfma_f32_16x16x32_bf16 v[16:19], v[128:131], v[210:213], v[16:19]
	v_mfma_f32_16x16x32_bf16 v[8:11], v[136:139], v[210:213], v[8:11]
	v_mfma_f32_16x16x32_bf16 v[60:63], v[132:135], v[184:187], v[60:63]
	v_mfma_f32_16x16x32_bf16 v[56:59], v[140:143], v[184:187], v[56:59]
	v_mfma_f32_16x16x32_bf16 v[52:55], v[132:135], v[192:195], v[52:55]
	v_mfma_f32_16x16x32_bf16 v[48:51], v[140:143], v[192:195], v[48:51]
	v_mfma_f32_16x16x32_bf16 v[28:31], v[132:135], v[206:209], v[28:31]
	v_mfma_f32_16x16x32_bf16 v[24:27], v[140:143], v[206:209], v[24:27]
	v_mfma_f32_16x16x32_bf16 v[16:19], v[132:135], v[214:217], v[16:19]
	v_mfma_f32_16x16x32_bf16 v[8:11], v[140:143], v[214:217], v[8:11]
	v_mfma_f32_16x16x32_bf16 v[44:47], v[144:147], v[180:183], v[44:47]
	v_mfma_f32_16x16x32_bf16 v[40:43], v[172:175], v[180:183], v[40:43]
	v_mfma_f32_16x16x32_bf16 v[36:39], v[144:147], v[188:191], v[36:39]
	v_mfma_f32_16x16x32_bf16 v[32:35], v[172:175], v[188:191], v[32:35]
	v_mfma_f32_16x16x32_bf16 v[20:23], v[144:147], v[196:199], v[20:23]
	v_mfma_f32_16x16x32_bf16 v[12:15], v[172:175], v[196:199], v[12:15]
	v_mfma_f32_16x16x32_bf16 v[4:7], v[144:147], v[210:213], v[4:7]
	v_mfma_f32_16x16x32_bf16 v[0:3], v[172:175], v[210:213], v[0:3]
	v_mfma_f32_16x16x32_bf16 v[44:47], v[148:151], v[184:187], v[44:47]
	v_mfma_f32_16x16x32_bf16 v[40:43], v[176:179], v[184:187], v[40:43]
	v_mfma_f32_16x16x32_bf16 v[36:39], v[148:151], v[192:195], v[36:39]
	v_mfma_f32_16x16x32_bf16 v[32:35], v[176:179], v[192:195], v[32:35]
	v_mfma_f32_16x16x32_bf16 v[20:23], v[148:151], v[206:209], v[20:23]
	v_mfma_f32_16x16x32_bf16 v[12:15], v[176:179], v[206:209], v[12:15]
	v_mfma_f32_16x16x32_bf16 v[4:7], v[148:151], v[214:217], v[4:7]
	v_mfma_f32_16x16x32_bf16 v[0:3], v[176:179], v[214:217], v[0:3]
	s_barrier
	s_setprio 0
	s_add_i32 s54, s54, 2
	s_add_u32 s58, s58, 0x100
	s_addc_u32 s59, s59, 0
	s_add_u32 s46, s46, 0x100
	s_addc_u32 s47, s47, 0
	s_cmp_gt_u32 s54, 13
	s_cbranch_scc0 .LBB0_1005

.LBB0_1137:
	s_ashr_i32 s37, s36, 31
	s_lshl_b64 s[18:19], s[36:37], 19
	s_add_u32 s40, s96, s18
	s_addc_u32 s41, s97, s19
	s_and_b64 s[18:19], s[42:43], exec
	s_cselect_b32 s17, s41, s59
	s_cselect_b32 s37, s40, s58
	s_ashr_i32 s39, s38, 31
	s_lshl_b64 s[18:19], s[38:39], 19
	s_add_u32 s48, s5, s18
	s_addc_u32 s49, s6, s19
	s_and_b64 s[18:19], s[42:43], exec
	s_cselect_b32 s39, s49, s51
	s_cselect_b32 s46, s48, s50
	s_add_u32 s58, s58, 0x40080
	s_addc_u32 s59, s59, 0
	s_add_u32 s47, s50, 0x100
	s_addc_u32 s62, s51, 0
	s_mov_b32 s63, -2
	s_add_u32 s18, s58, 0xfffc0080
	s_addc_u32 s19, s59, -1
	s_add_i32 s20, 0, 0x10000
	s_cmp_eq_u32 s63, 12
	s_cselect_b32 s61, s17, s19
	s_cselect_b32 s60, s37, s18
	v_add_u32_e32 v140, s20, v143
	s_cselect_b32 s51, s39, s62
	s_cselect_b32 s50, s46, s47
	s_add_i32 s21, 0, 0x14000
	ds_read_b128 v[146:149], v140
	ds_read_b128 v[150:153], v140 offset:1024
	ds_read_b128 v[154:157], v140 offset:2048
	ds_read_b128 v[164:167], v140 offset:3072
	v_add_u32_e32 v140, s21, v143
	ds_read_b128 v[168:171], v140
	ds_read_b128 v[172:175], v140 offset:1024
	ds_read_b128 v[176:179], v140 offset:2048
	ds_read_b128 v[180:183], v140 offset:3072
	v_lshl_add_u64 v[140:141], s[58:59], 0, v[136:137]
	s_add_i32 m0, s8, 0xc000
	ds_read_b128 v[184:187], v144
	ds_read_b128 v[188:191], v144 offset:1024
	ds_read_b128 v[192:195], v144 offset:2048
	ds_read_b128 v[196:199], v144 offset:3072
	ds_read_b128 v[206:209], v144 offset:4096
	ds_read_b128 v[210:213], v144 offset:5120
	ds_read_b128 v[214:217], v144 offset:6144
	ds_read_b128 v[218:221], v144 offset:7168
	global_load_lds_dwordx4 v[140:141], off
	v_lshl_add_u64 v[140:141], s[58:59], 0, v[138:139]
	s_add_i32 m0, s8, 0xe000
	s_nop 0
	global_load_lds_dwordx4 v[140:141], off
	s_waitcnt vmcnt(8)
	s_waitcnt lgkmcnt(0)
	s_setprio 1
	s_barrier
	v_mfma_f32_16x16x32_bf16 v[124:127], v[146:149], v[184:187], 0
	v_mfma_f32_16x16x32_bf16 v[120:123], v[154:157], v[184:187], 0
	v_mfma_f32_16x16x32_bf16 v[108:111], v[146:149], v[192:195], 0
	v_mfma_f32_16x16x32_bf16 v[104:107], v[154:157], v[192:195], 0
	v_mfma_f32_16x16x32_bf16 v[92:95], v[146:149], v[206:209], 0
	v_mfma_f32_16x16x32_bf16 v[88:91], v[154:157], v[206:209], 0
	v_mfma_f32_16x16x32_bf16 v[76:79], v[146:149], v[214:217], 0
	v_mfma_f32_16x16x32_bf16 v[72:75], v[154:157], v[214:217], 0
	v_mfma_f32_16x16x32_bf16 v[124:127], v[150:153], v[188:191], v[124:127]
	v_mfma_f32_16x16x32_bf16 v[120:123], v[164:167], v[188:191], v[120:123]
	v_mfma_f32_16x16x32_bf16 v[108:111], v[150:153], v[196:199], v[108:111]
	v_mfma_f32_16x16x32_bf16 v[104:107], v[164:167], v[196:199], v[104:107]
	v_mfma_f32_16x16x32_bf16 v[92:95], v[150:153], v[210:213], v[92:95]
	v_mfma_f32_16x16x32_bf16 v[88:91], v[164:167], v[210:213], v[88:91]
	v_mfma_f32_16x16x32_bf16 v[76:79], v[150:153], v[218:221], v[76:79]
	v_mfma_f32_16x16x32_bf16 v[72:75], v[164:167], v[218:221], v[72:75]
	v_mfma_f32_16x16x32_bf16 v[116:119], v[168:171], v[184:187], 0
	v_mfma_f32_16x16x32_bf16 v[112:115], v[176:179], v[184:187], 0
	v_mfma_f32_16x16x32_bf16 v[100:103], v[168:171], v[192:195], 0
	v_mfma_f32_16x16x32_bf16 v[96:99], v[176:179], v[192:195], 0
	v_mfma_f32_16x16x32_bf16 v[84:87], v[168:171], v[206:209], 0
	v_mfma_f32_16x16x32_bf16 v[80:83], v[176:179], v[206:209], 0
	v_mfma_f32_16x16x32_bf16 v[68:71], v[168:171], v[214:217], 0
	v_mfma_f32_16x16x32_bf16 v[64:67], v[176:179], v[214:217], 0
	v_mfma_f32_16x16x32_bf16 v[116:119], v[172:175], v[188:191], v[116:119]
	v_mfma_f32_16x16x32_bf16 v[112:115], v[180:183], v[188:191], v[112:115]
	v_mfma_f32_16x16x32_bf16 v[100:103], v[172:175], v[196:199], v[100:103]
	v_mfma_f32_16x16x32_bf16 v[96:99], v[180:183], v[196:199], v[96:99]
	v_mfma_f32_16x16x32_bf16 v[84:87], v[172:175], v[210:213], v[84:87]
	v_mfma_f32_16x16x32_bf16 v[80:83], v[180:183], v[210:213], v[80:83]
	v_mfma_f32_16x16x32_bf16 v[68:71], v[172:175], v[218:221], v[68:71]
	v_mfma_f32_16x16x32_bf16 v[64:67], v[180:183], v[218:221], v[64:67]
	s_barrier
	s_setprio 0
	s_add_i32 s18, s20, s7
	v_lshl_add_u64 v[140:141], s[50:51], 0, v[132:133]
	s_mov_b32 m0, s18
	ds_read_b128 v[184:187], v144 offset:16384
	ds_read_b128 v[188:191], v144 offset:17408
	ds_read_b128 v[192:195], v144 offset:18432
	ds_read_b128 v[196:199], v144 offset:19456
	ds_read_b128 v[206:209], v144 offset:20480
	ds_read_b128 v[210:213], v144 offset:21504
	ds_read_b128 v[214:217], v144 offset:22528
	ds_read_b128 v[218:221], v144 offset:23552
	global_load_lds_dwordx4 v[140:141], off
	s_add_i32 m0, s18, 0x2000
	s_add_u32 s18, s50, 0x40000
	v_lshl_add_u64 v[158:159], s[50:51], 0, v[128:129]
	s_addc_u32 s19, s51, 0
	s_add_i32 s20, s21, s7
	global_load_lds_dwordx4 v[158:159], off
	v_lshl_add_u64 v[200:201], s[18:19], 0, v[132:133]
	s_mov_b32 m0, s20
	v_lshl_add_u64 v[222:223], s[60:61], 0, v[130:131]
	global_load_lds_dwordx4 v[200:201], off
	v_lshl_add_u64 v[200:201], s[18:19], 0, v[128:129]
	s_add_i32 m0, s20, 0x2000
	s_nop 0
	global_load_lds_dwordx4 v[200:201], off
	v_lshl_add_u64 v[200:201], s[60:61], 0, v[134:135]
	s_mov_b32 m0, s8
	s_nop 0
	global_load_lds_dwordx4 v[200:201], off
	s_mov_b32 m0, s9
	s_nop 0
	global_load_lds_dwordx4 v[222:223], off
	s_waitcnt vmcnt(8)
	s_waitcnt lgkmcnt(0)
	s_setprio 1
	s_barrier
	v_mfma_f32_16x16x32_bf16 v[60:63], v[146:149], v[184:187], 0
	v_mfma_f32_16x16x32_bf16 v[56:59], v[154:157], v[184:187], 0
	v_mfma_f32_16x16x32_bf16 v[44:47], v[146:149], v[192:195], 0
	v_mfma_f32_16x16x32_bf16 v[40:43], v[154:157], v[192:195], 0
	v_mfma_f32_16x16x32_bf16 v[28:31], v[146:149], v[206:209], 0
	v_mfma_f32_16x16x32_bf16 v[24:27], v[154:157], v[206:209], 0
	v_mfma_f32_16x16x32_bf16 v[12:15], v[146:149], v[214:217], 0
	v_mfma_f32_16x16x32_bf16 v[8:11], v[154:157], v[214:217], 0
	v_mfma_f32_16x16x32_bf16 v[60:63], v[150:153], v[188:191], v[60:63]
	v_mfma_f32_16x16x32_bf16 v[56:59], v[164:167], v[188:191], v[56:59]
	v_mfma_f32_16x16x32_bf16 v[44:47], v[150:153], v[196:199], v[44:47]
	v_mfma_f32_16x16x32_bf16 v[40:43], v[164:167], v[196:199], v[40:43]
	v_mfma_f32_16x16x32_bf16 v[28:31], v[150:153], v[210:213], v[28:31]
	v_mfma_f32_16x16x32_bf16 v[24:27], v[164:167], v[210:213], v[24:27]
	v_mfma_f32_16x16x32_bf16 v[12:15], v[150:153], v[218:221], v[12:15]
	v_mfma_f32_16x16x32_bf16 v[8:11], v[164:167], v[218:221], v[8:11]
	v_mfma_f32_16x16x32_bf16 v[52:55], v[168:171], v[184:187], 0
	v_mfma_f32_16x16x32_bf16 v[48:51], v[176:179], v[184:187], 0
	v_mfma_f32_16x16x32_bf16 v[36:39], v[168:171], v[192:195], 0
	v_mfma_f32_16x16x32_bf16 v[32:35], v[176:179], v[192:195], 0
	v_mfma_f32_16x16x32_bf16 v[20:23], v[168:171], v[206:209], 0
	v_mfma_f32_16x16x32_bf16 v[16:19], v[176:179], v[206:209], 0
	v_mfma_f32_16x16x32_bf16 v[4:7], v[168:171], v[214:217], 0
	v_mfma_f32_16x16x32_bf16 v[0:3], v[176:179], v[214:217], 0
	v_mfma_f32_16x16x32_bf16 v[52:55], v[172:175], v[188:191], v[52:55]
	v_mfma_f32_16x16x32_bf16 v[48:51], v[180:183], v[188:191], v[48:51]
	v_mfma_f32_16x16x32_bf16 v[36:39], v[172:175], v[196:199], v[36:39]
	v_mfma_f32_16x16x32_bf16 v[32:35], v[180:183], v[196:199], v[32:35]
	v_mfma_f32_16x16x32_bf16 v[20:23], v[172:175], v[210:213], v[20:23]
	v_mfma_f32_16x16x32_bf16 v[16:19], v[180:183], v[210:213], v[16:19]
	v_mfma_f32_16x16x32_bf16 v[4:7], v[172:175], v[218:221], v[4:7]
	v_mfma_f32_16x16x32_bf16 v[0:3], v[180:183], v[218:221], v[0:3]
	s_barrier
	s_setprio 0
	s_add_i32 s20, 0, 0x18000
	v_add_u32_e32 v145, s20, v143
	s_add_i32 s21, 0, 0x1c000
	ds_read_b128 v[146:149], v145
	ds_read_b128 v[150:153], v145 offset:1024
	ds_read_b128 v[154:157], v145 offset:2048
	ds_read_b128 v[164:167], v145 offset:3072
	v_add_u32_e32 v145, s21, v143
	ds_read_b128 v[168:171], v145
	ds_read_b128 v[172:175], v145 offset:1024
	ds_read_b128 v[176:179], v145 offset:2048
	ds_read_b128 v[180:183], v145 offset:3072
	s_add_u32 s18, s60, 0x40000
	s_addc_u32 s19, s61, 0
	s_mov_b32 m0, s10
	v_lshl_add_u64 v[224:225], s[18:19], 0, v[134:135]
	ds_read_b128 v[184:187], v144 offset:32768
	ds_read_b128 v[188:191], v144 offset:33792
	ds_read_b128 v[192:195], v144 offset:34816
	ds_read_b128 v[196:199], v144 offset:35840
	ds_read_b128 v[206:209], v144 offset:36864
	ds_read_b128 v[210:213], v144 offset:37888
	ds_read_b128 v[214:217], v144 offset:38912
	ds_read_b128 v[218:221], v144 offset:39936
	global_load_lds_dwordx4 v[224:225], off
	v_lshl_add_u64 v[224:225], s[18:19], 0, v[130:131]
	s_mov_b32 m0, s11
	s_nop 0
	global_load_lds_dwordx4 v[224:225], off
	s_waitcnt vmcnt(8)
	s_waitcnt lgkmcnt(0)
	s_setprio 1
	s_barrier
	v_mfma_f32_16x16x32_bf16 v[124:127], v[146:149], v[184:187], v[124:127]
	v_mfma_f32_16x16x32_bf16 v[120:123], v[154:157], v[184:187], v[120:123]
	v_mfma_f32_16x16x32_bf16 v[108:111], v[146:149], v[192:195], v[108:111]
	v_mfma_f32_16x16x32_bf16 v[104:107], v[154:157], v[192:195], v[104:107]
	v_mfma_f32_16x16x32_bf16 v[92:95], v[146:149], v[206:209], v[92:95]
	v_mfma_f32_16x16x32_bf16 v[88:91], v[154:157], v[206:209], v[88:91]
	v_mfma_f32_16x16x32_bf16 v[76:79], v[146:149], v[214:217], v[76:79]
	v_mfma_f32_16x16x32_bf16 v[72:75], v[154:157], v[214:217], v[72:75]
	v_mfma_f32_16x16x32_bf16 v[124:127], v[150:153], v[188:191], v[124:127]
	v_mfma_f32_16x16x32_bf16 v[120:123], v[164:167], v[188:191], v[120:123]
	v_mfma_f32_16x16x32_bf16 v[108:111], v[150:153], v[196:199], v[108:111]
	v_mfma_f32_16x16x32_bf16 v[104:107], v[164:167], v[196:199], v[104:107]
	v_mfma_f32_16x16x32_bf16 v[92:95], v[150:153], v[210:213], v[92:95]
	v_mfma_f32_16x16x32_bf16 v[88:91], v[164:167], v[210:213], v[88:91]
	v_mfma_f32_16x16x32_bf16 v[76:79], v[150:153], v[218:221], v[76:79]
	v_mfma_f32_16x16x32_bf16 v[72:75], v[164:167], v[218:221], v[72:75]
	v_mfma_f32_16x16x32_bf16 v[116:119], v[168:171], v[184:187], v[116:119]
	v_mfma_f32_16x16x32_bf16 v[112:115], v[176:179], v[184:187], v[112:115]
	v_mfma_f32_16x16x32_bf16 v[100:103], v[168:171], v[192:195], v[100:103]
	v_mfma_f32_16x16x32_bf16 v[96:99], v[176:179], v[192:195], v[96:99]
	v_mfma_f32_16x16x32_bf16 v[84:87], v[168:171], v[206:209], v[84:87]
	v_mfma_f32_16x16x32_bf16 v[80:83], v[176:179], v[206:209], v[80:83]
	v_mfma_f32_16x16x32_bf16 v[68:71], v[168:171], v[214:217], v[68:71]
	v_mfma_f32_16x16x32_bf16 v[64:67], v[176:179], v[214:217], v[64:67]
	v_mfma_f32_16x16x32_bf16 v[116:119], v[172:175], v[188:191], v[116:119]
	v_mfma_f32_16x16x32_bf16 v[112:115], v[180:183], v[188:191], v[112:115]
	v_mfma_f32_16x16x32_bf16 v[100:103], v[172:175], v[196:199], v[100:103]
	v_mfma_f32_16x16x32_bf16 v[96:99], v[180:183], v[196:199], v[96:99]
	v_mfma_f32_16x16x32_bf16 v[84:87], v[172:175], v[210:213], v[84:87]
	v_mfma_f32_16x16x32_bf16 v[80:83], v[180:183], v[210:213], v[80:83]
	v_mfma_f32_16x16x32_bf16 v[68:71], v[172:175], v[218:221], v[68:71]
	v_mfma_f32_16x16x32_bf16 v[64:67], v[180:183], v[218:221], v[64:67]
	s_barrier
	s_setprio 0
	s_add_i32 s18, s20, s7
	v_lshl_add_u64 v[140:141], v[140:141], 0, s[76:77]
	s_mov_b32 m0, s18
	ds_read_b128 v[184:187], v144 offset:49152
	ds_read_b128 v[188:191], v144 offset:50176
	ds_read_b128 v[192:195], v144 offset:51200
	ds_read_b128 v[196:199], v144 offset:52224
	ds_read_b128 v[206:209], v144 offset:53248
	ds_read_b128 v[210:213], v144 offset:54272
	ds_read_b128 v[214:217], v144 offset:55296
	ds_read_b128 v[218:221], v144 offset:56320
	global_load_lds_dwordx4 v[140:141], off
	s_add_i32 m0, s18, 0x2000
	s_add_u32 s18, s50, 0x40080
	v_lshl_add_u64 v[140:141], v[158:159], 0, s[76:77]
	s_addc_u32 s19, s51, 0
	s_add_i32 s20, s21, s7
	global_load_lds_dwordx4 v[140:141], off
	v_lshl_add_u64 v[140:141], s[18:19], 0, v[132:133]
	s_mov_b32 m0, s20
	s_nop 0
	global_load_lds_dwordx4 v[140:141], off
	v_lshl_add_u64 v[140:141], s[18:19], 0, v[128:129]
	s_add_i32 m0, s20, 0x2000
	s_nop 0
	global_load_lds_dwordx4 v[140:141], off
	v_lshl_add_u64 v[140:141], v[200:201], 0, s[76:77]
	s_mov_b32 m0, s12
	s_nop 0
	global_load_lds_dwordx4 v[140:141], off
	v_lshl_add_u64 v[140:141], v[222:223], 0, s[76:77]
	s_mov_b32 m0, s13
	s_nop 0
	global_load_lds_dwordx4 v[140:141], off
	s_waitcnt vmcnt(8)
	s_waitcnt lgkmcnt(0)
	s_setprio 1
	s_barrier
	v_mfma_f32_16x16x32_bf16 v[60:63], v[146:149], v[184:187], v[60:63]
	v_mfma_f32_16x16x32_bf16 v[56:59], v[154:157], v[184:187], v[56:59]
	v_mfma_f32_16x16x32_bf16 v[44:47], v[146:149], v[192:195], v[44:47]
	v_mfma_f32_16x16x32_bf16 v[40:43], v[154:157], v[192:195], v[40:43]
	v_mfma_f32_16x16x32_bf16 v[28:31], v[146:149], v[206:209], v[28:31]
	v_mfma_f32_16x16x32_bf16 v[24:27], v[154:157], v[206:209], v[24:27]
	v_mfma_f32_16x16x32_bf16 v[12:15], v[146:149], v[214:217], v[12:15]
	v_mfma_f32_16x16x32_bf16 v[8:11], v[154:157], v[214:217], v[8:11]
	v_mfma_f32_16x16x32_bf16 v[60:63], v[150:153], v[188:191], v[60:63]
	v_mfma_f32_16x16x32_bf16 v[56:59], v[164:167], v[188:191], v[56:59]
	v_mfma_f32_16x16x32_bf16 v[44:47], v[150:153], v[196:199], v[44:47]
	v_mfma_f32_16x16x32_bf16 v[40:43], v[164:167], v[196:199], v[40:43]
	v_mfma_f32_16x16x32_bf16 v[28:31], v[150:153], v[210:213], v[28:31]
	v_mfma_f32_16x16x32_bf16 v[24:27], v[164:167], v[210:213], v[24:27]
	v_mfma_f32_16x16x32_bf16 v[12:15], v[150:153], v[218:221], v[12:15]
	v_mfma_f32_16x16x32_bf16 v[8:11], v[164:167], v[218:221], v[8:11]
	v_mfma_f32_16x16x32_bf16 v[52:55], v[168:171], v[184:187], v[52:55]
	v_mfma_f32_16x16x32_bf16 v[48:51], v[176:179], v[184:187], v[48:51]
	v_mfma_f32_16x16x32_bf16 v[36:39], v[168:171], v[192:195], v[36:39]
	v_mfma_f32_16x16x32_bf16 v[32:35], v[176:179], v[192:195], v[32:35]
	v_mfma_f32_16x16x32_bf16 v[20:23], v[168:171], v[206:209], v[20:23]
	v_mfma_f32_16x16x32_bf16 v[16:19], v[176:179], v[206:209], v[16:19]
	v_mfma_f32_16x16x32_bf16 v[4:7], v[168:171], v[214:217], v[4:7]
	v_mfma_f32_16x16x32_bf16 v[0:3], v[176:179], v[214:217], v[0:3]
	v_mfma_f32_16x16x32_bf16 v[52:55], v[172:175], v[188:191], v[52:55]
	v_mfma_f32_16x16x32_bf16 v[48:51], v[180:183], v[188:191], v[48:51]
	v_mfma_f32_16x16x32_bf16 v[36:39], v[172:175], v[196:199], v[36:39]
	v_mfma_f32_16x16x32_bf16 v[32:35], v[180:183], v[196:199], v[32:35]
	v_mfma_f32_16x16x32_bf16 v[20:23], v[172:175], v[210:213], v[20:23]
	v_mfma_f32_16x16x32_bf16 v[16:19], v[180:183], v[210:213], v[16:19]
	v_mfma_f32_16x16x32_bf16 v[4:7], v[172:175], v[218:221], v[4:7]
	v_mfma_f32_16x16x32_bf16 v[0:3], v[180:183], v[218:221], v[0:3]
	s_barrier
	s_setprio 0
	s_add_i32 s63, s63, 2
	s_add_u32 s58, s58, 0x100
	s_addc_u32 s59, s59, 0
	s_add_u32 s47, s47, 0x100
	s_addc_u32 s62, s62, 0
	s_cmp_gt_u32 s63, 13
	s_cbranch_scc0 .LBB0_1138
	s_branch .Lpeel_x_1138
.LBB0_1138:
	s_add_u32 s18, s58, 0xfffc0080
	s_addc_u32 s19, s59, -1
	s_add_i32 s20, 0, 0x10000
	s_cmp_eq_u32 s63, 12
	s_cselect_b32 s61, s17, s19
	s_cselect_b32 s60, s37, s18
	v_add_u32_e32 v140, s20, v143
	s_cselect_b32 s51, s39, s62
	s_cselect_b32 s50, s46, s47
	s_add_i32 s21, 0, 0x14000
	ds_read_b128 v[146:149], v140
	ds_read_b128 v[150:153], v140 offset:1024
	ds_read_b128 v[154:157], v140 offset:2048
	ds_read_b128 v[164:167], v140 offset:3072
	v_add_u32_e32 v140, s21, v143
	ds_read_b128 v[168:171], v140
	ds_read_b128 v[172:175], v140 offset:1024
	ds_read_b128 v[176:179], v140 offset:2048
	ds_read_b128 v[180:183], v140 offset:3072
	v_lshl_add_u64 v[140:141], s[58:59], 0, v[136:137]
	s_add_i32 m0, s8, 0xc000
	ds_read_b128 v[184:187], v144
	ds_read_b128 v[188:191], v144 offset:1024
	ds_read_b128 v[192:195], v144 offset:2048
	ds_read_b128 v[196:199], v144 offset:3072
	ds_read_b128 v[206:209], v144 offset:4096
	ds_read_b128 v[210:213], v144 offset:5120
	ds_read_b128 v[214:217], v144 offset:6144
	ds_read_b128 v[218:221], v144 offset:7168
	global_load_lds_dwordx4 v[140:141], off
	v_lshl_add_u64 v[140:141], s[58:59], 0, v[138:139]
	s_add_i32 m0, s8, 0xe000
	s_nop 0
	global_load_lds_dwordx4 v[140:141], off
	s_waitcnt vmcnt(8)
	s_waitcnt lgkmcnt(0)
	s_setprio 1
	s_barrier
	v_mfma_f32_16x16x32_bf16 v[124:127], v[146:149], v[184:187], v[124:127]
	v_mfma_f32_16x16x32_bf16 v[120:123], v[154:157], v[184:187], v[120:123]
	v_mfma_f32_16x16x32_bf16 v[108:111], v[146:149], v[192:195], v[108:111]
	v_mfma_f32_16x16x32_bf16 v[104:107], v[154:157], v[192:195], v[104:107]
	v_mfma_f32_16x16x32_bf16 v[92:95], v[146:149], v[206:209], v[92:95]
	v_mfma_f32_16x16x32_bf16 v[88:91], v[154:157], v[206:209], v[88:91]
	v_mfma_f32_16x16x32_bf16 v[76:79], v[146:149], v[214:217], v[76:79]
	v_mfma_f32_16x16x32_bf16 v[72:75], v[154:157], v[214:217], v[72:75]
	v_mfma_f32_16x16x32_bf16 v[124:127], v[150:153], v[188:191], v[124:127]
	v_mfma_f32_16x16x32_bf16 v[120:123], v[164:167], v[188:191], v[120:123]
	v_mfma_f32_16x16x32_bf16 v[108:111], v[150:153], v[196:199], v[108:111]
	v_mfma_f32_16x16x32_bf16 v[104:107], v[164:167], v[196:199], v[104:107]
	v_mfma_f32_16x16x32_bf16 v[92:95], v[150:153], v[210:213], v[92:95]
	v_mfma_f32_16x16x32_bf16 v[88:91], v[164:167], v[210:213], v[88:91]
	v_mfma_f32_16x16x32_bf16 v[76:79], v[150:153], v[218:221], v[76:79]
	v_mfma_f32_16x16x32_bf16 v[72:75], v[164:167], v[218:221], v[72:75]
	v_mfma_f32_16x16x32_bf16 v[116:119], v[168:171], v[184:187], v[116:119]
	v_mfma_f32_16x16x32_bf16 v[112:115], v[176:179], v[184:187], v[112:115]
	v_mfma_f32_16x16x32_bf16 v[100:103], v[168:171], v[192:195], v[100:103]
	v_mfma_f32_16x16x32_bf16 v[96:99], v[176:179], v[192:195], v[96:99]
	v_mfma_f32_16x16x32_bf16 v[84:87], v[168:171], v[206:209], v[84:87]
	v_mfma_f32_16x16x32_bf16 v[80:83], v[176:179], v[206:209], v[80:83]
	v_mfma_f32_16x16x32_bf16 v[68:71], v[168:171], v[214:217], v[68:71]
	v_mfma_f32_16x16x32_bf16 v[64:67], v[176:179], v[214:217], v[64:67]
	v_mfma_f32_16x16x32_bf16 v[116:119], v[172:175], v[188:191], v[116:119]
	v_mfma_f32_16x16x32_bf16 v[112:115], v[180:183], v[188:191], v[112:115]
	v_mfma_f32_16x16x32_bf16 v[100:103], v[172:175], v[196:199], v[100:103]
	v_mfma_f32_16x16x32_bf16 v[96:99], v[180:183], v[196:199], v[96:99]
	v_mfma_f32_16x16x32_bf16 v[84:87], v[172:175], v[210:213], v[84:87]
	v_mfma_f32_16x16x32_bf16 v[80:83], v[180:183], v[210:213], v[80:83]
	v_mfma_f32_16x16x32_bf16 v[68:71], v[172:175], v[218:221], v[68:71]
	v_mfma_f32_16x16x32_bf16 v[64:67], v[180:183], v[218:221], v[64:67]
	s_barrier
	s_setprio 0
	s_add_i32 s18, s20, s7
	v_lshl_add_u64 v[140:141], s[50:51], 0, v[132:133]
	s_mov_b32 m0, s18
	ds_read_b128 v[184:187], v144 offset:16384
	ds_read_b128 v[188:191], v144 offset:17408
	ds_read_b128 v[192:195], v144 offset:18432
	ds_read_b128 v[196:199], v144 offset:19456
	ds_read_b128 v[206:209], v144 offset:20480
	ds_read_b128 v[210:213], v144 offset:21504
	ds_read_b128 v[214:217], v144 offset:22528
	ds_read_b128 v[218:221], v144 offset:23552
	global_load_lds_dwordx4 v[140:141], off
	s_add_i32 m0, s18, 0x2000
	s_add_u32 s18, s50, 0x40000
	v_lshl_add_u64 v[158:159], s[50:51], 0, v[128:129]
	s_addc_u32 s19, s51, 0
	s_add_i32 s20, s21, s7
	global_load_lds_dwordx4 v[158:159], off
	v_lshl_add_u64 v[200:201], s[18:19], 0, v[132:133]
	s_mov_b32 m0, s20
	v_lshl_add_u64 v[222:223], s[60:61], 0, v[130:131]
	global_load_lds_dwordx4 v[200:201], off
	v_lshl_add_u64 v[200:201], s[18:19], 0, v[128:129]
	s_add_i32 m0, s20, 0x2000
	s_nop 0
	global_load_lds_dwordx4 v[200:201], off
	v_lshl_add_u64 v[200:201], s[60:61], 0, v[134:135]
	s_mov_b32 m0, s8
	s_nop 0
	global_load_lds_dwordx4 v[200:201], off
	s_mov_b32 m0, s9
	s_nop 0
	global_load_lds_dwordx4 v[222:223], off
	s_waitcnt vmcnt(8)
	s_waitcnt lgkmcnt(0)
	s_setprio 1
	s_barrier
	v_mfma_f32_16x16x32_bf16 v[60:63], v[146:149], v[184:187], v[60:63]
	v_mfma_f32_16x16x32_bf16 v[56:59], v[154:157], v[184:187], v[56:59]
	v_mfma_f32_16x16x32_bf16 v[44:47], v[146:149], v[192:195], v[44:47]
	v_mfma_f32_16x16x32_bf16 v[40:43], v[154:157], v[192:195], v[40:43]
	v_mfma_f32_16x16x32_bf16 v[28:31], v[146:149], v[206:209], v[28:31]
	v_mfma_f32_16x16x32_bf16 v[24:27], v[154:157], v[206:209], v[24:27]
	v_mfma_f32_16x16x32_bf16 v[12:15], v[146:149], v[214:217], v[12:15]
	v_mfma_f32_16x16x32_bf16 v[8:11], v[154:157], v[214:217], v[8:11]
	v_mfma_f32_16x16x32_bf16 v[60:63], v[150:153], v[188:191], v[60:63]
	v_mfma_f32_16x16x32_bf16 v[56:59], v[164:167], v[188:191], v[56:59]
	v_mfma_f32_16x16x32_bf16 v[44:47], v[150:153], v[196:199], v[44:47]
	v_mfma_f32_16x16x32_bf16 v[40:43], v[164:167], v[196:199], v[40:43]
	v_mfma_f32_16x16x32_bf16 v[28:31], v[150:153], v[210:213], v[28:31]
	v_mfma_f32_16x16x32_bf16 v[24:27], v[164:167], v[210:213], v[24:27]
	v_mfma_f32_16x16x32_bf16 v[12:15], v[150:153], v[218:221], v[12:15]
	v_mfma_f32_16x16x32_bf16 v[8:11], v[164:167], v[218:221], v[8:11]
	v_mfma_f32_16x16x32_bf16 v[52:55], v[168:171], v[184:187], v[52:55]
	v_mfma_f32_16x16x32_bf16 v[48:51], v[176:179], v[184:187], v[48:51]
	v_mfma_f32_16x16x32_bf16 v[36:39], v[168:171], v[192:195], v[36:39]
	v_mfma_f32_16x16x32_bf16 v[32:35], v[176:179], v[192:195], v[32:35]
	v_mfma_f32_16x16x32_bf16 v[20:23], v[168:171], v[206:209], v[20:23]
	v_mfma_f32_16x16x32_bf16 v[16:19], v[176:179], v[206:209], v[16:19]
	v_mfma_f32_16x16x32_bf16 v[4:7], v[168:171], v[214:217], v[4:7]
	v_mfma_f32_16x16x32_bf16 v[0:3], v[176:179], v[214:217], v[0:3]
	v_mfma_f32_16x16x32_bf16 v[52:55], v[172:175], v[188:191], v[52:55]
	v_mfma_f32_16x16x32_bf16 v[48:51], v[180:183], v[188:191], v[48:51]
	v_mfma_f32_16x16x32_bf16 v[36:39], v[172:175], v[196:199], v[36:39]
	v_mfma_f32_16x16x32_bf16 v[32:35], v[180:183], v[196:199], v[32:35]
	v_mfma_f32_16x16x32_bf16 v[20:23], v[172:175], v[210:213], v[20:23]
	v_mfma_f32_16x16x32_bf16 v[16:19], v[180:183], v[210:213], v[16:19]
	v_mfma_f32_16x16x32_bf16 v[4:7], v[172:175], v[218:221], v[4:7]
	v_mfma_f32_16x16x32_bf16 v[0:3], v[180:183], v[218:221], v[0:3]
	s_barrier
	s_setprio 0
	s_add_i32 s20, 0, 0x18000
	v_add_u32_e32 v145, s20, v143
	s_add_i32 s21, 0, 0x1c000
	ds_read_b128 v[146:149], v145
	ds_read_b128 v[150:153], v145 offset:1024
	ds_read_b128 v[154:157], v145 offset:2048
	ds_read_b128 v[164:167], v145 offset:3072
	v_add_u32_e32 v145, s21, v143
	ds_read_b128 v[168:171], v145
	ds_read_b128 v[172:175], v145 offset:1024
	ds_read_b128 v[176:179], v145 offset:2048
	ds_read_b128 v[180:183], v145 offset:3072
	s_add_u32 s18, s60, 0x40000
	s_addc_u32 s19, s61, 0
	s_mov_b32 m0, s10
	v_lshl_add_u64 v[224:225], s[18:19], 0, v[134:135]
	ds_read_b128 v[184:187], v144 offset:32768
	ds_read_b128 v[188:191], v144 offset:33792
	ds_read_b128 v[192:195], v144 offset:34816
	ds_read_b128 v[196:199], v144 offset:35840
	ds_read_b128 v[206:209], v144 offset:36864
	ds_read_b128 v[210:213], v144 offset:37888
	ds_read_b128 v[214:217], v144 offset:38912
	ds_read_b128 v[218:221], v144 offset:39936
	global_load_lds_dwordx4 v[224:225], off
	v_lshl_add_u64 v[224:225], s[18:19], 0, v[130:131]
	s_mov_b32 m0, s11
	s_nop 0
	global_load_lds_dwordx4 v[224:225], off
	s_waitcnt vmcnt(8)
	s_waitcnt lgkmcnt(0)
	s_setprio 1
	s_barrier
	v_mfma_f32_16x16x32_bf16 v[124:127], v[146:149], v[184:187], v[124:127]
	v_mfma_f32_16x16x32_bf16 v[120:123], v[154:157], v[184:187], v[120:123]
	v_mfma_f32_16x16x32_bf16 v[108:111], v[146:149], v[192:195], v[108:111]
	v_mfma_f32_16x16x32_bf16 v[104:107], v[154:157], v[192:195], v[104:107]
	v_mfma_f32_16x16x32_bf16 v[92:95], v[146:149], v[206:209], v[92:95]
	v_mfma_f32_16x16x32_bf16 v[88:91], v[154:157], v[206:209], v[88:91]
	v_mfma_f32_16x16x32_bf16 v[76:79], v[146:149], v[214:217], v[76:79]
	v_mfma_f32_16x16x32_bf16 v[72:75], v[154:157], v[214:217], v[72:75]
	v_mfma_f32_16x16x32_bf16 v[124:127], v[150:153], v[188:191], v[124:127]
	v_mfma_f32_16x16x32_bf16 v[120:123], v[164:167], v[188:191], v[120:123]
	v_mfma_f32_16x16x32_bf16 v[108:111], v[150:153], v[196:199], v[108:111]
	v_mfma_f32_16x16x32_bf16 v[104:107], v[164:167], v[196:199], v[104:107]
	v_mfma_f32_16x16x32_bf16 v[92:95], v[150:153], v[210:213], v[92:95]
	v_mfma_f32_16x16x32_bf16 v[88:91], v[164:167], v[210:213], v[88:91]
	v_mfma_f32_16x16x32_bf16 v[76:79], v[150:153], v[218:221], v[76:79]
	v_mfma_f32_16x16x32_bf16 v[72:75], v[164:167], v[218:221], v[72:75]
	v_mfma_f32_16x16x32_bf16 v[116:119], v[168:171], v[184:187], v[116:119]
	v_mfma_f32_16x16x32_bf16 v[112:115], v[176:179], v[184:187], v[112:115]
	v_mfma_f32_16x16x32_bf16 v[100:103], v[168:171], v[192:195], v[100:103]
	v_mfma_f32_16x16x32_bf16 v[96:99], v[176:179], v[192:195], v[96:99]
	v_mfma_f32_16x16x32_bf16 v[84:87], v[168:171], v[206:209], v[84:87]
	v_mfma_f32_16x16x32_bf16 v[80:83], v[176:179], v[206:209], v[80:83]
	v_mfma_f32_16x16x32_bf16 v[68:71], v[168:171], v[214:217], v[68:71]
	v_mfma_f32_16x16x32_bf16 v[64:67], v[176:179], v[214:217], v[64:67]
	v_mfma_f32_16x16x32_bf16 v[116:119], v[172:175], v[188:191], v[116:119]
	v_mfma_f32_16x16x32_bf16 v[112:115], v[180:183], v[188:191], v[112:115]
	v_mfma_f32_16x16x32_bf16 v[100:103], v[172:175], v[196:199], v[100:103]
	v_mfma_f32_16x16x32_bf16 v[96:99], v[180:183], v[196:199], v[96:99]
	v_mfma_f32_16x16x32_bf16 v[84:87], v[172:175], v[210:213], v[84:87]
	v_mfma_f32_16x16x32_bf16 v[80:83], v[180:183], v[210:213], v[80:83]
	v_mfma_f32_16x16x32_bf16 v[68:71], v[172:175], v[218:221], v[68:71]
	v_mfma_f32_16x16x32_bf16 v[64:67], v[180:183], v[218:221], v[64:67]
	s_barrier
	s_setprio 0
	s_add_i32 s18, s20, s7
	v_lshl_add_u64 v[140:141], v[140:141], 0, s[76:77]
	s_mov_b32 m0, s18
	ds_read_b128 v[184:187], v144 offset:49152
	ds_read_b128 v[188:191], v144 offset:50176
	ds_read_b128 v[192:195], v144 offset:51200
	ds_read_b128 v[196:199], v144 offset:52224
	ds_read_b128 v[206:209], v144 offset:53248
	ds_read_b128 v[210:213], v144 offset:54272
	ds_read_b128 v[214:217], v144 offset:55296
	ds_read_b128 v[218:221], v144 offset:56320
	global_load_lds_dwordx4 v[140:141], off
	s_add_i32 m0, s18, 0x2000
	s_add_u32 s18, s50, 0x40080
	v_lshl_add_u64 v[140:141], v[158:159], 0, s[76:77]
	s_addc_u32 s19, s51, 0
	s_add_i32 s20, s21, s7
	global_load_lds_dwordx4 v[140:141], off
	v_lshl_add_u64 v[140:141], s[18:19], 0, v[132:133]
	s_mov_b32 m0, s20
	s_nop 0
	global_load_lds_dwordx4 v[140:141], off
	v_lshl_add_u64 v[140:141], s[18:19], 0, v[128:129]
	s_add_i32 m0, s20, 0x2000
	s_nop 0
	global_load_lds_dwordx4 v[140:141], off
	v_lshl_add_u64 v[140:141], v[200:201], 0, s[76:77]
	s_mov_b32 m0, s12
	s_nop 0
	global_load_lds_dwordx4 v[140:141], off
	v_lshl_add_u64 v[140:141], v[222:223], 0, s[76:77]
	s_mov_b32 m0, s13
	s_nop 0
	global_load_lds_dwordx4 v[140:141], off
	s_waitcnt vmcnt(8)
	s_waitcnt lgkmcnt(0)
	s_setprio 1
	s_barrier
	v_mfma_f32_16x16x32_bf16 v[60:63], v[146:149], v[184:187], v[60:63]
	v_mfma_f32_16x16x32_bf16 v[56:59], v[154:157], v[184:187], v[56:59]
	v_mfma_f32_16x16x32_bf16 v[44:47], v[146:149], v[192:195], v[44:47]
	v_mfma_f32_16x16x32_bf16 v[40:43], v[154:157], v[192:195], v[40:43]
	v_mfma_f32_16x16x32_bf16 v[28:31], v[146:149], v[206:209], v[28:31]
	v_mfma_f32_16x16x32_bf16 v[24:27], v[154:157], v[206:209], v[24:27]
	v_mfma_f32_16x16x32_bf16 v[12:15], v[146:149], v[214:217], v[12:15]
	v_mfma_f32_16x16x32_bf16 v[8:11], v[154:157], v[214:217], v[8:11]
	v_mfma_f32_16x16x32_bf16 v[60:63], v[150:153], v[188:191], v[60:63]
	v_mfma_f32_16x16x32_bf16 v[56:59], v[164:167], v[188:191], v[56:59]
	v_mfma_f32_16x16x32_bf16 v[44:47], v[150:153], v[196:199], v[44:47]
	v_mfma_f32_16x16x32_bf16 v[40:43], v[164:167], v[196:199], v[40:43]
	v_mfma_f32_16x16x32_bf16 v[28:31], v[150:153], v[210:213], v[28:31]
	v_mfma_f32_16x16x32_bf16 v[24:27], v[164:167], v[210:213], v[24:27]
	v_mfma_f32_16x16x32_bf16 v[12:15], v[150:153], v[218:221], v[12:15]
	v_mfma_f32_16x16x32_bf16 v[8:11], v[164:167], v[218:221], v[8:11]
	v_mfma_f32_16x16x32_bf16 v[52:55], v[168:171], v[184:187], v[52:55]
	v_mfma_f32_16x16x32_bf16 v[48:51], v[176:179], v[184:187], v[48:51]
	v_mfma_f32_16x16x32_bf16 v[36:39], v[168:171], v[192:195], v[36:39]
	v_mfma_f32_16x16x32_bf16 v[32:35], v[176:179], v[192:195], v[32:35]
	v_mfma_f32_16x16x32_bf16 v[20:23], v[168:171], v[206:209], v[20:23]
	v_mfma_f32_16x16x32_bf16 v[16:19], v[176:179], v[206:209], v[16:19]
	v_mfma_f32_16x16x32_bf16 v[4:7], v[168:171], v[214:217], v[4:7]
	v_mfma_f32_16x16x32_bf16 v[0:3], v[176:179], v[214:217], v[0:3]
	v_mfma_f32_16x16x32_bf16 v[52:55], v[172:175], v[188:191], v[52:55]
	v_mfma_f32_16x16x32_bf16 v[48:51], v[180:183], v[188:191], v[48:51]
	v_mfma_f32_16x16x32_bf16 v[36:39], v[172:175], v[196:199], v[36:39]
	v_mfma_f32_16x16x32_bf16 v[32:35], v[180:183], v[196:199], v[32:35]
	v_mfma_f32_16x16x32_bf16 v[20:23], v[172:175], v[210:213], v[20:23]
	v_mfma_f32_16x16x32_bf16 v[16:19], v[180:183], v[210:213], v[16:19]
	v_mfma_f32_16x16x32_bf16 v[4:7], v[172:175], v[218:221], v[4:7]
	v_mfma_f32_16x16x32_bf16 v[0:3], v[180:183], v[218:221], v[0:3]
	s_barrier
	s_setprio 0
	s_add_i32 s63, s63, 2
	s_add_u32 s58, s58, 0x100
	s_addc_u32 s59, s59, 0
	s_add_u32 s47, s47, 0x100
	s_addc_u32 s62, s62, 0
	s_cmp_gt_u32 s63, 13
	s_cbranch_scc0 .LBB0_1138

.LBB0_1209:
	s_add_u32 s54, s48, 0x100
	s_addc_u32 s60, s49, 0
	s_mov_b32 s61, -2
	s_add_u32 s48, s42, 0x100
	s_addc_u32 s49, s43, 0
	s_add_i32 s18, 0, 0x10000
	s_cmp_eq_u32 s61, 40
	s_cselect_b32 s59, s39, s49
	s_cselect_b32 s58, s38, s48
	s_cselect_b32 s51, s41, s60
	s_cselect_b32 s50, s40, s54
	s_add_i32 s20, 0, 0x14000
	v_add_u32_e32 v140, s18, v174
	v_add_u32_e32 v162, s20, v174
	ds_read_b128 v[128:131], v140
	ds_read_b128 v[132:135], v140 offset:1024
	ds_read_b128 v[136:139], v140 offset:2048
	ds_read_b128 v[140:143], v140 offset:3072
	ds_read_b128 v[156:159], v162
	ds_read_b128 v[164:167], v162 offset:1024
	ds_read_b128 v[168:171], v162 offset:2048
	ds_read_b128 v[176:179], v162 offset:3072
	v_lshl_add_u64 v[200:201], s[42:43], 0, v[152:153]
	s_add_i32 m0, s4, 0xc000
	ds_read_b128 v[180:183], v175
	ds_read_b128 v[184:187], v175 offset:1024
	ds_read_b128 v[188:191], v175 offset:2048
	ds_read_b128 v[192:195], v175 offset:3072
	ds_read_b128 v[196:199], v175 offset:4096
	ds_read_b128 v[206:209], v175 offset:5120
	ds_read_b128 v[210:213], v175 offset:6144
	ds_read_b128 v[214:217], v175 offset:7168
	global_load_lds_dwordx4 v[200:201], off
	v_lshl_add_u64 v[200:201], s[42:43], 0, v[154:155]
	s_add_i32 m0, s4, 0xe000
	s_nop 0
	global_load_lds_dwordx4 v[200:201], off
	s_waitcnt vmcnt(8)
	s_waitcnt lgkmcnt(0)
	s_setprio 1
	s_barrier
	v_mfma_f32_16x16x32_bf16 v[124:127], v[128:131], v[180:183], 0
	v_mfma_f32_16x16x32_bf16 v[120:123], v[136:139], v[180:183], 0
	v_mfma_f32_16x16x32_bf16 v[112:115], v[128:131], v[188:191], 0
	v_mfma_f32_16x16x32_bf16 v[104:107], v[136:139], v[188:191], 0
	v_mfma_f32_16x16x32_bf16 v[96:99], v[128:131], v[196:199], 0
	v_mfma_f32_16x16x32_bf16 v[88:91], v[136:139], v[196:199], 0
	v_mfma_f32_16x16x32_bf16 v[80:83], v[128:131], v[210:213], 0
	v_mfma_f32_16x16x32_bf16 v[72:75], v[136:139], v[210:213], 0
	v_mfma_f32_16x16x32_bf16 v[124:127], v[132:135], v[184:187], v[124:127]
	v_mfma_f32_16x16x32_bf16 v[120:123], v[140:143], v[184:187], v[120:123]
	v_mfma_f32_16x16x32_bf16 v[112:115], v[132:135], v[192:195], v[112:115]
	v_mfma_f32_16x16x32_bf16 v[104:107], v[140:143], v[192:195], v[104:107]
	v_mfma_f32_16x16x32_bf16 v[96:99], v[132:135], v[206:209], v[96:99]
	v_mfma_f32_16x16x32_bf16 v[88:91], v[140:143], v[206:209], v[88:91]
	v_mfma_f32_16x16x32_bf16 v[80:83], v[132:135], v[214:217], v[80:83]
	v_mfma_f32_16x16x32_bf16 v[72:75], v[140:143], v[214:217], v[72:75]
	v_mfma_f32_16x16x32_bf16 v[116:119], v[156:159], v[180:183], 0
	v_mfma_f32_16x16x32_bf16 v[108:111], v[168:171], v[180:183], 0
	v_mfma_f32_16x16x32_bf16 v[100:103], v[156:159], v[188:191], 0
	v_mfma_f32_16x16x32_bf16 v[92:95], v[168:171], v[188:191], 0
	v_mfma_f32_16x16x32_bf16 v[84:87], v[156:159], v[196:199], 0
	v_mfma_f32_16x16x32_bf16 v[76:79], v[168:171], v[196:199], 0
	v_mfma_f32_16x16x32_bf16 v[68:71], v[156:159], v[210:213], 0
	v_mfma_f32_16x16x32_bf16 v[64:67], v[168:171], v[210:213], 0
	v_mfma_f32_16x16x32_bf16 v[116:119], v[164:167], v[184:187], v[116:119]
	v_mfma_f32_16x16x32_bf16 v[108:111], v[176:179], v[184:187], v[108:111]
	v_mfma_f32_16x16x32_bf16 v[100:103], v[164:167], v[192:195], v[100:103]
	v_mfma_f32_16x16x32_bf16 v[92:95], v[176:179], v[192:195], v[92:95]
	v_mfma_f32_16x16x32_bf16 v[84:87], v[164:167], v[206:209], v[84:87]
	v_mfma_f32_16x16x32_bf16 v[76:79], v[176:179], v[206:209], v[76:79]
	v_mfma_f32_16x16x32_bf16 v[68:71], v[164:167], v[214:217], v[68:71]
	v_mfma_f32_16x16x32_bf16 v[64:67], v[176:179], v[214:217], v[64:67]
	s_barrier
	s_setprio 0
	s_add_i32 s18, s18, s46
	v_lshl_add_u64 v[200:201], s[50:51], 0, v[148:149]
	s_mov_b32 m0, s18
	ds_read_b128 v[180:183], v175 offset:16384
	ds_read_b128 v[184:187], v175 offset:17408
	ds_read_b128 v[188:191], v175 offset:18432
	ds_read_b128 v[192:195], v175 offset:19456
	ds_read_b128 v[196:199], v175 offset:20480
	ds_read_b128 v[206:209], v175 offset:21504
	ds_read_b128 v[210:213], v175 offset:22528
	ds_read_b128 v[214:217], v175 offset:23552
	global_load_lds_dwordx4 v[200:201], off
	s_add_i32 m0, s18, 0x2000
	s_add_u32 s18, s50, 0xb0000
	v_lshl_add_u64 v[218:219], s[50:51], 0, v[144:145]
	s_addc_u32 s19, s51, 0
	s_add_i32 s20, s20, s46
	global_load_lds_dwordx4 v[218:219], off
	v_lshl_add_u64 v[220:221], s[18:19], 0, v[148:149]
	s_mov_b32 m0, s20
	v_lshl_add_u64 v[222:223], s[58:59], 0, v[146:147]
	global_load_lds_dwordx4 v[220:221], off
	v_lshl_add_u64 v[220:221], s[18:19], 0, v[144:145]
	s_add_i32 m0, s20, 0x2000
	s_nop 0
	global_load_lds_dwordx4 v[220:221], off
	v_lshl_add_u64 v[220:221], s[58:59], 0, v[150:151]
	s_mov_b32 m0, s4
	s_nop 0
	global_load_lds_dwordx4 v[220:221], off
	s_mov_b32 m0, s5
	s_nop 0
	global_load_lds_dwordx4 v[222:223], off
	s_waitcnt vmcnt(8)
	s_waitcnt lgkmcnt(0)
	s_setprio 1
	s_barrier
	v_mfma_f32_16x16x32_bf16 v[60:63], v[128:131], v[180:183], 0
	v_mfma_f32_16x16x32_bf16 v[56:59], v[136:139], v[180:183], 0
	v_mfma_f32_16x16x32_bf16 v[48:51], v[128:131], v[188:191], 0
	v_mfma_f32_16x16x32_bf16 v[40:43], v[136:139], v[188:191], 0
	v_mfma_f32_16x16x32_bf16 v[32:35], v[128:131], v[196:199], 0
	v_mfma_f32_16x16x32_bf16 v[24:27], v[136:139], v[196:199], 0
	v_mfma_f32_16x16x32_bf16 v[16:19], v[128:131], v[210:213], 0
	v_mfma_f32_16x16x32_bf16 v[8:11], v[136:139], v[210:213], 0
	v_mfma_f32_16x16x32_bf16 v[60:63], v[132:135], v[184:187], v[60:63]
	v_mfma_f32_16x16x32_bf16 v[56:59], v[140:143], v[184:187], v[56:59]
	v_mfma_f32_16x16x32_bf16 v[48:51], v[132:135], v[192:195], v[48:51]
	v_mfma_f32_16x16x32_bf16 v[40:43], v[140:143], v[192:195], v[40:43]
	v_mfma_f32_16x16x32_bf16 v[32:35], v[132:135], v[206:209], v[32:35]
	v_mfma_f32_16x16x32_bf16 v[24:27], v[140:143], v[206:209], v[24:27]
	v_mfma_f32_16x16x32_bf16 v[16:19], v[132:135], v[214:217], v[16:19]
	v_mfma_f32_16x16x32_bf16 v[8:11], v[140:143], v[214:217], v[8:11]
	v_mfma_f32_16x16x32_bf16 v[52:55], v[156:159], v[180:183], 0
	v_mfma_f32_16x16x32_bf16 v[44:47], v[168:171], v[180:183], 0
	v_mfma_f32_16x16x32_bf16 v[36:39], v[156:159], v[188:191], 0
	v_mfma_f32_16x16x32_bf16 v[28:31], v[168:171], v[188:191], 0
	v_mfma_f32_16x16x32_bf16 v[20:23], v[156:159], v[196:199], 0
	v_mfma_f32_16x16x32_bf16 v[12:15], v[168:171], v[196:199], 0
	v_mfma_f32_16x16x32_bf16 v[4:7], v[156:159], v[210:213], 0
	v_mfma_f32_16x16x32_bf16 v[0:3], v[168:171], v[210:213], 0
	v_mfma_f32_16x16x32_bf16 v[52:55], v[164:167], v[184:187], v[52:55]
	v_mfma_f32_16x16x32_bf16 v[44:47], v[176:179], v[184:187], v[44:47]
	v_mfma_f32_16x16x32_bf16 v[36:39], v[164:167], v[192:195], v[36:39]
	v_mfma_f32_16x16x32_bf16 v[28:31], v[176:179], v[192:195], v[28:31]
	v_mfma_f32_16x16x32_bf16 v[20:23], v[164:167], v[206:209], v[20:23]
	v_mfma_f32_16x16x32_bf16 v[12:15], v[176:179], v[206:209], v[12:15]
	v_mfma_f32_16x16x32_bf16 v[4:7], v[164:167], v[214:217], v[4:7]
	v_mfma_f32_16x16x32_bf16 v[0:3], v[176:179], v[214:217], v[0:3]
	s_barrier
	s_setprio 0
	s_add_i32 s20, 0, 0x18000
	s_add_i32 s21, 0, 0x1c000
	v_add_u32_e32 v140, s20, v174
	v_add_u32_e32 v162, s21, v174
	ds_read_b128 v[128:131], v140
	ds_read_b128 v[132:135], v140 offset:1024
	ds_read_b128 v[136:139], v140 offset:2048
	ds_read_b128 v[140:143], v140 offset:3072
	ds_read_b128 v[156:159], v162
	ds_read_b128 v[164:167], v162 offset:1024
	ds_read_b128 v[168:171], v162 offset:2048
	ds_read_b128 v[176:179], v162 offset:3072
	s_add_u32 s18, s58, 0xb0000
	s_addc_u32 s19, s59, 0
	s_mov_b32 m0, s6
	v_lshl_add_u64 v[224:225], s[18:19], 0, v[150:151]
	ds_read_b128 v[180:183], v175 offset:32768
	ds_read_b128 v[184:187], v175 offset:33792
	ds_read_b128 v[188:191], v175 offset:34816
	ds_read_b128 v[192:195], v175 offset:35840
	ds_read_b128 v[196:199], v175 offset:36864
	ds_read_b128 v[206:209], v175 offset:37888
	ds_read_b128 v[210:213], v175 offset:38912
	ds_read_b128 v[214:217], v175 offset:39936
	global_load_lds_dwordx4 v[224:225], off
	v_lshl_add_u64 v[224:225], s[18:19], 0, v[146:147]
	s_mov_b32 m0, s7
	s_nop 0
	global_load_lds_dwordx4 v[224:225], off
	s_waitcnt vmcnt(8)
	s_waitcnt lgkmcnt(0)
	s_setprio 1
	s_barrier
	v_mfma_f32_16x16x32_bf16 v[124:127], v[128:131], v[180:183], v[124:127]
	v_mfma_f32_16x16x32_bf16 v[120:123], v[136:139], v[180:183], v[120:123]
	v_mfma_f32_16x16x32_bf16 v[112:115], v[128:131], v[188:191], v[112:115]
	v_mfma_f32_16x16x32_bf16 v[104:107], v[136:139], v[188:191], v[104:107]
	v_mfma_f32_16x16x32_bf16 v[96:99], v[128:131], v[196:199], v[96:99]
	v_mfma_f32_16x16x32_bf16 v[88:91], v[136:139], v[196:199], v[88:91]
	v_mfma_f32_16x16x32_bf16 v[80:83], v[128:131], v[210:213], v[80:83]
	v_mfma_f32_16x16x32_bf16 v[72:75], v[136:139], v[210:213], v[72:75]
	v_mfma_f32_16x16x32_bf16 v[124:127], v[132:135], v[184:187], v[124:127]
	v_mfma_f32_16x16x32_bf16 v[120:123], v[140:143], v[184:187], v[120:123]
	v_mfma_f32_16x16x32_bf16 v[112:115], v[132:135], v[192:195], v[112:115]
	v_mfma_f32_16x16x32_bf16 v[104:107], v[140:143], v[192:195], v[104:107]
	v_mfma_f32_16x16x32_bf16 v[96:99], v[132:135], v[206:209], v[96:99]
	v_mfma_f32_16x16x32_bf16 v[88:91], v[140:143], v[206:209], v[88:91]
	v_mfma_f32_16x16x32_bf16 v[80:83], v[132:135], v[214:217], v[80:83]
	v_mfma_f32_16x16x32_bf16 v[72:75], v[140:143], v[214:217], v[72:75]
	v_mfma_f32_16x16x32_bf16 v[116:119], v[156:159], v[180:183], v[116:119]
	v_mfma_f32_16x16x32_bf16 v[108:111], v[168:171], v[180:183], v[108:111]
	v_mfma_f32_16x16x32_bf16 v[100:103], v[156:159], v[188:191], v[100:103]
	v_mfma_f32_16x16x32_bf16 v[92:95], v[168:171], v[188:191], v[92:95]
	v_mfma_f32_16x16x32_bf16 v[84:87], v[156:159], v[196:199], v[84:87]
	v_mfma_f32_16x16x32_bf16 v[76:79], v[168:171], v[196:199], v[76:79]
	v_mfma_f32_16x16x32_bf16 v[68:71], v[156:159], v[210:213], v[68:71]
	v_mfma_f32_16x16x32_bf16 v[64:67], v[168:171], v[210:213], v[64:67]
	v_mfma_f32_16x16x32_bf16 v[116:119], v[164:167], v[184:187], v[116:119]
	v_mfma_f32_16x16x32_bf16 v[108:111], v[176:179], v[184:187], v[108:111]
	v_mfma_f32_16x16x32_bf16 v[100:103], v[164:167], v[192:195], v[100:103]
	v_mfma_f32_16x16x32_bf16 v[92:95], v[176:179], v[192:195], v[92:95]
	v_mfma_f32_16x16x32_bf16 v[84:87], v[164:167], v[206:209], v[84:87]
	v_mfma_f32_16x16x32_bf16 v[76:79], v[176:179], v[206:209], v[76:79]
	v_mfma_f32_16x16x32_bf16 v[68:71], v[164:167], v[214:217], v[68:71]
	v_mfma_f32_16x16x32_bf16 v[64:67], v[176:179], v[214:217], v[64:67]
	s_barrier
	s_setprio 0
	s_add_i32 s18, s20, s46
	v_lshl_add_u64 v[200:201], v[200:201], 0, s[76:77]
	s_mov_b32 m0, s18
	ds_read_b128 v[180:183], v175 offset:49152
	ds_read_b128 v[184:187], v175 offset:50176
	ds_read_b128 v[188:191], v175 offset:51200
	ds_read_b128 v[192:195], v175 offset:52224
	ds_read_b128 v[196:199], v175 offset:53248
	ds_read_b128 v[206:209], v175 offset:54272
	ds_read_b128 v[210:213], v175 offset:55296
	ds_read_b128 v[214:217], v175 offset:56320
	global_load_lds_dwordx4 v[200:201], off
	s_add_i32 m0, s18, 0x2000
	s_add_u32 s18, s50, 0xb0080
	v_lshl_add_u64 v[200:201], v[218:219], 0, s[76:77]
	s_addc_u32 s19, s51, 0
	s_add_i32 s20, s21, s46
	global_load_lds_dwordx4 v[200:201], off
	v_lshl_add_u64 v[200:201], s[18:19], 0, v[148:149]
	s_mov_b32 m0, s20
	s_nop 0
	global_load_lds_dwordx4 v[200:201], off
	v_lshl_add_u64 v[200:201], s[18:19], 0, v[144:145]
	s_add_i32 m0, s20, 0x2000
	s_nop 0
	global_load_lds_dwordx4 v[200:201], off
	v_lshl_add_u64 v[200:201], v[220:221], 0, s[76:77]
	s_mov_b32 m0, s11
	s_nop 0
	global_load_lds_dwordx4 v[200:201], off
	v_lshl_add_u64 v[200:201], v[222:223], 0, s[76:77]
	s_mov_b32 m0, s12
	s_nop 0
	global_load_lds_dwordx4 v[200:201], off
	s_waitcnt vmcnt(8)
	s_waitcnt lgkmcnt(0)
	s_setprio 1
	s_barrier
	v_mfma_f32_16x16x32_bf16 v[60:63], v[128:131], v[180:183], v[60:63]
	v_mfma_f32_16x16x32_bf16 v[56:59], v[136:139], v[180:183], v[56:59]
	v_mfma_f32_16x16x32_bf16 v[48:51], v[128:131], v[188:191], v[48:51]
	v_mfma_f32_16x16x32_bf16 v[40:43], v[136:139], v[188:191], v[40:43]
	v_mfma_f32_16x16x32_bf16 v[32:35], v[128:131], v[196:199], v[32:35]
	v_mfma_f32_16x16x32_bf16 v[24:27], v[136:139], v[196:199], v[24:27]
	v_mfma_f32_16x16x32_bf16 v[16:19], v[128:131], v[210:213], v[16:19]
	v_mfma_f32_16x16x32_bf16 v[8:11], v[136:139], v[210:213], v[8:11]
	v_mfma_f32_16x16x32_bf16 v[60:63], v[132:135], v[184:187], v[60:63]
	v_mfma_f32_16x16x32_bf16 v[56:59], v[140:143], v[184:187], v[56:59]
	v_mfma_f32_16x16x32_bf16 v[48:51], v[132:135], v[192:195], v[48:51]
	v_mfma_f32_16x16x32_bf16 v[40:43], v[140:143], v[192:195], v[40:43]
	v_mfma_f32_16x16x32_bf16 v[32:35], v[132:135], v[206:209], v[32:35]
	v_mfma_f32_16x16x32_bf16 v[24:27], v[140:143], v[206:209], v[24:27]
	v_mfma_f32_16x16x32_bf16 v[16:19], v[132:135], v[214:217], v[16:19]
	v_mfma_f32_16x16x32_bf16 v[8:11], v[140:143], v[214:217], v[8:11]
	v_mfma_f32_16x16x32_bf16 v[52:55], v[156:159], v[180:183], v[52:55]
	v_mfma_f32_16x16x32_bf16 v[44:47], v[168:171], v[180:183], v[44:47]
	v_mfma_f32_16x16x32_bf16 v[36:39], v[156:159], v[188:191], v[36:39]
	v_mfma_f32_16x16x32_bf16 v[28:31], v[168:171], v[188:191], v[28:31]
	v_mfma_f32_16x16x32_bf16 v[20:23], v[156:159], v[196:199], v[20:23]
	v_mfma_f32_16x16x32_bf16 v[12:15], v[168:171], v[196:199], v[12:15]
	v_mfma_f32_16x16x32_bf16 v[4:7], v[156:159], v[210:213], v[4:7]
	v_mfma_f32_16x16x32_bf16 v[0:3], v[168:171], v[210:213], v[0:3]
	v_mfma_f32_16x16x32_bf16 v[52:55], v[164:167], v[184:187], v[52:55]
	v_mfma_f32_16x16x32_bf16 v[44:47], v[176:179], v[184:187], v[44:47]
	v_mfma_f32_16x16x32_bf16 v[36:39], v[164:167], v[192:195], v[36:39]
	v_mfma_f32_16x16x32_bf16 v[28:31], v[176:179], v[192:195], v[28:31]
	v_mfma_f32_16x16x32_bf16 v[20:23], v[164:167], v[206:209], v[20:23]
	v_mfma_f32_16x16x32_bf16 v[12:15], v[176:179], v[206:209], v[12:15]
	v_mfma_f32_16x16x32_bf16 v[4:7], v[164:167], v[214:217], v[4:7]
	v_mfma_f32_16x16x32_bf16 v[0:3], v[176:179], v[214:217], v[0:3]
	s_barrier
	s_setprio 0
	s_add_i32 s61, s61, 2
	s_add_u32 s54, s54, 0x100
	s_addc_u32 s60, s60, 0
	s_cmp_gt_u32 s61, 41
	s_mov_b64 s[42:43], s[48:49]
	s_cbranch_scc0 .LBB0_1210
	s_branch .Lpeel_x_1210
.LBB0_1210:
	s_add_u32 s48, s42, 0x100
	s_addc_u32 s49, s43, 0
	s_add_i32 s18, 0, 0x10000
	s_cmp_eq_u32 s61, 40
	s_cselect_b32 s59, s39, s49
	s_cselect_b32 s58, s38, s48
	s_cselect_b32 s51, s41, s60
	s_cselect_b32 s50, s40, s54
	s_add_i32 s20, 0, 0x14000
	v_add_u32_e32 v140, s18, v174
	v_add_u32_e32 v162, s20, v174
	ds_read_b128 v[128:131], v140
	ds_read_b128 v[132:135], v140 offset:1024
	ds_read_b128 v[136:139], v140 offset:2048
	ds_read_b128 v[140:143], v140 offset:3072
	ds_read_b128 v[156:159], v162
	ds_read_b128 v[164:167], v162 offset:1024
	ds_read_b128 v[168:171], v162 offset:2048
	ds_read_b128 v[176:179], v162 offset:3072
	v_lshl_add_u64 v[200:201], s[42:43], 0, v[152:153]
	s_add_i32 m0, s4, 0xc000
	ds_read_b128 v[180:183], v175
	ds_read_b128 v[184:187], v175 offset:1024
	ds_read_b128 v[188:191], v175 offset:2048
	ds_read_b128 v[192:195], v175 offset:3072
	ds_read_b128 v[196:199], v175 offset:4096
	ds_read_b128 v[206:209], v175 offset:5120
	ds_read_b128 v[210:213], v175 offset:6144
	ds_read_b128 v[214:217], v175 offset:7168
	global_load_lds_dwordx4 v[200:201], off
	v_lshl_add_u64 v[200:201], s[42:43], 0, v[154:155]
	s_add_i32 m0, s4, 0xe000
	s_nop 0
	global_load_lds_dwordx4 v[200:201], off
	s_waitcnt vmcnt(8)
	s_waitcnt lgkmcnt(0)
	s_setprio 1
	s_barrier
	v_mfma_f32_16x16x32_bf16 v[124:127], v[128:131], v[180:183], v[124:127]
	v_mfma_f32_16x16x32_bf16 v[120:123], v[136:139], v[180:183], v[120:123]
	v_mfma_f32_16x16x32_bf16 v[112:115], v[128:131], v[188:191], v[112:115]
	v_mfma_f32_16x16x32_bf16 v[104:107], v[136:139], v[188:191], v[104:107]
	v_mfma_f32_16x16x32_bf16 v[96:99], v[128:131], v[196:199], v[96:99]
	v_mfma_f32_16x16x32_bf16 v[88:91], v[136:139], v[196:199], v[88:91]
	v_mfma_f32_16x16x32_bf16 v[80:83], v[128:131], v[210:213], v[80:83]
	v_mfma_f32_16x16x32_bf16 v[72:75], v[136:139], v[210:213], v[72:75]
	v_mfma_f32_16x16x32_bf16 v[124:127], v[132:135], v[184:187], v[124:127]
	v_mfma_f32_16x16x32_bf16 v[120:123], v[140:143], v[184:187], v[120:123]
	v_mfma_f32_16x16x32_bf16 v[112:115], v[132:135], v[192:195], v[112:115]
	v_mfma_f32_16x16x32_bf16 v[104:107], v[140:143], v[192:195], v[104:107]
	v_mfma_f32_16x16x32_bf16 v[96:99], v[132:135], v[206:209], v[96:99]
	v_mfma_f32_16x16x32_bf16 v[88:91], v[140:143], v[206:209], v[88:91]
	v_mfma_f32_16x16x32_bf16 v[80:83], v[132:135], v[214:217], v[80:83]
	v_mfma_f32_16x16x32_bf16 v[72:75], v[140:143], v[214:217], v[72:75]
	v_mfma_f32_16x16x32_bf16 v[116:119], v[156:159], v[180:183], v[116:119]
	v_mfma_f32_16x16x32_bf16 v[108:111], v[168:171], v[180:183], v[108:111]
	v_mfma_f32_16x16x32_bf16 v[100:103], v[156:159], v[188:191], v[100:103]
	v_mfma_f32_16x16x32_bf16 v[92:95], v[168:171], v[188:191], v[92:95]
	v_mfma_f32_16x16x32_bf16 v[84:87], v[156:159], v[196:199], v[84:87]
	v_mfma_f32_16x16x32_bf16 v[76:79], v[168:171], v[196:199], v[76:79]
	v_mfma_f32_16x16x32_bf16 v[68:71], v[156:159], v[210:213], v[68:71]
	v_mfma_f32_16x16x32_bf16 v[64:67], v[168:171], v[210:213], v[64:67]
	v_mfma_f32_16x16x32_bf16 v[116:119], v[164:167], v[184:187], v[116:119]
	v_mfma_f32_16x16x32_bf16 v[108:111], v[176:179], v[184:187], v[108:111]
	v_mfma_f32_16x16x32_bf16 v[100:103], v[164:167], v[192:195], v[100:103]
	v_mfma_f32_16x16x32_bf16 v[92:95], v[176:179], v[192:195], v[92:95]
	v_mfma_f32_16x16x32_bf16 v[84:87], v[164:167], v[206:209], v[84:87]
	v_mfma_f32_16x16x32_bf16 v[76:79], v[176:179], v[206:209], v[76:79]
	v_mfma_f32_16x16x32_bf16 v[68:71], v[164:167], v[214:217], v[68:71]
	v_mfma_f32_16x16x32_bf16 v[64:67], v[176:179], v[214:217], v[64:67]
	s_barrier
	s_setprio 0
	s_add_i32 s18, s18, s46
	v_lshl_add_u64 v[200:201], s[50:51], 0, v[148:149]
	s_mov_b32 m0, s18
	ds_read_b128 v[180:183], v175 offset:16384
	ds_read_b128 v[184:187], v175 offset:17408
	ds_read_b128 v[188:191], v175 offset:18432
	ds_read_b128 v[192:195], v175 offset:19456
	ds_read_b128 v[196:199], v175 offset:20480
	ds_read_b128 v[206:209], v175 offset:21504
	ds_read_b128 v[210:213], v175 offset:22528
	ds_read_b128 v[214:217], v175 offset:23552
	global_load_lds_dwordx4 v[200:201], off
	s_add_i32 m0, s18, 0x2000
	s_add_u32 s18, s50, 0xb0000
	v_lshl_add_u64 v[218:219], s[50:51], 0, v[144:145]
	s_addc_u32 s19, s51, 0
	s_add_i32 s20, s20, s46
	global_load_lds_dwordx4 v[218:219], off
	v_lshl_add_u64 v[220:221], s[18:19], 0, v[148:149]
	s_mov_b32 m0, s20
	v_lshl_add_u64 v[222:223], s[58:59], 0, v[146:147]
	global_load_lds_dwordx4 v[220:221], off
	v_lshl_add_u64 v[220:221], s[18:19], 0, v[144:145]
	s_add_i32 m0, s20, 0x2000
	s_nop 0
	global_load_lds_dwordx4 v[220:221], off
	v_lshl_add_u64 v[220:221], s[58:59], 0, v[150:151]
	s_mov_b32 m0, s4
	s_nop 0
	global_load_lds_dwordx4 v[220:221], off
	s_mov_b32 m0, s5
	s_nop 0
	global_load_lds_dwordx4 v[222:223], off
	s_waitcnt vmcnt(8)
	s_waitcnt lgkmcnt(0)
	s_setprio 1
	s_barrier
	v_mfma_f32_16x16x32_bf16 v[60:63], v[128:131], v[180:183], v[60:63]
	v_mfma_f32_16x16x32_bf16 v[56:59], v[136:139], v[180:183], v[56:59]
	v_mfma_f32_16x16x32_bf16 v[48:51], v[128:131], v[188:191], v[48:51]
	v_mfma_f32_16x16x32_bf16 v[40:43], v[136:139], v[188:191], v[40:43]
	v_mfma_f32_16x16x32_bf16 v[32:35], v[128:131], v[196:199], v[32:35]
	v_mfma_f32_16x16x32_bf16 v[24:27], v[136:139], v[196:199], v[24:27]
	v_mfma_f32_16x16x32_bf16 v[16:19], v[128:131], v[210:213], v[16:19]
	v_mfma_f32_16x16x32_bf16 v[8:11], v[136:139], v[210:213], v[8:11]
	v_mfma_f32_16x16x32_bf16 v[60:63], v[132:135], v[184:187], v[60:63]
	v_mfma_f32_16x16x32_bf16 v[56:59], v[140:143], v[184:187], v[56:59]
	v_mfma_f32_16x16x32_bf16 v[48:51], v[132:135], v[192:195], v[48:51]
	v_mfma_f32_16x16x32_bf16 v[40:43], v[140:143], v[192:195], v[40:43]
	v_mfma_f32_16x16x32_bf16 v[32:35], v[132:135], v[206:209], v[32:35]
	v_mfma_f32_16x16x32_bf16 v[24:27], v[140:143], v[206:209], v[24:27]
	v_mfma_f32_16x16x32_bf16 v[16:19], v[132:135], v[214:217], v[16:19]
	v_mfma_f32_16x16x32_bf16 v[8:11], v[140:143], v[214:217], v[8:11]
	v_mfma_f32_16x16x32_bf16 v[52:55], v[156:159], v[180:183], v[52:55]
	v_mfma_f32_16x16x32_bf16 v[44:47], v[168:171], v[180:183], v[44:47]
	v_mfma_f32_16x16x32_bf16 v[36:39], v[156:159], v[188:191], v[36:39]
	v_mfma_f32_16x16x32_bf16 v[28:31], v[168:171], v[188:191], v[28:31]
	v_mfma_f32_16x16x32_bf16 v[20:23], v[156:159], v[196:199], v[20:23]
	v_mfma_f32_16x16x32_bf16 v[12:15], v[168:171], v[196:199], v[12:15]
	v_mfma_f32_16x16x32_bf16 v[4:7], v[156:159], v[210:213], v[4:7]
	v_mfma_f32_16x16x32_bf16 v[0:3], v[168:171], v[210:213], v[0:3]
	v_mfma_f32_16x16x32_bf16 v[52:55], v[164:167], v[184:187], v[52:55]
	v_mfma_f32_16x16x32_bf16 v[44:47], v[176:179], v[184:187], v[44:47]
	v_mfma_f32_16x16x32_bf16 v[36:39], v[164:167], v[192:195], v[36:39]
	v_mfma_f32_16x16x32_bf16 v[28:31], v[176:179], v[192:195], v[28:31]
	v_mfma_f32_16x16x32_bf16 v[20:23], v[164:167], v[206:209], v[20:23]
	v_mfma_f32_16x16x32_bf16 v[12:15], v[176:179], v[206:209], v[12:15]
	v_mfma_f32_16x16x32_bf16 v[4:7], v[164:167], v[214:217], v[4:7]
	v_mfma_f32_16x16x32_bf16 v[0:3], v[176:179], v[214:217], v[0:3]
	s_barrier
	s_setprio 0
	s_add_i32 s20, 0, 0x18000
	s_add_i32 s21, 0, 0x1c000
	v_add_u32_e32 v140, s20, v174
	v_add_u32_e32 v162, s21, v174
	ds_read_b128 v[128:131], v140
	ds_read_b128 v[132:135], v140 offset:1024
	ds_read_b128 v[136:139], v140 offset:2048
	ds_read_b128 v[140:143], v140 offset:3072
	ds_read_b128 v[156:159], v162
	ds_read_b128 v[164:167], v162 offset:1024
	ds_read_b128 v[168:171], v162 offset:2048
	ds_read_b128 v[176:179], v162 offset:3072
	s_add_u32 s18, s58, 0xb0000
	s_addc_u32 s19, s59, 0
	s_mov_b32 m0, s6
	v_lshl_add_u64 v[224:225], s[18:19], 0, v[150:151]
	ds_read_b128 v[180:183], v175 offset:32768
	ds_read_b128 v[184:187], v175 offset:33792
	ds_read_b128 v[188:191], v175 offset:34816
	ds_read_b128 v[192:195], v175 offset:35840
	ds_read_b128 v[196:199], v175 offset:36864
	ds_read_b128 v[206:209], v175 offset:37888
	ds_read_b128 v[210:213], v175 offset:38912
	ds_read_b128 v[214:217], v175 offset:39936
	global_load_lds_dwordx4 v[224:225], off
	v_lshl_add_u64 v[224:225], s[18:19], 0, v[146:147]
	s_mov_b32 m0, s7
	s_nop 0
	global_load_lds_dwordx4 v[224:225], off
	s_waitcnt vmcnt(8)
	s_waitcnt lgkmcnt(0)
	s_setprio 1
	s_barrier
	v_mfma_f32_16x16x32_bf16 v[124:127], v[128:131], v[180:183], v[124:127]
	v_mfma_f32_16x16x32_bf16 v[120:123], v[136:139], v[180:183], v[120:123]
	v_mfma_f32_16x16x32_bf16 v[112:115], v[128:131], v[188:191], v[112:115]
	v_mfma_f32_16x16x32_bf16 v[104:107], v[136:139], v[188:191], v[104:107]
	v_mfma_f32_16x16x32_bf16 v[96:99], v[128:131], v[196:199], v[96:99]
	v_mfma_f32_16x16x32_bf16 v[88:91], v[136:139], v[196:199], v[88:91]
	v_mfma_f32_16x16x32_bf16 v[80:83], v[128:131], v[210:213], v[80:83]
	v_mfma_f32_16x16x32_bf16 v[72:75], v[136:139], v[210:213], v[72:75]
	v_mfma_f32_16x16x32_bf16 v[124:127], v[132:135], v[184:187], v[124:127]
	v_mfma_f32_16x16x32_bf16 v[120:123], v[140:143], v[184:187], v[120:123]
	v_mfma_f32_16x16x32_bf16 v[112:115], v[132:135], v[192:195], v[112:115]
	v_mfma_f32_16x16x32_bf16 v[104:107], v[140:143], v[192:195], v[104:107]
	v_mfma_f32_16x16x32_bf16 v[96:99], v[132:135], v[206:209], v[96:99]
	v_mfma_f32_16x16x32_bf16 v[88:91], v[140:143], v[206:209], v[88:91]
	v_mfma_f32_16x16x32_bf16 v[80:83], v[132:135], v[214:217], v[80:83]
	v_mfma_f32_16x16x32_bf16 v[72:75], v[140:143], v[214:217], v[72:75]
	v_mfma_f32_16x16x32_bf16 v[116:119], v[156:159], v[180:183], v[116:119]
	v_mfma_f32_16x16x32_bf16 v[108:111], v[168:171], v[180:183], v[108:111]
	v_mfma_f32_16x16x32_bf16 v[100:103], v[156:159], v[188:191], v[100:103]
	v_mfma_f32_16x16x32_bf16 v[92:95], v[168:171], v[188:191], v[92:95]
	v_mfma_f32_16x16x32_bf16 v[84:87], v[156:159], v[196:199], v[84:87]
	v_mfma_f32_16x16x32_bf16 v[76:79], v[168:171], v[196:199], v[76:79]
	v_mfma_f32_16x16x32_bf16 v[68:71], v[156:159], v[210:213], v[68:71]
	v_mfma_f32_16x16x32_bf16 v[64:67], v[168:171], v[210:213], v[64:67]
	v_mfma_f32_16x16x32_bf16 v[116:119], v[164:167], v[184:187], v[116:119]
	v_mfma_f32_16x16x32_bf16 v[108:111], v[176:179], v[184:187], v[108:111]
	v_mfma_f32_16x16x32_bf16 v[100:103], v[164:167], v[192:195], v[100:103]
	v_mfma_f32_16x16x32_bf16 v[92:95], v[176:179], v[192:195], v[92:95]
	v_mfma_f32_16x16x32_bf16 v[84:87], v[164:167], v[206:209], v[84:87]
	v_mfma_f32_16x16x32_bf16 v[76:79], v[176:179], v[206:209], v[76:79]
	v_mfma_f32_16x16x32_bf16 v[68:71], v[164:167], v[214:217], v[68:71]
	v_mfma_f32_16x16x32_bf16 v[64:67], v[176:179], v[214:217], v[64:67]
	s_barrier
	s_setprio 0
	s_add_i32 s18, s20, s46
	v_lshl_add_u64 v[200:201], v[200:201], 0, s[76:77]
	s_mov_b32 m0, s18
	ds_read_b128 v[180:183], v175 offset:49152
	ds_read_b128 v[184:187], v175 offset:50176
	ds_read_b128 v[188:191], v175 offset:51200
	ds_read_b128 v[192:195], v175 offset:52224
	ds_read_b128 v[196:199], v175 offset:53248
	ds_read_b128 v[206:209], v175 offset:54272
	ds_read_b128 v[210:213], v175 offset:55296
	ds_read_b128 v[214:217], v175 offset:56320
	global_load_lds_dwordx4 v[200:201], off
	s_add_i32 m0, s18, 0x2000
	s_add_u32 s18, s50, 0xb0080
	v_lshl_add_u64 v[200:201], v[218:219], 0, s[76:77]
	s_addc_u32 s19, s51, 0
	s_add_i32 s20, s21, s46
	global_load_lds_dwordx4 v[200:201], off
	v_lshl_add_u64 v[200:201], s[18:19], 0, v[148:149]
	s_mov_b32 m0, s20
	s_nop 0
	global_load_lds_dwordx4 v[200:201], off
	v_lshl_add_u64 v[200:201], s[18:19], 0, v[144:145]
	s_add_i32 m0, s20, 0x2000
	s_nop 0
	global_load_lds_dwordx4 v[200:201], off
	v_lshl_add_u64 v[200:201], v[220:221], 0, s[76:77]
	s_mov_b32 m0, s11
	s_nop 0
	global_load_lds_dwordx4 v[200:201], off
	v_lshl_add_u64 v[200:201], v[222:223], 0, s[76:77]
	s_mov_b32 m0, s12
	s_nop 0
	global_load_lds_dwordx4 v[200:201], off
	s_waitcnt vmcnt(8)
	s_waitcnt lgkmcnt(0)
	s_setprio 1
	s_barrier
	v_mfma_f32_16x16x32_bf16 v[60:63], v[128:131], v[180:183], v[60:63]
	v_mfma_f32_16x16x32_bf16 v[56:59], v[136:139], v[180:183], v[56:59]
	v_mfma_f32_16x16x32_bf16 v[48:51], v[128:131], v[188:191], v[48:51]
	v_mfma_f32_16x16x32_bf16 v[40:43], v[136:139], v[188:191], v[40:43]
	v_mfma_f32_16x16x32_bf16 v[32:35], v[128:131], v[196:199], v[32:35]
	v_mfma_f32_16x16x32_bf16 v[24:27], v[136:139], v[196:199], v[24:27]
	v_mfma_f32_16x16x32_bf16 v[16:19], v[128:131], v[210:213], v[16:19]
	v_mfma_f32_16x16x32_bf16 v[8:11], v[136:139], v[210:213], v[8:11]
	v_mfma_f32_16x16x32_bf16 v[60:63], v[132:135], v[184:187], v[60:63]
	v_mfma_f32_16x16x32_bf16 v[56:59], v[140:143], v[184:187], v[56:59]
	v_mfma_f32_16x16x32_bf16 v[48:51], v[132:135], v[192:195], v[48:51]
	v_mfma_f32_16x16x32_bf16 v[40:43], v[140:143], v[192:195], v[40:43]
	v_mfma_f32_16x16x32_bf16 v[32:35], v[132:135], v[206:209], v[32:35]
	v_mfma_f32_16x16x32_bf16 v[24:27], v[140:143], v[206:209], v[24:27]
	v_mfma_f32_16x16x32_bf16 v[16:19], v[132:135], v[214:217], v[16:19]
	v_mfma_f32_16x16x32_bf16 v[8:11], v[140:143], v[214:217], v[8:11]
	v_mfma_f32_16x16x32_bf16 v[52:55], v[156:159], v[180:183], v[52:55]
	v_mfma_f32_16x16x32_bf16 v[44:47], v[168:171], v[180:183], v[44:47]
	v_mfma_f32_16x16x32_bf16 v[36:39], v[156:159], v[188:191], v[36:39]
	v_mfma_f32_16x16x32_bf16 v[28:31], v[168:171], v[188:191], v[28:31]
	v_mfma_f32_16x16x32_bf16 v[20:23], v[156:159], v[196:199], v[20:23]
	v_mfma_f32_16x16x32_bf16 v[12:15], v[168:171], v[196:199], v[12:15]
	v_mfma_f32_16x16x32_bf16 v[4:7], v[156:159], v[210:213], v[4:7]
	v_mfma_f32_16x16x32_bf16 v[0:3], v[168:171], v[210:213], v[0:3]
	v_mfma_f32_16x16x32_bf16 v[52:55], v[164:167], v[184:187], v[52:55]
	v_mfma_f32_16x16x32_bf16 v[44:47], v[176:179], v[184:187], v[44:47]
	v_mfma_f32_16x16x32_bf16 v[36:39], v[164:167], v[192:195], v[36:39]
	v_mfma_f32_16x16x32_bf16 v[28:31], v[176:179], v[192:195], v[28:31]
	v_mfma_f32_16x16x32_bf16 v[20:23], v[164:167], v[206:209], v[20:23]
	v_mfma_f32_16x16x32_bf16 v[12:15], v[176:179], v[206:209], v[12:15]
	v_mfma_f32_16x16x32_bf16 v[4:7], v[164:167], v[214:217], v[4:7]
	v_mfma_f32_16x16x32_bf16 v[0:3], v[176:179], v[214:217], v[0:3]
	s_barrier
	s_setprio 0
	s_add_i32 s61, s61, 2
	s_add_u32 s54, s54, 0x100
	s_addc_u32 s60, s60, 0
	s_cmp_gt_u32 s61, 41
	s_mov_b64 s[42:43], s[48:49]
	s_cbranch_scc0 .LBB0_1210

.LBB0_1234:
	s_add_u32 s43, s58, 0x100
	s_addc_u32 s46, s59, 0
	s_mov_b32 s47, -2
	s_add_u32 s58, s48, 0x100
	s_addc_u32 s59, s49, 0
	s_add_i32 s18, 0, 0x10000
	s_cmp_eq_u32 s47, 18
	s_cselect_b32 s61, s39, s59
	s_cselect_b32 s60, s38, s58
	v_add_u32_e32 v158, s18, v152
	s_cselect_b32 s51, s41, s46
	s_cselect_b32 s50, s40, s43
	s_add_i32 s20, 0, 0x14000
	ds_read_b128 v[154:157], v158
	ds_read_b128 v[164:167], v158 offset:1024
	ds_read_b128 v[168:171], v158 offset:2048
	ds_read_b128 v[172:175], v158 offset:3072
	v_add_u32_e32 v158, s20, v152
	ds_read_b128 v[176:179], v158
	ds_read_b128 v[180:183], v158 offset:1024
	ds_read_b128 v[184:187], v158 offset:2048
	ds_read_b128 v[188:191], v158 offset:3072
	v_lshl_add_u64 v[158:159], s[48:49], 0, v[148:149]
	s_add_i32 m0, s5, 0xc000
	ds_read_b128 v[192:195], v153
	ds_read_b128 v[196:199], v153 offset:1024
	ds_read_b128 v[206:209], v153 offset:2048
	ds_read_b128 v[210:213], v153 offset:3072
	ds_read_b128 v[214:217], v153 offset:4096
	ds_read_b128 v[218:221], v153 offset:5120
	ds_read_b128 v[222:225], v153 offset:6144
	ds_read_b128 v[226:229], v153 offset:7168
	global_load_lds_dwordx4 v[158:159], off
	v_lshl_add_u64 v[158:159], s[48:49], 0, v[150:151]
	s_add_i32 m0, s5, 0xe000
	s_nop 0
	global_load_lds_dwordx4 v[158:159], off
	s_waitcnt vmcnt(8)
	s_waitcnt lgkmcnt(0)
	s_setprio 1
	s_barrier
	v_mfma_f32_16x16x32_bf16 v[124:127], v[154:157], v[192:195], 0
	v_mfma_f32_16x16x32_bf16 v[120:123], v[168:171], v[192:195], 0
	v_mfma_f32_16x16x32_bf16 v[116:119], v[154:157], v[206:209], 0
	v_mfma_f32_16x16x32_bf16 v[112:115], v[168:171], v[206:209], 0
	v_mfma_f32_16x16x32_bf16 v[108:111], v[154:157], v[214:217], 0
	v_mfma_f32_16x16x32_bf16 v[104:107], v[168:171], v[214:217], 0
	v_mfma_f32_16x16x32_bf16 v[96:99], v[154:157], v[222:225], 0
	v_mfma_f32_16x16x32_bf16 v[88:91], v[168:171], v[222:225], 0
	v_mfma_f32_16x16x32_bf16 v[124:127], v[164:167], v[196:199], v[124:127]
	v_mfma_f32_16x16x32_bf16 v[120:123], v[172:175], v[196:199], v[120:123]
	v_mfma_f32_16x16x32_bf16 v[116:119], v[164:167], v[210:213], v[116:119]
	v_mfma_f32_16x16x32_bf16 v[112:115], v[172:175], v[210:213], v[112:115]
	v_mfma_f32_16x16x32_bf16 v[108:111], v[164:167], v[218:221], v[108:111]
	v_mfma_f32_16x16x32_bf16 v[104:107], v[172:175], v[218:221], v[104:107]
	v_mfma_f32_16x16x32_bf16 v[96:99], v[164:167], v[226:229], v[96:99]
	v_mfma_f32_16x16x32_bf16 v[88:91], v[172:175], v[226:229], v[88:91]
	v_mfma_f32_16x16x32_bf16 v[100:103], v[176:179], v[192:195], 0
	v_mfma_f32_16x16x32_bf16 v[92:95], v[184:187], v[192:195], 0
	v_mfma_f32_16x16x32_bf16 v[84:87], v[176:179], v[206:209], 0
	v_mfma_f32_16x16x32_bf16 v[80:83], v[184:187], v[206:209], 0
	v_mfma_f32_16x16x32_bf16 v[76:79], v[176:179], v[214:217], 0
	v_mfma_f32_16x16x32_bf16 v[72:75], v[184:187], v[214:217], 0
	v_mfma_f32_16x16x32_bf16 v[68:71], v[176:179], v[222:225], 0
	v_mfma_f32_16x16x32_bf16 v[64:67], v[184:187], v[222:225], 0
	v_mfma_f32_16x16x32_bf16 v[100:103], v[180:183], v[196:199], v[100:103]
	v_mfma_f32_16x16x32_bf16 v[92:95], v[188:191], v[196:199], v[92:95]
	v_mfma_f32_16x16x32_bf16 v[84:87], v[180:183], v[210:213], v[84:87]
	v_mfma_f32_16x16x32_bf16 v[80:83], v[188:191], v[210:213], v[80:83]
	v_mfma_f32_16x16x32_bf16 v[76:79], v[180:183], v[218:221], v[76:79]
	v_mfma_f32_16x16x32_bf16 v[72:75], v[188:191], v[218:221], v[72:75]
	v_mfma_f32_16x16x32_bf16 v[68:71], v[180:183], v[226:229], v[68:71]
	v_mfma_f32_16x16x32_bf16 v[64:67], v[188:191], v[226:229], v[64:67]
	s_barrier
	s_setprio 0
	s_add_i32 s18, s18, s4
	v_lshl_add_u64 v[158:159], s[50:51], 0, v[130:131]
	s_mov_b32 m0, s18
	ds_read_b128 v[192:195], v153 offset:16384
	ds_read_b128 v[196:199], v153 offset:17408
	ds_read_b128 v[206:209], v153 offset:18432
	ds_read_b128 v[210:213], v153 offset:19456
	ds_read_b128 v[214:217], v153 offset:20480
	ds_read_b128 v[218:221], v153 offset:21504
	ds_read_b128 v[222:225], v153 offset:22528
	ds_read_b128 v[226:229], v153 offset:23552
	global_load_lds_dwordx4 v[158:159], off
	s_add_i32 m0, s18, 0x2000
	s_add_u32 s18, s50, 0xb0000
	v_lshl_add_u64 v[200:201], s[50:51], 0, v[128:129]
	s_addc_u32 s19, s51, 0
	s_add_i32 s20, s20, s4
	global_load_lds_dwordx4 v[200:201], off
	v_lshl_add_u64 v[230:231], s[18:19], 0, v[130:131]
	s_mov_b32 m0, s20
	v_lshl_add_u64 v[232:233], s[60:61], 0, v[128:129]
	global_load_lds_dwordx4 v[230:231], off
	v_lshl_add_u64 v[230:231], s[18:19], 0, v[128:129]
	s_add_i32 m0, s20, 0x2000
	s_nop 0
	global_load_lds_dwordx4 v[230:231], off
	v_lshl_add_u64 v[230:231], s[60:61], 0, v[130:131]
	s_mov_b32 m0, s5
	s_nop 0
	global_load_lds_dwordx4 v[230:231], off
	s_mov_b32 m0, s6
	s_nop 0
	global_load_lds_dwordx4 v[232:233], off
	s_waitcnt vmcnt(8)
	s_waitcnt lgkmcnt(0)
	s_setprio 1
	s_barrier
	v_mfma_f32_16x16x32_bf16 v[60:63], v[154:157], v[192:195], 0
	v_mfma_f32_16x16x32_bf16 v[56:59], v[168:171], v[192:195], 0
	v_mfma_f32_16x16x32_bf16 v[52:55], v[154:157], v[206:209], 0
	v_mfma_f32_16x16x32_bf16 v[48:51], v[168:171], v[206:209], 0
	v_mfma_f32_16x16x32_bf16 v[44:47], v[154:157], v[214:217], 0
	v_mfma_f32_16x16x32_bf16 v[40:43], v[168:171], v[214:217], 0
	v_mfma_f32_16x16x32_bf16 v[32:35], v[154:157], v[222:225], 0
	v_mfma_f32_16x16x32_bf16 v[24:27], v[168:171], v[222:225], 0
	v_mfma_f32_16x16x32_bf16 v[60:63], v[164:167], v[196:199], v[60:63]
	v_mfma_f32_16x16x32_bf16 v[56:59], v[172:175], v[196:199], v[56:59]
	v_mfma_f32_16x16x32_bf16 v[52:55], v[164:167], v[210:213], v[52:55]
	v_mfma_f32_16x16x32_bf16 v[48:51], v[172:175], v[210:213], v[48:51]
	v_mfma_f32_16x16x32_bf16 v[44:47], v[164:167], v[218:221], v[44:47]
	v_mfma_f32_16x16x32_bf16 v[40:43], v[172:175], v[218:221], v[40:43]
	v_mfma_f32_16x16x32_bf16 v[32:35], v[164:167], v[226:229], v[32:35]
	v_mfma_f32_16x16x32_bf16 v[24:27], v[172:175], v[226:229], v[24:27]
	v_mfma_f32_16x16x32_bf16 v[36:39], v[176:179], v[192:195], 0
	v_mfma_f32_16x16x32_bf16 v[28:31], v[184:187], v[192:195], 0
	v_mfma_f32_16x16x32_bf16 v[20:23], v[176:179], v[206:209], 0
	v_mfma_f32_16x16x32_bf16 v[16:19], v[184:187], v[206:209], 0
	v_mfma_f32_16x16x32_bf16 v[12:15], v[176:179], v[214:217], 0
	v_mfma_f32_16x16x32_bf16 v[8:11], v[184:187], v[214:217], 0
	v_mfma_f32_16x16x32_bf16 v[4:7], v[176:179], v[222:225], 0
	v_mfma_f32_16x16x32_bf16 v[0:3], v[184:187], v[222:225], 0
	v_mfma_f32_16x16x32_bf16 v[36:39], v[180:183], v[196:199], v[36:39]
	v_mfma_f32_16x16x32_bf16 v[28:31], v[188:191], v[196:199], v[28:31]
	v_mfma_f32_16x16x32_bf16 v[20:23], v[180:183], v[210:213], v[20:23]
	v_mfma_f32_16x16x32_bf16 v[16:19], v[188:191], v[210:213], v[16:19]
	v_mfma_f32_16x16x32_bf16 v[12:15], v[180:183], v[218:221], v[12:15]
	v_mfma_f32_16x16x32_bf16 v[8:11], v[188:191], v[218:221], v[8:11]
	v_mfma_f32_16x16x32_bf16 v[4:7], v[180:183], v[226:229], v[4:7]
	v_mfma_f32_16x16x32_bf16 v[0:3], v[188:191], v[226:229], v[0:3]
	s_barrier
	s_setprio 0
	s_add_i32 s20, 0, 0x18000
	s_add_i32 s21, 0, 0x1c000
	v_add_u32_e32 v172, s20, v152
	v_add_u32_e32 v188, s21, v152
	ds_read_b128 v[154:157], v172
	ds_read_b128 v[164:167], v172 offset:1024
	ds_read_b128 v[168:171], v172 offset:2048
	ds_read_b128 v[172:175], v172 offset:3072
	ds_read_b128 v[176:179], v188
	ds_read_b128 v[180:183], v188 offset:1024
	ds_read_b128 v[184:187], v188 offset:2048
	ds_read_b128 v[188:191], v188 offset:3072
	s_add_u32 s18, s60, 0xb0000
	s_addc_u32 s19, s61, 0
	s_mov_b32 m0, s7
	v_lshl_add_u64 v[234:235], s[18:19], 0, v[130:131]
	ds_read_b128 v[192:195], v153 offset:32768
	ds_read_b128 v[196:199], v153 offset:33792
	ds_read_b128 v[206:209], v153 offset:34816
	ds_read_b128 v[210:213], v153 offset:35840
	ds_read_b128 v[214:217], v153 offset:36864
	ds_read_b128 v[218:221], v153 offset:37888
	ds_read_b128 v[222:225], v153 offset:38912
	ds_read_b128 v[226:229], v153 offset:39936
	global_load_lds_dwordx4 v[234:235], off
	v_lshl_add_u64 v[234:235], s[18:19], 0, v[128:129]
	s_mov_b32 m0, s8
	s_nop 0
	global_load_lds_dwordx4 v[234:235], off
	s_waitcnt vmcnt(8)
	s_waitcnt lgkmcnt(0)
	s_setprio 1
	s_barrier
	v_mfma_f32_16x16x32_bf16 v[124:127], v[154:157], v[192:195], v[124:127]
	v_mfma_f32_16x16x32_bf16 v[120:123], v[168:171], v[192:195], v[120:123]
	v_mfma_f32_16x16x32_bf16 v[116:119], v[154:157], v[206:209], v[116:119]
	v_mfma_f32_16x16x32_bf16 v[112:115], v[168:171], v[206:209], v[112:115]
	v_mfma_f32_16x16x32_bf16 v[108:111], v[154:157], v[214:217], v[108:111]
	v_mfma_f32_16x16x32_bf16 v[104:107], v[168:171], v[214:217], v[104:107]
	v_mfma_f32_16x16x32_bf16 v[96:99], v[154:157], v[222:225], v[96:99]
	v_mfma_f32_16x16x32_bf16 v[88:91], v[168:171], v[222:225], v[88:91]
	v_mfma_f32_16x16x32_bf16 v[124:127], v[164:167], v[196:199], v[124:127]
	v_mfma_f32_16x16x32_bf16 v[120:123], v[172:175], v[196:199], v[120:123]
	v_mfma_f32_16x16x32_bf16 v[116:119], v[164:167], v[210:213], v[116:119]
	v_mfma_f32_16x16x32_bf16 v[112:115], v[172:175], v[210:213], v[112:115]
	v_mfma_f32_16x16x32_bf16 v[108:111], v[164:167], v[218:221], v[108:111]
	v_mfma_f32_16x16x32_bf16 v[104:107], v[172:175], v[218:221], v[104:107]
	v_mfma_f32_16x16x32_bf16 v[96:99], v[164:167], v[226:229], v[96:99]
	v_mfma_f32_16x16x32_bf16 v[88:91], v[172:175], v[226:229], v[88:91]
	v_mfma_f32_16x16x32_bf16 v[100:103], v[176:179], v[192:195], v[100:103]
	v_mfma_f32_16x16x32_bf16 v[92:95], v[184:187], v[192:195], v[92:95]
	v_mfma_f32_16x16x32_bf16 v[84:87], v[176:179], v[206:209], v[84:87]
	v_mfma_f32_16x16x32_bf16 v[80:83], v[184:187], v[206:209], v[80:83]
	v_mfma_f32_16x16x32_bf16 v[76:79], v[176:179], v[214:217], v[76:79]
	v_mfma_f32_16x16x32_bf16 v[72:75], v[184:187], v[214:217], v[72:75]
	v_mfma_f32_16x16x32_bf16 v[68:71], v[176:179], v[222:225], v[68:71]
	v_mfma_f32_16x16x32_bf16 v[64:67], v[184:187], v[222:225], v[64:67]
	v_mfma_f32_16x16x32_bf16 v[100:103], v[180:183], v[196:199], v[100:103]
	v_mfma_f32_16x16x32_bf16 v[92:95], v[188:191], v[196:199], v[92:95]
	v_mfma_f32_16x16x32_bf16 v[84:87], v[180:183], v[210:213], v[84:87]
	v_mfma_f32_16x16x32_bf16 v[80:83], v[188:191], v[210:213], v[80:83]
	v_mfma_f32_16x16x32_bf16 v[76:79], v[180:183], v[218:221], v[76:79]
	v_mfma_f32_16x16x32_bf16 v[72:75], v[188:191], v[218:221], v[72:75]
	v_mfma_f32_16x16x32_bf16 v[68:71], v[180:183], v[226:229], v[68:71]
	v_mfma_f32_16x16x32_bf16 v[64:67], v[188:191], v[226:229], v[64:67]
	s_barrier
	s_setprio 0
	s_add_i32 s18, s20, s4
	v_lshl_add_u64 v[158:159], v[158:159], 0, s[76:77]
	s_mov_b32 m0, s18
	ds_read_b128 v[192:195], v153 offset:49152
	ds_read_b128 v[196:199], v153 offset:50176
	ds_read_b128 v[206:209], v153 offset:51200
	ds_read_b128 v[210:213], v153 offset:52224
	ds_read_b128 v[214:217], v153 offset:53248
	ds_read_b128 v[218:221], v153 offset:54272
	ds_read_b128 v[222:225], v153 offset:55296
	ds_read_b128 v[226:229], v153 offset:56320
	global_load_lds_dwordx4 v[158:159], off
	s_add_i32 m0, s18, 0x2000
	s_add_u32 s18, s50, 0xb0080
	v_lshl_add_u64 v[158:159], v[200:201], 0, s[76:77]
	s_addc_u32 s19, s51, 0
	s_add_i32 s20, s21, s4
	global_load_lds_dwordx4 v[158:159], off
	v_lshl_add_u64 v[158:159], s[18:19], 0, v[130:131]
	s_mov_b32 m0, s20
	s_nop 0
	global_load_lds_dwordx4 v[158:159], off
	v_lshl_add_u64 v[158:159], s[18:19], 0, v[128:129]
	s_add_i32 m0, s20, 0x2000
	s_nop 0
	global_load_lds_dwordx4 v[158:159], off
	v_lshl_add_u64 v[158:159], v[230:231], 0, s[76:77]
	s_mov_b32 m0, s9
	s_nop 0
	global_load_lds_dwordx4 v[158:159], off
	v_lshl_add_u64 v[158:159], v[232:233], 0, s[76:77]
	s_mov_b32 m0, s10
	s_nop 0
	global_load_lds_dwordx4 v[158:159], off
	s_waitcnt vmcnt(8)
	s_waitcnt lgkmcnt(0)
	s_setprio 1
	s_barrier
	v_mfma_f32_16x16x32_bf16 v[60:63], v[154:157], v[192:195], v[60:63]
	v_mfma_f32_16x16x32_bf16 v[56:59], v[168:171], v[192:195], v[56:59]
	v_mfma_f32_16x16x32_bf16 v[52:55], v[154:157], v[206:209], v[52:55]
	v_mfma_f32_16x16x32_bf16 v[48:51], v[168:171], v[206:209], v[48:51]
	v_mfma_f32_16x16x32_bf16 v[44:47], v[154:157], v[214:217], v[44:47]
	v_mfma_f32_16x16x32_bf16 v[40:43], v[168:171], v[214:217], v[40:43]
	v_mfma_f32_16x16x32_bf16 v[32:35], v[154:157], v[222:225], v[32:35]
	v_mfma_f32_16x16x32_bf16 v[24:27], v[168:171], v[222:225], v[24:27]
	v_mfma_f32_16x16x32_bf16 v[60:63], v[164:167], v[196:199], v[60:63]
	v_mfma_f32_16x16x32_bf16 v[56:59], v[172:175], v[196:199], v[56:59]
	v_mfma_f32_16x16x32_bf16 v[52:55], v[164:167], v[210:213], v[52:55]
	v_mfma_f32_16x16x32_bf16 v[48:51], v[172:175], v[210:213], v[48:51]
	v_mfma_f32_16x16x32_bf16 v[44:47], v[164:167], v[218:221], v[44:47]
	v_mfma_f32_16x16x32_bf16 v[40:43], v[172:175], v[218:221], v[40:43]
	v_mfma_f32_16x16x32_bf16 v[32:35], v[164:167], v[226:229], v[32:35]
	v_mfma_f32_16x16x32_bf16 v[24:27], v[172:175], v[226:229], v[24:27]
	v_mfma_f32_16x16x32_bf16 v[36:39], v[176:179], v[192:195], v[36:39]
	v_mfma_f32_16x16x32_bf16 v[28:31], v[184:187], v[192:195], v[28:31]
	v_mfma_f32_16x16x32_bf16 v[20:23], v[176:179], v[206:209], v[20:23]
	v_mfma_f32_16x16x32_bf16 v[16:19], v[184:187], v[206:209], v[16:19]
	v_mfma_f32_16x16x32_bf16 v[12:15], v[176:179], v[214:217], v[12:15]
	v_mfma_f32_16x16x32_bf16 v[8:11], v[184:187], v[214:217], v[8:11]
	v_mfma_f32_16x16x32_bf16 v[4:7], v[176:179], v[222:225], v[4:7]
	v_mfma_f32_16x16x32_bf16 v[0:3], v[184:187], v[222:225], v[0:3]
	v_mfma_f32_16x16x32_bf16 v[36:39], v[180:183], v[196:199], v[36:39]
	v_mfma_f32_16x16x32_bf16 v[28:31], v[188:191], v[196:199], v[28:31]
	v_mfma_f32_16x16x32_bf16 v[20:23], v[180:183], v[210:213], v[20:23]
	v_mfma_f32_16x16x32_bf16 v[16:19], v[188:191], v[210:213], v[16:19]
	v_mfma_f32_16x16x32_bf16 v[12:15], v[180:183], v[218:221], v[12:15]
	v_mfma_f32_16x16x32_bf16 v[8:11], v[188:191], v[218:221], v[8:11]
	v_mfma_f32_16x16x32_bf16 v[4:7], v[180:183], v[226:229], v[4:7]
	v_mfma_f32_16x16x32_bf16 v[0:3], v[188:191], v[226:229], v[0:3]
	s_barrier
	s_setprio 0
	s_add_i32 s47, s47, 2
	s_add_u32 s43, s43, 0x100
	s_addc_u32 s46, s46, 0
	s_cmp_gt_u32 s47, 19
	s_mov_b64 s[48:49], s[58:59]
	s_cbranch_scc0 .LBB0_1235
	s_branch .Lpeel_x_1235
.LBB0_1235:
	s_add_u32 s58, s48, 0x100
	s_addc_u32 s59, s49, 0
	s_add_i32 s18, 0, 0x10000
	s_cmp_eq_u32 s47, 18
	s_cselect_b32 s61, s39, s59
	s_cselect_b32 s60, s38, s58
	v_add_u32_e32 v158, s18, v152
	s_cselect_b32 s51, s41, s46
	s_cselect_b32 s50, s40, s43
	s_add_i32 s20, 0, 0x14000
	ds_read_b128 v[154:157], v158
	ds_read_b128 v[164:167], v158 offset:1024
	ds_read_b128 v[168:171], v158 offset:2048
	ds_read_b128 v[172:175], v158 offset:3072
	v_add_u32_e32 v158, s20, v152
	ds_read_b128 v[176:179], v158
	ds_read_b128 v[180:183], v158 offset:1024
	ds_read_b128 v[184:187], v158 offset:2048
	ds_read_b128 v[188:191], v158 offset:3072
	v_lshl_add_u64 v[158:159], s[48:49], 0, v[148:149]
	s_add_i32 m0, s5, 0xc000
	ds_read_b128 v[192:195], v153
	ds_read_b128 v[196:199], v153 offset:1024
	ds_read_b128 v[206:209], v153 offset:2048
	ds_read_b128 v[210:213], v153 offset:3072
	ds_read_b128 v[214:217], v153 offset:4096
	ds_read_b128 v[218:221], v153 offset:5120
	ds_read_b128 v[222:225], v153 offset:6144
	ds_read_b128 v[226:229], v153 offset:7168
	global_load_lds_dwordx4 v[158:159], off
	v_lshl_add_u64 v[158:159], s[48:49], 0, v[150:151]
	s_add_i32 m0, s5, 0xe000
	s_nop 0
	global_load_lds_dwordx4 v[158:159], off
	s_waitcnt vmcnt(8)
	s_waitcnt lgkmcnt(0)
	s_setprio 1
	s_barrier
	v_mfma_f32_16x16x32_bf16 v[124:127], v[154:157], v[192:195], v[124:127]
	v_mfma_f32_16x16x32_bf16 v[120:123], v[168:171], v[192:195], v[120:123]
	v_mfma_f32_16x16x32_bf16 v[116:119], v[154:157], v[206:209], v[116:119]
	v_mfma_f32_16x16x32_bf16 v[112:115], v[168:171], v[206:209], v[112:115]
	v_mfma_f32_16x16x32_bf16 v[108:111], v[154:157], v[214:217], v[108:111]
	v_mfma_f32_16x16x32_bf16 v[104:107], v[168:171], v[214:217], v[104:107]
	v_mfma_f32_16x16x32_bf16 v[96:99], v[154:157], v[222:225], v[96:99]
	v_mfma_f32_16x16x32_bf16 v[88:91], v[168:171], v[222:225], v[88:91]
	v_mfma_f32_16x16x32_bf16 v[124:127], v[164:167], v[196:199], v[124:127]
	v_mfma_f32_16x16x32_bf16 v[120:123], v[172:175], v[196:199], v[120:123]
	v_mfma_f32_16x16x32_bf16 v[116:119], v[164:167], v[210:213], v[116:119]
	v_mfma_f32_16x16x32_bf16 v[112:115], v[172:175], v[210:213], v[112:115]
	v_mfma_f32_16x16x32_bf16 v[108:111], v[164:167], v[218:221], v[108:111]
	v_mfma_f32_16x16x32_bf16 v[104:107], v[172:175], v[218:221], v[104:107]
	v_mfma_f32_16x16x32_bf16 v[96:99], v[164:167], v[226:229], v[96:99]
	v_mfma_f32_16x16x32_bf16 v[88:91], v[172:175], v[226:229], v[88:91]
	v_mfma_f32_16x16x32_bf16 v[100:103], v[176:179], v[192:195], v[100:103]
	v_mfma_f32_16x16x32_bf16 v[92:95], v[184:187], v[192:195], v[92:95]
	v_mfma_f32_16x16x32_bf16 v[84:87], v[176:179], v[206:209], v[84:87]
	v_mfma_f32_16x16x32_bf16 v[80:83], v[184:187], v[206:209], v[80:83]
	v_mfma_f32_16x16x32_bf16 v[76:79], v[176:179], v[214:217], v[76:79]
	v_mfma_f32_16x16x32_bf16 v[72:75], v[184:187], v[214:217], v[72:75]
	v_mfma_f32_16x16x32_bf16 v[68:71], v[176:179], v[222:225], v[68:71]
	v_mfma_f32_16x16x32_bf16 v[64:67], v[184:187], v[222:225], v[64:67]
	v_mfma_f32_16x16x32_bf16 v[100:103], v[180:183], v[196:199], v[100:103]
	v_mfma_f32_16x16x32_bf16 v[92:95], v[188:191], v[196:199], v[92:95]
	v_mfma_f32_16x16x32_bf16 v[84:87], v[180:183], v[210:213], v[84:87]
	v_mfma_f32_16x16x32_bf16 v[80:83], v[188:191], v[210:213], v[80:83]
	v_mfma_f32_16x16x32_bf16 v[76:79], v[180:183], v[218:221], v[76:79]
	v_mfma_f32_16x16x32_bf16 v[72:75], v[188:191], v[218:221], v[72:75]
	v_mfma_f32_16x16x32_bf16 v[68:71], v[180:183], v[226:229], v[68:71]
	v_mfma_f32_16x16x32_bf16 v[64:67], v[188:191], v[226:229], v[64:67]
	s_barrier
	s_setprio 0
	s_add_i32 s18, s18, s4
	v_lshl_add_u64 v[158:159], s[50:51], 0, v[130:131]
	s_mov_b32 m0, s18
	ds_read_b128 v[192:195], v153 offset:16384
	ds_read_b128 v[196:199], v153 offset:17408
	ds_read_b128 v[206:209], v153 offset:18432
	ds_read_b128 v[210:213], v153 offset:19456
	ds_read_b128 v[214:217], v153 offset:20480
	ds_read_b128 v[218:221], v153 offset:21504
	ds_read_b128 v[222:225], v153 offset:22528
	ds_read_b128 v[226:229], v153 offset:23552
	global_load_lds_dwordx4 v[158:159], off
	s_add_i32 m0, s18, 0x2000
	s_add_u32 s18, s50, 0xb0000
	v_lshl_add_u64 v[200:201], s[50:51], 0, v[128:129]
	s_addc_u32 s19, s51, 0
	s_add_i32 s20, s20, s4
	global_load_lds_dwordx4 v[200:201], off
	v_lshl_add_u64 v[230:231], s[18:19], 0, v[130:131]
	s_mov_b32 m0, s20
	v_lshl_add_u64 v[232:233], s[60:61], 0, v[128:129]
	global_load_lds_dwordx4 v[230:231], off
	v_lshl_add_u64 v[230:231], s[18:19], 0, v[128:129]
	s_add_i32 m0, s20, 0x2000
	s_nop 0
	global_load_lds_dwordx4 v[230:231], off
	v_lshl_add_u64 v[230:231], s[60:61], 0, v[130:131]
	s_mov_b32 m0, s5
	s_nop 0
	global_load_lds_dwordx4 v[230:231], off
	s_mov_b32 m0, s6
	s_nop 0
	global_load_lds_dwordx4 v[232:233], off
	s_waitcnt vmcnt(8)
	s_waitcnt lgkmcnt(0)
	s_setprio 1
	s_barrier
	v_mfma_f32_16x16x32_bf16 v[60:63], v[154:157], v[192:195], v[60:63]
	v_mfma_f32_16x16x32_bf16 v[56:59], v[168:171], v[192:195], v[56:59]
	v_mfma_f32_16x16x32_bf16 v[52:55], v[154:157], v[206:209], v[52:55]
	v_mfma_f32_16x16x32_bf16 v[48:51], v[168:171], v[206:209], v[48:51]
	v_mfma_f32_16x16x32_bf16 v[44:47], v[154:157], v[214:217], v[44:47]
	v_mfma_f32_16x16x32_bf16 v[40:43], v[168:171], v[214:217], v[40:43]
	v_mfma_f32_16x16x32_bf16 v[32:35], v[154:157], v[222:225], v[32:35]
	v_mfma_f32_16x16x32_bf16 v[24:27], v[168:171], v[222:225], v[24:27]
	v_mfma_f32_16x16x32_bf16 v[60:63], v[164:167], v[196:199], v[60:63]
	v_mfma_f32_16x16x32_bf16 v[56:59], v[172:175], v[196:199], v[56:59]
	v_mfma_f32_16x16x32_bf16 v[52:55], v[164:167], v[210:213], v[52:55]
	v_mfma_f32_16x16x32_bf16 v[48:51], v[172:175], v[210:213], v[48:51]
	v_mfma_f32_16x16x32_bf16 v[44:47], v[164:167], v[218:221], v[44:47]
	v_mfma_f32_16x16x32_bf16 v[40:43], v[172:175], v[218:221], v[40:43]
	v_mfma_f32_16x16x32_bf16 v[32:35], v[164:167], v[226:229], v[32:35]
	v_mfma_f32_16x16x32_bf16 v[24:27], v[172:175], v[226:229], v[24:27]
	v_mfma_f32_16x16x32_bf16 v[36:39], v[176:179], v[192:195], v[36:39]
	v_mfma_f32_16x16x32_bf16 v[28:31], v[184:187], v[192:195], v[28:31]
	v_mfma_f32_16x16x32_bf16 v[20:23], v[176:179], v[206:209], v[20:23]
	v_mfma_f32_16x16x32_bf16 v[16:19], v[184:187], v[206:209], v[16:19]
	v_mfma_f32_16x16x32_bf16 v[12:15], v[176:179], v[214:217], v[12:15]
	v_mfma_f32_16x16x32_bf16 v[8:11], v[184:187], v[214:217], v[8:11]
	v_mfma_f32_16x16x32_bf16 v[4:7], v[176:179], v[222:225], v[4:7]
	v_mfma_f32_16x16x32_bf16 v[0:3], v[184:187], v[222:225], v[0:3]
	v_mfma_f32_16x16x32_bf16 v[36:39], v[180:183], v[196:199], v[36:39]
	v_mfma_f32_16x16x32_bf16 v[28:31], v[188:191], v[196:199], v[28:31]
	v_mfma_f32_16x16x32_bf16 v[20:23], v[180:183], v[210:213], v[20:23]
	v_mfma_f32_16x16x32_bf16 v[16:19], v[188:191], v[210:213], v[16:19]
	v_mfma_f32_16x16x32_bf16 v[12:15], v[180:183], v[218:221], v[12:15]
	v_mfma_f32_16x16x32_bf16 v[8:11], v[188:191], v[218:221], v[8:11]
	v_mfma_f32_16x16x32_bf16 v[4:7], v[180:183], v[226:229], v[4:7]
	v_mfma_f32_16x16x32_bf16 v[0:3], v[188:191], v[226:229], v[0:3]
	s_barrier
	s_setprio 0
	s_add_i32 s20, 0, 0x18000
	s_add_i32 s21, 0, 0x1c000
	v_add_u32_e32 v172, s20, v152
	v_add_u32_e32 v188, s21, v152
	ds_read_b128 v[154:157], v172
	ds_read_b128 v[164:167], v172 offset:1024
	ds_read_b128 v[168:171], v172 offset:2048
	ds_read_b128 v[172:175], v172 offset:3072
	ds_read_b128 v[176:179], v188
	ds_read_b128 v[180:183], v188 offset:1024
	ds_read_b128 v[184:187], v188 offset:2048
	ds_read_b128 v[188:191], v188 offset:3072
	s_add_u32 s18, s60, 0xb0000
	s_addc_u32 s19, s61, 0
	s_mov_b32 m0, s7
	v_lshl_add_u64 v[234:235], s[18:19], 0, v[130:131]
	ds_read_b128 v[192:195], v153 offset:32768
	ds_read_b128 v[196:199], v153 offset:33792
	ds_read_b128 v[206:209], v153 offset:34816
	ds_read_b128 v[210:213], v153 offset:35840
	ds_read_b128 v[214:217], v153 offset:36864
	ds_read_b128 v[218:221], v153 offset:37888
	ds_read_b128 v[222:225], v153 offset:38912
	ds_read_b128 v[226:229], v153 offset:39936
	global_load_lds_dwordx4 v[234:235], off
	v_lshl_add_u64 v[234:235], s[18:19], 0, v[128:129]
	s_mov_b32 m0, s8
	s_nop 0
	global_load_lds_dwordx4 v[234:235], off
	s_waitcnt vmcnt(8)
	s_waitcnt lgkmcnt(0)
	s_setprio 1
	s_barrier
	v_mfma_f32_16x16x32_bf16 v[124:127], v[154:157], v[192:195], v[124:127]
	v_mfma_f32_16x16x32_bf16 v[120:123], v[168:171], v[192:195], v[120:123]
	v_mfma_f32_16x16x32_bf16 v[116:119], v[154:157], v[206:209], v[116:119]
	v_mfma_f32_16x16x32_bf16 v[112:115], v[168:171], v[206:209], v[112:115]
	v_mfma_f32_16x16x32_bf16 v[108:111], v[154:157], v[214:217], v[108:111]
	v_mfma_f32_16x16x32_bf16 v[104:107], v[168:171], v[214:217], v[104:107]
	v_mfma_f32_16x16x32_bf16 v[96:99], v[154:157], v[222:225], v[96:99]
	v_mfma_f32_16x16x32_bf16 v[88:91], v[168:171], v[222:225], v[88:91]
	v_mfma_f32_16x16x32_bf16 v[124:127], v[164:167], v[196:199], v[124:127]
	v_mfma_f32_16x16x32_bf16 v[120:123], v[172:175], v[196:199], v[120:123]
	v_mfma_f32_16x16x32_bf16 v[116:119], v[164:167], v[210:213], v[116:119]
	v_mfma_f32_16x16x32_bf16 v[112:115], v[172:175], v[210:213], v[112:115]
	v_mfma_f32_16x16x32_bf16 v[108:111], v[164:167], v[218:221], v[108:111]
	v_mfma_f32_16x16x32_bf16 v[104:107], v[172:175], v[218:221], v[104:107]
	v_mfma_f32_16x16x32_bf16 v[96:99], v[164:167], v[226:229], v[96:99]
	v_mfma_f32_16x16x32_bf16 v[88:91], v[172:175], v[226:229], v[88:91]
	v_mfma_f32_16x16x32_bf16 v[100:103], v[176:179], v[192:195], v[100:103]
	v_mfma_f32_16x16x32_bf16 v[92:95], v[184:187], v[192:195], v[92:95]
	v_mfma_f32_16x16x32_bf16 v[84:87], v[176:179], v[206:209], v[84:87]
	v_mfma_f32_16x16x32_bf16 v[80:83], v[184:187], v[206:209], v[80:83]
	v_mfma_f32_16x16x32_bf16 v[76:79], v[176:179], v[214:217], v[76:79]
	v_mfma_f32_16x16x32_bf16 v[72:75], v[184:187], v[214:217], v[72:75]
	v_mfma_f32_16x16x32_bf16 v[68:71], v[176:179], v[222:225], v[68:71]
	v_mfma_f32_16x16x32_bf16 v[64:67], v[184:187], v[222:225], v[64:67]
	v_mfma_f32_16x16x32_bf16 v[100:103], v[180:183], v[196:199], v[100:103]
	v_mfma_f32_16x16x32_bf16 v[92:95], v[188:191], v[196:199], v[92:95]
	v_mfma_f32_16x16x32_bf16 v[84:87], v[180:183], v[210:213], v[84:87]
	v_mfma_f32_16x16x32_bf16 v[80:83], v[188:191], v[210:213], v[80:83]
	v_mfma_f32_16x16x32_bf16 v[76:79], v[180:183], v[218:221], v[76:79]
	v_mfma_f32_16x16x32_bf16 v[72:75], v[188:191], v[218:221], v[72:75]
	v_mfma_f32_16x16x32_bf16 v[68:71], v[180:183], v[226:229], v[68:71]
	v_mfma_f32_16x16x32_bf16 v[64:67], v[188:191], v[226:229], v[64:67]
	s_barrier
	s_setprio 0
	s_add_i32 s18, s20, s4
	v_lshl_add_u64 v[158:159], v[158:159], 0, s[76:77]
	s_mov_b32 m0, s18
	ds_read_b128 v[192:195], v153 offset:49152
	ds_read_b128 v[196:199], v153 offset:50176
	ds_read_b128 v[206:209], v153 offset:51200
	ds_read_b128 v[210:213], v153 offset:52224
	ds_read_b128 v[214:217], v153 offset:53248
	ds_read_b128 v[218:221], v153 offset:54272
	ds_read_b128 v[222:225], v153 offset:55296
	ds_read_b128 v[226:229], v153 offset:56320
	global_load_lds_dwordx4 v[158:159], off
	s_add_i32 m0, s18, 0x2000
	s_add_u32 s18, s50, 0xb0080
	v_lshl_add_u64 v[158:159], v[200:201], 0, s[76:77]
	s_addc_u32 s19, s51, 0
	s_add_i32 s20, s21, s4
	global_load_lds_dwordx4 v[158:159], off
	v_lshl_add_u64 v[158:159], s[18:19], 0, v[130:131]
	s_mov_b32 m0, s20
	s_nop 0
	global_load_lds_dwordx4 v[158:159], off
	v_lshl_add_u64 v[158:159], s[18:19], 0, v[128:129]
	s_add_i32 m0, s20, 0x2000
	s_nop 0
	global_load_lds_dwordx4 v[158:159], off
	v_lshl_add_u64 v[158:159], v[230:231], 0, s[76:77]
	s_mov_b32 m0, s9
	s_nop 0
	global_load_lds_dwordx4 v[158:159], off
	v_lshl_add_u64 v[158:159], v[232:233], 0, s[76:77]
	s_mov_b32 m0, s10
	s_nop 0
	global_load_lds_dwordx4 v[158:159], off
	s_waitcnt vmcnt(8)
	s_waitcnt lgkmcnt(0)
	s_setprio 1
	s_barrier
	v_mfma_f32_16x16x32_bf16 v[60:63], v[154:157], v[192:195], v[60:63]
	v_mfma_f32_16x16x32_bf16 v[56:59], v[168:171], v[192:195], v[56:59]
	v_mfma_f32_16x16x32_bf16 v[52:55], v[154:157], v[206:209], v[52:55]
	v_mfma_f32_16x16x32_bf16 v[48:51], v[168:171], v[206:209], v[48:51]
	v_mfma_f32_16x16x32_bf16 v[44:47], v[154:157], v[214:217], v[44:47]
	v_mfma_f32_16x16x32_bf16 v[40:43], v[168:171], v[214:217], v[40:43]
	v_mfma_f32_16x16x32_bf16 v[32:35], v[154:157], v[222:225], v[32:35]
	v_mfma_f32_16x16x32_bf16 v[24:27], v[168:171], v[222:225], v[24:27]
	v_mfma_f32_16x16x32_bf16 v[60:63], v[164:167], v[196:199], v[60:63]
	v_mfma_f32_16x16x32_bf16 v[56:59], v[172:175], v[196:199], v[56:59]
	v_mfma_f32_16x16x32_bf16 v[52:55], v[164:167], v[210:213], v[52:55]
	v_mfma_f32_16x16x32_bf16 v[48:51], v[172:175], v[210:213], v[48:51]
	v_mfma_f32_16x16x32_bf16 v[44:47], v[164:167], v[218:221], v[44:47]
	v_mfma_f32_16x16x32_bf16 v[40:43], v[172:175], v[218:221], v[40:43]
	v_mfma_f32_16x16x32_bf16 v[32:35], v[164:167], v[226:229], v[32:35]
	v_mfma_f32_16x16x32_bf16 v[24:27], v[172:175], v[226:229], v[24:27]
	v_mfma_f32_16x16x32_bf16 v[36:39], v[176:179], v[192:195], v[36:39]
	v_mfma_f32_16x16x32_bf16 v[28:31], v[184:187], v[192:195], v[28:31]
	v_mfma_f32_16x16x32_bf16 v[20:23], v[176:179], v[206:209], v[20:23]
	v_mfma_f32_16x16x32_bf16 v[16:19], v[184:187], v[206:209], v[16:19]
	v_mfma_f32_16x16x32_bf16 v[12:15], v[176:179], v[214:217], v[12:15]
	v_mfma_f32_16x16x32_bf16 v[8:11], v[184:187], v[214:217], v[8:11]
	v_mfma_f32_16x16x32_bf16 v[4:7], v[176:179], v[222:225], v[4:7]
	v_mfma_f32_16x16x32_bf16 v[0:3], v[184:187], v[222:225], v[0:3]
	v_mfma_f32_16x16x32_bf16 v[36:39], v[180:183], v[196:199], v[36:39]
	v_mfma_f32_16x16x32_bf16 v[28:31], v[188:191], v[196:199], v[28:31]
	v_mfma_f32_16x16x32_bf16 v[20:23], v[180:183], v[210:213], v[20:23]
	v_mfma_f32_16x16x32_bf16 v[16:19], v[188:191], v[210:213], v[16:19]
	v_mfma_f32_16x16x32_bf16 v[12:15], v[180:183], v[218:221], v[12:15]
	v_mfma_f32_16x16x32_bf16 v[8:11], v[188:191], v[218:221], v[8:11]
	v_mfma_f32_16x16x32_bf16 v[4:7], v[180:183], v[226:229], v[4:7]
	v_mfma_f32_16x16x32_bf16 v[0:3], v[188:191], v[226:229], v[0:3]
	s_barrier
	s_setprio 0
	s_add_i32 s47, s47, 2
	s_add_u32 s43, s43, 0x100
	s_addc_u32 s46, s46, 0
	s_cmp_gt_u32 s47, 19
	s_mov_b64 s[48:49], s[58:59]
	s_cbranch_scc0 .LBB0_1235
